# MMA-path cleanup in GEMM loops: drop setprio 0/1 pairs, raise prio before barrier, drop redundant lgkmcnt(0)
# speedup vs baseline: 1.0087x; 1.0087x over previous
.LBB0_265:
	s_ashr_i32 s45, s44, 31
	ds_read_b128 v[2:5], v150
	ds_read_b128 v[6:9], v150 offset:1024
	ds_read_b128 v[10:13], v150 offset:2048
	ds_read_b128 v[14:17], v150 offset:3072
	ds_read_b128 v[18:21], v151
	ds_read_b128 v[22:25], v151 offset:1024
	ds_read_b128 v[26:29], v151 offset:2048
	ds_read_b128 v[30:33], v151 offset:3072
	s_lshl_b64 s[46:47], s[44:45], 21
	s_add_u32 s46, s26, s46
	s_addc_u32 s47, s27, s47
	s_and_b64 s[48:49], s[4:5], exec
	s_cselect_b32 s45, s47, s55
	s_cselect_b32 s73, s46, s54
	s_ashr_i32 s43, s42, 31
	s_lshl_b64 s[48:49], s[42:43], 21
	s_add_u32 s48, s24, s48
	s_addc_u32 s49, s25, s49
	s_and_b64 s[56:57], s[4:5], exec
	s_cselect_b32 s43, s49, s53
	s_cselect_b32 s74, s48, s52
	s_add_u32 s56, s54, 0x100080
	s_addc_u32 s57, s55, 0
	s_add_i32 s75, s51, 0xc000
	v_lshl_add_u64 v[66:67], s[56:57], 0, v[130:131]
	s_mov_b32 m0, s75
	s_add_i32 s76, s51, 0xe000
	ds_read_b128 v[34:37], v152
	ds_read_b128 v[38:41], v152 offset:1024
	ds_read_b128 v[42:45], v152 offset:2048
	ds_read_b128 v[46:49], v152 offset:3072
	ds_read_b128 v[50:53], v152 offset:4096
	ds_read_b128 v[54:57], v152 offset:5120
	ds_read_b128 v[58:61], v152 offset:6144
	ds_read_b128 v[62:65], v152 offset:7168
	global_load_lds_dwordx4 v[66:67], off
	v_lshl_add_u64 v[66:67], s[56:57], 0, v[134:135]
	s_mov_b32 m0, s76
	s_nop 0
	global_load_lds_dwordx4 v[66:67], off
	s_waitcnt vmcnt(24)
	s_waitcnt lgkmcnt(0)
	s_setprio 1
	s_barrier
	v_mfma_f32_16x16x32_bf16 v[90:93], v[2:5], v[58:61], 0
	v_mfma_f32_16x16x32_bf16 v[66:69], v[2:5], v[34:37], 0
	v_mfma_f32_16x16x32_bf16 v[70:73], v[10:13], v[34:37], 0
	v_mfma_f32_16x16x32_bf16 v[74:77], v[2:5], v[42:45], 0
	v_mfma_f32_16x16x32_bf16 v[78:81], v[10:13], v[42:45], 0
	v_mfma_f32_16x16x32_bf16 v[82:85], v[2:5], v[50:53], 0
	v_mfma_f32_16x16x32_bf16 v[86:89], v[10:13], v[50:53], 0
	v_mfma_f32_16x16x32_bf16 v[94:97], v[6:9], v[62:65], v[90:93]
	v_mfma_f32_16x16x32_bf16 v[90:93], v[10:13], v[58:61], 0
	v_mfma_f32_16x16x32_bf16 v[66:69], v[6:9], v[38:41], v[66:69]
	v_mfma_f32_16x16x32_bf16 v[126:129], v[14:17], v[38:41], v[70:73]
	v_mfma_f32_16x16x32_bf16 v[74:77], v[6:9], v[46:49], v[74:77]
	v_mfma_f32_16x16x32_bf16 v[78:81], v[14:17], v[46:49], v[78:81]
	v_mfma_f32_16x16x32_bf16 v[82:85], v[6:9], v[54:57], v[82:85]
	v_mfma_f32_16x16x32_bf16 v[86:89], v[14:17], v[54:57], v[86:89]
	v_mfma_f32_16x16x32_bf16 v[102:105], v[14:17], v[62:65], v[90:93]
	v_mfma_f32_16x16x32_bf16 v[90:93], v[18:21], v[34:37], 0
	v_mfma_f32_16x16x32_bf16 v[34:37], v[26:29], v[34:37], 0
	v_mfma_f32_16x16x32_bf16 v[110:113], v[22:25], v[38:41], v[90:93]
	v_mfma_f32_16x16x32_bf16 v[34:37], v[30:33], v[38:41], v[34:37]
	v_mfma_f32_16x16x32_bf16 v[38:41], v[18:21], v[42:45], 0
	v_mfma_f32_16x16x32_bf16 v[42:45], v[26:29], v[42:45], 0
	v_mfma_f32_16x16x32_bf16 v[38:41], v[22:25], v[46:49], v[38:41]
	v_mfma_f32_16x16x32_bf16 v[42:45], v[30:33], v[46:49], v[42:45]
	v_mfma_f32_16x16x32_bf16 v[46:49], v[18:21], v[50:53], 0
	v_mfma_f32_16x16x32_bf16 v[50:53], v[26:29], v[50:53], 0
	v_mfma_f32_16x16x32_bf16 v[46:49], v[22:25], v[54:57], v[46:49]
	v_mfma_f32_16x16x32_bf16 v[54:57], v[30:33], v[54:57], v[50:53]
	v_mfma_f32_16x16x32_bf16 v[50:53], v[18:21], v[58:61], 0
	v_mfma_f32_16x16x32_bf16 v[154:157], v[22:25], v[62:65], v[50:53]
	v_mfma_f32_16x16x32_bf16 v[50:53], v[26:29], v[58:61], 0
	v_mfma_f32_16x16x32_bf16 v[158:161], v[30:33], v[62:65], v[50:53]
	s_setprio 0
	s_barrier
	s_add_i32 s77, s66, s58
	v_lshl_add_u64 v[142:143], s[52:53], 0, v[132:133]
	s_add_i32 s78, s77, 0x2000
	v_lshl_add_u64 v[122:123], v[142:143], 0, s[16:17]
	s_mov_b32 m0, s77
	v_lshl_add_u64 v[144:145], s[52:53], 0, v[136:137]
	s_add_u32 s56, s52, 0x100100
	ds_read_b128 v[50:53], v152 offset:16384
	ds_read_b128 v[58:61], v152 offset:17408
	ds_read_b128 v[62:65], v152 offset:18432
	ds_read_b128 v[90:93], v152 offset:19456
	ds_read_b128 v[98:101], v152 offset:20480
	ds_read_b128 v[106:109], v152 offset:21504
	ds_read_b128 v[114:117], v152 offset:22528
	ds_read_b128 v[118:121], v152 offset:23552
	global_load_lds_dwordx4 v[122:123], off
	v_lshl_add_u64 v[122:123], v[144:145], 0, s[16:17]
	s_mov_b32 m0, s78
	s_addc_u32 s57, s53, 0
	s_add_i32 s79, s67, s58
	global_load_lds_dwordx4 v[122:123], off
	v_lshl_add_u64 v[122:123], s[56:57], 0, v[132:133]
	s_mov_b32 m0, s79
	s_add_i32 s80, s79, 0x2000
	global_load_lds_dwordx4 v[122:123], off
	v_lshl_add_u64 v[122:123], s[56:57], 0, v[136:137]
	s_mov_b32 m0, s80
	v_lshl_add_u64 v[148:149], s[54:55], 0, v[130:131]
	global_load_lds_dwordx4 v[122:123], off
	v_lshl_add_u64 v[122:123], v[148:149], 0, s[16:17]
	s_mov_b32 m0, s51
	v_lshl_add_u64 v[70:71], s[54:55], 0, v[134:135]
	global_load_lds_dwordx4 v[122:123], off
	v_lshl_add_u64 v[72:73], v[70:71], 0, s[16:17]
	s_mov_b32 m0, s59
	s_nop 0
	global_load_lds_dwordx4 v[72:73], off
	s_waitcnt vmcnt(24)
	s_waitcnt lgkmcnt(0)
	s_setprio 1
	s_barrier
	v_mfma_f32_16x16x32_bf16 v[122:125], v[2:5], v[50:53], 0
	v_mfma_f32_16x16x32_bf16 v[162:165], v[6:9], v[58:61], v[122:125]
	v_mfma_f32_16x16x32_bf16 v[122:125], v[10:13], v[50:53], 0
	v_mfma_f32_16x16x32_bf16 v[166:169], v[14:17], v[58:61], v[122:125]
	v_mfma_f32_16x16x32_bf16 v[122:125], v[2:5], v[62:65], 0
	v_mfma_f32_16x16x32_bf16 v[170:173], v[6:9], v[90:93], v[122:125]
	v_mfma_f32_16x16x32_bf16 v[122:125], v[10:13], v[62:65], 0
	v_mfma_f32_16x16x32_bf16 v[174:177], v[14:17], v[90:93], v[122:125]
	v_mfma_f32_16x16x32_bf16 v[122:125], v[2:5], v[98:101], 0
	v_mfma_f32_16x16x32_bf16 v[2:5], v[2:5], v[114:117], 0
	v_mfma_f32_16x16x32_bf16 v[178:181], v[6:9], v[106:109], v[122:125]
	v_mfma_f32_16x16x32_bf16 v[2:5], v[6:9], v[118:121], v[2:5]
	v_mfma_f32_16x16x32_bf16 v[6:9], v[10:13], v[114:117], 0
	v_mfma_f32_16x16x32_bf16 v[122:125], v[10:13], v[98:101], 0
	v_mfma_f32_16x16x32_bf16 v[6:9], v[14:17], v[118:121], v[6:9]
	v_mfma_f32_16x16x32_bf16 v[182:185], v[14:17], v[106:109], v[122:125]
	v_mfma_f32_16x16x32_bf16 v[14:17], v[26:29], v[50:53], 0
	v_mfma_f32_16x16x32_bf16 v[186:189], v[30:33], v[58:61], v[14:17]
	v_mfma_f32_16x16x32_bf16 v[14:17], v[18:21], v[62:65], 0
	v_mfma_f32_16x16x32_bf16 v[190:193], v[22:25], v[90:93], v[14:17]
	v_mfma_f32_16x16x32_bf16 v[14:17], v[26:29], v[62:65], 0
	v_mfma_f32_16x16x32_bf16 v[194:197], v[30:33], v[90:93], v[14:17]
	v_mfma_f32_16x16x32_bf16 v[14:17], v[18:21], v[98:101], 0
	v_mfma_f32_16x16x32_bf16 v[198:201], v[22:25], v[106:109], v[14:17]
	v_mfma_f32_16x16x32_bf16 v[14:17], v[26:29], v[98:101], 0
	v_mfma_f32_16x16x32_bf16 v[10:13], v[18:21], v[50:53], 0
	v_mfma_f32_16x16x32_bf16 v[202:205], v[30:33], v[106:109], v[14:17]
	v_mfma_f32_16x16x32_bf16 v[14:17], v[18:21], v[114:117], 0
	v_mfma_f32_16x16x32_bf16 v[10:13], v[22:25], v[58:61], v[10:13]
	v_mfma_f32_16x16x32_bf16 v[206:209], v[22:25], v[118:121], v[14:17]
	v_mfma_f32_16x16x32_bf16 v[14:17], v[26:29], v[114:117], 0
	v_mfma_f32_16x16x32_bf16 v[210:213], v[30:33], v[118:121], v[14:17]
	s_setprio 0
	s_barrier
	s_add_i32 s81, 0, 0x18000
	s_add_i32 s83, 0, 0x1c000
	v_add_u32_e32 v146, s81, v153
	v_add_u32_e32 v147, s83, v153
	s_nop 0
	ds_read_b128 v[14:17], v146
	ds_read_b128 v[18:21], v146 offset:1024
	ds_read_b128 v[26:29], v146 offset:2048
	ds_read_b128 v[214:217], v146 offset:3072
	ds_read_b128 v[218:221], v147
	ds_read_b128 v[222:225], v147 offset:1024
	ds_read_b128 v[226:229], v147 offset:2048
	ds_read_b128 v[230:233], v147 offset:3072
	s_add_u32 s56, s54, 0x100100
	s_addc_u32 s57, s55, 0
	s_mov_b32 m0, s60
	v_lshl_add_u64 v[50:51], s[56:57], 0, v[130:131]
	ds_read_b128 v[22:25], v152 offset:32768
	ds_read_b128 v[30:33], v152 offset:33792
	ds_read_b128 v[62:65], v152 offset:34816
	ds_read_b128 v[234:237], v152 offset:35840
	ds_read_b128 v[238:241], v152 offset:36864
	ds_read_b128 v[242:245], v152 offset:37888
	ds_read_b128 v[246:249], v152 offset:38912
	ds_read_b128 v[250:253], v152 offset:39936
	global_load_lds_dwordx4 v[50:51], off
	v_lshl_add_u64 v[50:51], s[56:57], 0, v[134:135]
	s_mov_b32 m0, s61
	s_nop 0
	global_load_lds_dwordx4 v[50:51], off
	s_waitcnt vmcnt(8)
	s_waitcnt lgkmcnt(0)
	s_setprio 1
	s_barrier
	v_mfma_f32_16x16x32_bf16 v[50:53], v[14:17], v[22:25], v[66:69]
	v_mfma_f32_16x16x32_bf16 v[122:125], v[18:21], v[30:33], v[50:53]
	v_mfma_f32_16x16x32_bf16 v[50:53], v[26:29], v[22:25], v[126:129]
	v_mfma_f32_16x16x32_bf16 v[114:117], v[214:217], v[30:33], v[50:53]
	v_mfma_f32_16x16x32_bf16 v[50:53], v[14:17], v[62:65], v[74:77]
	v_mfma_f32_16x16x32_bf16 v[106:109], v[18:21], v[234:237], v[50:53]
	v_mfma_f32_16x16x32_bf16 v[50:53], v[26:29], v[62:65], v[78:81]
	v_mfma_f32_16x16x32_bf16 v[98:101], v[214:217], v[234:237], v[50:53]
	v_mfma_f32_16x16x32_bf16 v[50:53], v[14:17], v[238:241], v[82:85]
	v_mfma_f32_16x16x32_bf16 v[90:93], v[18:21], v[242:245], v[50:53]
	v_mfma_f32_16x16x32_bf16 v[50:53], v[26:29], v[238:241], v[86:89]
	v_mfma_f32_16x16x32_bf16 v[82:85], v[214:217], v[242:245], v[50:53]
	v_mfma_f32_16x16x32_bf16 v[50:53], v[14:17], v[246:249], v[94:97]
	v_mfma_f32_16x16x32_bf16 v[58:61], v[18:21], v[250:253], v[50:53]
	v_mfma_f32_16x16x32_bf16 v[50:53], v[26:29], v[246:249], v[102:105]
	v_mfma_f32_16x16x32_bf16 v[50:53], v[214:217], v[250:253], v[50:53]
	v_mfma_f32_16x16x32_bf16 v[66:69], v[218:221], v[22:25], v[110:113]
	v_mfma_f32_16x16x32_bf16 v[22:25], v[226:229], v[22:25], v[34:37]
	v_mfma_f32_16x16x32_bf16 v[118:121], v[230:233], v[30:33], v[22:25]
	v_mfma_f32_16x16x32_bf16 v[22:25], v[218:221], v[62:65], v[38:41]
	v_mfma_f32_16x16x32_bf16 v[110:113], v[222:225], v[234:237], v[22:25]
	v_mfma_f32_16x16x32_bf16 v[22:25], v[226:229], v[62:65], v[42:45]
	v_mfma_f32_16x16x32_bf16 v[102:105], v[230:233], v[234:237], v[22:25]
	v_mfma_f32_16x16x32_bf16 v[22:25], v[218:221], v[238:241], v[46:49]
	v_mfma_f32_16x16x32_bf16 v[94:97], v[222:225], v[242:245], v[22:25]
	v_mfma_f32_16x16x32_bf16 v[22:25], v[226:229], v[238:241], v[54:57]
	v_mfma_f32_16x16x32_bf16 v[86:89], v[230:233], v[242:245], v[22:25]
	v_mfma_f32_16x16x32_bf16 v[22:25], v[218:221], v[246:249], v[154:157]
	v_mfma_f32_16x16x32_bf16 v[62:65], v[222:225], v[250:253], v[22:25]
	v_mfma_f32_16x16x32_bf16 v[22:25], v[226:229], v[246:249], v[158:161]
	v_mfma_f32_16x16x32_bf16 v[126:129], v[222:225], v[30:33], v[66:69]
	v_mfma_f32_16x16x32_bf16 v[54:57], v[230:233], v[250:253], v[22:25]
	s_setprio 0
	s_barrier
	s_add_i32 s81, s81, s58
	s_add_i32 s82, s81, 0x2000
	s_nop 1
	v_lshl_add_u64 v[22:23], v[142:143], 0, s[30:31]
	s_mov_b32 m0, s81
	s_add_u32 s56, s52, 0x100180
	ds_read_b128 v[34:37], v152 offset:49152
	ds_read_b128 v[42:45], v152 offset:50176
	ds_read_b128 v[154:157], v152 offset:51200
	ds_read_b128 v[158:161], v152 offset:52224
	ds_read_b128 v[234:237], v152 offset:53248
	ds_read_b128 v[238:241], v152 offset:54272
	ds_read_b128 v[242:245], v152 offset:55296
	ds_read_b128 v[246:249], v152 offset:56320
	global_load_lds_dwordx4 v[22:23], off
	v_lshl_add_u64 v[22:23], v[144:145], 0, s[30:31]
	s_mov_b32 m0, s82
	s_addc_u32 s57, s53, 0
	s_add_i32 s83, s83, s58
	global_load_lds_dwordx4 v[22:23], off
	v_lshl_add_u64 v[22:23], s[56:57], 0, v[132:133]
	s_mov_b32 m0, s83
	s_add_i32 s84, s83, 0x2000
	global_load_lds_dwordx4 v[22:23], off
	v_lshl_add_u64 v[22:23], s[56:57], 0, v[136:137]
	s_mov_b32 m0, s84
	s_nop 0
	global_load_lds_dwordx4 v[22:23], off
	v_lshl_add_u64 v[22:23], v[148:149], 0, s[30:31]
	s_mov_b32 m0, s63
	s_nop 0
	global_load_lds_dwordx4 v[22:23], off
	v_lshl_add_u64 v[22:23], v[70:71], 0, s[30:31]
	s_mov_b32 m0, s64
	s_nop 0
	global_load_lds_dwordx4 v[22:23], off
	s_waitcnt vmcnt(8)
	s_waitcnt lgkmcnt(0)
	s_setprio 1
	s_barrier
	v_mfma_f32_16x16x32_bf16 v[22:25], v[14:17], v[34:37], v[162:165]
	v_mfma_f32_16x16x32_bf16 v[78:81], v[18:21], v[42:45], v[22:25]
	v_mfma_f32_16x16x32_bf16 v[22:25], v[26:29], v[34:37], v[166:169]
	v_mfma_f32_16x16x32_bf16 v[70:73], v[214:217], v[42:45], v[22:25]
	v_mfma_f32_16x16x32_bf16 v[22:25], v[14:17], v[154:157], v[170:173]
	v_mfma_f32_16x16x32_bf16 v[46:49], v[18:21], v[158:161], v[22:25]
	v_mfma_f32_16x16x32_bf16 v[22:25], v[26:29], v[154:157], v[174:177]
	v_mfma_f32_16x16x32_bf16 v[38:41], v[214:217], v[158:161], v[22:25]
	v_mfma_f32_16x16x32_bf16 v[22:25], v[14:17], v[234:237], v[178:181]
	v_mfma_f32_16x16x32_bf16 v[2:5], v[14:17], v[242:245], v[2:5]
	v_mfma_f32_16x16x32_bf16 v[30:33], v[18:21], v[238:241], v[22:25]
	v_mfma_f32_16x16x32_bf16 v[22:25], v[26:29], v[234:237], v[182:185]
	v_mfma_f32_16x16x32_bf16 v[14:17], v[18:21], v[246:249], v[2:5]
	v_mfma_f32_16x16x32_bf16 v[2:5], v[26:29], v[242:245], v[6:9]
	v_mfma_f32_16x16x32_bf16 v[22:25], v[214:217], v[238:241], v[22:25]
	v_mfma_f32_16x16x32_bf16 v[6:9], v[214:217], v[246:249], v[2:5]
	v_mfma_f32_16x16x32_bf16 v[2:5], v[218:221], v[34:37], v[10:13]
	v_mfma_f32_16x16x32_bf16 v[74:77], v[222:225], v[42:45], v[2:5]
	v_mfma_f32_16x16x32_bf16 v[2:5], v[226:229], v[34:37], v[186:189]
	v_mfma_f32_16x16x32_bf16 v[66:69], v[230:233], v[42:45], v[2:5]
	v_mfma_f32_16x16x32_bf16 v[2:5], v[218:221], v[154:157], v[190:193]
	v_mfma_f32_16x16x32_bf16 v[42:45], v[222:225], v[158:161], v[2:5]
	v_mfma_f32_16x16x32_bf16 v[2:5], v[226:229], v[154:157], v[194:197]
	v_mfma_f32_16x16x32_bf16 v[34:37], v[230:233], v[158:161], v[2:5]
	v_mfma_f32_16x16x32_bf16 v[2:5], v[218:221], v[234:237], v[198:201]
	v_mfma_f32_16x16x32_bf16 v[26:29], v[222:225], v[238:241], v[2:5]
	v_mfma_f32_16x16x32_bf16 v[2:5], v[226:229], v[234:237], v[202:205]
	v_mfma_f32_16x16x32_bf16 v[18:21], v[230:233], v[238:241], v[2:5]
	v_mfma_f32_16x16x32_bf16 v[2:5], v[218:221], v[242:245], v[206:209]
	v_mfma_f32_16x16x32_bf16 v[10:13], v[222:225], v[246:249], v[2:5]
	v_mfma_f32_16x16x32_bf16 v[2:5], v[226:229], v[242:245], v[210:213]
	v_mfma_f32_16x16x32_bf16 v[2:5], v[230:233], v[246:249], v[2:5]
	s_setprio 0
	s_barrier
	s_add_u32 s85, s52, 0x200
	s_addc_u32 s86, s53, 0
	s_add_u32 s52, s54, 0x100180
	s_addc_u32 s53, s55, 0
	s_mov_b32 s87, 0
.LBB0_266:
	ds_read_b128 v[154:157], v150
	ds_read_b128 v[158:161], v150 offset:1024
	ds_read_b128 v[162:165], v150 offset:2048
	ds_read_b128 v[166:169], v150 offset:3072
	ds_read_b128 v[170:173], v151
	ds_read_b128 v[174:177], v151 offset:1024
	ds_read_b128 v[178:181], v151 offset:2048
	ds_read_b128 v[182:185], v151 offset:3072
	s_add_u32 s54, s52, 0xfff00080
	s_addc_u32 s55, s53, -1
	s_cmp_eq_u32 s87, 60
	s_cselect_b32 s57, s45, s55
	s_cselect_b32 s56, s73, s54
	s_cselect_b32 s55, s43, s86
	s_cselect_b32 s54, s74, s85
	s_mov_b32 m0, s75
	v_lshl_add_u64 v[142:143], s[52:53], 0, v[140:141]
	ds_read_b128 v[186:189], v152
	ds_read_b128 v[190:193], v152 offset:1024
	ds_read_b128 v[194:197], v152 offset:2048
	ds_read_b128 v[198:201], v152 offset:3072
	ds_read_b128 v[202:205], v152 offset:4096
	ds_read_b128 v[206:209], v152 offset:5120
	ds_read_b128 v[210:213], v152 offset:6144
	ds_read_b128 v[214:217], v152 offset:7168
	global_load_lds_dwordx4 v[142:143], off
	v_lshl_add_u64 v[142:143], s[52:53], 0, v[138:139]
	s_mov_b32 m0, s76
	s_nop 0
	global_load_lds_dwordx4 v[142:143], off
	s_waitcnt vmcnt(8)
	s_waitcnt lgkmcnt(0)
	s_setprio 1
	s_barrier
	v_mfma_f32_16x16x32_bf16 v[122:125], v[154:157], v[186:189], v[122:125]
	v_mfma_f32_16x16x32_bf16 v[114:117], v[162:165], v[186:189], v[114:117]
	v_mfma_f32_16x16x32_bf16 v[106:109], v[154:157], v[194:197], v[106:109]
	v_mfma_f32_16x16x32_bf16 v[98:101], v[162:165], v[194:197], v[98:101]
	v_mfma_f32_16x16x32_bf16 v[90:93], v[154:157], v[202:205], v[90:93]
	v_mfma_f32_16x16x32_bf16 v[82:85], v[162:165], v[202:205], v[82:85]
	v_mfma_f32_16x16x32_bf16 v[58:61], v[154:157], v[210:213], v[58:61]
	v_mfma_f32_16x16x32_bf16 v[50:53], v[162:165], v[210:213], v[50:53]
	v_mfma_f32_16x16x32_bf16 v[122:125], v[158:161], v[190:193], v[122:125]
	v_mfma_f32_16x16x32_bf16 v[114:117], v[166:169], v[190:193], v[114:117]
	v_mfma_f32_16x16x32_bf16 v[106:109], v[158:161], v[198:201], v[106:109]
	v_mfma_f32_16x16x32_bf16 v[98:101], v[166:169], v[198:201], v[98:101]
	v_mfma_f32_16x16x32_bf16 v[90:93], v[158:161], v[206:209], v[90:93]
	v_mfma_f32_16x16x32_bf16 v[82:85], v[166:169], v[206:209], v[82:85]
	v_mfma_f32_16x16x32_bf16 v[58:61], v[158:161], v[214:217], v[58:61]
	v_mfma_f32_16x16x32_bf16 v[50:53], v[166:169], v[214:217], v[50:53]
	v_mfma_f32_16x16x32_bf16 v[126:129], v[170:173], v[186:189], v[126:129]
	v_mfma_f32_16x16x32_bf16 v[118:121], v[178:181], v[186:189], v[118:121]
	v_mfma_f32_16x16x32_bf16 v[110:113], v[170:173], v[194:197], v[110:113]
	v_mfma_f32_16x16x32_bf16 v[102:105], v[178:181], v[194:197], v[102:105]
	v_mfma_f32_16x16x32_bf16 v[94:97], v[170:173], v[202:205], v[94:97]
	v_mfma_f32_16x16x32_bf16 v[86:89], v[178:181], v[202:205], v[86:89]
	v_mfma_f32_16x16x32_bf16 v[62:65], v[170:173], v[210:213], v[62:65]
	v_mfma_f32_16x16x32_bf16 v[54:57], v[178:181], v[210:213], v[54:57]
	v_mfma_f32_16x16x32_bf16 v[126:129], v[174:177], v[190:193], v[126:129]
	v_mfma_f32_16x16x32_bf16 v[118:121], v[182:185], v[190:193], v[118:121]
	v_mfma_f32_16x16x32_bf16 v[110:113], v[174:177], v[198:201], v[110:113]
	v_mfma_f32_16x16x32_bf16 v[102:105], v[182:185], v[198:201], v[102:105]
	v_mfma_f32_16x16x32_bf16 v[94:97], v[174:177], v[206:209], v[94:97]
	v_mfma_f32_16x16x32_bf16 v[86:89], v[182:185], v[206:209], v[86:89]
	v_mfma_f32_16x16x32_bf16 v[62:65], v[174:177], v[214:217], v[62:65]
	v_mfma_f32_16x16x32_bf16 v[54:57], v[182:185], v[214:217], v[54:57]
	s_setprio 0
	s_barrier
	s_mov_b32 m0, s77
	v_lshl_add_u64 v[142:143], s[54:55], 0, v[132:133]
	s_add_u32 s88, s54, 0x100000
	ds_read_b128 v[186:189], v152 offset:16384
	ds_read_b128 v[190:193], v152 offset:17408
	ds_read_b128 v[194:197], v152 offset:18432
	ds_read_b128 v[198:201], v152 offset:19456
	ds_read_b128 v[202:205], v152 offset:20480
	ds_read_b128 v[206:209], v152 offset:21504
	ds_read_b128 v[210:213], v152 offset:22528
	ds_read_b128 v[214:217], v152 offset:23552
	global_load_lds_dwordx4 v[142:143], off
	v_lshl_add_u64 v[144:145], s[54:55], 0, v[136:137]
	s_mov_b32 m0, s78
	s_addc_u32 s89, s55, 0
	global_load_lds_dwordx4 v[144:145], off
	v_lshl_add_u64 v[148:149], s[88:89], 0, v[132:133]
	s_mov_b32 m0, s79
	v_lshl_add_u64 v[218:219], s[56:57], 0, v[134:135]
	global_load_lds_dwordx4 v[148:149], off
	v_lshl_add_u64 v[148:149], s[88:89], 0, v[136:137]
	s_mov_b32 m0, s80
	s_nop 0
	global_load_lds_dwordx4 v[148:149], off
	v_lshl_add_u64 v[148:149], s[56:57], 0, v[130:131]
	s_mov_b32 m0, s51
	s_nop 0
	global_load_lds_dwordx4 v[148:149], off
	s_mov_b32 m0, s59
	s_nop 0
	global_load_lds_dwordx4 v[218:219], off
	s_waitcnt vmcnt(8)
	s_waitcnt lgkmcnt(0)
	s_setprio 1
	s_barrier
	v_mfma_f32_16x16x32_bf16 v[78:81], v[154:157], v[186:189], v[78:81]
	v_mfma_f32_16x16x32_bf16 v[70:73], v[162:165], v[186:189], v[70:73]
	v_mfma_f32_16x16x32_bf16 v[46:49], v[154:157], v[194:197], v[46:49]
	v_mfma_f32_16x16x32_bf16 v[38:41], v[162:165], v[194:197], v[38:41]
	v_mfma_f32_16x16x32_bf16 v[30:33], v[154:157], v[202:205], v[30:33]
	v_mfma_f32_16x16x32_bf16 v[22:25], v[162:165], v[202:205], v[22:25]
	v_mfma_f32_16x16x32_bf16 v[14:17], v[154:157], v[210:213], v[14:17]
	v_mfma_f32_16x16x32_bf16 v[6:9], v[162:165], v[210:213], v[6:9]
	v_mfma_f32_16x16x32_bf16 v[78:81], v[158:161], v[190:193], v[78:81]
	v_mfma_f32_16x16x32_bf16 v[70:73], v[166:169], v[190:193], v[70:73]
	v_mfma_f32_16x16x32_bf16 v[46:49], v[158:161], v[198:201], v[46:49]
	v_mfma_f32_16x16x32_bf16 v[38:41], v[166:169], v[198:201], v[38:41]
	v_mfma_f32_16x16x32_bf16 v[30:33], v[158:161], v[206:209], v[30:33]
	v_mfma_f32_16x16x32_bf16 v[22:25], v[166:169], v[206:209], v[22:25]
	v_mfma_f32_16x16x32_bf16 v[14:17], v[158:161], v[214:217], v[14:17]
	v_mfma_f32_16x16x32_bf16 v[6:9], v[166:169], v[214:217], v[6:9]
	v_mfma_f32_16x16x32_bf16 v[74:77], v[170:173], v[186:189], v[74:77]
	v_mfma_f32_16x16x32_bf16 v[66:69], v[178:181], v[186:189], v[66:69]
	v_mfma_f32_16x16x32_bf16 v[42:45], v[170:173], v[194:197], v[42:45]
	v_mfma_f32_16x16x32_bf16 v[34:37], v[178:181], v[194:197], v[34:37]
	v_mfma_f32_16x16x32_bf16 v[26:29], v[170:173], v[202:205], v[26:29]
	v_mfma_f32_16x16x32_bf16 v[18:21], v[178:181], v[202:205], v[18:21]
	v_mfma_f32_16x16x32_bf16 v[10:13], v[170:173], v[210:213], v[10:13]
	v_mfma_f32_16x16x32_bf16 v[2:5], v[178:181], v[210:213], v[2:5]
	v_mfma_f32_16x16x32_bf16 v[74:77], v[174:177], v[190:193], v[74:77]
	v_mfma_f32_16x16x32_bf16 v[66:69], v[182:185], v[190:193], v[66:69]
	v_mfma_f32_16x16x32_bf16 v[42:45], v[174:177], v[198:201], v[42:45]
	v_mfma_f32_16x16x32_bf16 v[34:37], v[182:185], v[198:201], v[34:37]
	v_mfma_f32_16x16x32_bf16 v[26:29], v[174:177], v[206:209], v[26:29]
	v_mfma_f32_16x16x32_bf16 v[18:21], v[182:185], v[206:209], v[18:21]
	v_mfma_f32_16x16x32_bf16 v[10:13], v[174:177], v[214:217], v[10:13]
	v_mfma_f32_16x16x32_bf16 v[2:5], v[182:185], v[214:217], v[2:5]
	s_setprio 0
	s_barrier
	ds_read_b128 v[154:157], v146
	ds_read_b128 v[158:161], v146 offset:1024
	ds_read_b128 v[162:165], v146 offset:2048
	ds_read_b128 v[166:169], v146 offset:3072
	ds_read_b128 v[170:173], v147
	ds_read_b128 v[174:177], v147 offset:1024
	ds_read_b128 v[178:181], v147 offset:2048
	ds_read_b128 v[182:185], v147 offset:3072
	s_add_u32 s56, s56, 0x100000
	s_addc_u32 s57, s57, 0
	s_mov_b32 m0, s60
	v_lshl_add_u64 v[220:221], s[56:57], 0, v[130:131]
	ds_read_b128 v[186:189], v152 offset:32768
	ds_read_b128 v[190:193], v152 offset:33792
	ds_read_b128 v[194:197], v152 offset:34816
	ds_read_b128 v[198:201], v152 offset:35840
	ds_read_b128 v[202:205], v152 offset:36864
	ds_read_b128 v[206:209], v152 offset:37888
	ds_read_b128 v[210:213], v152 offset:38912
	ds_read_b128 v[214:217], v152 offset:39936
	global_load_lds_dwordx4 v[220:221], off
	v_lshl_add_u64 v[220:221], s[56:57], 0, v[134:135]
	s_mov_b32 m0, s61
	s_nop 0
	global_load_lds_dwordx4 v[220:221], off
	s_waitcnt vmcnt(8)
	s_waitcnt lgkmcnt(0)
	s_setprio 1
	s_barrier
	v_mfma_f32_16x16x32_bf16 v[122:125], v[154:157], v[186:189], v[122:125]
	v_mfma_f32_16x16x32_bf16 v[114:117], v[162:165], v[186:189], v[114:117]
	v_mfma_f32_16x16x32_bf16 v[106:109], v[154:157], v[194:197], v[106:109]
	v_mfma_f32_16x16x32_bf16 v[98:101], v[162:165], v[194:197], v[98:101]
	v_mfma_f32_16x16x32_bf16 v[90:93], v[154:157], v[202:205], v[90:93]
	v_mfma_f32_16x16x32_bf16 v[82:85], v[162:165], v[202:205], v[82:85]
	v_mfma_f32_16x16x32_bf16 v[58:61], v[154:157], v[210:213], v[58:61]
	v_mfma_f32_16x16x32_bf16 v[50:53], v[162:165], v[210:213], v[50:53]
	v_mfma_f32_16x16x32_bf16 v[122:125], v[158:161], v[190:193], v[122:125]
	v_mfma_f32_16x16x32_bf16 v[114:117], v[166:169], v[190:193], v[114:117]
	v_mfma_f32_16x16x32_bf16 v[106:109], v[158:161], v[198:201], v[106:109]
	v_mfma_f32_16x16x32_bf16 v[98:101], v[166:169], v[198:201], v[98:101]
	v_mfma_f32_16x16x32_bf16 v[90:93], v[158:161], v[206:209], v[90:93]
	v_mfma_f32_16x16x32_bf16 v[82:85], v[166:169], v[206:209], v[82:85]
	v_mfma_f32_16x16x32_bf16 v[58:61], v[158:161], v[214:217], v[58:61]
	v_mfma_f32_16x16x32_bf16 v[50:53], v[166:169], v[214:217], v[50:53]
	v_mfma_f32_16x16x32_bf16 v[126:129], v[170:173], v[186:189], v[126:129]
	v_mfma_f32_16x16x32_bf16 v[118:121], v[178:181], v[186:189], v[118:121]
	v_mfma_f32_16x16x32_bf16 v[110:113], v[170:173], v[194:197], v[110:113]
	v_mfma_f32_16x16x32_bf16 v[102:105], v[178:181], v[194:197], v[102:105]
	v_mfma_f32_16x16x32_bf16 v[94:97], v[170:173], v[202:205], v[94:97]
	v_mfma_f32_16x16x32_bf16 v[86:89], v[178:181], v[202:205], v[86:89]
	v_mfma_f32_16x16x32_bf16 v[62:65], v[170:173], v[210:213], v[62:65]
	v_mfma_f32_16x16x32_bf16 v[54:57], v[178:181], v[210:213], v[54:57]
	v_mfma_f32_16x16x32_bf16 v[126:129], v[174:177], v[190:193], v[126:129]
	v_mfma_f32_16x16x32_bf16 v[118:121], v[182:185], v[190:193], v[118:121]
	v_mfma_f32_16x16x32_bf16 v[110:113], v[174:177], v[198:201], v[110:113]
	v_mfma_f32_16x16x32_bf16 v[102:105], v[182:185], v[198:201], v[102:105]
	v_mfma_f32_16x16x32_bf16 v[94:97], v[174:177], v[206:209], v[94:97]
	v_mfma_f32_16x16x32_bf16 v[86:89], v[182:185], v[206:209], v[86:89]
	v_mfma_f32_16x16x32_bf16 v[62:65], v[174:177], v[214:217], v[62:65]
	v_mfma_f32_16x16x32_bf16 v[54:57], v[182:185], v[214:217], v[54:57]
	s_setprio 0
	s_barrier
	s_mov_b32 m0, s81
	v_lshl_add_u64 v[142:143], v[142:143], 0, s[12:13]
	s_add_u32 s54, s54, 0x100080
	ds_read_b128 v[186:189], v152 offset:49152
	ds_read_b128 v[190:193], v152 offset:50176
	ds_read_b128 v[194:197], v152 offset:51200
	ds_read_b128 v[198:201], v152 offset:52224
	ds_read_b128 v[202:205], v152 offset:53248
	ds_read_b128 v[206:209], v152 offset:54272
	ds_read_b128 v[210:213], v152 offset:55296
	ds_read_b128 v[214:217], v152 offset:56320
	global_load_lds_dwordx4 v[142:143], off
	v_lshl_add_u64 v[142:143], v[144:145], 0, s[12:13]
	s_mov_b32 m0, s82
	s_addc_u32 s55, s55, 0
	global_load_lds_dwordx4 v[142:143], off
	v_lshl_add_u64 v[142:143], s[54:55], 0, v[132:133]
	s_mov_b32 m0, s83
	s_nop 0
	global_load_lds_dwordx4 v[142:143], off
	v_lshl_add_u64 v[142:143], s[54:55], 0, v[136:137]
	s_mov_b32 m0, s84
	s_nop 0
	global_load_lds_dwordx4 v[142:143], off
	v_lshl_add_u64 v[142:143], v[148:149], 0, s[12:13]
	s_mov_b32 m0, s63
	s_nop 0
	global_load_lds_dwordx4 v[142:143], off
	v_lshl_add_u64 v[142:143], v[218:219], 0, s[12:13]
	s_mov_b32 m0, s64
	s_nop 0
	global_load_lds_dwordx4 v[142:143], off
	s_waitcnt vmcnt(8)
	s_waitcnt lgkmcnt(0)
	s_setprio 1
	s_barrier
	v_mfma_f32_16x16x32_bf16 v[78:81], v[154:157], v[186:189], v[78:81]
	v_mfma_f32_16x16x32_bf16 v[70:73], v[162:165], v[186:189], v[70:73]
	v_mfma_f32_16x16x32_bf16 v[46:49], v[154:157], v[194:197], v[46:49]
	v_mfma_f32_16x16x32_bf16 v[38:41], v[162:165], v[194:197], v[38:41]
	v_mfma_f32_16x16x32_bf16 v[30:33], v[154:157], v[202:205], v[30:33]
	v_mfma_f32_16x16x32_bf16 v[22:25], v[162:165], v[202:205], v[22:25]
	v_mfma_f32_16x16x32_bf16 v[14:17], v[154:157], v[210:213], v[14:17]
	v_mfma_f32_16x16x32_bf16 v[6:9], v[162:165], v[210:213], v[6:9]
	v_mfma_f32_16x16x32_bf16 v[78:81], v[158:161], v[190:193], v[78:81]
	v_mfma_f32_16x16x32_bf16 v[70:73], v[166:169], v[190:193], v[70:73]
	v_mfma_f32_16x16x32_bf16 v[46:49], v[158:161], v[198:201], v[46:49]
	v_mfma_f32_16x16x32_bf16 v[38:41], v[166:169], v[198:201], v[38:41]
	v_mfma_f32_16x16x32_bf16 v[30:33], v[158:161], v[206:209], v[30:33]
	v_mfma_f32_16x16x32_bf16 v[22:25], v[166:169], v[206:209], v[22:25]
	v_mfma_f32_16x16x32_bf16 v[14:17], v[158:161], v[214:217], v[14:17]
	v_mfma_f32_16x16x32_bf16 v[6:9], v[166:169], v[214:217], v[6:9]
	v_mfma_f32_16x16x32_bf16 v[74:77], v[170:173], v[186:189], v[74:77]
	v_mfma_f32_16x16x32_bf16 v[66:69], v[178:181], v[186:189], v[66:69]
	v_mfma_f32_16x16x32_bf16 v[42:45], v[170:173], v[194:197], v[42:45]
	v_mfma_f32_16x16x32_bf16 v[34:37], v[178:181], v[194:197], v[34:37]
	v_mfma_f32_16x16x32_bf16 v[26:29], v[170:173], v[202:205], v[26:29]
	v_mfma_f32_16x16x32_bf16 v[18:21], v[178:181], v[202:205], v[18:21]
	v_mfma_f32_16x16x32_bf16 v[10:13], v[170:173], v[210:213], v[10:13]
	v_mfma_f32_16x16x32_bf16 v[2:5], v[178:181], v[210:213], v[2:5]
	v_mfma_f32_16x16x32_bf16 v[74:77], v[174:177], v[190:193], v[74:77]
	v_mfma_f32_16x16x32_bf16 v[66:69], v[182:185], v[190:193], v[66:69]
	v_mfma_f32_16x16x32_bf16 v[42:45], v[174:177], v[198:201], v[42:45]
	v_mfma_f32_16x16x32_bf16 v[34:37], v[182:185], v[198:201], v[34:37]
	v_mfma_f32_16x16x32_bf16 v[26:29], v[174:177], v[206:209], v[26:29]
	v_mfma_f32_16x16x32_bf16 v[18:21], v[182:185], v[206:209], v[18:21]
	v_mfma_f32_16x16x32_bf16 v[10:13], v[174:177], v[214:217], v[10:13]
	v_mfma_f32_16x16x32_bf16 v[2:5], v[182:185], v[214:217], v[2:5]
	s_setprio 0
	s_barrier
	s_add_i32 s87, s87, 2
	s_add_u32 s85, s85, 0x100
	s_addc_u32 s86, s86, 0
	s_add_u32 s52, s52, 0x100
	s_addc_u32 s53, s53, 0
	s_cmp_gt_u32 s87, 61
	s_cbranch_scc0 .LBB0_266
	s_and_b64 vcc, exec, s[14:15]
	s_cbranch_vccz .LBB0_269
	s_barrier

.LBB0_281:
	s_ashr_i32 s49, s48, 31
	ds_read_b128 v[2:5], v188
	ds_read_b128 v[6:9], v188 offset:1024
	ds_read_b128 v[10:13], v188 offset:2048
	ds_read_b128 v[14:17], v188 offset:3072
	ds_read_b128 v[18:21], v189
	ds_read_b128 v[22:25], v189 offset:1024
	ds_read_b128 v[26:29], v189 offset:2048
	ds_read_b128 v[30:33], v189 offset:3072
	s_lshl_b64 s[8:9], s[48:49], 20
	s_add_u32 s50, s20, s8
	s_addc_u32 s51, s21, s9
	s_and_b64 s[8:9], s[4:5], exec
	s_cselect_b32 s49, s51, s59
	s_cselect_b32 s73, s50, s58
	s_ashr_i32 s47, s46, 31
	s_lshl_b64 s[8:9], s[46:47], 20
	s_add_u32 s52, s19, s8
	s_addc_u32 s53, s24, s9
	s_and_b64 s[8:9], s[4:5], exec
	s_cselect_b32 s47, s53, s57
	s_cselect_b32 s74, s52, s56
	s_add_u32 s8, s58, 0x80080
	s_addc_u32 s9, s59, 0
	s_add_i32 s75, s37, 0xc000
	v_lshl_add_u64 v[34:35], s[8:9], 0, v[168:169]
	s_mov_b32 m0, s75
	s_add_i32 s76, s37, 0xe000
	ds_read_b128 v[38:41], v190
	ds_read_b128 v[42:45], v190 offset:1024
	ds_read_b128 v[46:49], v190 offset:2048
	ds_read_b128 v[50:53], v190 offset:3072
	ds_read_b128 v[54:57], v190 offset:4096
	ds_read_b128 v[58:61], v190 offset:5120
	ds_read_b128 v[62:65], v190 offset:6144
	ds_read_b128 v[66:69], v190 offset:7168
	global_load_lds_dwordx4 v[34:35], off
	v_lshl_add_u64 v[34:35], s[8:9], 0, v[164:165]
	s_mov_b32 m0, s76
	s_nop 0
	global_load_lds_dwordx4 v[34:35], off
	s_waitcnt vmcnt(24)
	s_waitcnt lgkmcnt(0)
	s_setprio 1
	s_barrier
	s_mov_b32 s8, 0
	s_mov_b32 s10, s8
	s_mov_b32 s11, s8
	s_mov_b32 s9, s8
	v_mov_b64_e32 v[36:37], s[10:11]
	v_mov_b64_e32 v[160:161], s[10:11]
	v_mov_b64_e32 v[156:157], s[10:11]
	v_mov_b64_e32 v[144:145], s[10:11]
	v_mov_b64_e32 v[140:141], s[10:11]
	v_mov_b64_e32 v[128:129], s[10:11]
	v_mov_b64_e32 v[120:121], s[10:11]
	v_mov_b64_e32 v[92:93], s[10:11]
	v_mov_b64_e32 v[84:85], s[10:11]
	v_mov_b64_e32 v[34:35], s[8:9]
	v_mov_b64_e32 v[158:159], s[8:9]
	v_mov_b64_e32 v[154:155], s[8:9]
	v_mov_b64_e32 v[142:143], s[8:9]
	v_mov_b64_e32 v[138:139], s[8:9]
	v_mov_b64_e32 v[126:127], s[8:9]
	v_mov_b64_e32 v[118:119], s[8:9]
	v_mov_b64_e32 v[90:91], s[8:9]
	v_mov_b64_e32 v[82:83], s[8:9]
	s_waitcnt lgkmcnt(0)
	v_mfma_f32_16x16x128_f8f6f4 v[158:161], v[2:9], v[38:45], v[158:161]
	v_mfma_f32_16x16x128_f8f6f4 v[154:157], v[10:17], v[38:45], v[154:157]
	v_mfma_f32_16x16x128_f8f6f4 v[142:145], v[2:9], v[46:53], v[142:145]
	v_mfma_f32_16x16x128_f8f6f4 v[138:141], v[10:17], v[46:53], v[138:141]
	v_mfma_f32_16x16x128_f8f6f4 v[126:129], v[2:9], v[54:61], v[126:129]
	v_mfma_f32_16x16x128_f8f6f4 v[118:121], v[10:17], v[54:61], v[118:121]
	v_mfma_f32_16x16x128_f8f6f4 v[90:93], v[2:9], v[62:69], v[90:93]
	v_mfma_f32_16x16x128_f8f6f4 v[82:85], v[10:17], v[62:69], v[82:85]
	v_mov_b64_e32 v[152:153], s[10:11]
	v_mov_b64_e32 v[148:149], s[10:11]
	v_mov_b64_e32 v[136:137], s[10:11]
	v_mov_b64_e32 v[132:133], s[10:11]
	v_mov_b64_e32 v[112:113], s[10:11]
	v_mov_b64_e32 v[108:109], s[10:11]
	v_mov_b64_e32 v[80:81], s[10:11]
	v_mov_b64_e32 v[76:77], s[10:11]
	v_mov_b64_e32 v[150:151], s[8:9]
	v_mov_b64_e32 v[146:147], s[8:9]
	v_mov_b64_e32 v[134:135], s[8:9]
	v_mov_b64_e32 v[130:131], s[8:9]
	v_mov_b64_e32 v[110:111], s[8:9]
	v_mov_b64_e32 v[106:107], s[8:9]
	v_mov_b64_e32 v[78:79], s[8:9]
	v_mov_b64_e32 v[74:75], s[8:9]
	v_mfma_f32_16x16x128_f8f6f4 v[150:153], v[18:25], v[38:45], v[150:153]
	v_mfma_f32_16x16x128_f8f6f4 v[146:149], v[26:33], v[38:45], v[146:149]
	v_mfma_f32_16x16x128_f8f6f4 v[134:137], v[18:25], v[46:53], v[134:137]
	v_mfma_f32_16x16x128_f8f6f4 v[130:133], v[26:33], v[46:53], v[130:133]
	v_mfma_f32_16x16x128_f8f6f4 v[110:113], v[18:25], v[54:61], v[110:113]
	v_mfma_f32_16x16x128_f8f6f4 v[106:109], v[26:33], v[54:61], v[106:109]
	v_mfma_f32_16x16x128_f8f6f4 v[78:81], v[18:25], v[62:69], v[78:81]
	v_mfma_f32_16x16x128_f8f6f4 v[74:77], v[26:33], v[62:69], v[74:77]
	s_setprio 0
	s_barrier
	s_add_i32 s9, s66, s25
	v_lshl_add_u64 v[178:179], s[56:57], 0, v[166:167]
	s_add_i32 s77, s9, 0x2000
	v_lshl_add_u64 v[38:39], v[178:179], 0, s[30:31]
	s_mov_b32 m0, s9
	v_lshl_add_u64 v[180:181], s[56:57], 0, v[162:163]
	s_add_u32 s10, s56, 0x80100
	ds_read_b128 v[50:53], v190 offset:16384
	ds_read_b128 v[54:57], v190 offset:17408
	ds_read_b128 v[192:195], v190 offset:18432
	ds_read_b128 v[196:199], v190 offset:19456
	ds_read_b128 v[200:203], v190 offset:20480
	ds_read_b128 v[204:207], v190 offset:21504
	ds_read_b128 v[208:211], v190 offset:22528
	ds_read_b128 v[212:215], v190 offset:23552
	global_load_lds_dwordx4 v[38:39], off
	v_lshl_add_u64 v[38:39], v[180:181], 0, s[30:31]
	s_mov_b32 m0, s77
	s_addc_u32 s11, s57, 0
	s_add_i32 s78, s67, s25
	global_load_lds_dwordx4 v[38:39], off
	v_lshl_add_u64 v[38:39], s[10:11], 0, v[166:167]
	s_mov_b32 m0, s78
	s_add_i32 s79, s78, 0x2000
	global_load_lds_dwordx4 v[38:39], off
	v_lshl_add_u64 v[38:39], s[10:11], 0, v[162:163]
	s_mov_b32 m0, s79
	v_lshl_add_u64 v[182:183], s[58:59], 0, v[168:169]
	global_load_lds_dwordx4 v[38:39], off
	v_lshl_add_u64 v[38:39], v[182:183], 0, s[30:31]
	s_mov_b32 m0, s37
	v_lshl_add_u64 v[184:185], s[58:59], 0, v[164:165]
	global_load_lds_dwordx4 v[38:39], off
	v_lshl_add_u64 v[38:39], v[184:185], 0, s[30:31]
	s_mov_b32 m0, s55
	s_nop 0
	global_load_lds_dwordx4 v[38:39], off
	s_waitcnt vmcnt(24)
	s_waitcnt lgkmcnt(0)
	s_setprio 1
	s_barrier
	v_mov_b64_e32 v[124:125], v[36:37]
	v_mov_b64_e32 v[116:117], v[36:37]
	v_mov_b64_e32 v[96:97], v[36:37]
	v_mov_b64_e32 v[88:89], v[36:37]
	v_mov_b64_e32 v[64:65], v[36:37]
	v_mov_b64_e32 v[60:61], v[36:37]
	v_mov_b64_e32 v[48:49], v[36:37]
	v_mov_b64_e32 v[44:45], v[36:37]
	v_mov_b64_e32 v[122:123], v[34:35]
	v_mov_b64_e32 v[114:115], v[34:35]
	v_mov_b64_e32 v[94:95], v[34:35]
	v_mov_b64_e32 v[86:87], v[34:35]
	v_mov_b64_e32 v[62:63], v[34:35]
	v_mov_b64_e32 v[58:59], v[34:35]
	v_mov_b64_e32 v[46:47], v[34:35]
	v_mov_b64_e32 v[42:43], v[34:35]
	s_waitcnt lgkmcnt(0)
	v_mfma_f32_16x16x128_f8f6f4 v[122:125], v[2:9], v[50:57], v[122:125]
	v_mfma_f32_16x16x128_f8f6f4 v[114:117], v[10:17], v[50:57], v[114:117]
	v_mfma_f32_16x16x128_f8f6f4 v[94:97], v[2:9], v[192:199], v[94:97]
	v_mfma_f32_16x16x128_f8f6f4 v[86:89], v[10:17], v[192:199], v[86:89]
	v_mfma_f32_16x16x128_f8f6f4 v[62:65], v[2:9], v[200:207], v[62:65]
	v_mfma_f32_16x16x128_f8f6f4 v[58:61], v[10:17], v[200:207], v[58:61]
	v_mfma_f32_16x16x128_f8f6f4 v[46:49], v[2:9], v[208:215], v[46:49]
	v_mfma_f32_16x16x128_f8f6f4 v[42:45], v[10:17], v[208:215], v[42:45]
	v_mov_b64_e32 v[104:105], v[36:37]
	v_mov_b64_e32 v[100:101], v[36:37]
	v_mov_b64_e32 v[102:103], v[34:35]
	v_mov_b64_e32 v[98:99], v[34:35]
	v_mfma_f32_16x16x128_f8f6f4 v[102:105], v[18:25], v[50:57], v[102:105]
	v_mfma_f32_16x16x128_f8f6f4 v[98:101], v[26:33], v[50:57], v[98:101]
	v_mov_b64_e32 v[72:73], v[36:37]
	v_mov_b64_e32 v[68:69], v[36:37]
	v_mov_b64_e32 v[56:57], v[36:37]
	v_mov_b64_e32 v[52:53], v[36:37]
	v_mov_b64_e32 v[40:41], v[36:37]
	v_mov_b64_e32 v[70:71], v[34:35]
	v_mov_b64_e32 v[66:67], v[34:35]
	v_mov_b64_e32 v[54:55], v[34:35]
	v_mov_b64_e32 v[50:51], v[34:35]
	v_mov_b64_e32 v[38:39], v[34:35]
	v_mfma_f32_16x16x128_f8f6f4 v[70:73], v[18:25], v[192:199], v[70:73]
	v_mfma_f32_16x16x128_f8f6f4 v[66:69], v[26:33], v[192:199], v[66:69]
	v_mfma_f32_16x16x128_f8f6f4 v[54:57], v[18:25], v[200:207], v[54:57]
	v_mfma_f32_16x16x128_f8f6f4 v[50:53], v[26:33], v[200:207], v[50:53]
	v_mfma_f32_16x16x128_f8f6f4 v[38:41], v[18:25], v[208:215], v[38:41]
	v_mfma_f32_16x16x128_f8f6f4 v[34:37], v[26:33], v[208:215], v[34:37]
	s_setprio 0
	s_barrier
	s_add_i32 s80, 0, 0x18000
	s_add_i32 s82, 0, 0x1c000
	v_add_u32_e32 v191, s80, v186
	v_add_u32_e32 v192, s82, v186
	ds_read_b128 v[18:21], v191
	ds_read_b128 v[22:25], v191 offset:1024
	ds_read_b128 v[26:29], v191 offset:2048
	ds_read_b128 v[30:33], v191 offset:3072
	ds_read_b128 v[2:5], v192
	ds_read_b128 v[6:9], v192 offset:1024
	ds_read_b128 v[10:13], v192 offset:2048
	ds_read_b128 v[14:17], v192 offset:3072
	s_add_u32 s10, s58, 0x80100
	s_addc_u32 s11, s59, 0
	s_mov_b32 m0, s60
	v_lshl_add_u64 v[226:227], s[10:11], 0, v[168:169]
	ds_read_b128 v[194:197], v190 offset:32768
	ds_read_b128 v[198:201], v190 offset:33792
	ds_read_b128 v[202:205], v190 offset:34816
	ds_read_b128 v[206:209], v190 offset:35840
	ds_read_b128 v[210:213], v190 offset:36864
	ds_read_b128 v[214:217], v190 offset:37888
	ds_read_b128 v[218:221], v190 offset:38912
	ds_read_b128 v[222:225], v190 offset:39936
	global_load_lds_dwordx4 v[226:227], off
	v_lshl_add_u64 v[226:227], s[10:11], 0, v[164:165]
	s_mov_b32 m0, s61
	s_nop 0
	global_load_lds_dwordx4 v[226:227], off
	s_waitcnt vmcnt(8)
	s_waitcnt lgkmcnt(0)
	s_setprio 1
	s_barrier
	v_mfma_f32_16x16x128_f8f6f4 v[158:161], v[18:25], v[194:201], v[158:161]
	v_mfma_f32_16x16x128_f8f6f4 v[154:157], v[26:33], v[194:201], v[154:157]
	v_mfma_f32_16x16x128_f8f6f4 v[142:145], v[18:25], v[202:209], v[142:145]
	v_mfma_f32_16x16x128_f8f6f4 v[138:141], v[26:33], v[202:209], v[138:141]
	v_mfma_f32_16x16x128_f8f6f4 v[126:129], v[18:25], v[210:217], v[126:129]
	v_mfma_f32_16x16x128_f8f6f4 v[118:121], v[26:33], v[210:217], v[118:121]
	v_mfma_f32_16x16x128_f8f6f4 v[90:93], v[18:25], v[218:225], v[90:93]
	v_mfma_f32_16x16x128_f8f6f4 v[82:85], v[26:33], v[218:225], v[82:85]
	v_mfma_f32_16x16x128_f8f6f4 v[150:153], v[2:9], v[194:201], v[150:153]
	v_mfma_f32_16x16x128_f8f6f4 v[146:149], v[10:17], v[194:201], v[146:149]
	v_mfma_f32_16x16x128_f8f6f4 v[134:137], v[2:9], v[202:209], v[134:137]
	v_mfma_f32_16x16x128_f8f6f4 v[130:133], v[10:17], v[202:209], v[130:133]
	v_mfma_f32_16x16x128_f8f6f4 v[110:113], v[2:9], v[210:217], v[110:113]
	v_mfma_f32_16x16x128_f8f6f4 v[106:109], v[10:17], v[210:217], v[106:109]
	v_mfma_f32_16x16x128_f8f6f4 v[78:81], v[2:9], v[218:225], v[78:81]
	v_mfma_f32_16x16x128_f8f6f4 v[74:77], v[10:17], v[218:225], v[74:77]
	s_setprio 0
	s_barrier
	s_add_i32 s80, s80, s25
	s_add_i32 s81, s80, 0x2000
	v_lshl_add_u64 v[178:179], v[178:179], 0, s[34:35]
	s_mov_b32 m0, s80
	s_add_u32 s10, s56, 0x80180
	ds_read_b128 v[194:197], v190 offset:49152
	ds_read_b128 v[198:201], v190 offset:50176
	ds_read_b128 v[202:205], v190 offset:51200
	ds_read_b128 v[206:209], v190 offset:52224
	ds_read_b128 v[210:213], v190 offset:53248
	ds_read_b128 v[214:217], v190 offset:54272
	ds_read_b128 v[218:221], v190 offset:55296
	ds_read_b128 v[222:225], v190 offset:56320
	global_load_lds_dwordx4 v[178:179], off
	v_lshl_add_u64 v[178:179], v[180:181], 0, s[34:35]
	s_mov_b32 m0, s81
	s_addc_u32 s11, s57, 0
	s_add_i32 s82, s82, s25
	global_load_lds_dwordx4 v[178:179], off
	v_lshl_add_u64 v[178:179], s[10:11], 0, v[166:167]
	s_mov_b32 m0, s82
	s_add_i32 s83, s82, 0x2000
	global_load_lds_dwordx4 v[178:179], off
	v_lshl_add_u64 v[178:179], s[10:11], 0, v[162:163]
	s_mov_b32 m0, s83
	s_nop 0
	global_load_lds_dwordx4 v[178:179], off
	v_lshl_add_u64 v[178:179], v[182:183], 0, s[34:35]
	s_mov_b32 m0, s63
	s_nop 0
	global_load_lds_dwordx4 v[178:179], off
	v_lshl_add_u64 v[178:179], v[184:185], 0, s[34:35]
	s_mov_b32 m0, s64
	s_nop 0
	global_load_lds_dwordx4 v[178:179], off
	s_waitcnt vmcnt(8)
	s_waitcnt lgkmcnt(0)
	s_setprio 1
	s_barrier
	v_mfma_f32_16x16x128_f8f6f4 v[122:125], v[18:25], v[194:201], v[122:125]
	v_mfma_f32_16x16x128_f8f6f4 v[114:117], v[26:33], v[194:201], v[114:117]
	v_mfma_f32_16x16x128_f8f6f4 v[94:97], v[18:25], v[202:209], v[94:97]
	v_mfma_f32_16x16x128_f8f6f4 v[86:89], v[26:33], v[202:209], v[86:89]
	v_mfma_f32_16x16x128_f8f6f4 v[62:65], v[18:25], v[210:217], v[62:65]
	v_mfma_f32_16x16x128_f8f6f4 v[58:61], v[26:33], v[210:217], v[58:61]
	v_mfma_f32_16x16x128_f8f6f4 v[46:49], v[18:25], v[218:225], v[46:49]
	v_mfma_f32_16x16x128_f8f6f4 v[42:45], v[26:33], v[218:225], v[42:45]
	v_mfma_f32_16x16x128_f8f6f4 v[102:105], v[2:9], v[194:201], v[102:105]
	v_mfma_f32_16x16x128_f8f6f4 v[98:101], v[10:17], v[194:201], v[98:101]
	v_mfma_f32_16x16x128_f8f6f4 v[70:73], v[2:9], v[202:209], v[70:73]
	v_mfma_f32_16x16x128_f8f6f4 v[66:69], v[10:17], v[202:209], v[66:69]
	v_mfma_f32_16x16x128_f8f6f4 v[54:57], v[2:9], v[210:217], v[54:57]
	v_mfma_f32_16x16x128_f8f6f4 v[50:53], v[10:17], v[210:217], v[50:53]
	v_mfma_f32_16x16x128_f8f6f4 v[38:41], v[2:9], v[218:225], v[38:41]
	v_mfma_f32_16x16x128_f8f6f4 v[34:37], v[10:17], v[218:225], v[34:37]
	s_setprio 0
	s_barrier
	s_add_u32 s10, s58, 0x80180
	s_addc_u32 s11, s59, 0
	s_add_u32 s84, s56, 0x200
	s_addc_u32 s85, s57, 0
.LBB0_282:
	ds_read_b128 v[2:5], v188
	ds_read_b128 v[6:9], v188 offset:1024
	ds_read_b128 v[18:21], v188 offset:2048
	ds_read_b128 v[22:25], v188 offset:3072
	ds_read_b128 v[26:29], v189
	ds_read_b128 v[30:33], v189 offset:1024
	ds_read_b128 v[178:181], v189 offset:2048
	ds_read_b128 v[182:185], v189 offset:3072
	s_add_u32 s56, s10, 0xfff80080
	s_addc_u32 s57, s11, -1
	s_cmp_eq_u32 s8, 28
	s_cselect_b32 s59, s49, s57
	s_cselect_b32 s58, s73, s56
	s_cselect_b32 s57, s47, s85
	s_cselect_b32 s56, s74, s84
	s_mov_b32 m0, s75
	v_lshl_add_u64 v[218:219], s[10:11], 0, v[170:171]
	ds_read_b128 v[10:13], v190
	ds_read_b128 v[14:17], v190 offset:1024
	ds_read_b128 v[194:197], v190 offset:2048
	ds_read_b128 v[198:201], v190 offset:3072
	ds_read_b128 v[202:205], v190 offset:4096
	ds_read_b128 v[206:209], v190 offset:5120
	ds_read_b128 v[210:213], v190 offset:6144
	ds_read_b128 v[214:217], v190 offset:7168
	global_load_lds_dwordx4 v[218:219], off
	v_lshl_add_u64 v[218:219], s[10:11], 0, v[172:173]
	s_mov_b32 m0, s76
	s_nop 0
	global_load_lds_dwordx4 v[218:219], off
	s_waitcnt vmcnt(8)
	s_waitcnt lgkmcnt(0)
	s_setprio 1
	s_barrier
	v_mfma_f32_16x16x128_f8f6f4 v[158:161], v[2:9], v[10:17], v[158:161]
	v_mfma_f32_16x16x128_f8f6f4 v[154:157], v[18:25], v[10:17], v[154:157]
	v_mfma_f32_16x16x128_f8f6f4 v[142:145], v[2:9], v[194:201], v[142:145]
	v_mfma_f32_16x16x128_f8f6f4 v[138:141], v[18:25], v[194:201], v[138:141]
	v_mfma_f32_16x16x128_f8f6f4 v[126:129], v[2:9], v[202:209], v[126:129]
	v_mfma_f32_16x16x128_f8f6f4 v[118:121], v[18:25], v[202:209], v[118:121]
	v_mfma_f32_16x16x128_f8f6f4 v[90:93], v[2:9], v[210:217], v[90:93]
	v_mfma_f32_16x16x128_f8f6f4 v[82:85], v[18:25], v[210:217], v[82:85]
	v_mfma_f32_16x16x128_f8f6f4 v[150:153], v[26:33], v[10:17], v[150:153]
	v_mfma_f32_16x16x128_f8f6f4 v[146:149], v[178:185], v[10:17], v[146:149]
	v_mfma_f32_16x16x128_f8f6f4 v[134:137], v[26:33], v[194:201], v[134:137]
	v_mfma_f32_16x16x128_f8f6f4 v[130:133], v[178:185], v[194:201], v[130:133]
	v_mfma_f32_16x16x128_f8f6f4 v[110:113], v[26:33], v[202:209], v[110:113]
	v_mfma_f32_16x16x128_f8f6f4 v[106:109], v[178:185], v[202:209], v[106:109]
	v_mfma_f32_16x16x128_f8f6f4 v[78:81], v[26:33], v[210:217], v[78:81]
	v_mfma_f32_16x16x128_f8f6f4 v[74:77], v[178:185], v[210:217], v[74:77]
	s_setprio 0
	s_barrier
	s_mov_b32 m0, s9
	v_lshl_add_u64 v[10:11], s[56:57], 0, v[166:167]
	s_add_u32 s86, s56, 0x80000
	ds_read_b128 v[194:197], v190 offset:16384
	ds_read_b128 v[198:201], v190 offset:17408
	ds_read_b128 v[202:205], v190 offset:18432
	ds_read_b128 v[206:209], v190 offset:19456
	ds_read_b128 v[210:213], v190 offset:20480
	ds_read_b128 v[214:217], v190 offset:21504
	ds_read_b128 v[218:221], v190 offset:22528
	ds_read_b128 v[222:225], v190 offset:23552
	global_load_lds_dwordx4 v[10:11], off
	v_lshl_add_u64 v[12:13], s[56:57], 0, v[162:163]
	s_mov_b32 m0, s77
	s_addc_u32 s87, s57, 0
	global_load_lds_dwordx4 v[12:13], off
	v_lshl_add_u64 v[14:15], s[86:87], 0, v[166:167]
	s_mov_b32 m0, s78
	v_lshl_add_u64 v[16:17], s[58:59], 0, v[164:165]
	global_load_lds_dwordx4 v[14:15], off
	v_lshl_add_u64 v[14:15], s[86:87], 0, v[162:163]
	s_mov_b32 m0, s79
	s_nop 0
	global_load_lds_dwordx4 v[14:15], off
	v_lshl_add_u64 v[14:15], s[58:59], 0, v[168:169]
	s_mov_b32 m0, s37
	s_nop 0
	global_load_lds_dwordx4 v[14:15], off
	s_mov_b32 m0, s55
	s_nop 0
	global_load_lds_dwordx4 v[16:17], off
	s_waitcnt vmcnt(8)
	s_waitcnt lgkmcnt(0)
	s_setprio 1
	s_barrier
	v_mfma_f32_16x16x128_f8f6f4 v[122:125], v[2:9], v[194:201], v[122:125]
	v_mfma_f32_16x16x128_f8f6f4 v[114:117], v[18:25], v[194:201], v[114:117]
	v_mfma_f32_16x16x128_f8f6f4 v[94:97], v[2:9], v[202:209], v[94:97]
	v_mfma_f32_16x16x128_f8f6f4 v[86:89], v[18:25], v[202:209], v[86:89]
	v_mfma_f32_16x16x128_f8f6f4 v[62:65], v[2:9], v[210:217], v[62:65]
	v_mfma_f32_16x16x128_f8f6f4 v[58:61], v[18:25], v[210:217], v[58:61]
	v_mfma_f32_16x16x128_f8f6f4 v[46:49], v[2:9], v[218:225], v[46:49]
	v_mfma_f32_16x16x128_f8f6f4 v[42:45], v[18:25], v[218:225], v[42:45]
	v_mfma_f32_16x16x128_f8f6f4 v[102:105], v[26:33], v[194:201], v[102:105]
	v_mfma_f32_16x16x128_f8f6f4 v[98:101], v[178:185], v[194:201], v[98:101]
	v_mfma_f32_16x16x128_f8f6f4 v[70:73], v[26:33], v[202:209], v[70:73]
	v_mfma_f32_16x16x128_f8f6f4 v[66:69], v[178:185], v[202:209], v[66:69]
	v_mfma_f32_16x16x128_f8f6f4 v[54:57], v[26:33], v[210:217], v[54:57]
	v_mfma_f32_16x16x128_f8f6f4 v[50:53], v[178:185], v[210:217], v[50:53]
	v_mfma_f32_16x16x128_f8f6f4 v[38:41], v[26:33], v[218:225], v[38:41]
	v_mfma_f32_16x16x128_f8f6f4 v[34:37], v[178:185], v[218:225], v[34:37]
	s_setprio 0
	s_barrier
	ds_read_b128 v[18:21], v191
	ds_read_b128 v[22:25], v191 offset:1024
	ds_read_b128 v[26:29], v191 offset:2048
	ds_read_b128 v[30:33], v191 offset:3072
	ds_read_b128 v[2:5], v192
	ds_read_b128 v[6:9], v192 offset:1024
	ds_read_b128 v[178:181], v192 offset:2048
	ds_read_b128 v[182:185], v192 offset:3072
	s_add_u32 s58, s58, 0x80000
	s_addc_u32 s59, s59, 0
	s_mov_b32 m0, s60
	v_lshl_add_u64 v[226:227], s[58:59], 0, v[168:169]
	ds_read_b128 v[194:197], v190 offset:32768
	ds_read_b128 v[198:201], v190 offset:33792
	ds_read_b128 v[202:205], v190 offset:34816
	ds_read_b128 v[206:209], v190 offset:35840
	ds_read_b128 v[210:213], v190 offset:36864
	ds_read_b128 v[214:217], v190 offset:37888
	ds_read_b128 v[218:221], v190 offset:38912
	ds_read_b128 v[222:225], v190 offset:39936
	global_load_lds_dwordx4 v[226:227], off
	v_lshl_add_u64 v[226:227], s[58:59], 0, v[164:165]
	s_mov_b32 m0, s61
	s_nop 0
	global_load_lds_dwordx4 v[226:227], off
	s_waitcnt vmcnt(8)
	s_waitcnt lgkmcnt(0)
	s_setprio 1
	s_barrier
	v_mfma_f32_16x16x128_f8f6f4 v[158:161], v[18:25], v[194:201], v[158:161]
	v_mfma_f32_16x16x128_f8f6f4 v[154:157], v[26:33], v[194:201], v[154:157]
	v_mfma_f32_16x16x128_f8f6f4 v[142:145], v[18:25], v[202:209], v[142:145]
	v_mfma_f32_16x16x128_f8f6f4 v[138:141], v[26:33], v[202:209], v[138:141]
	v_mfma_f32_16x16x128_f8f6f4 v[126:129], v[18:25], v[210:217], v[126:129]
	v_mfma_f32_16x16x128_f8f6f4 v[118:121], v[26:33], v[210:217], v[118:121]
	v_mfma_f32_16x16x128_f8f6f4 v[90:93], v[18:25], v[218:225], v[90:93]
	v_mfma_f32_16x16x128_f8f6f4 v[82:85], v[26:33], v[218:225], v[82:85]
	v_mfma_f32_16x16x128_f8f6f4 v[150:153], v[2:9], v[194:201], v[150:153]
	v_mfma_f32_16x16x128_f8f6f4 v[146:149], v[178:185], v[194:201], v[146:149]
	v_mfma_f32_16x16x128_f8f6f4 v[134:137], v[2:9], v[202:209], v[134:137]
	v_mfma_f32_16x16x128_f8f6f4 v[130:133], v[178:185], v[202:209], v[130:133]
	v_mfma_f32_16x16x128_f8f6f4 v[110:113], v[2:9], v[210:217], v[110:113]
	v_mfma_f32_16x16x128_f8f6f4 v[106:109], v[178:185], v[210:217], v[106:109]
	v_mfma_f32_16x16x128_f8f6f4 v[78:81], v[2:9], v[218:225], v[78:81]
	v_mfma_f32_16x16x128_f8f6f4 v[74:77], v[178:185], v[218:225], v[74:77]
	s_setprio 0
	s_barrier
	s_mov_b32 m0, s80
	v_lshl_add_u64 v[10:11], v[10:11], 0, s[14:15]
	s_add_u32 s56, s56, 0x80080
	ds_read_b128 v[194:197], v190 offset:49152
	ds_read_b128 v[198:201], v190 offset:50176
	ds_read_b128 v[202:205], v190 offset:51200
	ds_read_b128 v[206:209], v190 offset:52224
	ds_read_b128 v[210:213], v190 offset:53248
	ds_read_b128 v[214:217], v190 offset:54272
	ds_read_b128 v[218:221], v190 offset:55296
	ds_read_b128 v[222:225], v190 offset:56320
	global_load_lds_dwordx4 v[10:11], off
	v_lshl_add_u64 v[10:11], v[12:13], 0, s[14:15]
	s_mov_b32 m0, s81
	s_addc_u32 s57, s57, 0
	global_load_lds_dwordx4 v[10:11], off
	v_lshl_add_u64 v[10:11], s[56:57], 0, v[166:167]
	s_mov_b32 m0, s82
	s_nop 0
	global_load_lds_dwordx4 v[10:11], off
	v_lshl_add_u64 v[10:11], s[56:57], 0, v[162:163]
	s_mov_b32 m0, s83
	s_nop 0
	global_load_lds_dwordx4 v[10:11], off
	v_lshl_add_u64 v[10:11], v[14:15], 0, s[14:15]
	s_mov_b32 m0, s63
	s_nop 0
	global_load_lds_dwordx4 v[10:11], off
	v_lshl_add_u64 v[10:11], v[16:17], 0, s[14:15]
	s_mov_b32 m0, s64
	s_nop 0
	global_load_lds_dwordx4 v[10:11], off
	s_waitcnt vmcnt(8)
	s_waitcnt lgkmcnt(0)
	s_setprio 1
	s_barrier
	v_mfma_f32_16x16x128_f8f6f4 v[122:125], v[18:25], v[194:201], v[122:125]
	v_mfma_f32_16x16x128_f8f6f4 v[114:117], v[26:33], v[194:201], v[114:117]
	v_mfma_f32_16x16x128_f8f6f4 v[94:97], v[18:25], v[202:209], v[94:97]
	v_mfma_f32_16x16x128_f8f6f4 v[86:89], v[26:33], v[202:209], v[86:89]
	v_mfma_f32_16x16x128_f8f6f4 v[62:65], v[18:25], v[210:217], v[62:65]
	v_mfma_f32_16x16x128_f8f6f4 v[58:61], v[26:33], v[210:217], v[58:61]
	v_mfma_f32_16x16x128_f8f6f4 v[46:49], v[18:25], v[218:225], v[46:49]
	v_mfma_f32_16x16x128_f8f6f4 v[42:45], v[26:33], v[218:225], v[42:45]
	v_mfma_f32_16x16x128_f8f6f4 v[102:105], v[2:9], v[194:201], v[102:105]
	v_mfma_f32_16x16x128_f8f6f4 v[98:101], v[178:185], v[194:201], v[98:101]
	v_mfma_f32_16x16x128_f8f6f4 v[70:73], v[2:9], v[202:209], v[70:73]
	v_mfma_f32_16x16x128_f8f6f4 v[66:69], v[178:185], v[202:209], v[66:69]
	v_mfma_f32_16x16x128_f8f6f4 v[54:57], v[2:9], v[210:217], v[54:57]
	v_mfma_f32_16x16x128_f8f6f4 v[50:53], v[178:185], v[210:217], v[50:53]
	v_mfma_f32_16x16x128_f8f6f4 v[38:41], v[2:9], v[218:225], v[38:41]
	v_mfma_f32_16x16x128_f8f6f4 v[34:37], v[178:185], v[218:225], v[34:37]
	s_setprio 0
	s_barrier
	s_add_i32 s8, s8, 2
	s_add_u32 s10, s10, 0x100
	s_addc_u32 s11, s11, 0
	s_add_u32 s84, s84, 0x100
	s_addc_u32 s85, s85, 0
	s_cmp_gt_u32 s8, 29
	s_cbranch_scc0 .LBB0_282
	s_and_b64 vcc, exec, s[16:17]
	s_cbranch_vccz .LBB0_285
	s_barrier

.LBB0_305:
	s_ashr_i32 s45, s44, 31
	ds_read_b128 v[2:5], v150
	ds_read_b128 v[6:9], v150 offset:1024
	ds_read_b128 v[10:13], v150 offset:2048
	ds_read_b128 v[14:17], v150 offset:3072
	ds_read_b128 v[18:21], v151
	ds_read_b128 v[22:25], v151 offset:1024
	ds_read_b128 v[26:29], v151 offset:2048
	ds_read_b128 v[30:33], v151 offset:3072
	s_lshl_b64 s[46:47], s[44:45], 21
	s_add_u32 s46, s24, s46
	s_addc_u32 s47, s25, s47
	s_and_b64 s[48:49], s[4:5], exec
	s_cselect_b32 s45, s47, s55
	s_cselect_b32 s73, s46, s54
	s_ashr_i32 s43, s42, 31
	s_lshl_b64 s[48:49], s[42:43], 21
	s_add_u32 s48, s26, s48
	s_addc_u32 s49, s27, s49
	s_and_b64 s[56:57], s[4:5], exec
	s_cselect_b32 s43, s49, s53
	s_cselect_b32 s74, s48, s52
	s_add_u32 s56, s54, 0x100080
	s_addc_u32 s57, s55, 0
	s_add_i32 s75, s51, 0xc000
	v_lshl_add_u64 v[66:67], s[56:57], 0, v[130:131]
	s_mov_b32 m0, s75
	s_add_i32 s76, s51, 0xe000
	ds_read_b128 v[34:37], v152
	ds_read_b128 v[38:41], v152 offset:1024
	ds_read_b128 v[42:45], v152 offset:2048
	ds_read_b128 v[46:49], v152 offset:3072
	ds_read_b128 v[50:53], v152 offset:4096
	ds_read_b128 v[54:57], v152 offset:5120
	ds_read_b128 v[58:61], v152 offset:6144
	ds_read_b128 v[62:65], v152 offset:7168
	global_load_lds_dwordx4 v[66:67], off
	v_lshl_add_u64 v[66:67], s[56:57], 0, v[134:135]
	s_mov_b32 m0, s76
	s_nop 0
	global_load_lds_dwordx4 v[66:67], off
	s_waitcnt vmcnt(24)
	s_waitcnt lgkmcnt(0)
	s_setprio 1
	s_barrier
	v_mfma_f32_16x16x32_bf16 v[90:93], v[2:5], v[58:61], 0
	v_mfma_f32_16x16x32_bf16 v[66:69], v[2:5], v[34:37], 0
	v_mfma_f32_16x16x32_bf16 v[70:73], v[10:13], v[34:37], 0
	v_mfma_f32_16x16x32_bf16 v[74:77], v[2:5], v[42:45], 0
	v_mfma_f32_16x16x32_bf16 v[78:81], v[10:13], v[42:45], 0
	v_mfma_f32_16x16x32_bf16 v[82:85], v[2:5], v[50:53], 0
	v_mfma_f32_16x16x32_bf16 v[86:89], v[10:13], v[50:53], 0
	v_mfma_f32_16x16x32_bf16 v[94:97], v[6:9], v[62:65], v[90:93]
	v_mfma_f32_16x16x32_bf16 v[90:93], v[10:13], v[58:61], 0
	v_mfma_f32_16x16x32_bf16 v[66:69], v[6:9], v[38:41], v[66:69]
	v_mfma_f32_16x16x32_bf16 v[126:129], v[14:17], v[38:41], v[70:73]
	v_mfma_f32_16x16x32_bf16 v[74:77], v[6:9], v[46:49], v[74:77]
	v_mfma_f32_16x16x32_bf16 v[78:81], v[14:17], v[46:49], v[78:81]
	v_mfma_f32_16x16x32_bf16 v[82:85], v[6:9], v[54:57], v[82:85]
	v_mfma_f32_16x16x32_bf16 v[86:89], v[14:17], v[54:57], v[86:89]
	v_mfma_f32_16x16x32_bf16 v[102:105], v[14:17], v[62:65], v[90:93]
	v_mfma_f32_16x16x32_bf16 v[90:93], v[18:21], v[34:37], 0
	v_mfma_f32_16x16x32_bf16 v[34:37], v[26:29], v[34:37], 0
	v_mfma_f32_16x16x32_bf16 v[110:113], v[22:25], v[38:41], v[90:93]
	v_mfma_f32_16x16x32_bf16 v[34:37], v[30:33], v[38:41], v[34:37]
	v_mfma_f32_16x16x32_bf16 v[38:41], v[18:21], v[42:45], 0
	v_mfma_f32_16x16x32_bf16 v[42:45], v[26:29], v[42:45], 0
	v_mfma_f32_16x16x32_bf16 v[38:41], v[22:25], v[46:49], v[38:41]
	v_mfma_f32_16x16x32_bf16 v[42:45], v[30:33], v[46:49], v[42:45]
	v_mfma_f32_16x16x32_bf16 v[46:49], v[18:21], v[50:53], 0
	v_mfma_f32_16x16x32_bf16 v[50:53], v[26:29], v[50:53], 0
	v_mfma_f32_16x16x32_bf16 v[46:49], v[22:25], v[54:57], v[46:49]
	v_mfma_f32_16x16x32_bf16 v[54:57], v[30:33], v[54:57], v[50:53]
	v_mfma_f32_16x16x32_bf16 v[50:53], v[18:21], v[58:61], 0
	v_mfma_f32_16x16x32_bf16 v[154:157], v[22:25], v[62:65], v[50:53]
	v_mfma_f32_16x16x32_bf16 v[50:53], v[26:29], v[58:61], 0
	v_mfma_f32_16x16x32_bf16 v[158:161], v[30:33], v[62:65], v[50:53]
	s_setprio 0
	s_barrier
	s_add_i32 s77, s66, s58
	v_lshl_add_u64 v[142:143], s[52:53], 0, v[132:133]
	s_add_i32 s78, s77, 0x2000
	v_lshl_add_u64 v[122:123], v[142:143], 0, s[30:31]
	s_mov_b32 m0, s77
	v_lshl_add_u64 v[144:145], s[52:53], 0, v[136:137]
	s_add_u32 s56, s52, 0x100100
	ds_read_b128 v[50:53], v152 offset:16384
	ds_read_b128 v[58:61], v152 offset:17408
	ds_read_b128 v[62:65], v152 offset:18432
	ds_read_b128 v[90:93], v152 offset:19456
	ds_read_b128 v[98:101], v152 offset:20480
	ds_read_b128 v[106:109], v152 offset:21504
	ds_read_b128 v[114:117], v152 offset:22528
	ds_read_b128 v[118:121], v152 offset:23552
	global_load_lds_dwordx4 v[122:123], off
	v_lshl_add_u64 v[122:123], v[144:145], 0, s[30:31]
	s_mov_b32 m0, s78
	s_addc_u32 s57, s53, 0
	s_add_i32 s79, s67, s58
	global_load_lds_dwordx4 v[122:123], off
	v_lshl_add_u64 v[122:123], s[56:57], 0, v[132:133]
	s_mov_b32 m0, s79
	s_add_i32 s80, s79, 0x2000
	global_load_lds_dwordx4 v[122:123], off
	v_lshl_add_u64 v[122:123], s[56:57], 0, v[136:137]
	s_mov_b32 m0, s80
	v_lshl_add_u64 v[148:149], s[54:55], 0, v[130:131]
	global_load_lds_dwordx4 v[122:123], off
	v_lshl_add_u64 v[122:123], v[148:149], 0, s[30:31]
	s_mov_b32 m0, s51
	v_lshl_add_u64 v[70:71], s[54:55], 0, v[134:135]
	global_load_lds_dwordx4 v[122:123], off
	v_lshl_add_u64 v[72:73], v[70:71], 0, s[30:31]
	s_mov_b32 m0, s59
	s_nop 0
	global_load_lds_dwordx4 v[72:73], off
	s_waitcnt vmcnt(24)
	s_waitcnt lgkmcnt(0)
	s_setprio 1
	s_barrier
	v_mfma_f32_16x16x32_bf16 v[122:125], v[2:5], v[50:53], 0
	v_mfma_f32_16x16x32_bf16 v[162:165], v[6:9], v[58:61], v[122:125]
	v_mfma_f32_16x16x32_bf16 v[122:125], v[10:13], v[50:53], 0
	v_mfma_f32_16x16x32_bf16 v[166:169], v[14:17], v[58:61], v[122:125]
	v_mfma_f32_16x16x32_bf16 v[122:125], v[2:5], v[62:65], 0
	v_mfma_f32_16x16x32_bf16 v[170:173], v[6:9], v[90:93], v[122:125]
	v_mfma_f32_16x16x32_bf16 v[122:125], v[10:13], v[62:65], 0
	v_mfma_f32_16x16x32_bf16 v[174:177], v[14:17], v[90:93], v[122:125]
	v_mfma_f32_16x16x32_bf16 v[122:125], v[2:5], v[98:101], 0
	v_mfma_f32_16x16x32_bf16 v[2:5], v[2:5], v[114:117], 0
	v_mfma_f32_16x16x32_bf16 v[178:181], v[6:9], v[106:109], v[122:125]
	v_mfma_f32_16x16x32_bf16 v[2:5], v[6:9], v[118:121], v[2:5]
	v_mfma_f32_16x16x32_bf16 v[6:9], v[10:13], v[114:117], 0
	v_mfma_f32_16x16x32_bf16 v[122:125], v[10:13], v[98:101], 0
	v_mfma_f32_16x16x32_bf16 v[6:9], v[14:17], v[118:121], v[6:9]
	v_mfma_f32_16x16x32_bf16 v[182:185], v[14:17], v[106:109], v[122:125]
	v_mfma_f32_16x16x32_bf16 v[14:17], v[26:29], v[50:53], 0
	v_mfma_f32_16x16x32_bf16 v[186:189], v[30:33], v[58:61], v[14:17]
	v_mfma_f32_16x16x32_bf16 v[14:17], v[18:21], v[62:65], 0
	v_mfma_f32_16x16x32_bf16 v[190:193], v[22:25], v[90:93], v[14:17]
	v_mfma_f32_16x16x32_bf16 v[14:17], v[26:29], v[62:65], 0
	v_mfma_f32_16x16x32_bf16 v[194:197], v[30:33], v[90:93], v[14:17]
	v_mfma_f32_16x16x32_bf16 v[14:17], v[18:21], v[98:101], 0
	v_mfma_f32_16x16x32_bf16 v[198:201], v[22:25], v[106:109], v[14:17]
	v_mfma_f32_16x16x32_bf16 v[14:17], v[26:29], v[98:101], 0
	v_mfma_f32_16x16x32_bf16 v[10:13], v[18:21], v[50:53], 0
	v_mfma_f32_16x16x32_bf16 v[202:205], v[30:33], v[106:109], v[14:17]
	v_mfma_f32_16x16x32_bf16 v[14:17], v[18:21], v[114:117], 0
	v_mfma_f32_16x16x32_bf16 v[10:13], v[22:25], v[58:61], v[10:13]
	v_mfma_f32_16x16x32_bf16 v[206:209], v[22:25], v[118:121], v[14:17]
	v_mfma_f32_16x16x32_bf16 v[14:17], v[26:29], v[114:117], 0
	v_mfma_f32_16x16x32_bf16 v[210:213], v[30:33], v[118:121], v[14:17]
	s_setprio 0
	s_barrier
	s_add_i32 s81, 0, 0x18000
	s_add_i32 s83, 0, 0x1c000
	v_add_u32_e32 v146, s81, v153
	v_add_u32_e32 v147, s83, v153
	s_nop 0
	ds_read_b128 v[14:17], v146
	ds_read_b128 v[18:21], v146 offset:1024
	ds_read_b128 v[26:29], v146 offset:2048
	ds_read_b128 v[214:217], v146 offset:3072
	ds_read_b128 v[218:221], v147
	ds_read_b128 v[222:225], v147 offset:1024
	ds_read_b128 v[226:229], v147 offset:2048
	ds_read_b128 v[230:233], v147 offset:3072
	s_add_u32 s56, s54, 0x100100
	s_addc_u32 s57, s55, 0
	s_mov_b32 m0, s60
	v_lshl_add_u64 v[50:51], s[56:57], 0, v[130:131]
	ds_read_b128 v[22:25], v152 offset:32768
	ds_read_b128 v[30:33], v152 offset:33792
	ds_read_b128 v[62:65], v152 offset:34816
	ds_read_b128 v[234:237], v152 offset:35840
	ds_read_b128 v[238:241], v152 offset:36864
	ds_read_b128 v[242:245], v152 offset:37888
	ds_read_b128 v[246:249], v152 offset:38912
	ds_read_b128 v[250:253], v152 offset:39936
	global_load_lds_dwordx4 v[50:51], off
	v_lshl_add_u64 v[50:51], s[56:57], 0, v[134:135]
	s_mov_b32 m0, s61
	s_nop 0
	global_load_lds_dwordx4 v[50:51], off
	s_waitcnt vmcnt(8)
	s_waitcnt lgkmcnt(0)
	s_setprio 1
	s_barrier
	v_mfma_f32_16x16x32_bf16 v[50:53], v[14:17], v[22:25], v[66:69]
	v_mfma_f32_16x16x32_bf16 v[122:125], v[18:21], v[30:33], v[50:53]
	v_mfma_f32_16x16x32_bf16 v[50:53], v[26:29], v[22:25], v[126:129]
	v_mfma_f32_16x16x32_bf16 v[114:117], v[214:217], v[30:33], v[50:53]
	v_mfma_f32_16x16x32_bf16 v[50:53], v[14:17], v[62:65], v[74:77]
	v_mfma_f32_16x16x32_bf16 v[106:109], v[18:21], v[234:237], v[50:53]
	v_mfma_f32_16x16x32_bf16 v[50:53], v[26:29], v[62:65], v[78:81]
	v_mfma_f32_16x16x32_bf16 v[98:101], v[214:217], v[234:237], v[50:53]
	v_mfma_f32_16x16x32_bf16 v[50:53], v[14:17], v[238:241], v[82:85]
	v_mfma_f32_16x16x32_bf16 v[90:93], v[18:21], v[242:245], v[50:53]
	v_mfma_f32_16x16x32_bf16 v[50:53], v[26:29], v[238:241], v[86:89]
	v_mfma_f32_16x16x32_bf16 v[82:85], v[214:217], v[242:245], v[50:53]
	v_mfma_f32_16x16x32_bf16 v[50:53], v[14:17], v[246:249], v[94:97]
	v_mfma_f32_16x16x32_bf16 v[58:61], v[18:21], v[250:253], v[50:53]
	v_mfma_f32_16x16x32_bf16 v[50:53], v[26:29], v[246:249], v[102:105]
	v_mfma_f32_16x16x32_bf16 v[50:53], v[214:217], v[250:253], v[50:53]
	v_mfma_f32_16x16x32_bf16 v[66:69], v[218:221], v[22:25], v[110:113]
	v_mfma_f32_16x16x32_bf16 v[22:25], v[226:229], v[22:25], v[34:37]
	v_mfma_f32_16x16x32_bf16 v[118:121], v[230:233], v[30:33], v[22:25]
	v_mfma_f32_16x16x32_bf16 v[22:25], v[218:221], v[62:65], v[38:41]
	v_mfma_f32_16x16x32_bf16 v[110:113], v[222:225], v[234:237], v[22:25]
	v_mfma_f32_16x16x32_bf16 v[22:25], v[226:229], v[62:65], v[42:45]
	v_mfma_f32_16x16x32_bf16 v[102:105], v[230:233], v[234:237], v[22:25]
	v_mfma_f32_16x16x32_bf16 v[22:25], v[218:221], v[238:241], v[46:49]
	v_mfma_f32_16x16x32_bf16 v[94:97], v[222:225], v[242:245], v[22:25]
	v_mfma_f32_16x16x32_bf16 v[22:25], v[226:229], v[238:241], v[54:57]
	v_mfma_f32_16x16x32_bf16 v[86:89], v[230:233], v[242:245], v[22:25]
	v_mfma_f32_16x16x32_bf16 v[22:25], v[218:221], v[246:249], v[154:157]
	v_mfma_f32_16x16x32_bf16 v[62:65], v[222:225], v[250:253], v[22:25]
	v_mfma_f32_16x16x32_bf16 v[22:25], v[226:229], v[246:249], v[158:161]
	v_mfma_f32_16x16x32_bf16 v[126:129], v[222:225], v[30:33], v[66:69]
	v_mfma_f32_16x16x32_bf16 v[54:57], v[230:233], v[250:253], v[22:25]
	s_setprio 0
	s_barrier
	s_add_i32 s81, s81, s58
	s_add_i32 s82, s81, 0x2000
	s_nop 1
	v_lshl_add_u64 v[22:23], v[142:143], 0, s[34:35]
	s_mov_b32 m0, s81
	s_add_u32 s56, s52, 0x100180
	ds_read_b128 v[34:37], v152 offset:49152
	ds_read_b128 v[42:45], v152 offset:50176
	ds_read_b128 v[154:157], v152 offset:51200
	ds_read_b128 v[158:161], v152 offset:52224
	ds_read_b128 v[234:237], v152 offset:53248
	ds_read_b128 v[238:241], v152 offset:54272
	ds_read_b128 v[242:245], v152 offset:55296
	ds_read_b128 v[246:249], v152 offset:56320
	global_load_lds_dwordx4 v[22:23], off
	v_lshl_add_u64 v[22:23], v[144:145], 0, s[34:35]
	s_mov_b32 m0, s82
	s_addc_u32 s57, s53, 0
	s_add_i32 s83, s83, s58
	global_load_lds_dwordx4 v[22:23], off
	v_lshl_add_u64 v[22:23], s[56:57], 0, v[132:133]
	s_mov_b32 m0, s83
	s_add_i32 s84, s83, 0x2000
	global_load_lds_dwordx4 v[22:23], off
	v_lshl_add_u64 v[22:23], s[56:57], 0, v[136:137]
	s_mov_b32 m0, s84
	s_nop 0
	global_load_lds_dwordx4 v[22:23], off
	v_lshl_add_u64 v[22:23], v[148:149], 0, s[34:35]
	s_mov_b32 m0, s63
	s_nop 0
	global_load_lds_dwordx4 v[22:23], off
	v_lshl_add_u64 v[22:23], v[70:71], 0, s[34:35]
	s_mov_b32 m0, s64
	s_nop 0
	global_load_lds_dwordx4 v[22:23], off
	s_waitcnt vmcnt(8)
	s_waitcnt lgkmcnt(0)
	s_setprio 1
	s_barrier
	v_mfma_f32_16x16x32_bf16 v[22:25], v[14:17], v[34:37], v[162:165]
	v_mfma_f32_16x16x32_bf16 v[78:81], v[18:21], v[42:45], v[22:25]
	v_mfma_f32_16x16x32_bf16 v[22:25], v[26:29], v[34:37], v[166:169]
	v_mfma_f32_16x16x32_bf16 v[70:73], v[214:217], v[42:45], v[22:25]
	v_mfma_f32_16x16x32_bf16 v[22:25], v[14:17], v[154:157], v[170:173]
	v_mfma_f32_16x16x32_bf16 v[46:49], v[18:21], v[158:161], v[22:25]
	v_mfma_f32_16x16x32_bf16 v[22:25], v[26:29], v[154:157], v[174:177]
	v_mfma_f32_16x16x32_bf16 v[38:41], v[214:217], v[158:161], v[22:25]
	v_mfma_f32_16x16x32_bf16 v[22:25], v[14:17], v[234:237], v[178:181]
	v_mfma_f32_16x16x32_bf16 v[2:5], v[14:17], v[242:245], v[2:5]
	v_mfma_f32_16x16x32_bf16 v[30:33], v[18:21], v[238:241], v[22:25]
	v_mfma_f32_16x16x32_bf16 v[22:25], v[26:29], v[234:237], v[182:185]
	v_mfma_f32_16x16x32_bf16 v[14:17], v[18:21], v[246:249], v[2:5]
	v_mfma_f32_16x16x32_bf16 v[2:5], v[26:29], v[242:245], v[6:9]
	v_mfma_f32_16x16x32_bf16 v[22:25], v[214:217], v[238:241], v[22:25]
	v_mfma_f32_16x16x32_bf16 v[6:9], v[214:217], v[246:249], v[2:5]
	v_mfma_f32_16x16x32_bf16 v[2:5], v[218:221], v[34:37], v[10:13]
	v_mfma_f32_16x16x32_bf16 v[74:77], v[222:225], v[42:45], v[2:5]
	v_mfma_f32_16x16x32_bf16 v[2:5], v[226:229], v[34:37], v[186:189]
	v_mfma_f32_16x16x32_bf16 v[66:69], v[230:233], v[42:45], v[2:5]
	v_mfma_f32_16x16x32_bf16 v[2:5], v[218:221], v[154:157], v[190:193]
	v_mfma_f32_16x16x32_bf16 v[42:45], v[222:225], v[158:161], v[2:5]
	v_mfma_f32_16x16x32_bf16 v[2:5], v[226:229], v[154:157], v[194:197]
	v_mfma_f32_16x16x32_bf16 v[34:37], v[230:233], v[158:161], v[2:5]
	v_mfma_f32_16x16x32_bf16 v[2:5], v[218:221], v[234:237], v[198:201]
	v_mfma_f32_16x16x32_bf16 v[26:29], v[222:225], v[238:241], v[2:5]
	v_mfma_f32_16x16x32_bf16 v[2:5], v[226:229], v[234:237], v[202:205]
	v_mfma_f32_16x16x32_bf16 v[18:21], v[230:233], v[238:241], v[2:5]
	v_mfma_f32_16x16x32_bf16 v[2:5], v[218:221], v[242:245], v[206:209]
	v_mfma_f32_16x16x32_bf16 v[10:13], v[222:225], v[246:249], v[2:5]
	v_mfma_f32_16x16x32_bf16 v[2:5], v[226:229], v[242:245], v[210:213]
	v_mfma_f32_16x16x32_bf16 v[2:5], v[230:233], v[246:249], v[2:5]
	s_setprio 0
	s_barrier
	s_add_u32 s85, s52, 0x200
	s_addc_u32 s86, s53, 0
	s_add_u32 s52, s54, 0x100180
	s_addc_u32 s53, s55, 0
	s_mov_b32 s87, 0
.LBB0_306:
	ds_read_b128 v[154:157], v150
	ds_read_b128 v[158:161], v150 offset:1024
	ds_read_b128 v[162:165], v150 offset:2048
	ds_read_b128 v[166:169], v150 offset:3072
	ds_read_b128 v[170:173], v151
	ds_read_b128 v[174:177], v151 offset:1024
	ds_read_b128 v[178:181], v151 offset:2048
	ds_read_b128 v[182:185], v151 offset:3072
	s_add_u32 s54, s52, 0xfff00080
	s_addc_u32 s55, s53, -1
	s_cmp_eq_u32 s87, 60
	s_cselect_b32 s57, s45, s55
	s_cselect_b32 s56, s73, s54
	s_cselect_b32 s55, s43, s86
	s_cselect_b32 s54, s74, s85
	s_mov_b32 m0, s75
	v_lshl_add_u64 v[142:143], s[52:53], 0, v[140:141]
	ds_read_b128 v[186:189], v152
	ds_read_b128 v[190:193], v152 offset:1024
	ds_read_b128 v[194:197], v152 offset:2048
	ds_read_b128 v[198:201], v152 offset:3072
	ds_read_b128 v[202:205], v152 offset:4096
	ds_read_b128 v[206:209], v152 offset:5120
	ds_read_b128 v[210:213], v152 offset:6144
	ds_read_b128 v[214:217], v152 offset:7168
	global_load_lds_dwordx4 v[142:143], off
	v_lshl_add_u64 v[142:143], s[52:53], 0, v[138:139]
	s_mov_b32 m0, s76
	s_nop 0
	global_load_lds_dwordx4 v[142:143], off
	s_waitcnt vmcnt(8)
	s_waitcnt lgkmcnt(0)
	s_setprio 1
	s_barrier
	v_mfma_f32_16x16x32_bf16 v[122:125], v[154:157], v[186:189], v[122:125]
	v_mfma_f32_16x16x32_bf16 v[114:117], v[162:165], v[186:189], v[114:117]
	v_mfma_f32_16x16x32_bf16 v[106:109], v[154:157], v[194:197], v[106:109]
	v_mfma_f32_16x16x32_bf16 v[98:101], v[162:165], v[194:197], v[98:101]
	v_mfma_f32_16x16x32_bf16 v[90:93], v[154:157], v[202:205], v[90:93]
	v_mfma_f32_16x16x32_bf16 v[82:85], v[162:165], v[202:205], v[82:85]
	v_mfma_f32_16x16x32_bf16 v[58:61], v[154:157], v[210:213], v[58:61]
	v_mfma_f32_16x16x32_bf16 v[50:53], v[162:165], v[210:213], v[50:53]
	v_mfma_f32_16x16x32_bf16 v[122:125], v[158:161], v[190:193], v[122:125]
	v_mfma_f32_16x16x32_bf16 v[114:117], v[166:169], v[190:193], v[114:117]
	v_mfma_f32_16x16x32_bf16 v[106:109], v[158:161], v[198:201], v[106:109]
	v_mfma_f32_16x16x32_bf16 v[98:101], v[166:169], v[198:201], v[98:101]
	v_mfma_f32_16x16x32_bf16 v[90:93], v[158:161], v[206:209], v[90:93]
	v_mfma_f32_16x16x32_bf16 v[82:85], v[166:169], v[206:209], v[82:85]
	v_mfma_f32_16x16x32_bf16 v[58:61], v[158:161], v[214:217], v[58:61]
	v_mfma_f32_16x16x32_bf16 v[50:53], v[166:169], v[214:217], v[50:53]
	v_mfma_f32_16x16x32_bf16 v[126:129], v[170:173], v[186:189], v[126:129]
	v_mfma_f32_16x16x32_bf16 v[118:121], v[178:181], v[186:189], v[118:121]
	v_mfma_f32_16x16x32_bf16 v[110:113], v[170:173], v[194:197], v[110:113]
	v_mfma_f32_16x16x32_bf16 v[102:105], v[178:181], v[194:197], v[102:105]
	v_mfma_f32_16x16x32_bf16 v[94:97], v[170:173], v[202:205], v[94:97]
	v_mfma_f32_16x16x32_bf16 v[86:89], v[178:181], v[202:205], v[86:89]
	v_mfma_f32_16x16x32_bf16 v[62:65], v[170:173], v[210:213], v[62:65]
	v_mfma_f32_16x16x32_bf16 v[54:57], v[178:181], v[210:213], v[54:57]
	v_mfma_f32_16x16x32_bf16 v[126:129], v[174:177], v[190:193], v[126:129]
	v_mfma_f32_16x16x32_bf16 v[118:121], v[182:185], v[190:193], v[118:121]
	v_mfma_f32_16x16x32_bf16 v[110:113], v[174:177], v[198:201], v[110:113]
	v_mfma_f32_16x16x32_bf16 v[102:105], v[182:185], v[198:201], v[102:105]
	v_mfma_f32_16x16x32_bf16 v[94:97], v[174:177], v[206:209], v[94:97]
	v_mfma_f32_16x16x32_bf16 v[86:89], v[182:185], v[206:209], v[86:89]
	v_mfma_f32_16x16x32_bf16 v[62:65], v[174:177], v[214:217], v[62:65]
	v_mfma_f32_16x16x32_bf16 v[54:57], v[182:185], v[214:217], v[54:57]
	s_setprio 0
	s_barrier
	s_mov_b32 m0, s77
	v_lshl_add_u64 v[142:143], s[54:55], 0, v[132:133]
	s_add_u32 s88, s54, 0x100000
	ds_read_b128 v[186:189], v152 offset:16384
	ds_read_b128 v[190:193], v152 offset:17408
	ds_read_b128 v[194:197], v152 offset:18432
	ds_read_b128 v[198:201], v152 offset:19456
	ds_read_b128 v[202:205], v152 offset:20480
	ds_read_b128 v[206:209], v152 offset:21504
	ds_read_b128 v[210:213], v152 offset:22528
	ds_read_b128 v[214:217], v152 offset:23552
	global_load_lds_dwordx4 v[142:143], off
	v_lshl_add_u64 v[144:145], s[54:55], 0, v[136:137]
	s_mov_b32 m0, s78
	s_addc_u32 s89, s55, 0
	global_load_lds_dwordx4 v[144:145], off
	v_lshl_add_u64 v[148:149], s[88:89], 0, v[132:133]
	s_mov_b32 m0, s79
	v_lshl_add_u64 v[218:219], s[56:57], 0, v[134:135]
	global_load_lds_dwordx4 v[148:149], off
	v_lshl_add_u64 v[148:149], s[88:89], 0, v[136:137]
	s_mov_b32 m0, s80
	s_nop 0
	global_load_lds_dwordx4 v[148:149], off
	v_lshl_add_u64 v[148:149], s[56:57], 0, v[130:131]
	s_mov_b32 m0, s51
	s_nop 0
	global_load_lds_dwordx4 v[148:149], off
	s_mov_b32 m0, s59
	s_nop 0
	global_load_lds_dwordx4 v[218:219], off
	s_waitcnt vmcnt(8)
	s_waitcnt lgkmcnt(0)
	s_setprio 1
	s_barrier
	v_mfma_f32_16x16x32_bf16 v[78:81], v[154:157], v[186:189], v[78:81]
	v_mfma_f32_16x16x32_bf16 v[70:73], v[162:165], v[186:189], v[70:73]
	v_mfma_f32_16x16x32_bf16 v[46:49], v[154:157], v[194:197], v[46:49]
	v_mfma_f32_16x16x32_bf16 v[38:41], v[162:165], v[194:197], v[38:41]
	v_mfma_f32_16x16x32_bf16 v[30:33], v[154:157], v[202:205], v[30:33]
	v_mfma_f32_16x16x32_bf16 v[22:25], v[162:165], v[202:205], v[22:25]
	v_mfma_f32_16x16x32_bf16 v[14:17], v[154:157], v[210:213], v[14:17]
	v_mfma_f32_16x16x32_bf16 v[6:9], v[162:165], v[210:213], v[6:9]
	v_mfma_f32_16x16x32_bf16 v[78:81], v[158:161], v[190:193], v[78:81]
	v_mfma_f32_16x16x32_bf16 v[70:73], v[166:169], v[190:193], v[70:73]
	v_mfma_f32_16x16x32_bf16 v[46:49], v[158:161], v[198:201], v[46:49]
	v_mfma_f32_16x16x32_bf16 v[38:41], v[166:169], v[198:201], v[38:41]
	v_mfma_f32_16x16x32_bf16 v[30:33], v[158:161], v[206:209], v[30:33]
	v_mfma_f32_16x16x32_bf16 v[22:25], v[166:169], v[206:209], v[22:25]
	v_mfma_f32_16x16x32_bf16 v[14:17], v[158:161], v[214:217], v[14:17]
	v_mfma_f32_16x16x32_bf16 v[6:9], v[166:169], v[214:217], v[6:9]
	v_mfma_f32_16x16x32_bf16 v[74:77], v[170:173], v[186:189], v[74:77]
	v_mfma_f32_16x16x32_bf16 v[66:69], v[178:181], v[186:189], v[66:69]
	v_mfma_f32_16x16x32_bf16 v[42:45], v[170:173], v[194:197], v[42:45]
	v_mfma_f32_16x16x32_bf16 v[34:37], v[178:181], v[194:197], v[34:37]
	v_mfma_f32_16x16x32_bf16 v[26:29], v[170:173], v[202:205], v[26:29]
	v_mfma_f32_16x16x32_bf16 v[18:21], v[178:181], v[202:205], v[18:21]
	v_mfma_f32_16x16x32_bf16 v[10:13], v[170:173], v[210:213], v[10:13]
	v_mfma_f32_16x16x32_bf16 v[2:5], v[178:181], v[210:213], v[2:5]
	v_mfma_f32_16x16x32_bf16 v[74:77], v[174:177], v[190:193], v[74:77]
	v_mfma_f32_16x16x32_bf16 v[66:69], v[182:185], v[190:193], v[66:69]
	v_mfma_f32_16x16x32_bf16 v[42:45], v[174:177], v[198:201], v[42:45]
	v_mfma_f32_16x16x32_bf16 v[34:37], v[182:185], v[198:201], v[34:37]
	v_mfma_f32_16x16x32_bf16 v[26:29], v[174:177], v[206:209], v[26:29]
	v_mfma_f32_16x16x32_bf16 v[18:21], v[182:185], v[206:209], v[18:21]
	v_mfma_f32_16x16x32_bf16 v[10:13], v[174:177], v[214:217], v[10:13]
	v_mfma_f32_16x16x32_bf16 v[2:5], v[182:185], v[214:217], v[2:5]
	s_setprio 0
	s_barrier
	ds_read_b128 v[154:157], v146
	ds_read_b128 v[158:161], v146 offset:1024
	ds_read_b128 v[162:165], v146 offset:2048
	ds_read_b128 v[166:169], v146 offset:3072
	ds_read_b128 v[170:173], v147
	ds_read_b128 v[174:177], v147 offset:1024
	ds_read_b128 v[178:181], v147 offset:2048
	ds_read_b128 v[182:185], v147 offset:3072
	s_add_u32 s56, s56, 0x100000
	s_addc_u32 s57, s57, 0
	s_mov_b32 m0, s60
	v_lshl_add_u64 v[220:221], s[56:57], 0, v[130:131]
	ds_read_b128 v[186:189], v152 offset:32768
	ds_read_b128 v[190:193], v152 offset:33792
	ds_read_b128 v[194:197], v152 offset:34816
	ds_read_b128 v[198:201], v152 offset:35840
	ds_read_b128 v[202:205], v152 offset:36864
	ds_read_b128 v[206:209], v152 offset:37888
	ds_read_b128 v[210:213], v152 offset:38912
	ds_read_b128 v[214:217], v152 offset:39936
	global_load_lds_dwordx4 v[220:221], off
	v_lshl_add_u64 v[220:221], s[56:57], 0, v[134:135]
	s_mov_b32 m0, s61
	s_nop 0
	global_load_lds_dwordx4 v[220:221], off
	s_waitcnt vmcnt(8)
	s_waitcnt lgkmcnt(0)
	s_setprio 1
	s_barrier
	v_mfma_f32_16x16x32_bf16 v[122:125], v[154:157], v[186:189], v[122:125]
	v_mfma_f32_16x16x32_bf16 v[114:117], v[162:165], v[186:189], v[114:117]
	v_mfma_f32_16x16x32_bf16 v[106:109], v[154:157], v[194:197], v[106:109]
	v_mfma_f32_16x16x32_bf16 v[98:101], v[162:165], v[194:197], v[98:101]
	v_mfma_f32_16x16x32_bf16 v[90:93], v[154:157], v[202:205], v[90:93]
	v_mfma_f32_16x16x32_bf16 v[82:85], v[162:165], v[202:205], v[82:85]
	v_mfma_f32_16x16x32_bf16 v[58:61], v[154:157], v[210:213], v[58:61]
	v_mfma_f32_16x16x32_bf16 v[50:53], v[162:165], v[210:213], v[50:53]
	v_mfma_f32_16x16x32_bf16 v[122:125], v[158:161], v[190:193], v[122:125]
	v_mfma_f32_16x16x32_bf16 v[114:117], v[166:169], v[190:193], v[114:117]
	v_mfma_f32_16x16x32_bf16 v[106:109], v[158:161], v[198:201], v[106:109]
	v_mfma_f32_16x16x32_bf16 v[98:101], v[166:169], v[198:201], v[98:101]
	v_mfma_f32_16x16x32_bf16 v[90:93], v[158:161], v[206:209], v[90:93]
	v_mfma_f32_16x16x32_bf16 v[82:85], v[166:169], v[206:209], v[82:85]
	v_mfma_f32_16x16x32_bf16 v[58:61], v[158:161], v[214:217], v[58:61]
	v_mfma_f32_16x16x32_bf16 v[50:53], v[166:169], v[214:217], v[50:53]
	v_mfma_f32_16x16x32_bf16 v[126:129], v[170:173], v[186:189], v[126:129]
	v_mfma_f32_16x16x32_bf16 v[118:121], v[178:181], v[186:189], v[118:121]
	v_mfma_f32_16x16x32_bf16 v[110:113], v[170:173], v[194:197], v[110:113]
	v_mfma_f32_16x16x32_bf16 v[102:105], v[178:181], v[194:197], v[102:105]
	v_mfma_f32_16x16x32_bf16 v[94:97], v[170:173], v[202:205], v[94:97]
	v_mfma_f32_16x16x32_bf16 v[86:89], v[178:181], v[202:205], v[86:89]
	v_mfma_f32_16x16x32_bf16 v[62:65], v[170:173], v[210:213], v[62:65]
	v_mfma_f32_16x16x32_bf16 v[54:57], v[178:181], v[210:213], v[54:57]
	v_mfma_f32_16x16x32_bf16 v[126:129], v[174:177], v[190:193], v[126:129]
	v_mfma_f32_16x16x32_bf16 v[118:121], v[182:185], v[190:193], v[118:121]
	v_mfma_f32_16x16x32_bf16 v[110:113], v[174:177], v[198:201], v[110:113]
	v_mfma_f32_16x16x32_bf16 v[102:105], v[182:185], v[198:201], v[102:105]
	v_mfma_f32_16x16x32_bf16 v[94:97], v[174:177], v[206:209], v[94:97]
	v_mfma_f32_16x16x32_bf16 v[86:89], v[182:185], v[206:209], v[86:89]
	v_mfma_f32_16x16x32_bf16 v[62:65], v[174:177], v[214:217], v[62:65]
	v_mfma_f32_16x16x32_bf16 v[54:57], v[182:185], v[214:217], v[54:57]
	s_setprio 0
	s_barrier
	s_mov_b32 m0, s81
	v_lshl_add_u64 v[142:143], v[142:143], 0, s[14:15]
	s_add_u32 s54, s54, 0x100080
	ds_read_b128 v[186:189], v152 offset:49152
	ds_read_b128 v[190:193], v152 offset:50176
	ds_read_b128 v[194:197], v152 offset:51200
	ds_read_b128 v[198:201], v152 offset:52224
	ds_read_b128 v[202:205], v152 offset:53248
	ds_read_b128 v[206:209], v152 offset:54272
	ds_read_b128 v[210:213], v152 offset:55296
	ds_read_b128 v[214:217], v152 offset:56320
	global_load_lds_dwordx4 v[142:143], off
	v_lshl_add_u64 v[142:143], v[144:145], 0, s[14:15]
	s_mov_b32 m0, s82
	s_addc_u32 s55, s55, 0
	global_load_lds_dwordx4 v[142:143], off
	v_lshl_add_u64 v[142:143], s[54:55], 0, v[132:133]
	s_mov_b32 m0, s83
	s_nop 0
	global_load_lds_dwordx4 v[142:143], off
	v_lshl_add_u64 v[142:143], s[54:55], 0, v[136:137]
	s_mov_b32 m0, s84
	s_nop 0
	global_load_lds_dwordx4 v[142:143], off
	v_lshl_add_u64 v[142:143], v[148:149], 0, s[14:15]
	s_mov_b32 m0, s63
	s_nop 0
	global_load_lds_dwordx4 v[142:143], off
	v_lshl_add_u64 v[142:143], v[218:219], 0, s[14:15]
	s_mov_b32 m0, s64
	s_nop 0
	global_load_lds_dwordx4 v[142:143], off
	s_waitcnt vmcnt(8)
	s_waitcnt lgkmcnt(0)
	s_setprio 1
	s_barrier
	v_mfma_f32_16x16x32_bf16 v[78:81], v[154:157], v[186:189], v[78:81]
	v_mfma_f32_16x16x32_bf16 v[70:73], v[162:165], v[186:189], v[70:73]
	v_mfma_f32_16x16x32_bf16 v[46:49], v[154:157], v[194:197], v[46:49]
	v_mfma_f32_16x16x32_bf16 v[38:41], v[162:165], v[194:197], v[38:41]
	v_mfma_f32_16x16x32_bf16 v[30:33], v[154:157], v[202:205], v[30:33]
	v_mfma_f32_16x16x32_bf16 v[22:25], v[162:165], v[202:205], v[22:25]
	v_mfma_f32_16x16x32_bf16 v[14:17], v[154:157], v[210:213], v[14:17]
	v_mfma_f32_16x16x32_bf16 v[6:9], v[162:165], v[210:213], v[6:9]
	v_mfma_f32_16x16x32_bf16 v[78:81], v[158:161], v[190:193], v[78:81]
	v_mfma_f32_16x16x32_bf16 v[70:73], v[166:169], v[190:193], v[70:73]
	v_mfma_f32_16x16x32_bf16 v[46:49], v[158:161], v[198:201], v[46:49]
	v_mfma_f32_16x16x32_bf16 v[38:41], v[166:169], v[198:201], v[38:41]
	v_mfma_f32_16x16x32_bf16 v[30:33], v[158:161], v[206:209], v[30:33]
	v_mfma_f32_16x16x32_bf16 v[22:25], v[166:169], v[206:209], v[22:25]
	v_mfma_f32_16x16x32_bf16 v[14:17], v[158:161], v[214:217], v[14:17]
	v_mfma_f32_16x16x32_bf16 v[6:9], v[166:169], v[214:217], v[6:9]
	v_mfma_f32_16x16x32_bf16 v[74:77], v[170:173], v[186:189], v[74:77]
	v_mfma_f32_16x16x32_bf16 v[66:69], v[178:181], v[186:189], v[66:69]
	v_mfma_f32_16x16x32_bf16 v[42:45], v[170:173], v[194:197], v[42:45]
	v_mfma_f32_16x16x32_bf16 v[34:37], v[178:181], v[194:197], v[34:37]
	v_mfma_f32_16x16x32_bf16 v[26:29], v[170:173], v[202:205], v[26:29]
	v_mfma_f32_16x16x32_bf16 v[18:21], v[178:181], v[202:205], v[18:21]
	v_mfma_f32_16x16x32_bf16 v[10:13], v[170:173], v[210:213], v[10:13]
	v_mfma_f32_16x16x32_bf16 v[2:5], v[178:181], v[210:213], v[2:5]
	v_mfma_f32_16x16x32_bf16 v[74:77], v[174:177], v[190:193], v[74:77]
	v_mfma_f32_16x16x32_bf16 v[66:69], v[182:185], v[190:193], v[66:69]
	v_mfma_f32_16x16x32_bf16 v[42:45], v[174:177], v[198:201], v[42:45]
	v_mfma_f32_16x16x32_bf16 v[34:37], v[182:185], v[198:201], v[34:37]
	v_mfma_f32_16x16x32_bf16 v[26:29], v[174:177], v[206:209], v[26:29]
	v_mfma_f32_16x16x32_bf16 v[18:21], v[182:185], v[206:209], v[18:21]
	v_mfma_f32_16x16x32_bf16 v[10:13], v[174:177], v[214:217], v[10:13]
	v_mfma_f32_16x16x32_bf16 v[2:5], v[182:185], v[214:217], v[2:5]
	s_setprio 0
	s_barrier
	s_add_i32 s87, s87, 2
	s_add_u32 s85, s85, 0x100
	s_addc_u32 s86, s86, 0
	s_add_u32 s52, s52, 0x100
	s_addc_u32 s53, s53, 0
	s_cmp_gt_u32 s87, 61
	s_cbranch_scc0 .LBB0_306
	s_and_b64 vcc, exec, s[16:17]
	s_cbranch_vccz .LBB0_309
	s_barrier

.LBB0_746:
	s_ashr_i32 s45, s44, 31
	ds_read_b128 v[2:5], v150
	ds_read_b128 v[6:9], v150 offset:1024
	ds_read_b128 v[10:13], v150 offset:2048
	ds_read_b128 v[14:17], v150 offset:3072
	ds_read_b128 v[18:21], v151
	ds_read_b128 v[22:25], v151 offset:1024
	ds_read_b128 v[26:29], v151 offset:2048
	ds_read_b128 v[30:33], v151 offset:3072
	s_lshl_b64 s[46:47], s[44:45], 20
	s_add_u32 s46, s24, s46
	s_addc_u32 s47, s25, s47
	s_and_b64 s[48:49], s[4:5], exec
	s_cselect_b32 s45, s47, s55
	s_cselect_b32 s75, s46, s54
	s_ashr_i32 s43, s42, 31
	s_lshl_b64 s[48:49], s[42:43], 20
	s_add_u32 s48, s58, s48
	s_addc_u32 s49, s59, s49
	s_and_b64 s[56:57], s[4:5], exec
	s_cselect_b32 s43, s49, s53
	s_cselect_b32 s76, s48, s52
	s_add_u32 s56, s54, 0x80080
	s_addc_u32 s57, s55, 0
	s_add_i32 s77, s51, 0xc000
	v_lshl_add_u64 v[66:67], s[56:57], 0, v[130:131]
	s_mov_b32 m0, s77
	s_add_i32 s78, s51, 0xe000
	ds_read_b128 v[34:37], v152
	ds_read_b128 v[38:41], v152 offset:1024
	ds_read_b128 v[42:45], v152 offset:2048
	ds_read_b128 v[46:49], v152 offset:3072
	ds_read_b128 v[50:53], v152 offset:4096
	ds_read_b128 v[54:57], v152 offset:5120
	ds_read_b128 v[58:61], v152 offset:6144
	ds_read_b128 v[62:65], v152 offset:7168
	global_load_lds_dwordx4 v[66:67], off
	v_lshl_add_u64 v[66:67], s[56:57], 0, v[134:135]
	s_mov_b32 m0, s78
	s_nop 0
	global_load_lds_dwordx4 v[66:67], off
	s_waitcnt vmcnt(24)
	s_waitcnt lgkmcnt(0)
	s_setprio 1
	s_barrier
	v_mfma_f32_16x16x32_bf16 v[90:93], v[2:5], v[58:61], 0
	v_mfma_f32_16x16x32_bf16 v[66:69], v[2:5], v[34:37], 0
	v_mfma_f32_16x16x32_bf16 v[70:73], v[10:13], v[34:37], 0
	v_mfma_f32_16x16x32_bf16 v[74:77], v[2:5], v[42:45], 0
	v_mfma_f32_16x16x32_bf16 v[78:81], v[10:13], v[42:45], 0
	v_mfma_f32_16x16x32_bf16 v[82:85], v[2:5], v[50:53], 0
	v_mfma_f32_16x16x32_bf16 v[86:89], v[10:13], v[50:53], 0
	v_mfma_f32_16x16x32_bf16 v[94:97], v[6:9], v[62:65], v[90:93]
	v_mfma_f32_16x16x32_bf16 v[90:93], v[10:13], v[58:61], 0
	v_mfma_f32_16x16x32_bf16 v[66:69], v[6:9], v[38:41], v[66:69]
	v_mfma_f32_16x16x32_bf16 v[126:129], v[14:17], v[38:41], v[70:73]
	v_mfma_f32_16x16x32_bf16 v[74:77], v[6:9], v[46:49], v[74:77]
	v_mfma_f32_16x16x32_bf16 v[78:81], v[14:17], v[46:49], v[78:81]
	v_mfma_f32_16x16x32_bf16 v[82:85], v[6:9], v[54:57], v[82:85]
	v_mfma_f32_16x16x32_bf16 v[86:89], v[14:17], v[54:57], v[86:89]
	v_mfma_f32_16x16x32_bf16 v[102:105], v[14:17], v[62:65], v[90:93]
	v_mfma_f32_16x16x32_bf16 v[90:93], v[18:21], v[34:37], 0
	v_mfma_f32_16x16x32_bf16 v[34:37], v[26:29], v[34:37], 0
	v_mfma_f32_16x16x32_bf16 v[110:113], v[22:25], v[38:41], v[90:93]
	v_mfma_f32_16x16x32_bf16 v[34:37], v[30:33], v[38:41], v[34:37]
	v_mfma_f32_16x16x32_bf16 v[38:41], v[18:21], v[42:45], 0
	v_mfma_f32_16x16x32_bf16 v[42:45], v[26:29], v[42:45], 0
	v_mfma_f32_16x16x32_bf16 v[38:41], v[22:25], v[46:49], v[38:41]
	v_mfma_f32_16x16x32_bf16 v[42:45], v[30:33], v[46:49], v[42:45]
	v_mfma_f32_16x16x32_bf16 v[46:49], v[18:21], v[50:53], 0
	v_mfma_f32_16x16x32_bf16 v[50:53], v[26:29], v[50:53], 0
	v_mfma_f32_16x16x32_bf16 v[46:49], v[22:25], v[54:57], v[46:49]
	v_mfma_f32_16x16x32_bf16 v[54:57], v[30:33], v[54:57], v[50:53]
	v_mfma_f32_16x16x32_bf16 v[50:53], v[18:21], v[58:61], 0
	v_mfma_f32_16x16x32_bf16 v[154:157], v[22:25], v[62:65], v[50:53]
	v_mfma_f32_16x16x32_bf16 v[50:53], v[26:29], v[58:61], 0
	v_mfma_f32_16x16x32_bf16 v[158:161], v[30:33], v[62:65], v[50:53]
	s_setprio 0
	s_barrier
	s_add_i32 s79, s68, s60
	v_lshl_add_u64 v[142:143], s[52:53], 0, v[132:133]
	s_add_i32 s80, s79, 0x2000
	v_lshl_add_u64 v[122:123], v[142:143], 0, s[16:17]
	s_mov_b32 m0, s79
	v_lshl_add_u64 v[144:145], s[52:53], 0, v[136:137]
	s_add_u32 s56, s52, 0x80100
	ds_read_b128 v[50:53], v152 offset:16384
	ds_read_b128 v[58:61], v152 offset:17408
	ds_read_b128 v[62:65], v152 offset:18432
	ds_read_b128 v[90:93], v152 offset:19456
	ds_read_b128 v[98:101], v152 offset:20480
	ds_read_b128 v[106:109], v152 offset:21504
	ds_read_b128 v[114:117], v152 offset:22528
	ds_read_b128 v[118:121], v152 offset:23552
	global_load_lds_dwordx4 v[122:123], off
	v_lshl_add_u64 v[122:123], v[144:145], 0, s[16:17]
	s_mov_b32 m0, s80
	s_addc_u32 s57, s53, 0
	s_add_i32 s81, s69, s60
	global_load_lds_dwordx4 v[122:123], off
	v_lshl_add_u64 v[122:123], s[56:57], 0, v[132:133]
	s_mov_b32 m0, s81
	s_add_i32 s82, s81, 0x2000
	global_load_lds_dwordx4 v[122:123], off
	v_lshl_add_u64 v[122:123], s[56:57], 0, v[136:137]
	s_mov_b32 m0, s82
	v_lshl_add_u64 v[148:149], s[54:55], 0, v[130:131]
	global_load_lds_dwordx4 v[122:123], off
	v_lshl_add_u64 v[122:123], v[148:149], 0, s[16:17]
	s_mov_b32 m0, s51
	v_lshl_add_u64 v[70:71], s[54:55], 0, v[134:135]
	global_load_lds_dwordx4 v[122:123], off
	v_lshl_add_u64 v[72:73], v[70:71], 0, s[16:17]
	s_mov_b32 m0, s61
	s_nop 0
	global_load_lds_dwordx4 v[72:73], off
	s_waitcnt vmcnt(24)
	s_waitcnt lgkmcnt(0)
	s_setprio 1
	s_barrier
	v_mfma_f32_16x16x32_bf16 v[122:125], v[2:5], v[50:53], 0
	v_mfma_f32_16x16x32_bf16 v[162:165], v[6:9], v[58:61], v[122:125]
	v_mfma_f32_16x16x32_bf16 v[122:125], v[10:13], v[50:53], 0
	v_mfma_f32_16x16x32_bf16 v[166:169], v[14:17], v[58:61], v[122:125]
	v_mfma_f32_16x16x32_bf16 v[122:125], v[2:5], v[62:65], 0
	v_mfma_f32_16x16x32_bf16 v[170:173], v[6:9], v[90:93], v[122:125]
	v_mfma_f32_16x16x32_bf16 v[122:125], v[10:13], v[62:65], 0
	v_mfma_f32_16x16x32_bf16 v[174:177], v[14:17], v[90:93], v[122:125]
	v_mfma_f32_16x16x32_bf16 v[122:125], v[2:5], v[98:101], 0
	v_mfma_f32_16x16x32_bf16 v[2:5], v[2:5], v[114:117], 0
	v_mfma_f32_16x16x32_bf16 v[178:181], v[6:9], v[106:109], v[122:125]
	v_mfma_f32_16x16x32_bf16 v[2:5], v[6:9], v[118:121], v[2:5]
	v_mfma_f32_16x16x32_bf16 v[6:9], v[10:13], v[114:117], 0
	v_mfma_f32_16x16x32_bf16 v[122:125], v[10:13], v[98:101], 0
	v_mfma_f32_16x16x32_bf16 v[6:9], v[14:17], v[118:121], v[6:9]
	v_mfma_f32_16x16x32_bf16 v[182:185], v[14:17], v[106:109], v[122:125]
	v_mfma_f32_16x16x32_bf16 v[14:17], v[26:29], v[50:53], 0
	v_mfma_f32_16x16x32_bf16 v[186:189], v[30:33], v[58:61], v[14:17]
	v_mfma_f32_16x16x32_bf16 v[14:17], v[18:21], v[62:65], 0
	v_mfma_f32_16x16x32_bf16 v[190:193], v[22:25], v[90:93], v[14:17]
	v_mfma_f32_16x16x32_bf16 v[14:17], v[26:29], v[62:65], 0
	v_mfma_f32_16x16x32_bf16 v[194:197], v[30:33], v[90:93], v[14:17]
	v_mfma_f32_16x16x32_bf16 v[14:17], v[18:21], v[98:101], 0
	v_mfma_f32_16x16x32_bf16 v[198:201], v[22:25], v[106:109], v[14:17]
	v_mfma_f32_16x16x32_bf16 v[14:17], v[26:29], v[98:101], 0
	v_mfma_f32_16x16x32_bf16 v[10:13], v[18:21], v[50:53], 0
	v_mfma_f32_16x16x32_bf16 v[202:205], v[30:33], v[106:109], v[14:17]
	v_mfma_f32_16x16x32_bf16 v[14:17], v[18:21], v[114:117], 0
	v_mfma_f32_16x16x32_bf16 v[10:13], v[22:25], v[58:61], v[10:13]
	v_mfma_f32_16x16x32_bf16 v[206:209], v[22:25], v[118:121], v[14:17]
	v_mfma_f32_16x16x32_bf16 v[14:17], v[26:29], v[114:117], 0
	v_mfma_f32_16x16x32_bf16 v[210:213], v[30:33], v[118:121], v[14:17]
	s_setprio 0
	s_barrier
	s_add_i32 s83, 0, 0x18000
	s_add_i32 s85, 0, 0x1c000
	v_add_u32_e32 v146, s83, v153
	v_add_u32_e32 v147, s85, v153
	s_nop 0
	ds_read_b128 v[14:17], v146
	ds_read_b128 v[18:21], v146 offset:1024
	ds_read_b128 v[26:29], v146 offset:2048
	ds_read_b128 v[214:217], v146 offset:3072
	ds_read_b128 v[218:221], v147
	ds_read_b128 v[222:225], v147 offset:1024
	ds_read_b128 v[226:229], v147 offset:2048
	ds_read_b128 v[230:233], v147 offset:3072
	s_add_u32 s56, s54, 0x80100
	s_addc_u32 s57, s55, 0
	s_mov_b32 m0, s62
	v_lshl_add_u64 v[50:51], s[56:57], 0, v[130:131]
	ds_read_b128 v[22:25], v152 offset:32768
	ds_read_b128 v[30:33], v152 offset:33792
	ds_read_b128 v[62:65], v152 offset:34816
	ds_read_b128 v[234:237], v152 offset:35840
	ds_read_b128 v[238:241], v152 offset:36864
	ds_read_b128 v[242:245], v152 offset:37888
	ds_read_b128 v[246:249], v152 offset:38912
	ds_read_b128 v[250:253], v152 offset:39936
	global_load_lds_dwordx4 v[50:51], off
	v_lshl_add_u64 v[50:51], s[56:57], 0, v[134:135]
	s_mov_b32 m0, s63
	s_nop 0
	global_load_lds_dwordx4 v[50:51], off
	s_waitcnt vmcnt(8)
	s_waitcnt lgkmcnt(0)
	s_setprio 1
	s_barrier
	v_mfma_f32_16x16x32_bf16 v[50:53], v[14:17], v[22:25], v[66:69]
	v_mfma_f32_16x16x32_bf16 v[122:125], v[18:21], v[30:33], v[50:53]
	v_mfma_f32_16x16x32_bf16 v[50:53], v[26:29], v[22:25], v[126:129]
	v_mfma_f32_16x16x32_bf16 v[114:117], v[214:217], v[30:33], v[50:53]
	v_mfma_f32_16x16x32_bf16 v[50:53], v[14:17], v[62:65], v[74:77]
	v_mfma_f32_16x16x32_bf16 v[106:109], v[18:21], v[234:237], v[50:53]
	v_mfma_f32_16x16x32_bf16 v[50:53], v[26:29], v[62:65], v[78:81]
	v_mfma_f32_16x16x32_bf16 v[98:101], v[214:217], v[234:237], v[50:53]
	v_mfma_f32_16x16x32_bf16 v[50:53], v[14:17], v[238:241], v[82:85]
	v_mfma_f32_16x16x32_bf16 v[90:93], v[18:21], v[242:245], v[50:53]
	v_mfma_f32_16x16x32_bf16 v[50:53], v[26:29], v[238:241], v[86:89]
	v_mfma_f32_16x16x32_bf16 v[82:85], v[214:217], v[242:245], v[50:53]
	v_mfma_f32_16x16x32_bf16 v[50:53], v[14:17], v[246:249], v[94:97]
	v_mfma_f32_16x16x32_bf16 v[58:61], v[18:21], v[250:253], v[50:53]
	v_mfma_f32_16x16x32_bf16 v[50:53], v[26:29], v[246:249], v[102:105]
	v_mfma_f32_16x16x32_bf16 v[50:53], v[214:217], v[250:253], v[50:53]
	v_mfma_f32_16x16x32_bf16 v[66:69], v[218:221], v[22:25], v[110:113]
	v_mfma_f32_16x16x32_bf16 v[22:25], v[226:229], v[22:25], v[34:37]
	v_mfma_f32_16x16x32_bf16 v[118:121], v[230:233], v[30:33], v[22:25]
	v_mfma_f32_16x16x32_bf16 v[22:25], v[218:221], v[62:65], v[38:41]
	v_mfma_f32_16x16x32_bf16 v[110:113], v[222:225], v[234:237], v[22:25]
	v_mfma_f32_16x16x32_bf16 v[22:25], v[226:229], v[62:65], v[42:45]
	v_mfma_f32_16x16x32_bf16 v[102:105], v[230:233], v[234:237], v[22:25]
	v_mfma_f32_16x16x32_bf16 v[22:25], v[218:221], v[238:241], v[46:49]
	v_mfma_f32_16x16x32_bf16 v[94:97], v[222:225], v[242:245], v[22:25]
	v_mfma_f32_16x16x32_bf16 v[22:25], v[226:229], v[238:241], v[54:57]
	v_mfma_f32_16x16x32_bf16 v[86:89], v[230:233], v[242:245], v[22:25]
	v_mfma_f32_16x16x32_bf16 v[22:25], v[218:221], v[246:249], v[154:157]
	v_mfma_f32_16x16x32_bf16 v[62:65], v[222:225], v[250:253], v[22:25]
	v_mfma_f32_16x16x32_bf16 v[22:25], v[226:229], v[246:249], v[158:161]
	v_mfma_f32_16x16x32_bf16 v[126:129], v[222:225], v[30:33], v[66:69]
	v_mfma_f32_16x16x32_bf16 v[54:57], v[230:233], v[250:253], v[22:25]
	s_setprio 0
	s_barrier
	s_add_i32 s83, s83, s60
	s_add_i32 s84, s83, 0x2000
	s_nop 1
	v_lshl_add_u64 v[22:23], v[142:143], 0, s[30:31]
	s_mov_b32 m0, s83
	s_add_u32 s56, s52, 0x80180
	ds_read_b128 v[34:37], v152 offset:49152
	ds_read_b128 v[42:45], v152 offset:50176
	ds_read_b128 v[154:157], v152 offset:51200
	ds_read_b128 v[158:161], v152 offset:52224
	ds_read_b128 v[234:237], v152 offset:53248
	ds_read_b128 v[238:241], v152 offset:54272
	ds_read_b128 v[242:245], v152 offset:55296
	ds_read_b128 v[246:249], v152 offset:56320
	global_load_lds_dwordx4 v[22:23], off
	v_lshl_add_u64 v[22:23], v[144:145], 0, s[30:31]
	s_mov_b32 m0, s84
	s_addc_u32 s57, s53, 0
	s_add_i32 s85, s85, s60
	global_load_lds_dwordx4 v[22:23], off
	v_lshl_add_u64 v[22:23], s[56:57], 0, v[132:133]
	s_mov_b32 m0, s85
	s_add_i32 s86, s85, 0x2000
	global_load_lds_dwordx4 v[22:23], off
	v_lshl_add_u64 v[22:23], s[56:57], 0, v[136:137]
	s_mov_b32 m0, s86
	s_nop 0
	global_load_lds_dwordx4 v[22:23], off
	v_lshl_add_u64 v[22:23], v[148:149], 0, s[30:31]
	s_mov_b32 m0, s65
	s_nop 0
	global_load_lds_dwordx4 v[22:23], off
	v_lshl_add_u64 v[22:23], v[70:71], 0, s[30:31]
	s_mov_b32 m0, s66
	s_nop 0
	global_load_lds_dwordx4 v[22:23], off
	s_waitcnt vmcnt(8)
	s_waitcnt lgkmcnt(0)
	s_setprio 1
	s_barrier
	v_mfma_f32_16x16x32_bf16 v[22:25], v[14:17], v[34:37], v[162:165]
	v_mfma_f32_16x16x32_bf16 v[78:81], v[18:21], v[42:45], v[22:25]
	v_mfma_f32_16x16x32_bf16 v[22:25], v[26:29], v[34:37], v[166:169]
	v_mfma_f32_16x16x32_bf16 v[70:73], v[214:217], v[42:45], v[22:25]
	v_mfma_f32_16x16x32_bf16 v[22:25], v[14:17], v[154:157], v[170:173]
	v_mfma_f32_16x16x32_bf16 v[46:49], v[18:21], v[158:161], v[22:25]
	v_mfma_f32_16x16x32_bf16 v[22:25], v[26:29], v[154:157], v[174:177]
	v_mfma_f32_16x16x32_bf16 v[38:41], v[214:217], v[158:161], v[22:25]
	v_mfma_f32_16x16x32_bf16 v[22:25], v[14:17], v[234:237], v[178:181]
	v_mfma_f32_16x16x32_bf16 v[2:5], v[14:17], v[242:245], v[2:5]
	v_mfma_f32_16x16x32_bf16 v[30:33], v[18:21], v[238:241], v[22:25]
	v_mfma_f32_16x16x32_bf16 v[22:25], v[26:29], v[234:237], v[182:185]
	v_mfma_f32_16x16x32_bf16 v[14:17], v[18:21], v[246:249], v[2:5]
	v_mfma_f32_16x16x32_bf16 v[2:5], v[26:29], v[242:245], v[6:9]
	v_mfma_f32_16x16x32_bf16 v[22:25], v[214:217], v[238:241], v[22:25]
	v_mfma_f32_16x16x32_bf16 v[6:9], v[214:217], v[246:249], v[2:5]
	v_mfma_f32_16x16x32_bf16 v[2:5], v[218:221], v[34:37], v[10:13]
	v_mfma_f32_16x16x32_bf16 v[74:77], v[222:225], v[42:45], v[2:5]
	v_mfma_f32_16x16x32_bf16 v[2:5], v[226:229], v[34:37], v[186:189]
	v_mfma_f32_16x16x32_bf16 v[66:69], v[230:233], v[42:45], v[2:5]
	v_mfma_f32_16x16x32_bf16 v[2:5], v[218:221], v[154:157], v[190:193]
	v_mfma_f32_16x16x32_bf16 v[42:45], v[222:225], v[158:161], v[2:5]
	v_mfma_f32_16x16x32_bf16 v[2:5], v[226:229], v[154:157], v[194:197]
	v_mfma_f32_16x16x32_bf16 v[34:37], v[230:233], v[158:161], v[2:5]
	v_mfma_f32_16x16x32_bf16 v[2:5], v[218:221], v[234:237], v[198:201]
	v_mfma_f32_16x16x32_bf16 v[26:29], v[222:225], v[238:241], v[2:5]
	v_mfma_f32_16x16x32_bf16 v[2:5], v[226:229], v[234:237], v[202:205]
	v_mfma_f32_16x16x32_bf16 v[18:21], v[230:233], v[238:241], v[2:5]
	v_mfma_f32_16x16x32_bf16 v[2:5], v[218:221], v[242:245], v[206:209]
	v_mfma_f32_16x16x32_bf16 v[10:13], v[222:225], v[246:249], v[2:5]
	v_mfma_f32_16x16x32_bf16 v[2:5], v[226:229], v[242:245], v[210:213]
	v_mfma_f32_16x16x32_bf16 v[2:5], v[230:233], v[246:249], v[2:5]
	s_setprio 0
	s_barrier
	s_add_u32 s87, s52, 0x200
	s_addc_u32 s88, s53, 0
	s_add_u32 s52, s54, 0x80180
	s_addc_u32 s53, s55, 0
	s_mov_b32 s89, 0
.LBB0_747:
	ds_read_b128 v[154:157], v150
	ds_read_b128 v[158:161], v150 offset:1024
	ds_read_b128 v[162:165], v150 offset:2048
	ds_read_b128 v[166:169], v150 offset:3072
	ds_read_b128 v[170:173], v151
	ds_read_b128 v[174:177], v151 offset:1024
	ds_read_b128 v[178:181], v151 offset:2048
	ds_read_b128 v[182:185], v151 offset:3072
	s_add_u32 s54, s52, 0xfff80080
	s_addc_u32 s55, s53, -1
	s_cmp_eq_u32 s89, 28
	s_cselect_b32 s57, s45, s55
	s_cselect_b32 s56, s75, s54
	s_cselect_b32 s55, s43, s88
	s_cselect_b32 s54, s76, s87
	s_mov_b32 m0, s77
	v_lshl_add_u64 v[142:143], s[52:53], 0, v[140:141]
	ds_read_b128 v[186:189], v152
	ds_read_b128 v[190:193], v152 offset:1024
	ds_read_b128 v[194:197], v152 offset:2048
	ds_read_b128 v[198:201], v152 offset:3072
	ds_read_b128 v[202:205], v152 offset:4096
	ds_read_b128 v[206:209], v152 offset:5120
	ds_read_b128 v[210:213], v152 offset:6144
	ds_read_b128 v[214:217], v152 offset:7168
	global_load_lds_dwordx4 v[142:143], off
	v_lshl_add_u64 v[142:143], s[52:53], 0, v[138:139]
	s_mov_b32 m0, s78
	s_nop 0
	global_load_lds_dwordx4 v[142:143], off
	s_waitcnt vmcnt(8)
	s_waitcnt lgkmcnt(0)
	s_setprio 1
	s_barrier
	v_mfma_f32_16x16x32_bf16 v[122:125], v[154:157], v[186:189], v[122:125]
	v_mfma_f32_16x16x32_bf16 v[114:117], v[162:165], v[186:189], v[114:117]
	v_mfma_f32_16x16x32_bf16 v[106:109], v[154:157], v[194:197], v[106:109]
	v_mfma_f32_16x16x32_bf16 v[98:101], v[162:165], v[194:197], v[98:101]
	v_mfma_f32_16x16x32_bf16 v[90:93], v[154:157], v[202:205], v[90:93]
	v_mfma_f32_16x16x32_bf16 v[82:85], v[162:165], v[202:205], v[82:85]
	v_mfma_f32_16x16x32_bf16 v[58:61], v[154:157], v[210:213], v[58:61]
	v_mfma_f32_16x16x32_bf16 v[50:53], v[162:165], v[210:213], v[50:53]
	v_mfma_f32_16x16x32_bf16 v[122:125], v[158:161], v[190:193], v[122:125]
	v_mfma_f32_16x16x32_bf16 v[114:117], v[166:169], v[190:193], v[114:117]
	v_mfma_f32_16x16x32_bf16 v[106:109], v[158:161], v[198:201], v[106:109]
	v_mfma_f32_16x16x32_bf16 v[98:101], v[166:169], v[198:201], v[98:101]
	v_mfma_f32_16x16x32_bf16 v[90:93], v[158:161], v[206:209], v[90:93]
	v_mfma_f32_16x16x32_bf16 v[82:85], v[166:169], v[206:209], v[82:85]
	v_mfma_f32_16x16x32_bf16 v[58:61], v[158:161], v[214:217], v[58:61]
	v_mfma_f32_16x16x32_bf16 v[50:53], v[166:169], v[214:217], v[50:53]
	v_mfma_f32_16x16x32_bf16 v[126:129], v[170:173], v[186:189], v[126:129]
	v_mfma_f32_16x16x32_bf16 v[118:121], v[178:181], v[186:189], v[118:121]
	v_mfma_f32_16x16x32_bf16 v[110:113], v[170:173], v[194:197], v[110:113]
	v_mfma_f32_16x16x32_bf16 v[102:105], v[178:181], v[194:197], v[102:105]
	v_mfma_f32_16x16x32_bf16 v[94:97], v[170:173], v[202:205], v[94:97]
	v_mfma_f32_16x16x32_bf16 v[86:89], v[178:181], v[202:205], v[86:89]
	v_mfma_f32_16x16x32_bf16 v[62:65], v[170:173], v[210:213], v[62:65]
	v_mfma_f32_16x16x32_bf16 v[54:57], v[178:181], v[210:213], v[54:57]
	v_mfma_f32_16x16x32_bf16 v[126:129], v[174:177], v[190:193], v[126:129]
	v_mfma_f32_16x16x32_bf16 v[118:121], v[182:185], v[190:193], v[118:121]
	v_mfma_f32_16x16x32_bf16 v[110:113], v[174:177], v[198:201], v[110:113]
	v_mfma_f32_16x16x32_bf16 v[102:105], v[182:185], v[198:201], v[102:105]
	v_mfma_f32_16x16x32_bf16 v[94:97], v[174:177], v[206:209], v[94:97]
	v_mfma_f32_16x16x32_bf16 v[86:89], v[182:185], v[206:209], v[86:89]
	v_mfma_f32_16x16x32_bf16 v[62:65], v[174:177], v[214:217], v[62:65]
	v_mfma_f32_16x16x32_bf16 v[54:57], v[182:185], v[214:217], v[54:57]
	s_setprio 0
	s_barrier
	s_mov_b32 m0, s79
	v_lshl_add_u64 v[142:143], s[54:55], 0, v[132:133]
	s_add_u32 s90, s54, 0x80000
	ds_read_b128 v[186:189], v152 offset:16384
	ds_read_b128 v[190:193], v152 offset:17408
	ds_read_b128 v[194:197], v152 offset:18432
	ds_read_b128 v[198:201], v152 offset:19456
	ds_read_b128 v[202:205], v152 offset:20480
	ds_read_b128 v[206:209], v152 offset:21504
	ds_read_b128 v[210:213], v152 offset:22528
	ds_read_b128 v[214:217], v152 offset:23552
	global_load_lds_dwordx4 v[142:143], off
	v_lshl_add_u64 v[144:145], s[54:55], 0, v[136:137]
	s_mov_b32 m0, s80
	s_addc_u32 s91, s55, 0
	global_load_lds_dwordx4 v[144:145], off
	v_lshl_add_u64 v[148:149], s[90:91], 0, v[132:133]
	s_mov_b32 m0, s81
	v_lshl_add_u64 v[218:219], s[56:57], 0, v[134:135]
	global_load_lds_dwordx4 v[148:149], off
	v_lshl_add_u64 v[148:149], s[90:91], 0, v[136:137]
	s_mov_b32 m0, s82
	s_nop 0
	global_load_lds_dwordx4 v[148:149], off
	v_lshl_add_u64 v[148:149], s[56:57], 0, v[130:131]
	s_mov_b32 m0, s51
	s_nop 0
	global_load_lds_dwordx4 v[148:149], off
	s_mov_b32 m0, s61
	s_nop 0
	global_load_lds_dwordx4 v[218:219], off
	s_waitcnt vmcnt(8)
	s_waitcnt lgkmcnt(0)
	s_setprio 1
	s_barrier
	v_mfma_f32_16x16x32_bf16 v[78:81], v[154:157], v[186:189], v[78:81]
	v_mfma_f32_16x16x32_bf16 v[70:73], v[162:165], v[186:189], v[70:73]
	v_mfma_f32_16x16x32_bf16 v[46:49], v[154:157], v[194:197], v[46:49]
	v_mfma_f32_16x16x32_bf16 v[38:41], v[162:165], v[194:197], v[38:41]
	v_mfma_f32_16x16x32_bf16 v[30:33], v[154:157], v[202:205], v[30:33]
	v_mfma_f32_16x16x32_bf16 v[22:25], v[162:165], v[202:205], v[22:25]
	v_mfma_f32_16x16x32_bf16 v[14:17], v[154:157], v[210:213], v[14:17]
	v_mfma_f32_16x16x32_bf16 v[6:9], v[162:165], v[210:213], v[6:9]
	v_mfma_f32_16x16x32_bf16 v[78:81], v[158:161], v[190:193], v[78:81]
	v_mfma_f32_16x16x32_bf16 v[70:73], v[166:169], v[190:193], v[70:73]
	v_mfma_f32_16x16x32_bf16 v[46:49], v[158:161], v[198:201], v[46:49]
	v_mfma_f32_16x16x32_bf16 v[38:41], v[166:169], v[198:201], v[38:41]
	v_mfma_f32_16x16x32_bf16 v[30:33], v[158:161], v[206:209], v[30:33]
	v_mfma_f32_16x16x32_bf16 v[22:25], v[166:169], v[206:209], v[22:25]
	v_mfma_f32_16x16x32_bf16 v[14:17], v[158:161], v[214:217], v[14:17]
	v_mfma_f32_16x16x32_bf16 v[6:9], v[166:169], v[214:217], v[6:9]
	v_mfma_f32_16x16x32_bf16 v[74:77], v[170:173], v[186:189], v[74:77]
	v_mfma_f32_16x16x32_bf16 v[66:69], v[178:181], v[186:189], v[66:69]
	v_mfma_f32_16x16x32_bf16 v[42:45], v[170:173], v[194:197], v[42:45]
	v_mfma_f32_16x16x32_bf16 v[34:37], v[178:181], v[194:197], v[34:37]
	v_mfma_f32_16x16x32_bf16 v[26:29], v[170:173], v[202:205], v[26:29]
	v_mfma_f32_16x16x32_bf16 v[18:21], v[178:181], v[202:205], v[18:21]
	v_mfma_f32_16x16x32_bf16 v[10:13], v[170:173], v[210:213], v[10:13]
	v_mfma_f32_16x16x32_bf16 v[2:5], v[178:181], v[210:213], v[2:5]
	v_mfma_f32_16x16x32_bf16 v[74:77], v[174:177], v[190:193], v[74:77]
	v_mfma_f32_16x16x32_bf16 v[66:69], v[182:185], v[190:193], v[66:69]
	v_mfma_f32_16x16x32_bf16 v[42:45], v[174:177], v[198:201], v[42:45]
	v_mfma_f32_16x16x32_bf16 v[34:37], v[182:185], v[198:201], v[34:37]
	v_mfma_f32_16x16x32_bf16 v[26:29], v[174:177], v[206:209], v[26:29]
	v_mfma_f32_16x16x32_bf16 v[18:21], v[182:185], v[206:209], v[18:21]
	v_mfma_f32_16x16x32_bf16 v[10:13], v[174:177], v[214:217], v[10:13]
	v_mfma_f32_16x16x32_bf16 v[2:5], v[182:185], v[214:217], v[2:5]
	s_setprio 0
	s_barrier
	ds_read_b128 v[154:157], v146
	ds_read_b128 v[158:161], v146 offset:1024
	ds_read_b128 v[162:165], v146 offset:2048
	ds_read_b128 v[166:169], v146 offset:3072
	ds_read_b128 v[170:173], v147
	ds_read_b128 v[174:177], v147 offset:1024
	ds_read_b128 v[178:181], v147 offset:2048
	ds_read_b128 v[182:185], v147 offset:3072
	s_add_u32 s56, s56, 0x80000
	s_addc_u32 s57, s57, 0
	s_mov_b32 m0, s62
	v_lshl_add_u64 v[220:221], s[56:57], 0, v[130:131]
	ds_read_b128 v[186:189], v152 offset:32768
	ds_read_b128 v[190:193], v152 offset:33792
	ds_read_b128 v[194:197], v152 offset:34816
	ds_read_b128 v[198:201], v152 offset:35840
	ds_read_b128 v[202:205], v152 offset:36864
	ds_read_b128 v[206:209], v152 offset:37888
	ds_read_b128 v[210:213], v152 offset:38912
	ds_read_b128 v[214:217], v152 offset:39936
	global_load_lds_dwordx4 v[220:221], off
	v_lshl_add_u64 v[220:221], s[56:57], 0, v[134:135]
	s_mov_b32 m0, s63
	s_nop 0
	global_load_lds_dwordx4 v[220:221], off
	s_waitcnt vmcnt(8)
	s_waitcnt lgkmcnt(0)
	s_setprio 1
	s_barrier
	v_mfma_f32_16x16x32_bf16 v[122:125], v[154:157], v[186:189], v[122:125]
	v_mfma_f32_16x16x32_bf16 v[114:117], v[162:165], v[186:189], v[114:117]
	v_mfma_f32_16x16x32_bf16 v[106:109], v[154:157], v[194:197], v[106:109]
	v_mfma_f32_16x16x32_bf16 v[98:101], v[162:165], v[194:197], v[98:101]
	v_mfma_f32_16x16x32_bf16 v[90:93], v[154:157], v[202:205], v[90:93]
	v_mfma_f32_16x16x32_bf16 v[82:85], v[162:165], v[202:205], v[82:85]
	v_mfma_f32_16x16x32_bf16 v[58:61], v[154:157], v[210:213], v[58:61]
	v_mfma_f32_16x16x32_bf16 v[50:53], v[162:165], v[210:213], v[50:53]
	v_mfma_f32_16x16x32_bf16 v[122:125], v[158:161], v[190:193], v[122:125]
	v_mfma_f32_16x16x32_bf16 v[114:117], v[166:169], v[190:193], v[114:117]
	v_mfma_f32_16x16x32_bf16 v[106:109], v[158:161], v[198:201], v[106:109]
	v_mfma_f32_16x16x32_bf16 v[98:101], v[166:169], v[198:201], v[98:101]
	v_mfma_f32_16x16x32_bf16 v[90:93], v[158:161], v[206:209], v[90:93]
	v_mfma_f32_16x16x32_bf16 v[82:85], v[166:169], v[206:209], v[82:85]
	v_mfma_f32_16x16x32_bf16 v[58:61], v[158:161], v[214:217], v[58:61]
	v_mfma_f32_16x16x32_bf16 v[50:53], v[166:169], v[214:217], v[50:53]
	v_mfma_f32_16x16x32_bf16 v[126:129], v[170:173], v[186:189], v[126:129]
	v_mfma_f32_16x16x32_bf16 v[118:121], v[178:181], v[186:189], v[118:121]
	v_mfma_f32_16x16x32_bf16 v[110:113], v[170:173], v[194:197], v[110:113]
	v_mfma_f32_16x16x32_bf16 v[102:105], v[178:181], v[194:197], v[102:105]
	v_mfma_f32_16x16x32_bf16 v[94:97], v[170:173], v[202:205], v[94:97]
	v_mfma_f32_16x16x32_bf16 v[86:89], v[178:181], v[202:205], v[86:89]
	v_mfma_f32_16x16x32_bf16 v[62:65], v[170:173], v[210:213], v[62:65]
	v_mfma_f32_16x16x32_bf16 v[54:57], v[178:181], v[210:213], v[54:57]
	v_mfma_f32_16x16x32_bf16 v[126:129], v[174:177], v[190:193], v[126:129]
	v_mfma_f32_16x16x32_bf16 v[118:121], v[182:185], v[190:193], v[118:121]
	v_mfma_f32_16x16x32_bf16 v[110:113], v[174:177], v[198:201], v[110:113]
	v_mfma_f32_16x16x32_bf16 v[102:105], v[182:185], v[198:201], v[102:105]
	v_mfma_f32_16x16x32_bf16 v[94:97], v[174:177], v[206:209], v[94:97]
	v_mfma_f32_16x16x32_bf16 v[86:89], v[182:185], v[206:209], v[86:89]
	v_mfma_f32_16x16x32_bf16 v[62:65], v[174:177], v[214:217], v[62:65]
	v_mfma_f32_16x16x32_bf16 v[54:57], v[182:185], v[214:217], v[54:57]
	s_setprio 0
	s_barrier
	s_mov_b32 m0, s83
	v_lshl_add_u64 v[142:143], v[142:143], 0, s[12:13]
	s_add_u32 s54, s54, 0x80080
	ds_read_b128 v[186:189], v152 offset:49152
	ds_read_b128 v[190:193], v152 offset:50176
	ds_read_b128 v[194:197], v152 offset:51200
	ds_read_b128 v[198:201], v152 offset:52224
	ds_read_b128 v[202:205], v152 offset:53248
	ds_read_b128 v[206:209], v152 offset:54272
	ds_read_b128 v[210:213], v152 offset:55296
	ds_read_b128 v[214:217], v152 offset:56320
	global_load_lds_dwordx4 v[142:143], off
	v_lshl_add_u64 v[142:143], v[144:145], 0, s[12:13]
	s_mov_b32 m0, s84
	s_addc_u32 s55, s55, 0
	global_load_lds_dwordx4 v[142:143], off
	v_lshl_add_u64 v[142:143], s[54:55], 0, v[132:133]
	s_mov_b32 m0, s85
	s_nop 0
	global_load_lds_dwordx4 v[142:143], off
	v_lshl_add_u64 v[142:143], s[54:55], 0, v[136:137]
	s_mov_b32 m0, s86
	s_nop 0
	global_load_lds_dwordx4 v[142:143], off
	v_lshl_add_u64 v[142:143], v[148:149], 0, s[12:13]
	s_mov_b32 m0, s65
	s_nop 0
	global_load_lds_dwordx4 v[142:143], off
	v_lshl_add_u64 v[142:143], v[218:219], 0, s[12:13]
	s_mov_b32 m0, s66
	s_nop 0
	global_load_lds_dwordx4 v[142:143], off
	s_waitcnt vmcnt(8)
	s_waitcnt lgkmcnt(0)
	s_setprio 1
	s_barrier
	v_mfma_f32_16x16x32_bf16 v[78:81], v[154:157], v[186:189], v[78:81]
	v_mfma_f32_16x16x32_bf16 v[70:73], v[162:165], v[186:189], v[70:73]
	v_mfma_f32_16x16x32_bf16 v[46:49], v[154:157], v[194:197], v[46:49]
	v_mfma_f32_16x16x32_bf16 v[38:41], v[162:165], v[194:197], v[38:41]
	v_mfma_f32_16x16x32_bf16 v[30:33], v[154:157], v[202:205], v[30:33]
	v_mfma_f32_16x16x32_bf16 v[22:25], v[162:165], v[202:205], v[22:25]
	v_mfma_f32_16x16x32_bf16 v[14:17], v[154:157], v[210:213], v[14:17]
	v_mfma_f32_16x16x32_bf16 v[6:9], v[162:165], v[210:213], v[6:9]
	v_mfma_f32_16x16x32_bf16 v[78:81], v[158:161], v[190:193], v[78:81]
	v_mfma_f32_16x16x32_bf16 v[70:73], v[166:169], v[190:193], v[70:73]
	v_mfma_f32_16x16x32_bf16 v[46:49], v[158:161], v[198:201], v[46:49]
	v_mfma_f32_16x16x32_bf16 v[38:41], v[166:169], v[198:201], v[38:41]
	v_mfma_f32_16x16x32_bf16 v[30:33], v[158:161], v[206:209], v[30:33]
	v_mfma_f32_16x16x32_bf16 v[22:25], v[166:169], v[206:209], v[22:25]
	v_mfma_f32_16x16x32_bf16 v[14:17], v[158:161], v[214:217], v[14:17]
	v_mfma_f32_16x16x32_bf16 v[6:9], v[166:169], v[214:217], v[6:9]
	v_mfma_f32_16x16x32_bf16 v[74:77], v[170:173], v[186:189], v[74:77]
	v_mfma_f32_16x16x32_bf16 v[66:69], v[178:181], v[186:189], v[66:69]
	v_mfma_f32_16x16x32_bf16 v[42:45], v[170:173], v[194:197], v[42:45]
	v_mfma_f32_16x16x32_bf16 v[34:37], v[178:181], v[194:197], v[34:37]
	v_mfma_f32_16x16x32_bf16 v[26:29], v[170:173], v[202:205], v[26:29]
	v_mfma_f32_16x16x32_bf16 v[18:21], v[178:181], v[202:205], v[18:21]
	v_mfma_f32_16x16x32_bf16 v[10:13], v[170:173], v[210:213], v[10:13]
	v_mfma_f32_16x16x32_bf16 v[2:5], v[178:181], v[210:213], v[2:5]
	v_mfma_f32_16x16x32_bf16 v[74:77], v[174:177], v[190:193], v[74:77]
	v_mfma_f32_16x16x32_bf16 v[66:69], v[182:185], v[190:193], v[66:69]
	v_mfma_f32_16x16x32_bf16 v[42:45], v[174:177], v[198:201], v[42:45]
	v_mfma_f32_16x16x32_bf16 v[34:37], v[182:185], v[198:201], v[34:37]
	v_mfma_f32_16x16x32_bf16 v[26:29], v[174:177], v[206:209], v[26:29]
	v_mfma_f32_16x16x32_bf16 v[18:21], v[182:185], v[206:209], v[18:21]
	v_mfma_f32_16x16x32_bf16 v[10:13], v[174:177], v[214:217], v[10:13]
	v_mfma_f32_16x16x32_bf16 v[2:5], v[182:185], v[214:217], v[2:5]
	s_setprio 0
	s_barrier
	s_add_i32 s89, s89, 2
	s_add_u32 s87, s87, 0x100
	s_addc_u32 s88, s88, 0
	s_add_u32 s52, s52, 0x100
	s_addc_u32 s53, s53, 0
	s_cmp_gt_u32 s89, 29
	s_cbranch_scc0 .LBB0_747
	s_and_b64 vcc, exec, s[14:15]
	s_cbranch_vccz .LBB0_750
	s_barrier

.LBB0_770:
	s_ashr_i32 s49, s48, 31
	s_lshl_b64 s[8:9], s[48:49], 19
	s_add_u32 s50, s24, s8
	ds_read_b128 v[2:5], v188
	ds_read_b128 v[6:9], v188 offset:1024
	ds_read_b128 v[10:13], v188 offset:2048
	ds_read_b128 v[14:17], v188 offset:3072
	ds_read_b128 v[18:21], v189
	ds_read_b128 v[22:25], v189 offset:1024
	ds_read_b128 v[26:29], v189 offset:2048
	ds_read_b128 v[30:33], v189 offset:3072
	s_addc_u32 s51, s25, s9
	s_ashr_i32 s47, s46, 31
	s_lshl_b64 s[8:9], s[46:47], 19
	s_add_u32 s52, s26, s8
	s_addc_u32 s53, s27, s9
	s_and_b64 s[8:9], s[4:5], exec
	s_cselect_b32 s47, s51, s59
	s_cselect_b32 s49, s50, s58
	s_cselect_b32 s74, s53, s57
	s_cselect_b32 s75, s52, s56
	s_add_u32 s8, s58, 0x40080
	s_addc_u32 s9, s59, 0
	s_add_i32 s76, s55, 0xc000
	v_lshl_add_u64 v[34:35], s[8:9], 0, v[162:163]
	s_mov_b32 m0, s76
	s_add_i32 s77, s55, 0xe000
	ds_read_b128 v[38:41], v190
	ds_read_b128 v[42:45], v190 offset:1024
	ds_read_b128 v[46:49], v190 offset:2048
	ds_read_b128 v[50:53], v190 offset:3072
	ds_read_b128 v[54:57], v190 offset:4096
	ds_read_b128 v[58:61], v190 offset:5120
	ds_read_b128 v[62:65], v190 offset:6144
	ds_read_b128 v[66:69], v190 offset:7168
	global_load_lds_dwordx4 v[34:35], off
	v_lshl_add_u64 v[34:35], s[8:9], 0, v[166:167]
	s_mov_b32 m0, s77
	s_nop 0
	global_load_lds_dwordx4 v[34:35], off
	s_waitcnt vmcnt(24)
	s_waitcnt lgkmcnt(0)
	s_setprio 1
	s_barrier
	s_mov_b32 s8, 0
	s_mov_b32 s10, s8
	s_mov_b32 s11, s8
	s_mov_b32 s9, s8
	v_mov_b64_e32 v[36:37], s[10:11]
	v_mov_b64_e32 v[156:157], s[10:11]
	v_mov_b64_e32 v[160:161], s[10:11]
	v_mov_b64_e32 v[144:145], s[10:11]
	v_mov_b64_e32 v[140:141], s[10:11]
	v_mov_b64_e32 v[128:129], s[10:11]
	v_mov_b64_e32 v[124:125], s[10:11]
	v_mov_b64_e32 v[112:113], s[10:11]
	v_mov_b64_e32 v[108:109], s[10:11]
	v_mov_b64_e32 v[34:35], s[8:9]
	v_mov_b64_e32 v[154:155], s[8:9]
	v_mov_b64_e32 v[158:159], s[8:9]
	v_mov_b64_e32 v[142:143], s[8:9]
	v_mov_b64_e32 v[138:139], s[8:9]
	v_mov_b64_e32 v[126:127], s[8:9]
	v_mov_b64_e32 v[122:123], s[8:9]
	v_mov_b64_e32 v[110:111], s[8:9]
	v_mov_b64_e32 v[106:107], s[8:9]
	s_waitcnt lgkmcnt(0)
	v_mfma_f32_16x16x128_f8f6f4 v[154:157], v[2:9], v[38:45], v[154:157]
	v_mfma_f32_16x16x128_f8f6f4 v[158:161], v[10:17], v[38:45], v[158:161]
	v_mfma_f32_16x16x128_f8f6f4 v[142:145], v[2:9], v[46:53], v[142:145]
	v_mfma_f32_16x16x128_f8f6f4 v[138:141], v[10:17], v[46:53], v[138:141]
	v_mfma_f32_16x16x128_f8f6f4 v[126:129], v[2:9], v[54:61], v[126:129]
	v_mfma_f32_16x16x128_f8f6f4 v[122:125], v[10:17], v[54:61], v[122:125]
	v_mfma_f32_16x16x128_f8f6f4 v[110:113], v[2:9], v[62:69], v[110:113]
	v_mfma_f32_16x16x128_f8f6f4 v[106:109], v[10:17], v[62:69], v[106:109]
	v_mov_b64_e32 v[148:149], s[10:11]
	v_mov_b64_e32 v[152:153], s[10:11]
	v_mov_b64_e32 v[136:137], s[10:11]
	v_mov_b64_e32 v[132:133], s[10:11]
	v_mov_b64_e32 v[120:121], s[10:11]
	v_mov_b64_e32 v[116:117], s[10:11]
	v_mov_b64_e32 v[96:97], s[10:11]
	v_mov_b64_e32 v[92:93], s[10:11]
	v_mov_b64_e32 v[146:147], s[8:9]
	v_mov_b64_e32 v[150:151], s[8:9]
	v_mov_b64_e32 v[134:135], s[8:9]
	v_mov_b64_e32 v[130:131], s[8:9]
	v_mov_b64_e32 v[118:119], s[8:9]
	v_mov_b64_e32 v[114:115], s[8:9]
	v_mov_b64_e32 v[94:95], s[8:9]
	v_mov_b64_e32 v[90:91], s[8:9]
	v_mfma_f32_16x16x128_f8f6f4 v[146:149], v[18:25], v[38:45], v[146:149]
	v_mfma_f32_16x16x128_f8f6f4 v[150:153], v[26:33], v[38:45], v[150:153]
	v_mfma_f32_16x16x128_f8f6f4 v[134:137], v[18:25], v[46:53], v[134:137]
	v_mfma_f32_16x16x128_f8f6f4 v[130:133], v[26:33], v[46:53], v[130:133]
	v_mfma_f32_16x16x128_f8f6f4 v[118:121], v[18:25], v[54:61], v[118:121]
	v_mfma_f32_16x16x128_f8f6f4 v[114:117], v[26:33], v[54:61], v[114:117]
	v_mfma_f32_16x16x128_f8f6f4 v[94:97], v[18:25], v[62:69], v[94:97]
	v_mfma_f32_16x16x128_f8f6f4 v[90:93], v[26:33], v[62:69], v[90:93]
	s_setprio 0
	s_barrier
	s_add_i32 s9, s67, s37
	v_lshl_add_u64 v[178:179], s[56:57], 0, v[164:165]
	s_add_i32 s78, s9, 0x2000
	v_lshl_add_u64 v[38:39], v[178:179], 0, s[30:31]
	s_mov_b32 m0, s9
	v_lshl_add_u64 v[180:181], s[56:57], 0, v[168:169]
	s_add_u32 s10, s56, 0x40100
	ds_read_b128 v[50:53], v190 offset:16384
	ds_read_b128 v[54:57], v190 offset:17408
	ds_read_b128 v[192:195], v190 offset:18432
	ds_read_b128 v[196:199], v190 offset:19456
	ds_read_b128 v[200:203], v190 offset:20480
	ds_read_b128 v[204:207], v190 offset:21504
	ds_read_b128 v[208:211], v190 offset:22528
	ds_read_b128 v[212:215], v190 offset:23552
	global_load_lds_dwordx4 v[38:39], off
	v_lshl_add_u64 v[38:39], v[180:181], 0, s[30:31]
	s_mov_b32 m0, s78
	s_addc_u32 s11, s57, 0
	s_add_i32 s79, s68, s37
	global_load_lds_dwordx4 v[38:39], off
	v_lshl_add_u64 v[38:39], s[10:11], 0, v[164:165]
	s_mov_b32 m0, s79
	s_add_i32 s80, s79, 0x2000
	global_load_lds_dwordx4 v[38:39], off
	v_lshl_add_u64 v[38:39], s[10:11], 0, v[168:169]
	s_mov_b32 m0, s80
	v_lshl_add_u64 v[182:183], s[58:59], 0, v[162:163]
	global_load_lds_dwordx4 v[38:39], off
	v_lshl_add_u64 v[38:39], v[182:183], 0, s[30:31]
	s_mov_b32 m0, s55
	v_lshl_add_u64 v[184:185], s[58:59], 0, v[166:167]
	global_load_lds_dwordx4 v[38:39], off
	v_lshl_add_u64 v[38:39], v[184:185], 0, s[30:31]
	s_mov_b32 m0, s60
	s_nop 0
	global_load_lds_dwordx4 v[38:39], off
	s_waitcnt vmcnt(24)
	s_waitcnt lgkmcnt(0)
	s_setprio 1
	s_barrier
	v_mov_b64_e32 v[104:105], v[36:37]
	v_mov_b64_e32 v[100:101], v[36:37]
	v_mov_b64_e32 v[80:81], v[36:37]
	v_mov_b64_e32 v[76:77], v[36:37]
	v_mov_b64_e32 v[64:65], v[36:37]
	v_mov_b64_e32 v[60:61], v[36:37]
	v_mov_b64_e32 v[48:49], v[36:37]
	v_mov_b64_e32 v[44:45], v[36:37]
	v_mov_b64_e32 v[102:103], v[34:35]
	v_mov_b64_e32 v[98:99], v[34:35]
	v_mov_b64_e32 v[78:79], v[34:35]
	v_mov_b64_e32 v[74:75], v[34:35]
	v_mov_b64_e32 v[62:63], v[34:35]
	v_mov_b64_e32 v[58:59], v[34:35]
	v_mov_b64_e32 v[46:47], v[34:35]
	v_mov_b64_e32 v[42:43], v[34:35]
	s_waitcnt lgkmcnt(0)
	v_mfma_f32_16x16x128_f8f6f4 v[102:105], v[2:9], v[50:57], v[102:105]
	v_mfma_f32_16x16x128_f8f6f4 v[98:101], v[10:17], v[50:57], v[98:101]
	v_mfma_f32_16x16x128_f8f6f4 v[78:81], v[2:9], v[192:199], v[78:81]
	v_mfma_f32_16x16x128_f8f6f4 v[74:77], v[10:17], v[192:199], v[74:77]
	v_mfma_f32_16x16x128_f8f6f4 v[62:65], v[2:9], v[200:207], v[62:65]
	v_mfma_f32_16x16x128_f8f6f4 v[58:61], v[10:17], v[200:207], v[58:61]
	v_mfma_f32_16x16x128_f8f6f4 v[46:49], v[2:9], v[208:215], v[46:49]
	v_mfma_f32_16x16x128_f8f6f4 v[42:45], v[10:17], v[208:215], v[42:45]
	v_mov_b64_e32 v[88:89], v[36:37]
	v_mov_b64_e32 v[84:85], v[36:37]
	v_mov_b64_e32 v[86:87], v[34:35]
	v_mov_b64_e32 v[82:83], v[34:35]
	v_mfma_f32_16x16x128_f8f6f4 v[86:89], v[18:25], v[50:57], v[86:89]
	v_mfma_f32_16x16x128_f8f6f4 v[82:85], v[26:33], v[50:57], v[82:85]
	v_mov_b64_e32 v[72:73], v[36:37]
	v_mov_b64_e32 v[68:69], v[36:37]
	v_mov_b64_e32 v[56:57], v[36:37]
	v_mov_b64_e32 v[52:53], v[36:37]
	v_mov_b64_e32 v[40:41], v[36:37]
	v_mov_b64_e32 v[70:71], v[34:35]
	v_mov_b64_e32 v[66:67], v[34:35]
	v_mov_b64_e32 v[54:55], v[34:35]
	v_mov_b64_e32 v[50:51], v[34:35]
	v_mov_b64_e32 v[38:39], v[34:35]
	v_mfma_f32_16x16x128_f8f6f4 v[70:73], v[18:25], v[192:199], v[70:73]
	v_mfma_f32_16x16x128_f8f6f4 v[66:69], v[26:33], v[192:199], v[66:69]
	v_mfma_f32_16x16x128_f8f6f4 v[54:57], v[18:25], v[200:207], v[54:57]
	v_mfma_f32_16x16x128_f8f6f4 v[50:53], v[26:33], v[200:207], v[50:53]
	v_mfma_f32_16x16x128_f8f6f4 v[38:41], v[18:25], v[208:215], v[38:41]
	v_mfma_f32_16x16x128_f8f6f4 v[34:37], v[26:33], v[208:215], v[34:37]
	s_setprio 0
	s_barrier
	s_add_i32 s81, 0, 0x18000
	s_add_i32 s83, 0, 0x1c000
	v_add_u32_e32 v191, s81, v186
	v_add_u32_e32 v192, s83, v186
	ds_read_b128 v[18:21], v191
	ds_read_b128 v[22:25], v191 offset:1024
	ds_read_b128 v[26:29], v191 offset:2048
	ds_read_b128 v[30:33], v191 offset:3072
	ds_read_b128 v[2:5], v192
	ds_read_b128 v[6:9], v192 offset:1024
	ds_read_b128 v[10:13], v192 offset:2048
	ds_read_b128 v[14:17], v192 offset:3072
	s_add_u32 s10, s58, 0x40100
	s_addc_u32 s11, s59, 0
	s_mov_b32 m0, s61
	v_lshl_add_u64 v[226:227], s[10:11], 0, v[162:163]
	ds_read_b128 v[194:197], v190 offset:32768
	ds_read_b128 v[198:201], v190 offset:33792
	ds_read_b128 v[202:205], v190 offset:34816
	ds_read_b128 v[206:209], v190 offset:35840
	ds_read_b128 v[210:213], v190 offset:36864
	ds_read_b128 v[214:217], v190 offset:37888
	ds_read_b128 v[218:221], v190 offset:38912
	ds_read_b128 v[222:225], v190 offset:39936
	global_load_lds_dwordx4 v[226:227], off
	v_lshl_add_u64 v[226:227], s[10:11], 0, v[166:167]
	s_mov_b32 m0, s62
	s_nop 0
	global_load_lds_dwordx4 v[226:227], off
	s_waitcnt vmcnt(8)
	s_waitcnt lgkmcnt(0)
	s_setprio 1
	s_barrier
	v_mfma_f32_16x16x128_f8f6f4 v[154:157], v[18:25], v[194:201], v[154:157]
	v_mfma_f32_16x16x128_f8f6f4 v[158:161], v[26:33], v[194:201], v[158:161]
	v_mfma_f32_16x16x128_f8f6f4 v[142:145], v[18:25], v[202:209], v[142:145]
	v_mfma_f32_16x16x128_f8f6f4 v[138:141], v[26:33], v[202:209], v[138:141]
	v_mfma_f32_16x16x128_f8f6f4 v[126:129], v[18:25], v[210:217], v[126:129]
	v_mfma_f32_16x16x128_f8f6f4 v[122:125], v[26:33], v[210:217], v[122:125]
	v_mfma_f32_16x16x128_f8f6f4 v[110:113], v[18:25], v[218:225], v[110:113]
	v_mfma_f32_16x16x128_f8f6f4 v[106:109], v[26:33], v[218:225], v[106:109]
	v_mfma_f32_16x16x128_f8f6f4 v[146:149], v[2:9], v[194:201], v[146:149]
	v_mfma_f32_16x16x128_f8f6f4 v[150:153], v[10:17], v[194:201], v[150:153]
	v_mfma_f32_16x16x128_f8f6f4 v[134:137], v[2:9], v[202:209], v[134:137]
	v_mfma_f32_16x16x128_f8f6f4 v[130:133], v[10:17], v[202:209], v[130:133]
	v_mfma_f32_16x16x128_f8f6f4 v[118:121], v[2:9], v[210:217], v[118:121]
	v_mfma_f32_16x16x128_f8f6f4 v[114:117], v[10:17], v[210:217], v[114:117]
	v_mfma_f32_16x16x128_f8f6f4 v[94:97], v[2:9], v[218:225], v[94:97]
	v_mfma_f32_16x16x128_f8f6f4 v[90:93], v[10:17], v[218:225], v[90:93]
	s_setprio 0
	s_barrier
	s_add_i32 s81, s81, s37
	s_add_i32 s82, s81, 0x2000
	v_lshl_add_u64 v[178:179], v[178:179], 0, s[34:35]
	s_mov_b32 m0, s81
	s_add_u32 s10, s56, 0x40180
	ds_read_b128 v[194:197], v190 offset:49152
	ds_read_b128 v[198:201], v190 offset:50176
	ds_read_b128 v[202:205], v190 offset:51200
	ds_read_b128 v[206:209], v190 offset:52224
	ds_read_b128 v[210:213], v190 offset:53248
	ds_read_b128 v[214:217], v190 offset:54272
	ds_read_b128 v[218:221], v190 offset:55296
	ds_read_b128 v[222:225], v190 offset:56320
	global_load_lds_dwordx4 v[178:179], off
	v_lshl_add_u64 v[178:179], v[180:181], 0, s[34:35]
	s_mov_b32 m0, s82
	s_addc_u32 s11, s57, 0
	s_add_i32 s83, s83, s37
	global_load_lds_dwordx4 v[178:179], off
	v_lshl_add_u64 v[178:179], s[10:11], 0, v[164:165]
	s_mov_b32 m0, s83
	s_add_i32 s84, s83, 0x2000
	global_load_lds_dwordx4 v[178:179], off
	v_lshl_add_u64 v[178:179], s[10:11], 0, v[168:169]
	s_mov_b32 m0, s84
	s_nop 0
	global_load_lds_dwordx4 v[178:179], off
	v_lshl_add_u64 v[178:179], v[182:183], 0, s[34:35]
	s_mov_b32 m0, s64
	s_nop 0
	global_load_lds_dwordx4 v[178:179], off
	v_lshl_add_u64 v[178:179], v[184:185], 0, s[34:35]
	s_mov_b32 m0, s65
	s_nop 0
	global_load_lds_dwordx4 v[178:179], off
	s_waitcnt vmcnt(8)
	s_waitcnt lgkmcnt(0)
	s_setprio 1
	s_barrier
	v_mfma_f32_16x16x128_f8f6f4 v[102:105], v[18:25], v[194:201], v[102:105]
	v_mfma_f32_16x16x128_f8f6f4 v[98:101], v[26:33], v[194:201], v[98:101]
	v_mfma_f32_16x16x128_f8f6f4 v[78:81], v[18:25], v[202:209], v[78:81]
	v_mfma_f32_16x16x128_f8f6f4 v[74:77], v[26:33], v[202:209], v[74:77]
	v_mfma_f32_16x16x128_f8f6f4 v[62:65], v[18:25], v[210:217], v[62:65]
	v_mfma_f32_16x16x128_f8f6f4 v[58:61], v[26:33], v[210:217], v[58:61]
	v_mfma_f32_16x16x128_f8f6f4 v[46:49], v[18:25], v[218:225], v[46:49]
	v_mfma_f32_16x16x128_f8f6f4 v[42:45], v[26:33], v[218:225], v[42:45]
	v_mfma_f32_16x16x128_f8f6f4 v[86:89], v[2:9], v[194:201], v[86:89]
	v_mfma_f32_16x16x128_f8f6f4 v[82:85], v[10:17], v[194:201], v[82:85]
	v_mfma_f32_16x16x128_f8f6f4 v[70:73], v[2:9], v[202:209], v[70:73]
	v_mfma_f32_16x16x128_f8f6f4 v[66:69], v[10:17], v[202:209], v[66:69]
	v_mfma_f32_16x16x128_f8f6f4 v[54:57], v[2:9], v[210:217], v[54:57]
	v_mfma_f32_16x16x128_f8f6f4 v[50:53], v[10:17], v[210:217], v[50:53]
	v_mfma_f32_16x16x128_f8f6f4 v[38:41], v[2:9], v[218:225], v[38:41]
	v_mfma_f32_16x16x128_f8f6f4 v[34:37], v[10:17], v[218:225], v[34:37]
	s_setprio 0
	s_barrier
	s_add_u32 s85, s56, 0x200
	s_addc_u32 s86, s57, 0
	s_add_u32 s10, s58, 0x40180
	s_addc_u32 s11, s59, 0
.LBB0_771:
	ds_read_b128 v[2:5], v188
	ds_read_b128 v[6:9], v188 offset:1024
	ds_read_b128 v[18:21], v188 offset:2048
	ds_read_b128 v[22:25], v188 offset:3072
	ds_read_b128 v[26:29], v189
	ds_read_b128 v[30:33], v189 offset:1024
	ds_read_b128 v[178:181], v189 offset:2048
	ds_read_b128 v[182:185], v189 offset:3072
	s_add_u32 s56, s10, 0xfffc0080
	s_addc_u32 s57, s11, -1
	s_cmp_eq_u32 s8, 12
	s_cselect_b32 s59, s47, s57
	s_cselect_b32 s58, s49, s56
	s_cselect_b32 s57, s74, s86
	s_cselect_b32 s56, s75, s85
	s_mov_b32 m0, s76
	v_lshl_add_u64 v[218:219], s[10:11], 0, v[172:173]
	ds_read_b128 v[10:13], v190
	ds_read_b128 v[14:17], v190 offset:1024
	ds_read_b128 v[194:197], v190 offset:2048
	ds_read_b128 v[198:201], v190 offset:3072
	ds_read_b128 v[202:205], v190 offset:4096
	ds_read_b128 v[206:209], v190 offset:5120
	ds_read_b128 v[210:213], v190 offset:6144
	ds_read_b128 v[214:217], v190 offset:7168
	global_load_lds_dwordx4 v[218:219], off
	v_lshl_add_u64 v[218:219], s[10:11], 0, v[170:171]
	s_mov_b32 m0, s77
	s_nop 0
	global_load_lds_dwordx4 v[218:219], off
	s_waitcnt vmcnt(8)
	s_waitcnt lgkmcnt(0)
	s_setprio 1
	s_barrier
	v_mfma_f32_16x16x128_f8f6f4 v[154:157], v[2:9], v[10:17], v[154:157]
	v_mfma_f32_16x16x128_f8f6f4 v[158:161], v[18:25], v[10:17], v[158:161]
	v_mfma_f32_16x16x128_f8f6f4 v[142:145], v[2:9], v[194:201], v[142:145]
	v_mfma_f32_16x16x128_f8f6f4 v[138:141], v[18:25], v[194:201], v[138:141]
	v_mfma_f32_16x16x128_f8f6f4 v[126:129], v[2:9], v[202:209], v[126:129]
	v_mfma_f32_16x16x128_f8f6f4 v[122:125], v[18:25], v[202:209], v[122:125]
	v_mfma_f32_16x16x128_f8f6f4 v[110:113], v[2:9], v[210:217], v[110:113]
	v_mfma_f32_16x16x128_f8f6f4 v[106:109], v[18:25], v[210:217], v[106:109]
	v_mfma_f32_16x16x128_f8f6f4 v[146:149], v[26:33], v[10:17], v[146:149]
	v_mfma_f32_16x16x128_f8f6f4 v[150:153], v[178:185], v[10:17], v[150:153]
	v_mfma_f32_16x16x128_f8f6f4 v[134:137], v[26:33], v[194:201], v[134:137]
	v_mfma_f32_16x16x128_f8f6f4 v[130:133], v[178:185], v[194:201], v[130:133]
	v_mfma_f32_16x16x128_f8f6f4 v[118:121], v[26:33], v[202:209], v[118:121]
	v_mfma_f32_16x16x128_f8f6f4 v[114:117], v[178:185], v[202:209], v[114:117]
	v_mfma_f32_16x16x128_f8f6f4 v[94:97], v[26:33], v[210:217], v[94:97]
	v_mfma_f32_16x16x128_f8f6f4 v[90:93], v[178:185], v[210:217], v[90:93]
	s_setprio 0
	s_barrier
	s_mov_b32 m0, s9
	v_lshl_add_u64 v[10:11], s[56:57], 0, v[164:165]
	s_add_u32 s88, s56, 0x40000
	ds_read_b128 v[194:197], v190 offset:16384
	ds_read_b128 v[198:201], v190 offset:17408
	ds_read_b128 v[202:205], v190 offset:18432
	ds_read_b128 v[206:209], v190 offset:19456
	ds_read_b128 v[210:213], v190 offset:20480
	ds_read_b128 v[214:217], v190 offset:21504
	ds_read_b128 v[218:221], v190 offset:22528
	ds_read_b128 v[222:225], v190 offset:23552
	global_load_lds_dwordx4 v[10:11], off
	v_lshl_add_u64 v[12:13], s[56:57], 0, v[168:169]
	s_mov_b32 m0, s78
	s_addc_u32 s89, s57, 0
	global_load_lds_dwordx4 v[12:13], off
	v_lshl_add_u64 v[14:15], s[88:89], 0, v[164:165]
	s_mov_b32 m0, s79
	v_lshl_add_u64 v[16:17], s[58:59], 0, v[166:167]
	global_load_lds_dwordx4 v[14:15], off
	v_lshl_add_u64 v[14:15], s[88:89], 0, v[168:169]
	s_mov_b32 m0, s80
	s_nop 0
	global_load_lds_dwordx4 v[14:15], off
	v_lshl_add_u64 v[14:15], s[58:59], 0, v[162:163]
	s_mov_b32 m0, s55
	s_nop 0
	global_load_lds_dwordx4 v[14:15], off
	s_mov_b32 m0, s60
	s_nop 0
	global_load_lds_dwordx4 v[16:17], off
	s_waitcnt vmcnt(8)
	s_waitcnt lgkmcnt(0)
	s_setprio 1
	s_barrier
	v_mfma_f32_16x16x128_f8f6f4 v[102:105], v[2:9], v[194:201], v[102:105]
	v_mfma_f32_16x16x128_f8f6f4 v[98:101], v[18:25], v[194:201], v[98:101]
	v_mfma_f32_16x16x128_f8f6f4 v[78:81], v[2:9], v[202:209], v[78:81]
	v_mfma_f32_16x16x128_f8f6f4 v[74:77], v[18:25], v[202:209], v[74:77]
	v_mfma_f32_16x16x128_f8f6f4 v[62:65], v[2:9], v[210:217], v[62:65]
	v_mfma_f32_16x16x128_f8f6f4 v[58:61], v[18:25], v[210:217], v[58:61]
	v_mfma_f32_16x16x128_f8f6f4 v[46:49], v[2:9], v[218:225], v[46:49]
	v_mfma_f32_16x16x128_f8f6f4 v[42:45], v[18:25], v[218:225], v[42:45]
	v_mfma_f32_16x16x128_f8f6f4 v[86:89], v[26:33], v[194:201], v[86:89]
	v_mfma_f32_16x16x128_f8f6f4 v[82:85], v[178:185], v[194:201], v[82:85]
	v_mfma_f32_16x16x128_f8f6f4 v[70:73], v[26:33], v[202:209], v[70:73]
	v_mfma_f32_16x16x128_f8f6f4 v[66:69], v[178:185], v[202:209], v[66:69]
	v_mfma_f32_16x16x128_f8f6f4 v[54:57], v[26:33], v[210:217], v[54:57]
	v_mfma_f32_16x16x128_f8f6f4 v[50:53], v[178:185], v[210:217], v[50:53]
	v_mfma_f32_16x16x128_f8f6f4 v[38:41], v[26:33], v[218:225], v[38:41]
	v_mfma_f32_16x16x128_f8f6f4 v[34:37], v[178:185], v[218:225], v[34:37]
	s_setprio 0
	s_barrier
	ds_read_b128 v[18:21], v191
	ds_read_b128 v[22:25], v191 offset:1024
	ds_read_b128 v[26:29], v191 offset:2048
	ds_read_b128 v[30:33], v191 offset:3072
	ds_read_b128 v[2:5], v192
	ds_read_b128 v[6:9], v192 offset:1024
	ds_read_b128 v[178:181], v192 offset:2048
	ds_read_b128 v[182:185], v192 offset:3072
	s_add_u32 s58, s58, 0x40000
	s_addc_u32 s59, s59, 0
	s_mov_b32 m0, s61
	v_lshl_add_u64 v[226:227], s[58:59], 0, v[162:163]
	ds_read_b128 v[194:197], v190 offset:32768
	ds_read_b128 v[198:201], v190 offset:33792
	ds_read_b128 v[202:205], v190 offset:34816
	ds_read_b128 v[206:209], v190 offset:35840
	ds_read_b128 v[210:213], v190 offset:36864
	ds_read_b128 v[214:217], v190 offset:37888
	ds_read_b128 v[218:221], v190 offset:38912
	ds_read_b128 v[222:225], v190 offset:39936
	global_load_lds_dwordx4 v[226:227], off
	v_lshl_add_u64 v[226:227], s[58:59], 0, v[166:167]
	s_mov_b32 m0, s62
	s_nop 0
	global_load_lds_dwordx4 v[226:227], off
	s_waitcnt vmcnt(8)
	s_waitcnt lgkmcnt(0)
	s_setprio 1
	s_barrier
	v_mfma_f32_16x16x128_f8f6f4 v[154:157], v[18:25], v[194:201], v[154:157]
	v_mfma_f32_16x16x128_f8f6f4 v[158:161], v[26:33], v[194:201], v[158:161]
	v_mfma_f32_16x16x128_f8f6f4 v[142:145], v[18:25], v[202:209], v[142:145]
	v_mfma_f32_16x16x128_f8f6f4 v[138:141], v[26:33], v[202:209], v[138:141]
	v_mfma_f32_16x16x128_f8f6f4 v[126:129], v[18:25], v[210:217], v[126:129]
	v_mfma_f32_16x16x128_f8f6f4 v[122:125], v[26:33], v[210:217], v[122:125]
	v_mfma_f32_16x16x128_f8f6f4 v[110:113], v[18:25], v[218:225], v[110:113]
	v_mfma_f32_16x16x128_f8f6f4 v[106:109], v[26:33], v[218:225], v[106:109]
	v_mfma_f32_16x16x128_f8f6f4 v[146:149], v[2:9], v[194:201], v[146:149]
	v_mfma_f32_16x16x128_f8f6f4 v[150:153], v[178:185], v[194:201], v[150:153]
	v_mfma_f32_16x16x128_f8f6f4 v[134:137], v[2:9], v[202:209], v[134:137]
	v_mfma_f32_16x16x128_f8f6f4 v[130:133], v[178:185], v[202:209], v[130:133]
	v_mfma_f32_16x16x128_f8f6f4 v[118:121], v[2:9], v[210:217], v[118:121]
	v_mfma_f32_16x16x128_f8f6f4 v[114:117], v[178:185], v[210:217], v[114:117]
	v_mfma_f32_16x16x128_f8f6f4 v[94:97], v[2:9], v[218:225], v[94:97]
	v_mfma_f32_16x16x128_f8f6f4 v[90:93], v[178:185], v[218:225], v[90:93]
	s_setprio 0
	s_barrier
	s_mov_b32 m0, s81
	v_lshl_add_u64 v[10:11], v[10:11], 0, s[14:15]
	s_add_u32 s56, s56, 0x40080
	ds_read_b128 v[194:197], v190 offset:49152
	ds_read_b128 v[198:201], v190 offset:50176
	ds_read_b128 v[202:205], v190 offset:51200
	ds_read_b128 v[206:209], v190 offset:52224
	ds_read_b128 v[210:213], v190 offset:53248
	ds_read_b128 v[214:217], v190 offset:54272
	ds_read_b128 v[218:221], v190 offset:55296
	ds_read_b128 v[222:225], v190 offset:56320
	global_load_lds_dwordx4 v[10:11], off
	v_lshl_add_u64 v[10:11], v[12:13], 0, s[14:15]
	s_mov_b32 m0, s82
	s_addc_u32 s57, s57, 0
	global_load_lds_dwordx4 v[10:11], off
	v_lshl_add_u64 v[10:11], s[56:57], 0, v[164:165]
	s_mov_b32 m0, s83
	s_nop 0
	global_load_lds_dwordx4 v[10:11], off
	v_lshl_add_u64 v[10:11], s[56:57], 0, v[168:169]
	s_mov_b32 m0, s84
	s_nop 0
	global_load_lds_dwordx4 v[10:11], off
	v_lshl_add_u64 v[10:11], v[14:15], 0, s[14:15]
	s_mov_b32 m0, s64
	s_nop 0
	global_load_lds_dwordx4 v[10:11], off
	v_lshl_add_u64 v[10:11], v[16:17], 0, s[14:15]
	s_mov_b32 m0, s65
	s_nop 0
	global_load_lds_dwordx4 v[10:11], off
	s_waitcnt vmcnt(8)
	s_waitcnt lgkmcnt(0)
	s_setprio 1
	s_barrier
	v_mfma_f32_16x16x128_f8f6f4 v[102:105], v[18:25], v[194:201], v[102:105]
	v_mfma_f32_16x16x128_f8f6f4 v[98:101], v[26:33], v[194:201], v[98:101]
	v_mfma_f32_16x16x128_f8f6f4 v[78:81], v[18:25], v[202:209], v[78:81]
	v_mfma_f32_16x16x128_f8f6f4 v[74:77], v[26:33], v[202:209], v[74:77]
	v_mfma_f32_16x16x128_f8f6f4 v[62:65], v[18:25], v[210:217], v[62:65]
	v_mfma_f32_16x16x128_f8f6f4 v[58:61], v[26:33], v[210:217], v[58:61]
	v_mfma_f32_16x16x128_f8f6f4 v[46:49], v[18:25], v[218:225], v[46:49]
	v_mfma_f32_16x16x128_f8f6f4 v[42:45], v[26:33], v[218:225], v[42:45]
	v_mfma_f32_16x16x128_f8f6f4 v[86:89], v[2:9], v[194:201], v[86:89]
	v_mfma_f32_16x16x128_f8f6f4 v[82:85], v[178:185], v[194:201], v[82:85]
	v_mfma_f32_16x16x128_f8f6f4 v[70:73], v[2:9], v[202:209], v[70:73]
	v_mfma_f32_16x16x128_f8f6f4 v[66:69], v[178:185], v[202:209], v[66:69]
	v_mfma_f32_16x16x128_f8f6f4 v[54:57], v[2:9], v[210:217], v[54:57]
	v_mfma_f32_16x16x128_f8f6f4 v[50:53], v[178:185], v[210:217], v[50:53]
	v_mfma_f32_16x16x128_f8f6f4 v[38:41], v[2:9], v[218:225], v[38:41]
	v_mfma_f32_16x16x128_f8f6f4 v[34:37], v[178:185], v[218:225], v[34:37]
	s_setprio 0
	s_barrier
	s_add_i32 s8, s8, 2
	s_add_u32 s85, s85, 0x100
	s_addc_u32 s86, s86, 0
	s_add_u32 s10, s10, 0x100
	s_addc_u32 s11, s11, 0
	s_cmp_gt_u32 s8, 13
	s_cbranch_scc0 .LBB0_771
	s_and_b64 vcc, exec, s[16:17]
	s_cbranch_vccz .LBB0_774
	s_barrier

.LBB0_902:
	s_ashr_i32 s49, s48, 31
	ds_read_b128 v[2:5], v188
	ds_read_b128 v[6:9], v188 offset:1024
	ds_read_b128 v[10:13], v188 offset:2048
	ds_read_b128 v[14:17], v188 offset:3072
	ds_read_b128 v[18:21], v189
	ds_read_b128 v[22:25], v189 offset:1024
	ds_read_b128 v[26:29], v189 offset:2048
	ds_read_b128 v[30:33], v189 offset:3072
	s_lshl_b64 s[8:9], s[48:49], 20
	s_add_u32 s50, s19, s8
	s_addc_u32 s51, s24, s9
	s_and_b64 s[8:9], s[4:5], exec
	s_cselect_b32 s49, s51, s59
	s_cselect_b32 s74, s50, s58
	s_ashr_i32 s47, s46, 31
	s_lshl_b64 s[8:9], s[46:47], 20
	s_add_u32 s52, s25, s8
	s_addc_u32 s53, s26, s9
	s_and_b64 s[8:9], s[4:5], exec
	s_cselect_b32 s47, s53, s57
	s_cselect_b32 s75, s52, s56
	s_add_u32 s8, s58, 0x80080
	s_addc_u32 s9, s59, 0
	s_add_i32 s76, s55, 0xc000
	v_lshl_add_u64 v[34:35], s[8:9], 0, v[168:169]
	s_mov_b32 m0, s76
	s_add_i32 s77, s55, 0xe000
	ds_read_b128 v[38:41], v190
	ds_read_b128 v[42:45], v190 offset:1024
	ds_read_b128 v[46:49], v190 offset:2048
	ds_read_b128 v[50:53], v190 offset:3072
	ds_read_b128 v[54:57], v190 offset:4096
	ds_read_b128 v[58:61], v190 offset:5120
	ds_read_b128 v[62:65], v190 offset:6144
	ds_read_b128 v[66:69], v190 offset:7168
	global_load_lds_dwordx4 v[34:35], off
	v_lshl_add_u64 v[34:35], s[8:9], 0, v[164:165]
	s_mov_b32 m0, s77
	s_nop 0
	global_load_lds_dwordx4 v[34:35], off
	s_waitcnt vmcnt(24)
	s_waitcnt lgkmcnt(0)
	s_setprio 1
	s_barrier
	s_mov_b32 s8, 0
	s_mov_b32 s10, s8
	s_mov_b32 s11, s8
	s_mov_b32 s9, s8
	v_mov_b64_e32 v[36:37], s[10:11]
	v_mov_b64_e32 v[160:161], s[10:11]
	v_mov_b64_e32 v[156:157], s[10:11]
	v_mov_b64_e32 v[144:145], s[10:11]
	v_mov_b64_e32 v[140:141], s[10:11]
	v_mov_b64_e32 v[128:129], s[10:11]
	v_mov_b64_e32 v[120:121], s[10:11]
	v_mov_b64_e32 v[92:93], s[10:11]
	v_mov_b64_e32 v[84:85], s[10:11]
	v_mov_b64_e32 v[34:35], s[8:9]
	v_mov_b64_e32 v[158:159], s[8:9]
	v_mov_b64_e32 v[154:155], s[8:9]
	v_mov_b64_e32 v[142:143], s[8:9]
	v_mov_b64_e32 v[138:139], s[8:9]
	v_mov_b64_e32 v[126:127], s[8:9]
	v_mov_b64_e32 v[118:119], s[8:9]
	v_mov_b64_e32 v[90:91], s[8:9]
	v_mov_b64_e32 v[82:83], s[8:9]
	s_waitcnt lgkmcnt(0)
	v_mfma_f32_16x16x128_f8f6f4 v[158:161], v[2:9], v[38:45], v[158:161]
	v_mfma_f32_16x16x128_f8f6f4 v[154:157], v[10:17], v[38:45], v[154:157]
	v_mfma_f32_16x16x128_f8f6f4 v[142:145], v[2:9], v[46:53], v[142:145]
	v_mfma_f32_16x16x128_f8f6f4 v[138:141], v[10:17], v[46:53], v[138:141]
	v_mfma_f32_16x16x128_f8f6f4 v[126:129], v[2:9], v[54:61], v[126:129]
	v_mfma_f32_16x16x128_f8f6f4 v[118:121], v[10:17], v[54:61], v[118:121]
	v_mfma_f32_16x16x128_f8f6f4 v[90:93], v[2:9], v[62:69], v[90:93]
	v_mfma_f32_16x16x128_f8f6f4 v[82:85], v[10:17], v[62:69], v[82:85]
	v_mov_b64_e32 v[152:153], s[10:11]
	v_mov_b64_e32 v[148:149], s[10:11]
	v_mov_b64_e32 v[136:137], s[10:11]
	v_mov_b64_e32 v[132:133], s[10:11]
	v_mov_b64_e32 v[112:113], s[10:11]
	v_mov_b64_e32 v[108:109], s[10:11]
	v_mov_b64_e32 v[80:81], s[10:11]
	v_mov_b64_e32 v[76:77], s[10:11]
	v_mov_b64_e32 v[150:151], s[8:9]
	v_mov_b64_e32 v[146:147], s[8:9]
	v_mov_b64_e32 v[134:135], s[8:9]
	v_mov_b64_e32 v[130:131], s[8:9]
	v_mov_b64_e32 v[110:111], s[8:9]
	v_mov_b64_e32 v[106:107], s[8:9]
	v_mov_b64_e32 v[78:79], s[8:9]
	v_mov_b64_e32 v[74:75], s[8:9]
	v_mfma_f32_16x16x128_f8f6f4 v[150:153], v[18:25], v[38:45], v[150:153]
	v_mfma_f32_16x16x128_f8f6f4 v[146:149], v[26:33], v[38:45], v[146:149]
	v_mfma_f32_16x16x128_f8f6f4 v[134:137], v[18:25], v[46:53], v[134:137]
	v_mfma_f32_16x16x128_f8f6f4 v[130:133], v[26:33], v[46:53], v[130:133]
	v_mfma_f32_16x16x128_f8f6f4 v[110:113], v[18:25], v[54:61], v[110:113]
	v_mfma_f32_16x16x128_f8f6f4 v[106:109], v[26:33], v[54:61], v[106:109]
	v_mfma_f32_16x16x128_f8f6f4 v[78:81], v[18:25], v[62:69], v[78:81]
	v_mfma_f32_16x16x128_f8f6f4 v[74:77], v[26:33], v[62:69], v[74:77]
	s_setprio 0
	s_barrier
	s_add_i32 s9, s67, s27
	v_lshl_add_u64 v[178:179], s[56:57], 0, v[166:167]
	s_add_i32 s78, s9, 0x2000
	v_lshl_add_u64 v[38:39], v[178:179], 0, s[34:35]
	s_mov_b32 m0, s9
	v_lshl_add_u64 v[180:181], s[56:57], 0, v[162:163]
	s_add_u32 s10, s56, 0x80100
	ds_read_b128 v[50:53], v190 offset:16384
	ds_read_b128 v[54:57], v190 offset:17408
	ds_read_b128 v[192:195], v190 offset:18432
	ds_read_b128 v[196:199], v190 offset:19456
	ds_read_b128 v[200:203], v190 offset:20480
	ds_read_b128 v[204:207], v190 offset:21504
	ds_read_b128 v[208:211], v190 offset:22528
	ds_read_b128 v[212:215], v190 offset:23552
	global_load_lds_dwordx4 v[38:39], off
	v_lshl_add_u64 v[38:39], v[180:181], 0, s[34:35]
	s_mov_b32 m0, s78
	s_addc_u32 s11, s57, 0
	s_add_i32 s79, s68, s27
	global_load_lds_dwordx4 v[38:39], off
	v_lshl_add_u64 v[38:39], s[10:11], 0, v[166:167]
	s_mov_b32 m0, s79
	s_add_i32 s80, s79, 0x2000
	global_load_lds_dwordx4 v[38:39], off
	v_lshl_add_u64 v[38:39], s[10:11], 0, v[162:163]
	s_mov_b32 m0, s80
	v_lshl_add_u64 v[182:183], s[58:59], 0, v[168:169]
	global_load_lds_dwordx4 v[38:39], off
	v_lshl_add_u64 v[38:39], v[182:183], 0, s[34:35]
	s_mov_b32 m0, s55
	v_lshl_add_u64 v[184:185], s[58:59], 0, v[164:165]
	global_load_lds_dwordx4 v[38:39], off
	v_lshl_add_u64 v[38:39], v[184:185], 0, s[34:35]
	s_mov_b32 m0, s60
	s_nop 0
	global_load_lds_dwordx4 v[38:39], off
	s_waitcnt vmcnt(24)
	s_waitcnt lgkmcnt(0)
	s_setprio 1
	s_barrier
	v_mov_b64_e32 v[124:125], v[36:37]
	v_mov_b64_e32 v[116:117], v[36:37]
	v_mov_b64_e32 v[96:97], v[36:37]
	v_mov_b64_e32 v[88:89], v[36:37]
	v_mov_b64_e32 v[64:65], v[36:37]
	v_mov_b64_e32 v[60:61], v[36:37]
	v_mov_b64_e32 v[48:49], v[36:37]
	v_mov_b64_e32 v[44:45], v[36:37]
	v_mov_b64_e32 v[122:123], v[34:35]
	v_mov_b64_e32 v[114:115], v[34:35]
	v_mov_b64_e32 v[94:95], v[34:35]
	v_mov_b64_e32 v[86:87], v[34:35]
	v_mov_b64_e32 v[62:63], v[34:35]
	v_mov_b64_e32 v[58:59], v[34:35]
	v_mov_b64_e32 v[46:47], v[34:35]
	v_mov_b64_e32 v[42:43], v[34:35]
	s_waitcnt lgkmcnt(0)
	v_mfma_f32_16x16x128_f8f6f4 v[122:125], v[2:9], v[50:57], v[122:125]
	v_mfma_f32_16x16x128_f8f6f4 v[114:117], v[10:17], v[50:57], v[114:117]
	v_mfma_f32_16x16x128_f8f6f4 v[94:97], v[2:9], v[192:199], v[94:97]
	v_mfma_f32_16x16x128_f8f6f4 v[86:89], v[10:17], v[192:199], v[86:89]
	v_mfma_f32_16x16x128_f8f6f4 v[62:65], v[2:9], v[200:207], v[62:65]
	v_mfma_f32_16x16x128_f8f6f4 v[58:61], v[10:17], v[200:207], v[58:61]
	v_mfma_f32_16x16x128_f8f6f4 v[46:49], v[2:9], v[208:215], v[46:49]
	v_mfma_f32_16x16x128_f8f6f4 v[42:45], v[10:17], v[208:215], v[42:45]
	v_mov_b64_e32 v[104:105], v[36:37]
	v_mov_b64_e32 v[100:101], v[36:37]
	v_mov_b64_e32 v[102:103], v[34:35]
	v_mov_b64_e32 v[98:99], v[34:35]
	v_mfma_f32_16x16x128_f8f6f4 v[102:105], v[18:25], v[50:57], v[102:105]
	v_mfma_f32_16x16x128_f8f6f4 v[98:101], v[26:33], v[50:57], v[98:101]
	v_mov_b64_e32 v[72:73], v[36:37]
	v_mov_b64_e32 v[68:69], v[36:37]
	v_mov_b64_e32 v[56:57], v[36:37]
	v_mov_b64_e32 v[52:53], v[36:37]
	v_mov_b64_e32 v[40:41], v[36:37]
	v_mov_b64_e32 v[70:71], v[34:35]
	v_mov_b64_e32 v[66:67], v[34:35]
	v_mov_b64_e32 v[54:55], v[34:35]
	v_mov_b64_e32 v[50:51], v[34:35]
	v_mov_b64_e32 v[38:39], v[34:35]
	v_mfma_f32_16x16x128_f8f6f4 v[70:73], v[18:25], v[192:199], v[70:73]
	v_mfma_f32_16x16x128_f8f6f4 v[66:69], v[26:33], v[192:199], v[66:69]
	v_mfma_f32_16x16x128_f8f6f4 v[54:57], v[18:25], v[200:207], v[54:57]
	v_mfma_f32_16x16x128_f8f6f4 v[50:53], v[26:33], v[200:207], v[50:53]
	v_mfma_f32_16x16x128_f8f6f4 v[38:41], v[18:25], v[208:215], v[38:41]
	v_mfma_f32_16x16x128_f8f6f4 v[34:37], v[26:33], v[208:215], v[34:37]
	s_setprio 0
	s_barrier
	s_add_i32 s81, 0, 0x18000
	s_add_i32 s83, 0, 0x1c000
	v_add_u32_e32 v191, s81, v186
	v_add_u32_e32 v192, s83, v186
	ds_read_b128 v[18:21], v191
	ds_read_b128 v[22:25], v191 offset:1024
	ds_read_b128 v[26:29], v191 offset:2048
	ds_read_b128 v[30:33], v191 offset:3072
	ds_read_b128 v[2:5], v192
	ds_read_b128 v[6:9], v192 offset:1024
	ds_read_b128 v[10:13], v192 offset:2048
	ds_read_b128 v[14:17], v192 offset:3072
	s_add_u32 s10, s58, 0x80100
	s_addc_u32 s11, s59, 0
	s_mov_b32 m0, s61
	v_lshl_add_u64 v[226:227], s[10:11], 0, v[168:169]
	ds_read_b128 v[194:197], v190 offset:32768
	ds_read_b128 v[198:201], v190 offset:33792
	ds_read_b128 v[202:205], v190 offset:34816
	ds_read_b128 v[206:209], v190 offset:35840
	ds_read_b128 v[210:213], v190 offset:36864
	ds_read_b128 v[214:217], v190 offset:37888
	ds_read_b128 v[218:221], v190 offset:38912
	ds_read_b128 v[222:225], v190 offset:39936
	global_load_lds_dwordx4 v[226:227], off
	v_lshl_add_u64 v[226:227], s[10:11], 0, v[164:165]
	s_mov_b32 m0, s62
	s_nop 0
	global_load_lds_dwordx4 v[226:227], off
	s_waitcnt vmcnt(8)
	s_waitcnt lgkmcnt(0)
	s_setprio 1
	s_barrier
	v_mfma_f32_16x16x128_f8f6f4 v[158:161], v[18:25], v[194:201], v[158:161]
	v_mfma_f32_16x16x128_f8f6f4 v[154:157], v[26:33], v[194:201], v[154:157]
	v_mfma_f32_16x16x128_f8f6f4 v[142:145], v[18:25], v[202:209], v[142:145]
	v_mfma_f32_16x16x128_f8f6f4 v[138:141], v[26:33], v[202:209], v[138:141]
	v_mfma_f32_16x16x128_f8f6f4 v[126:129], v[18:25], v[210:217], v[126:129]
	v_mfma_f32_16x16x128_f8f6f4 v[118:121], v[26:33], v[210:217], v[118:121]
	v_mfma_f32_16x16x128_f8f6f4 v[90:93], v[18:25], v[218:225], v[90:93]
	v_mfma_f32_16x16x128_f8f6f4 v[82:85], v[26:33], v[218:225], v[82:85]
	v_mfma_f32_16x16x128_f8f6f4 v[150:153], v[2:9], v[194:201], v[150:153]
	v_mfma_f32_16x16x128_f8f6f4 v[146:149], v[10:17], v[194:201], v[146:149]
	v_mfma_f32_16x16x128_f8f6f4 v[134:137], v[2:9], v[202:209], v[134:137]
	v_mfma_f32_16x16x128_f8f6f4 v[130:133], v[10:17], v[202:209], v[130:133]
	v_mfma_f32_16x16x128_f8f6f4 v[110:113], v[2:9], v[210:217], v[110:113]
	v_mfma_f32_16x16x128_f8f6f4 v[106:109], v[10:17], v[210:217], v[106:109]
	v_mfma_f32_16x16x128_f8f6f4 v[78:81], v[2:9], v[218:225], v[78:81]
	v_mfma_f32_16x16x128_f8f6f4 v[74:77], v[10:17], v[218:225], v[74:77]
	s_setprio 0
	s_barrier
	s_add_i32 s81, s81, s27
	s_add_i32 s82, s81, 0x2000
	v_lshl_add_u64 v[178:179], v[178:179], 0, s[36:37]
	s_mov_b32 m0, s81
	s_add_u32 s10, s56, 0x80180
	ds_read_b128 v[194:197], v190 offset:49152
	ds_read_b128 v[198:201], v190 offset:50176
	ds_read_b128 v[202:205], v190 offset:51200
	ds_read_b128 v[206:209], v190 offset:52224
	ds_read_b128 v[210:213], v190 offset:53248
	ds_read_b128 v[214:217], v190 offset:54272
	ds_read_b128 v[218:221], v190 offset:55296
	ds_read_b128 v[222:225], v190 offset:56320
	global_load_lds_dwordx4 v[178:179], off
	v_lshl_add_u64 v[178:179], v[180:181], 0, s[36:37]
	s_mov_b32 m0, s82
	s_addc_u32 s11, s57, 0
	s_add_i32 s83, s83, s27
	global_load_lds_dwordx4 v[178:179], off
	v_lshl_add_u64 v[178:179], s[10:11], 0, v[166:167]
	s_mov_b32 m0, s83
	s_add_i32 s84, s83, 0x2000
	global_load_lds_dwordx4 v[178:179], off
	v_lshl_add_u64 v[178:179], s[10:11], 0, v[162:163]
	s_mov_b32 m0, s84
	s_nop 0
	global_load_lds_dwordx4 v[178:179], off
	v_lshl_add_u64 v[178:179], v[182:183], 0, s[36:37]
	s_mov_b32 m0, s63
	s_nop 0
	global_load_lds_dwordx4 v[178:179], off
	v_lshl_add_u64 v[178:179], v[184:185], 0, s[36:37]
	s_mov_b32 m0, s64
	s_nop 0
	global_load_lds_dwordx4 v[178:179], off
	s_waitcnt vmcnt(8)
	s_waitcnt lgkmcnt(0)
	s_setprio 1
	s_barrier
	v_mfma_f32_16x16x128_f8f6f4 v[122:125], v[18:25], v[194:201], v[122:125]
	v_mfma_f32_16x16x128_f8f6f4 v[114:117], v[26:33], v[194:201], v[114:117]
	v_mfma_f32_16x16x128_f8f6f4 v[94:97], v[18:25], v[202:209], v[94:97]
	v_mfma_f32_16x16x128_f8f6f4 v[86:89], v[26:33], v[202:209], v[86:89]
	v_mfma_f32_16x16x128_f8f6f4 v[62:65], v[18:25], v[210:217], v[62:65]
	v_mfma_f32_16x16x128_f8f6f4 v[58:61], v[26:33], v[210:217], v[58:61]
	v_mfma_f32_16x16x128_f8f6f4 v[46:49], v[18:25], v[218:225], v[46:49]
	v_mfma_f32_16x16x128_f8f6f4 v[42:45], v[26:33], v[218:225], v[42:45]
	v_mfma_f32_16x16x128_f8f6f4 v[102:105], v[2:9], v[194:201], v[102:105]
	v_mfma_f32_16x16x128_f8f6f4 v[98:101], v[10:17], v[194:201], v[98:101]
	v_mfma_f32_16x16x128_f8f6f4 v[70:73], v[2:9], v[202:209], v[70:73]
	v_mfma_f32_16x16x128_f8f6f4 v[66:69], v[10:17], v[202:209], v[66:69]
	v_mfma_f32_16x16x128_f8f6f4 v[54:57], v[2:9], v[210:217], v[54:57]
	v_mfma_f32_16x16x128_f8f6f4 v[50:53], v[10:17], v[210:217], v[50:53]
	v_mfma_f32_16x16x128_f8f6f4 v[38:41], v[2:9], v[218:225], v[38:41]
	v_mfma_f32_16x16x128_f8f6f4 v[34:37], v[10:17], v[218:225], v[34:37]
	s_setprio 0
	s_barrier
	s_add_u32 s85, s56, 0x200
	s_addc_u32 s86, s57, 0
	s_add_u32 s10, s58, 0x80180
	s_addc_u32 s11, s59, 0
.LBB0_903:
	ds_read_b128 v[2:5], v188
	ds_read_b128 v[6:9], v188 offset:1024
	ds_read_b128 v[18:21], v188 offset:2048
	ds_read_b128 v[22:25], v188 offset:3072
	ds_read_b128 v[26:29], v189
	ds_read_b128 v[30:33], v189 offset:1024
	ds_read_b128 v[178:181], v189 offset:2048
	ds_read_b128 v[182:185], v189 offset:3072
	s_add_u32 s56, s10, 0xfff80080
	s_addc_u32 s57, s11, -1
	s_cmp_eq_u32 s8, 28
	s_cselect_b32 s59, s49, s57
	s_cselect_b32 s58, s74, s56
	s_cselect_b32 s57, s47, s86
	s_cselect_b32 s56, s75, s85
	s_mov_b32 m0, s76
	v_lshl_add_u64 v[218:219], s[10:11], 0, v[172:173]
	ds_read_b128 v[10:13], v190
	ds_read_b128 v[14:17], v190 offset:1024
	ds_read_b128 v[194:197], v190 offset:2048
	ds_read_b128 v[198:201], v190 offset:3072
	ds_read_b128 v[202:205], v190 offset:4096
	ds_read_b128 v[206:209], v190 offset:5120
	ds_read_b128 v[210:213], v190 offset:6144
	ds_read_b128 v[214:217], v190 offset:7168
	global_load_lds_dwordx4 v[218:219], off
	v_lshl_add_u64 v[218:219], s[10:11], 0, v[170:171]
	s_mov_b32 m0, s77
	s_nop 0
	global_load_lds_dwordx4 v[218:219], off
	s_waitcnt vmcnt(8)
	s_waitcnt lgkmcnt(0)
	s_setprio 1
	s_barrier
	v_mfma_f32_16x16x128_f8f6f4 v[158:161], v[2:9], v[10:17], v[158:161]
	v_mfma_f32_16x16x128_f8f6f4 v[154:157], v[18:25], v[10:17], v[154:157]
	v_mfma_f32_16x16x128_f8f6f4 v[142:145], v[2:9], v[194:201], v[142:145]
	v_mfma_f32_16x16x128_f8f6f4 v[138:141], v[18:25], v[194:201], v[138:141]
	v_mfma_f32_16x16x128_f8f6f4 v[126:129], v[2:9], v[202:209], v[126:129]
	v_mfma_f32_16x16x128_f8f6f4 v[118:121], v[18:25], v[202:209], v[118:121]
	v_mfma_f32_16x16x128_f8f6f4 v[90:93], v[2:9], v[210:217], v[90:93]
	v_mfma_f32_16x16x128_f8f6f4 v[82:85], v[18:25], v[210:217], v[82:85]
	v_mfma_f32_16x16x128_f8f6f4 v[150:153], v[26:33], v[10:17], v[150:153]
	v_mfma_f32_16x16x128_f8f6f4 v[146:149], v[178:185], v[10:17], v[146:149]
	v_mfma_f32_16x16x128_f8f6f4 v[134:137], v[26:33], v[194:201], v[134:137]
	v_mfma_f32_16x16x128_f8f6f4 v[130:133], v[178:185], v[194:201], v[130:133]
	v_mfma_f32_16x16x128_f8f6f4 v[110:113], v[26:33], v[202:209], v[110:113]
	v_mfma_f32_16x16x128_f8f6f4 v[106:109], v[178:185], v[202:209], v[106:109]
	v_mfma_f32_16x16x128_f8f6f4 v[78:81], v[26:33], v[210:217], v[78:81]
	v_mfma_f32_16x16x128_f8f6f4 v[74:77], v[178:185], v[210:217], v[74:77]
	s_setprio 0
	s_barrier
	s_mov_b32 m0, s9
	v_lshl_add_u64 v[10:11], s[56:57], 0, v[166:167]
	s_add_u32 s88, s56, 0x80000
	ds_read_b128 v[194:197], v190 offset:16384
	ds_read_b128 v[198:201], v190 offset:17408
	ds_read_b128 v[202:205], v190 offset:18432
	ds_read_b128 v[206:209], v190 offset:19456
	ds_read_b128 v[210:213], v190 offset:20480
	ds_read_b128 v[214:217], v190 offset:21504
	ds_read_b128 v[218:221], v190 offset:22528
	ds_read_b128 v[222:225], v190 offset:23552
	global_load_lds_dwordx4 v[10:11], off
	v_lshl_add_u64 v[12:13], s[56:57], 0, v[162:163]
	s_mov_b32 m0, s78
	s_addc_u32 s89, s57, 0
	global_load_lds_dwordx4 v[12:13], off
	v_lshl_add_u64 v[14:15], s[88:89], 0, v[166:167]
	s_mov_b32 m0, s79
	v_lshl_add_u64 v[16:17], s[58:59], 0, v[164:165]
	global_load_lds_dwordx4 v[14:15], off
	v_lshl_add_u64 v[14:15], s[88:89], 0, v[162:163]
	s_mov_b32 m0, s80
	s_nop 0
	global_load_lds_dwordx4 v[14:15], off
	v_lshl_add_u64 v[14:15], s[58:59], 0, v[168:169]
	s_mov_b32 m0, s55
	s_nop 0
	global_load_lds_dwordx4 v[14:15], off
	s_mov_b32 m0, s60
	s_nop 0
	global_load_lds_dwordx4 v[16:17], off
	s_waitcnt vmcnt(8)
	s_waitcnt lgkmcnt(0)
	s_setprio 1
	s_barrier
	v_mfma_f32_16x16x128_f8f6f4 v[122:125], v[2:9], v[194:201], v[122:125]
	v_mfma_f32_16x16x128_f8f6f4 v[114:117], v[18:25], v[194:201], v[114:117]
	v_mfma_f32_16x16x128_f8f6f4 v[94:97], v[2:9], v[202:209], v[94:97]
	v_mfma_f32_16x16x128_f8f6f4 v[86:89], v[18:25], v[202:209], v[86:89]
	v_mfma_f32_16x16x128_f8f6f4 v[62:65], v[2:9], v[210:217], v[62:65]
	v_mfma_f32_16x16x128_f8f6f4 v[58:61], v[18:25], v[210:217], v[58:61]
	v_mfma_f32_16x16x128_f8f6f4 v[46:49], v[2:9], v[218:225], v[46:49]
	v_mfma_f32_16x16x128_f8f6f4 v[42:45], v[18:25], v[218:225], v[42:45]
	v_mfma_f32_16x16x128_f8f6f4 v[102:105], v[26:33], v[194:201], v[102:105]
	v_mfma_f32_16x16x128_f8f6f4 v[98:101], v[178:185], v[194:201], v[98:101]
	v_mfma_f32_16x16x128_f8f6f4 v[70:73], v[26:33], v[202:209], v[70:73]
	v_mfma_f32_16x16x128_f8f6f4 v[66:69], v[178:185], v[202:209], v[66:69]
	v_mfma_f32_16x16x128_f8f6f4 v[54:57], v[26:33], v[210:217], v[54:57]
	v_mfma_f32_16x16x128_f8f6f4 v[50:53], v[178:185], v[210:217], v[50:53]
	v_mfma_f32_16x16x128_f8f6f4 v[38:41], v[26:33], v[218:225], v[38:41]
	v_mfma_f32_16x16x128_f8f6f4 v[34:37], v[178:185], v[218:225], v[34:37]
	s_setprio 0
	s_barrier
	ds_read_b128 v[18:21], v191
	ds_read_b128 v[22:25], v191 offset:1024
	ds_read_b128 v[26:29], v191 offset:2048
	ds_read_b128 v[30:33], v191 offset:3072
	ds_read_b128 v[2:5], v192
	ds_read_b128 v[6:9], v192 offset:1024
	ds_read_b128 v[178:181], v192 offset:2048
	ds_read_b128 v[182:185], v192 offset:3072
	s_add_u32 s58, s58, 0x80000
	s_addc_u32 s59, s59, 0
	s_mov_b32 m0, s61
	v_lshl_add_u64 v[226:227], s[58:59], 0, v[168:169]
	ds_read_b128 v[194:197], v190 offset:32768
	ds_read_b128 v[198:201], v190 offset:33792
	ds_read_b128 v[202:205], v190 offset:34816
	ds_read_b128 v[206:209], v190 offset:35840
	ds_read_b128 v[210:213], v190 offset:36864
	ds_read_b128 v[214:217], v190 offset:37888
	ds_read_b128 v[218:221], v190 offset:38912
	ds_read_b128 v[222:225], v190 offset:39936
	global_load_lds_dwordx4 v[226:227], off
	v_lshl_add_u64 v[226:227], s[58:59], 0, v[164:165]
	s_mov_b32 m0, s62
	s_nop 0
	global_load_lds_dwordx4 v[226:227], off
	s_waitcnt vmcnt(8)
	s_waitcnt lgkmcnt(0)
	s_setprio 1
	s_barrier
	v_mfma_f32_16x16x128_f8f6f4 v[158:161], v[18:25], v[194:201], v[158:161]
	v_mfma_f32_16x16x128_f8f6f4 v[154:157], v[26:33], v[194:201], v[154:157]
	v_mfma_f32_16x16x128_f8f6f4 v[142:145], v[18:25], v[202:209], v[142:145]
	v_mfma_f32_16x16x128_f8f6f4 v[138:141], v[26:33], v[202:209], v[138:141]
	v_mfma_f32_16x16x128_f8f6f4 v[126:129], v[18:25], v[210:217], v[126:129]
	v_mfma_f32_16x16x128_f8f6f4 v[118:121], v[26:33], v[210:217], v[118:121]
	v_mfma_f32_16x16x128_f8f6f4 v[90:93], v[18:25], v[218:225], v[90:93]
	v_mfma_f32_16x16x128_f8f6f4 v[82:85], v[26:33], v[218:225], v[82:85]
	v_mfma_f32_16x16x128_f8f6f4 v[150:153], v[2:9], v[194:201], v[150:153]
	v_mfma_f32_16x16x128_f8f6f4 v[146:149], v[178:185], v[194:201], v[146:149]
	v_mfma_f32_16x16x128_f8f6f4 v[134:137], v[2:9], v[202:209], v[134:137]
	v_mfma_f32_16x16x128_f8f6f4 v[130:133], v[178:185], v[202:209], v[130:133]
	v_mfma_f32_16x16x128_f8f6f4 v[110:113], v[2:9], v[210:217], v[110:113]
	v_mfma_f32_16x16x128_f8f6f4 v[106:109], v[178:185], v[210:217], v[106:109]
	v_mfma_f32_16x16x128_f8f6f4 v[78:81], v[2:9], v[218:225], v[78:81]
	v_mfma_f32_16x16x128_f8f6f4 v[74:77], v[178:185], v[218:225], v[74:77]
	s_setprio 0
	s_barrier
	s_mov_b32 m0, s81
	v_lshl_add_u64 v[10:11], v[10:11], 0, s[16:17]
	s_add_u32 s56, s56, 0x80080
	ds_read_b128 v[194:197], v190 offset:49152
	ds_read_b128 v[198:201], v190 offset:50176
	ds_read_b128 v[202:205], v190 offset:51200
	ds_read_b128 v[206:209], v190 offset:52224
	ds_read_b128 v[210:213], v190 offset:53248
	ds_read_b128 v[214:217], v190 offset:54272
	ds_read_b128 v[218:221], v190 offset:55296
	ds_read_b128 v[222:225], v190 offset:56320
	global_load_lds_dwordx4 v[10:11], off
	v_lshl_add_u64 v[10:11], v[12:13], 0, s[16:17]
	s_mov_b32 m0, s82
	s_addc_u32 s57, s57, 0
	global_load_lds_dwordx4 v[10:11], off
	v_lshl_add_u64 v[10:11], s[56:57], 0, v[166:167]
	s_mov_b32 m0, s83
	s_nop 0
	global_load_lds_dwordx4 v[10:11], off
	v_lshl_add_u64 v[10:11], s[56:57], 0, v[162:163]
	s_mov_b32 m0, s84
	s_nop 0
	global_load_lds_dwordx4 v[10:11], off
	v_lshl_add_u64 v[10:11], v[14:15], 0, s[16:17]
	s_mov_b32 m0, s63
	s_nop 0
	global_load_lds_dwordx4 v[10:11], off
	v_lshl_add_u64 v[10:11], v[16:17], 0, s[16:17]
	s_mov_b32 m0, s64
	s_nop 0
	global_load_lds_dwordx4 v[10:11], off
	s_waitcnt vmcnt(8)
	s_waitcnt lgkmcnt(0)
	s_setprio 1
	s_barrier
	v_mfma_f32_16x16x128_f8f6f4 v[122:125], v[18:25], v[194:201], v[122:125]
	v_mfma_f32_16x16x128_f8f6f4 v[114:117], v[26:33], v[194:201], v[114:117]
	v_mfma_f32_16x16x128_f8f6f4 v[94:97], v[18:25], v[202:209], v[94:97]
	v_mfma_f32_16x16x128_f8f6f4 v[86:89], v[26:33], v[202:209], v[86:89]
	v_mfma_f32_16x16x128_f8f6f4 v[62:65], v[18:25], v[210:217], v[62:65]
	v_mfma_f32_16x16x128_f8f6f4 v[58:61], v[26:33], v[210:217], v[58:61]
	v_mfma_f32_16x16x128_f8f6f4 v[46:49], v[18:25], v[218:225], v[46:49]
	v_mfma_f32_16x16x128_f8f6f4 v[42:45], v[26:33], v[218:225], v[42:45]
	v_mfma_f32_16x16x128_f8f6f4 v[102:105], v[2:9], v[194:201], v[102:105]
	v_mfma_f32_16x16x128_f8f6f4 v[98:101], v[178:185], v[194:201], v[98:101]
	v_mfma_f32_16x16x128_f8f6f4 v[70:73], v[2:9], v[202:209], v[70:73]
	v_mfma_f32_16x16x128_f8f6f4 v[66:69], v[178:185], v[202:209], v[66:69]
	v_mfma_f32_16x16x128_f8f6f4 v[54:57], v[2:9], v[210:217], v[54:57]
	v_mfma_f32_16x16x128_f8f6f4 v[50:53], v[178:185], v[210:217], v[50:53]
	v_mfma_f32_16x16x128_f8f6f4 v[38:41], v[2:9], v[218:225], v[38:41]
	v_mfma_f32_16x16x128_f8f6f4 v[34:37], v[178:185], v[218:225], v[34:37]
	s_setprio 0
	s_barrier
	s_add_i32 s8, s8, 2
	s_add_u32 s85, s85, 0x100
	s_addc_u32 s86, s86, 0
	s_add_u32 s10, s10, 0x100
	s_addc_u32 s11, s11, 0
	s_cmp_gt_u32 s8, 29
	s_cbranch_scc0 .LBB0_903
	s_and_b64 vcc, exec, s[30:31]
	s_cbranch_vccz .LBB0_906
	s_barrier

.LBB0_1033:
	s_ashr_i32 s49, s48, 31
	ds_read_b128 v[2:5], v188
	ds_read_b128 v[6:9], v188 offset:1024
	ds_read_b128 v[10:13], v188 offset:2048
	ds_read_b128 v[14:17], v188 offset:3072
	ds_read_b128 v[18:21], v189
	ds_read_b128 v[22:25], v189 offset:1024
	ds_read_b128 v[26:29], v189 offset:2048
	ds_read_b128 v[30:33], v189 offset:3072
	s_lshl_b64 s[8:9], s[48:49], 18
	s_add_u32 s50, s19, s8
	s_addc_u32 s51, s24, s9
	s_and_b64 s[8:9], s[4:5], exec
	s_cselect_b32 s49, s51, s59
	s_cselect_b32 s75, s50, s58
	s_ashr_i32 s47, s46, 31
	s_lshl_b64 s[8:9], s[46:47], 18
	s_add_u32 s52, s25, s8
	s_addc_u32 s53, s26, s9
	s_and_b64 s[8:9], s[4:5], exec
	s_cselect_b32 s47, s53, s57
	s_cselect_b32 s76, s52, s56
	s_add_u32 s8, s58, 0x20080
	s_addc_u32 s9, s59, 0
	s_add_i32 s77, s55, 0xc000
	v_lshl_add_u64 v[34:35], s[8:9], 0, v[168:169]
	s_mov_b32 m0, s77
	s_add_i32 s78, s55, 0xe000
	ds_read_b128 v[38:41], v190
	ds_read_b128 v[42:45], v190 offset:1024
	ds_read_b128 v[46:49], v190 offset:2048
	ds_read_b128 v[50:53], v190 offset:3072
	ds_read_b128 v[54:57], v190 offset:4096
	ds_read_b128 v[58:61], v190 offset:5120
	ds_read_b128 v[62:65], v190 offset:6144
	ds_read_b128 v[66:69], v190 offset:7168
	global_load_lds_dwordx4 v[34:35], off
	v_lshl_add_u64 v[34:35], s[8:9], 0, v[164:165]
	s_mov_b32 m0, s78
	s_nop 0
	global_load_lds_dwordx4 v[34:35], off
	s_waitcnt vmcnt(24)
	s_waitcnt lgkmcnt(0)
	s_setprio 1
	s_barrier
	s_mov_b32 s8, 0
	s_mov_b32 s10, s8
	s_mov_b32 s11, s8
	s_mov_b32 s9, s8
	v_mov_b64_e32 v[36:37], s[10:11]
	v_mov_b64_e32 v[160:161], s[10:11]
	v_mov_b64_e32 v[156:157], s[10:11]
	v_mov_b64_e32 v[144:145], s[10:11]
	v_mov_b64_e32 v[140:141], s[10:11]
	v_mov_b64_e32 v[128:129], s[10:11]
	v_mov_b64_e32 v[120:121], s[10:11]
	v_mov_b64_e32 v[92:93], s[10:11]
	v_mov_b64_e32 v[84:85], s[10:11]
	v_mov_b64_e32 v[34:35], s[8:9]
	v_mov_b64_e32 v[158:159], s[8:9]
	v_mov_b64_e32 v[154:155], s[8:9]
	v_mov_b64_e32 v[142:143], s[8:9]
	v_mov_b64_e32 v[138:139], s[8:9]
	v_mov_b64_e32 v[126:127], s[8:9]
	v_mov_b64_e32 v[118:119], s[8:9]
	v_mov_b64_e32 v[90:91], s[8:9]
	v_mov_b64_e32 v[82:83], s[8:9]
	s_waitcnt lgkmcnt(0)
	v_mfma_f32_16x16x128_f8f6f4 v[158:161], v[2:9], v[38:45], v[158:161]
	v_mfma_f32_16x16x128_f8f6f4 v[154:157], v[10:17], v[38:45], v[154:157]
	v_mfma_f32_16x16x128_f8f6f4 v[142:145], v[2:9], v[46:53], v[142:145]
	v_mfma_f32_16x16x128_f8f6f4 v[138:141], v[10:17], v[46:53], v[138:141]
	v_mfma_f32_16x16x128_f8f6f4 v[126:129], v[2:9], v[54:61], v[126:129]
	v_mfma_f32_16x16x128_f8f6f4 v[118:121], v[10:17], v[54:61], v[118:121]
	v_mfma_f32_16x16x128_f8f6f4 v[90:93], v[2:9], v[62:69], v[90:93]
	v_mfma_f32_16x16x128_f8f6f4 v[82:85], v[10:17], v[62:69], v[82:85]
	v_mov_b64_e32 v[152:153], s[10:11]
	v_mov_b64_e32 v[148:149], s[10:11]
	v_mov_b64_e32 v[136:137], s[10:11]
	v_mov_b64_e32 v[132:133], s[10:11]
	v_mov_b64_e32 v[112:113], s[10:11]
	v_mov_b64_e32 v[108:109], s[10:11]
	v_mov_b64_e32 v[80:81], s[10:11]
	v_mov_b64_e32 v[76:77], s[10:11]
	v_mov_b64_e32 v[150:151], s[8:9]
	v_mov_b64_e32 v[146:147], s[8:9]
	v_mov_b64_e32 v[134:135], s[8:9]
	v_mov_b64_e32 v[130:131], s[8:9]
	v_mov_b64_e32 v[110:111], s[8:9]
	v_mov_b64_e32 v[106:107], s[8:9]
	v_mov_b64_e32 v[78:79], s[8:9]
	v_mov_b64_e32 v[74:75], s[8:9]
	v_mfma_f32_16x16x128_f8f6f4 v[150:153], v[18:25], v[38:45], v[150:153]
	v_mfma_f32_16x16x128_f8f6f4 v[146:149], v[26:33], v[38:45], v[146:149]
	v_mfma_f32_16x16x128_f8f6f4 v[134:137], v[18:25], v[46:53], v[134:137]
	v_mfma_f32_16x16x128_f8f6f4 v[130:133], v[26:33], v[46:53], v[130:133]
	v_mfma_f32_16x16x128_f8f6f4 v[110:113], v[18:25], v[54:61], v[110:113]
	v_mfma_f32_16x16x128_f8f6f4 v[106:109], v[26:33], v[54:61], v[106:109]
	v_mfma_f32_16x16x128_f8f6f4 v[78:81], v[18:25], v[62:69], v[78:81]
	v_mfma_f32_16x16x128_f8f6f4 v[74:77], v[26:33], v[62:69], v[74:77]
	s_setprio 0
	s_barrier
	s_add_i32 s9, s68, s27
	v_lshl_add_u64 v[178:179], s[56:57], 0, v[166:167]
	s_add_i32 s79, s9, 0x2000
	v_lshl_add_u64 v[38:39], v[178:179], 0, s[30:31]
	s_mov_b32 m0, s9
	v_lshl_add_u64 v[180:181], s[56:57], 0, v[162:163]
	s_add_u32 s10, s56, 0x20100
	ds_read_b128 v[50:53], v190 offset:16384
	ds_read_b128 v[54:57], v190 offset:17408
	ds_read_b128 v[192:195], v190 offset:18432
	ds_read_b128 v[196:199], v190 offset:19456
	ds_read_b128 v[200:203], v190 offset:20480
	ds_read_b128 v[204:207], v190 offset:21504
	ds_read_b128 v[208:211], v190 offset:22528
	ds_read_b128 v[212:215], v190 offset:23552
	global_load_lds_dwordx4 v[38:39], off
	v_lshl_add_u64 v[38:39], v[180:181], 0, s[30:31]
	s_mov_b32 m0, s79
	s_addc_u32 s11, s57, 0
	s_add_i32 s80, s69, s27
	global_load_lds_dwordx4 v[38:39], off
	v_lshl_add_u64 v[38:39], s[10:11], 0, v[166:167]
	s_mov_b32 m0, s80
	s_add_i32 s81, s80, 0x2000
	global_load_lds_dwordx4 v[38:39], off
	v_lshl_add_u64 v[38:39], s[10:11], 0, v[162:163]
	s_mov_b32 m0, s81
	v_lshl_add_u64 v[182:183], s[58:59], 0, v[168:169]
	global_load_lds_dwordx4 v[38:39], off
	v_lshl_add_u64 v[38:39], v[182:183], 0, s[30:31]
	s_mov_b32 m0, s55
	v_lshl_add_u64 v[184:185], s[58:59], 0, v[164:165]
	global_load_lds_dwordx4 v[38:39], off
	v_lshl_add_u64 v[38:39], v[184:185], 0, s[30:31]
	s_mov_b32 m0, s61
	s_nop 0
	global_load_lds_dwordx4 v[38:39], off
	s_waitcnt vmcnt(24)
	s_waitcnt lgkmcnt(0)
	s_setprio 1
	s_barrier
	v_mov_b64_e32 v[124:125], v[36:37]
	v_mov_b64_e32 v[116:117], v[36:37]
	v_mov_b64_e32 v[96:97], v[36:37]
	v_mov_b64_e32 v[88:89], v[36:37]
	v_mov_b64_e32 v[64:65], v[36:37]
	v_mov_b64_e32 v[60:61], v[36:37]
	v_mov_b64_e32 v[48:49], v[36:37]
	v_mov_b64_e32 v[44:45], v[36:37]
	v_mov_b64_e32 v[122:123], v[34:35]
	v_mov_b64_e32 v[114:115], v[34:35]
	v_mov_b64_e32 v[94:95], v[34:35]
	v_mov_b64_e32 v[86:87], v[34:35]
	v_mov_b64_e32 v[62:63], v[34:35]
	v_mov_b64_e32 v[58:59], v[34:35]
	v_mov_b64_e32 v[46:47], v[34:35]
	v_mov_b64_e32 v[42:43], v[34:35]
	s_waitcnt lgkmcnt(0)
	v_mfma_f32_16x16x128_f8f6f4 v[122:125], v[2:9], v[50:57], v[122:125]
	v_mfma_f32_16x16x128_f8f6f4 v[114:117], v[10:17], v[50:57], v[114:117]
	v_mfma_f32_16x16x128_f8f6f4 v[94:97], v[2:9], v[192:199], v[94:97]
	v_mfma_f32_16x16x128_f8f6f4 v[86:89], v[10:17], v[192:199], v[86:89]
	v_mfma_f32_16x16x128_f8f6f4 v[62:65], v[2:9], v[200:207], v[62:65]
	v_mfma_f32_16x16x128_f8f6f4 v[58:61], v[10:17], v[200:207], v[58:61]
	v_mfma_f32_16x16x128_f8f6f4 v[46:49], v[2:9], v[208:215], v[46:49]
	v_mfma_f32_16x16x128_f8f6f4 v[42:45], v[10:17], v[208:215], v[42:45]
	v_mov_b64_e32 v[104:105], v[36:37]
	v_mov_b64_e32 v[100:101], v[36:37]
	v_mov_b64_e32 v[102:103], v[34:35]
	v_mov_b64_e32 v[98:99], v[34:35]
	v_mfma_f32_16x16x128_f8f6f4 v[102:105], v[18:25], v[50:57], v[102:105]
	v_mfma_f32_16x16x128_f8f6f4 v[98:101], v[26:33], v[50:57], v[98:101]
	v_mov_b64_e32 v[72:73], v[36:37]
	v_mov_b64_e32 v[68:69], v[36:37]
	v_mov_b64_e32 v[56:57], v[36:37]
	v_mov_b64_e32 v[52:53], v[36:37]
	v_mov_b64_e32 v[40:41], v[36:37]
	v_mov_b64_e32 v[70:71], v[34:35]
	v_mov_b64_e32 v[66:67], v[34:35]
	v_mov_b64_e32 v[54:55], v[34:35]
	v_mov_b64_e32 v[50:51], v[34:35]
	v_mov_b64_e32 v[38:39], v[34:35]
	v_mfma_f32_16x16x128_f8f6f4 v[70:73], v[18:25], v[192:199], v[70:73]
	v_mfma_f32_16x16x128_f8f6f4 v[66:69], v[26:33], v[192:199], v[66:69]
	v_mfma_f32_16x16x128_f8f6f4 v[54:57], v[18:25], v[200:207], v[54:57]
	v_mfma_f32_16x16x128_f8f6f4 v[50:53], v[26:33], v[200:207], v[50:53]
	v_mfma_f32_16x16x128_f8f6f4 v[38:41], v[18:25], v[208:215], v[38:41]
	v_mfma_f32_16x16x128_f8f6f4 v[34:37], v[26:33], v[208:215], v[34:37]
	s_setprio 0
	s_barrier
	s_add_i32 s82, 0, 0x18000
	s_add_i32 s84, 0, 0x1c000
	v_add_u32_e32 v191, s82, v186
	v_add_u32_e32 v192, s84, v186
	ds_read_b128 v[18:21], v191
	ds_read_b128 v[22:25], v191 offset:1024
	ds_read_b128 v[26:29], v191 offset:2048
	ds_read_b128 v[30:33], v191 offset:3072
	ds_read_b128 v[2:5], v192
	ds_read_b128 v[6:9], v192 offset:1024
	ds_read_b128 v[10:13], v192 offset:2048
	ds_read_b128 v[14:17], v192 offset:3072
	s_add_u32 s10, s58, 0x20100
	s_addc_u32 s11, s59, 0
	s_mov_b32 m0, s62
	v_lshl_add_u64 v[226:227], s[10:11], 0, v[168:169]
	ds_read_b128 v[194:197], v190 offset:32768
	ds_read_b128 v[198:201], v190 offset:33792
	ds_read_b128 v[202:205], v190 offset:34816
	ds_read_b128 v[206:209], v190 offset:35840
	ds_read_b128 v[210:213], v190 offset:36864
	ds_read_b128 v[214:217], v190 offset:37888
	ds_read_b128 v[218:221], v190 offset:38912
	ds_read_b128 v[222:225], v190 offset:39936
	global_load_lds_dwordx4 v[226:227], off
	v_lshl_add_u64 v[226:227], s[10:11], 0, v[164:165]
	s_mov_b32 m0, s63
	s_nop 0
	global_load_lds_dwordx4 v[226:227], off
	s_waitcnt vmcnt(8)
	s_waitcnt lgkmcnt(0)
	s_setprio 1
	s_barrier
	v_mfma_f32_16x16x128_f8f6f4 v[158:161], v[18:25], v[194:201], v[158:161]
	v_mfma_f32_16x16x128_f8f6f4 v[154:157], v[26:33], v[194:201], v[154:157]
	v_mfma_f32_16x16x128_f8f6f4 v[142:145], v[18:25], v[202:209], v[142:145]
	v_mfma_f32_16x16x128_f8f6f4 v[138:141], v[26:33], v[202:209], v[138:141]
	v_mfma_f32_16x16x128_f8f6f4 v[126:129], v[18:25], v[210:217], v[126:129]
	v_mfma_f32_16x16x128_f8f6f4 v[118:121], v[26:33], v[210:217], v[118:121]
	v_mfma_f32_16x16x128_f8f6f4 v[90:93], v[18:25], v[218:225], v[90:93]
	v_mfma_f32_16x16x128_f8f6f4 v[82:85], v[26:33], v[218:225], v[82:85]
	v_mfma_f32_16x16x128_f8f6f4 v[150:153], v[2:9], v[194:201], v[150:153]
	v_mfma_f32_16x16x128_f8f6f4 v[146:149], v[10:17], v[194:201], v[146:149]
	v_mfma_f32_16x16x128_f8f6f4 v[134:137], v[2:9], v[202:209], v[134:137]
	v_mfma_f32_16x16x128_f8f6f4 v[130:133], v[10:17], v[202:209], v[130:133]
	v_mfma_f32_16x16x128_f8f6f4 v[110:113], v[2:9], v[210:217], v[110:113]
	v_mfma_f32_16x16x128_f8f6f4 v[106:109], v[10:17], v[210:217], v[106:109]
	v_mfma_f32_16x16x128_f8f6f4 v[78:81], v[2:9], v[218:225], v[78:81]
	v_mfma_f32_16x16x128_f8f6f4 v[74:77], v[10:17], v[218:225], v[74:77]
	s_setprio 0
	s_barrier
	s_add_i32 s82, s82, s27
	s_add_i32 s83, s82, 0x2000
	v_lshl_add_u64 v[178:179], v[178:179], 0, s[34:35]
	s_mov_b32 m0, s82
	s_add_u32 s10, s56, 0x20180
	ds_read_b128 v[194:197], v190 offset:49152
	ds_read_b128 v[198:201], v190 offset:50176
	ds_read_b128 v[202:205], v190 offset:51200
	ds_read_b128 v[206:209], v190 offset:52224
	ds_read_b128 v[210:213], v190 offset:53248
	ds_read_b128 v[214:217], v190 offset:54272
	ds_read_b128 v[218:221], v190 offset:55296
	ds_read_b128 v[222:225], v190 offset:56320
	global_load_lds_dwordx4 v[178:179], off
	v_lshl_add_u64 v[178:179], v[180:181], 0, s[34:35]
	s_mov_b32 m0, s83
	s_addc_u32 s11, s57, 0
	s_add_i32 s84, s84, s27
	global_load_lds_dwordx4 v[178:179], off
	v_lshl_add_u64 v[178:179], s[10:11], 0, v[166:167]
	s_mov_b32 m0, s84
	s_add_i32 s85, s84, 0x2000
	global_load_lds_dwordx4 v[178:179], off
	v_lshl_add_u64 v[178:179], s[10:11], 0, v[162:163]
	s_mov_b32 m0, s85
	s_nop 0
	global_load_lds_dwordx4 v[178:179], off
	v_lshl_add_u64 v[178:179], v[182:183], 0, s[34:35]
	s_mov_b32 m0, s64
	s_nop 0
	global_load_lds_dwordx4 v[178:179], off
	v_lshl_add_u64 v[178:179], v[184:185], 0, s[34:35]
	s_mov_b32 m0, s65
	s_nop 0
	global_load_lds_dwordx4 v[178:179], off
	s_waitcnt vmcnt(8)
	s_waitcnt lgkmcnt(0)
	s_setprio 1
	s_barrier
	v_mfma_f32_16x16x128_f8f6f4 v[122:125], v[18:25], v[194:201], v[122:125]
	v_mfma_f32_16x16x128_f8f6f4 v[114:117], v[26:33], v[194:201], v[114:117]
	v_mfma_f32_16x16x128_f8f6f4 v[94:97], v[18:25], v[202:209], v[94:97]
	v_mfma_f32_16x16x128_f8f6f4 v[86:89], v[26:33], v[202:209], v[86:89]
	v_mfma_f32_16x16x128_f8f6f4 v[62:65], v[18:25], v[210:217], v[62:65]
	v_mfma_f32_16x16x128_f8f6f4 v[58:61], v[26:33], v[210:217], v[58:61]
	v_mfma_f32_16x16x128_f8f6f4 v[46:49], v[18:25], v[218:225], v[46:49]
	v_mfma_f32_16x16x128_f8f6f4 v[42:45], v[26:33], v[218:225], v[42:45]
	v_mfma_f32_16x16x128_f8f6f4 v[102:105], v[2:9], v[194:201], v[102:105]
	v_mfma_f32_16x16x128_f8f6f4 v[98:101], v[10:17], v[194:201], v[98:101]
	v_mfma_f32_16x16x128_f8f6f4 v[70:73], v[2:9], v[202:209], v[70:73]
	v_mfma_f32_16x16x128_f8f6f4 v[66:69], v[10:17], v[202:209], v[66:69]
	v_mfma_f32_16x16x128_f8f6f4 v[54:57], v[2:9], v[210:217], v[54:57]
	v_mfma_f32_16x16x128_f8f6f4 v[50:53], v[10:17], v[210:217], v[50:53]
	v_mfma_f32_16x16x128_f8f6f4 v[38:41], v[2:9], v[218:225], v[38:41]
	v_mfma_f32_16x16x128_f8f6f4 v[34:37], v[10:17], v[218:225], v[34:37]
	s_setprio 0
	s_barrier
	s_add_u32 s86, s56, 0x200
	s_addc_u32 s87, s57, 0
	s_add_u32 s10, s58, 0x20180
	s_addc_u32 s11, s59, 0
.LBB0_1034:
	ds_read_b128 v[2:5], v188
	ds_read_b128 v[6:9], v188 offset:1024
	ds_read_b128 v[18:21], v188 offset:2048
	ds_read_b128 v[22:25], v188 offset:3072
	ds_read_b128 v[26:29], v189
	ds_read_b128 v[30:33], v189 offset:1024
	ds_read_b128 v[178:181], v189 offset:2048
	ds_read_b128 v[182:185], v189 offset:3072
	s_add_u32 s56, s10, 0xfffe0080
	s_addc_u32 s57, s11, -1
	s_cmp_eq_u32 s8, 4
	s_cselect_b32 s59, s49, s57
	s_cselect_b32 s58, s75, s56
	s_cselect_b32 s57, s47, s87
	s_cselect_b32 s56, s76, s86
	s_mov_b32 m0, s77
	v_lshl_add_u64 v[218:219], s[10:11], 0, v[172:173]
	ds_read_b128 v[10:13], v190
	ds_read_b128 v[14:17], v190 offset:1024
	ds_read_b128 v[194:197], v190 offset:2048
	ds_read_b128 v[198:201], v190 offset:3072
	ds_read_b128 v[202:205], v190 offset:4096
	ds_read_b128 v[206:209], v190 offset:5120
	ds_read_b128 v[210:213], v190 offset:6144
	ds_read_b128 v[214:217], v190 offset:7168
	global_load_lds_dwordx4 v[218:219], off
	v_lshl_add_u64 v[218:219], s[10:11], 0, v[170:171]
	s_mov_b32 m0, s78
	s_nop 0
	global_load_lds_dwordx4 v[218:219], off
	s_waitcnt vmcnt(8)
	s_waitcnt lgkmcnt(0)
	s_setprio 1
	s_barrier
	v_mfma_f32_16x16x128_f8f6f4 v[158:161], v[2:9], v[10:17], v[158:161]
	v_mfma_f32_16x16x128_f8f6f4 v[154:157], v[18:25], v[10:17], v[154:157]
	v_mfma_f32_16x16x128_f8f6f4 v[142:145], v[2:9], v[194:201], v[142:145]
	v_mfma_f32_16x16x128_f8f6f4 v[138:141], v[18:25], v[194:201], v[138:141]
	v_mfma_f32_16x16x128_f8f6f4 v[126:129], v[2:9], v[202:209], v[126:129]
	v_mfma_f32_16x16x128_f8f6f4 v[118:121], v[18:25], v[202:209], v[118:121]
	v_mfma_f32_16x16x128_f8f6f4 v[90:93], v[2:9], v[210:217], v[90:93]
	v_mfma_f32_16x16x128_f8f6f4 v[82:85], v[18:25], v[210:217], v[82:85]
	v_mfma_f32_16x16x128_f8f6f4 v[150:153], v[26:33], v[10:17], v[150:153]
	v_mfma_f32_16x16x128_f8f6f4 v[146:149], v[178:185], v[10:17], v[146:149]
	v_mfma_f32_16x16x128_f8f6f4 v[134:137], v[26:33], v[194:201], v[134:137]
	v_mfma_f32_16x16x128_f8f6f4 v[130:133], v[178:185], v[194:201], v[130:133]
	v_mfma_f32_16x16x128_f8f6f4 v[110:113], v[26:33], v[202:209], v[110:113]
	v_mfma_f32_16x16x128_f8f6f4 v[106:109], v[178:185], v[202:209], v[106:109]
	v_mfma_f32_16x16x128_f8f6f4 v[78:81], v[26:33], v[210:217], v[78:81]
	v_mfma_f32_16x16x128_f8f6f4 v[74:77], v[178:185], v[210:217], v[74:77]
	s_setprio 0
	s_barrier
	s_mov_b32 m0, s9
	v_lshl_add_u64 v[10:11], s[56:57], 0, v[166:167]
	s_add_u32 s88, s56, 0x20000
	ds_read_b128 v[194:197], v190 offset:16384
	ds_read_b128 v[198:201], v190 offset:17408
	ds_read_b128 v[202:205], v190 offset:18432
	ds_read_b128 v[206:209], v190 offset:19456
	ds_read_b128 v[210:213], v190 offset:20480
	ds_read_b128 v[214:217], v190 offset:21504
	ds_read_b128 v[218:221], v190 offset:22528
	ds_read_b128 v[222:225], v190 offset:23552
	global_load_lds_dwordx4 v[10:11], off
	v_lshl_add_u64 v[12:13], s[56:57], 0, v[162:163]
	s_mov_b32 m0, s79
	s_addc_u32 s89, s57, 0
	global_load_lds_dwordx4 v[12:13], off
	v_lshl_add_u64 v[14:15], s[88:89], 0, v[166:167]
	s_mov_b32 m0, s80
	v_lshl_add_u64 v[16:17], s[58:59], 0, v[164:165]
	global_load_lds_dwordx4 v[14:15], off
	v_lshl_add_u64 v[14:15], s[88:89], 0, v[162:163]
	s_mov_b32 m0, s81
	s_nop 0
	global_load_lds_dwordx4 v[14:15], off
	v_lshl_add_u64 v[14:15], s[58:59], 0, v[168:169]
	s_mov_b32 m0, s55
	s_nop 0
	global_load_lds_dwordx4 v[14:15], off
	s_mov_b32 m0, s61
	s_nop 0
	global_load_lds_dwordx4 v[16:17], off
	s_waitcnt vmcnt(8)
	s_waitcnt lgkmcnt(0)
	s_setprio 1
	s_barrier
	v_mfma_f32_16x16x128_f8f6f4 v[122:125], v[2:9], v[194:201], v[122:125]
	v_mfma_f32_16x16x128_f8f6f4 v[114:117], v[18:25], v[194:201], v[114:117]
	v_mfma_f32_16x16x128_f8f6f4 v[94:97], v[2:9], v[202:209], v[94:97]
	v_mfma_f32_16x16x128_f8f6f4 v[86:89], v[18:25], v[202:209], v[86:89]
	v_mfma_f32_16x16x128_f8f6f4 v[62:65], v[2:9], v[210:217], v[62:65]
	v_mfma_f32_16x16x128_f8f6f4 v[58:61], v[18:25], v[210:217], v[58:61]
	v_mfma_f32_16x16x128_f8f6f4 v[46:49], v[2:9], v[218:225], v[46:49]
	v_mfma_f32_16x16x128_f8f6f4 v[42:45], v[18:25], v[218:225], v[42:45]
	v_mfma_f32_16x16x128_f8f6f4 v[102:105], v[26:33], v[194:201], v[102:105]
	v_mfma_f32_16x16x128_f8f6f4 v[98:101], v[178:185], v[194:201], v[98:101]
	v_mfma_f32_16x16x128_f8f6f4 v[70:73], v[26:33], v[202:209], v[70:73]
	v_mfma_f32_16x16x128_f8f6f4 v[66:69], v[178:185], v[202:209], v[66:69]
	v_mfma_f32_16x16x128_f8f6f4 v[54:57], v[26:33], v[210:217], v[54:57]
	v_mfma_f32_16x16x128_f8f6f4 v[50:53], v[178:185], v[210:217], v[50:53]
	v_mfma_f32_16x16x128_f8f6f4 v[38:41], v[26:33], v[218:225], v[38:41]
	v_mfma_f32_16x16x128_f8f6f4 v[34:37], v[178:185], v[218:225], v[34:37]
	s_setprio 0
	s_barrier
	ds_read_b128 v[18:21], v191
	ds_read_b128 v[22:25], v191 offset:1024
	ds_read_b128 v[26:29], v191 offset:2048
	ds_read_b128 v[30:33], v191 offset:3072
	ds_read_b128 v[2:5], v192
	ds_read_b128 v[6:9], v192 offset:1024
	ds_read_b128 v[178:181], v192 offset:2048
	ds_read_b128 v[182:185], v192 offset:3072
	s_add_u32 s58, s58, 0x20000
	s_addc_u32 s59, s59, 0
	s_mov_b32 m0, s62
	v_lshl_add_u64 v[226:227], s[58:59], 0, v[168:169]
	ds_read_b128 v[194:197], v190 offset:32768
	ds_read_b128 v[198:201], v190 offset:33792
	ds_read_b128 v[202:205], v190 offset:34816
	ds_read_b128 v[206:209], v190 offset:35840
	ds_read_b128 v[210:213], v190 offset:36864
	ds_read_b128 v[214:217], v190 offset:37888
	ds_read_b128 v[218:221], v190 offset:38912
	ds_read_b128 v[222:225], v190 offset:39936
	global_load_lds_dwordx4 v[226:227], off
	v_lshl_add_u64 v[226:227], s[58:59], 0, v[164:165]
	s_mov_b32 m0, s63
	s_nop 0
	global_load_lds_dwordx4 v[226:227], off
	s_waitcnt vmcnt(8)
	s_waitcnt lgkmcnt(0)
	s_setprio 1
	s_barrier
	v_mfma_f32_16x16x128_f8f6f4 v[158:161], v[18:25], v[194:201], v[158:161]
	v_mfma_f32_16x16x128_f8f6f4 v[154:157], v[26:33], v[194:201], v[154:157]
	v_mfma_f32_16x16x128_f8f6f4 v[142:145], v[18:25], v[202:209], v[142:145]
	v_mfma_f32_16x16x128_f8f6f4 v[138:141], v[26:33], v[202:209], v[138:141]
	v_mfma_f32_16x16x128_f8f6f4 v[126:129], v[18:25], v[210:217], v[126:129]
	v_mfma_f32_16x16x128_f8f6f4 v[118:121], v[26:33], v[210:217], v[118:121]
	v_mfma_f32_16x16x128_f8f6f4 v[90:93], v[18:25], v[218:225], v[90:93]
	v_mfma_f32_16x16x128_f8f6f4 v[82:85], v[26:33], v[218:225], v[82:85]
	v_mfma_f32_16x16x128_f8f6f4 v[150:153], v[2:9], v[194:201], v[150:153]
	v_mfma_f32_16x16x128_f8f6f4 v[146:149], v[178:185], v[194:201], v[146:149]
	v_mfma_f32_16x16x128_f8f6f4 v[134:137], v[2:9], v[202:209], v[134:137]
	v_mfma_f32_16x16x128_f8f6f4 v[130:133], v[178:185], v[202:209], v[130:133]
	v_mfma_f32_16x16x128_f8f6f4 v[110:113], v[2:9], v[210:217], v[110:113]
	v_mfma_f32_16x16x128_f8f6f4 v[106:109], v[178:185], v[210:217], v[106:109]
	v_mfma_f32_16x16x128_f8f6f4 v[78:81], v[2:9], v[218:225], v[78:81]
	v_mfma_f32_16x16x128_f8f6f4 v[74:77], v[178:185], v[218:225], v[74:77]
	s_setprio 0
	s_barrier
	s_mov_b32 m0, s82
	v_lshl_add_u64 v[10:11], v[10:11], 0, s[14:15]
	s_add_u32 s56, s56, 0x20080
	ds_read_b128 v[194:197], v190 offset:49152
	ds_read_b128 v[198:201], v190 offset:50176
	ds_read_b128 v[202:205], v190 offset:51200
	ds_read_b128 v[206:209], v190 offset:52224
	ds_read_b128 v[210:213], v190 offset:53248
	ds_read_b128 v[214:217], v190 offset:54272
	ds_read_b128 v[218:221], v190 offset:55296
	ds_read_b128 v[222:225], v190 offset:56320
	global_load_lds_dwordx4 v[10:11], off
	v_lshl_add_u64 v[10:11], v[12:13], 0, s[14:15]
	s_mov_b32 m0, s83
	s_addc_u32 s57, s57, 0
	global_load_lds_dwordx4 v[10:11], off
	v_lshl_add_u64 v[10:11], s[56:57], 0, v[166:167]
	s_mov_b32 m0, s84
	s_nop 0
	global_load_lds_dwordx4 v[10:11], off
	v_lshl_add_u64 v[10:11], s[56:57], 0, v[162:163]
	s_mov_b32 m0, s85
	s_nop 0
	global_load_lds_dwordx4 v[10:11], off
	v_lshl_add_u64 v[10:11], v[14:15], 0, s[14:15]
	s_mov_b32 m0, s64
	s_nop 0
	global_load_lds_dwordx4 v[10:11], off
	v_lshl_add_u64 v[10:11], v[16:17], 0, s[14:15]
	s_mov_b32 m0, s65
	s_nop 0
	global_load_lds_dwordx4 v[10:11], off
	s_waitcnt vmcnt(8)
	s_waitcnt lgkmcnt(0)
	s_setprio 1
	s_barrier
	v_mfma_f32_16x16x128_f8f6f4 v[122:125], v[18:25], v[194:201], v[122:125]
	v_mfma_f32_16x16x128_f8f6f4 v[114:117], v[26:33], v[194:201], v[114:117]
	v_mfma_f32_16x16x128_f8f6f4 v[94:97], v[18:25], v[202:209], v[94:97]
	v_mfma_f32_16x16x128_f8f6f4 v[86:89], v[26:33], v[202:209], v[86:89]
	v_mfma_f32_16x16x128_f8f6f4 v[62:65], v[18:25], v[210:217], v[62:65]
	v_mfma_f32_16x16x128_f8f6f4 v[58:61], v[26:33], v[210:217], v[58:61]
	v_mfma_f32_16x16x128_f8f6f4 v[46:49], v[18:25], v[218:225], v[46:49]
	v_mfma_f32_16x16x128_f8f6f4 v[42:45], v[26:33], v[218:225], v[42:45]
	v_mfma_f32_16x16x128_f8f6f4 v[102:105], v[2:9], v[194:201], v[102:105]
	v_mfma_f32_16x16x128_f8f6f4 v[98:101], v[178:185], v[194:201], v[98:101]
	v_mfma_f32_16x16x128_f8f6f4 v[70:73], v[2:9], v[202:209], v[70:73]
	v_mfma_f32_16x16x128_f8f6f4 v[66:69], v[178:185], v[202:209], v[66:69]
	v_mfma_f32_16x16x128_f8f6f4 v[54:57], v[2:9], v[210:217], v[54:57]
	v_mfma_f32_16x16x128_f8f6f4 v[50:53], v[178:185], v[210:217], v[50:53]
	v_mfma_f32_16x16x128_f8f6f4 v[38:41], v[2:9], v[218:225], v[38:41]
	v_mfma_f32_16x16x128_f8f6f4 v[34:37], v[178:185], v[218:225], v[34:37]
	s_setprio 0
	s_barrier
	s_add_i32 s8, s8, 2
	s_add_u32 s86, s86, 0x100
	s_addc_u32 s87, s87, 0
	s_add_u32 s10, s10, 0x100
	s_addc_u32 s11, s11, 0
	s_cmp_gt_u32 s8, 5
	s_cbranch_scc0 .LBB0_1034
	s_and_b64 vcc, exec, s[16:17]
	s_cbranch_vccz .LBB0_1037
	s_barrier

.LBB0_1173:
	s_ashr_i32 s43, s42, 31
	ds_read_b128 v[2:5], v150
	ds_read_b128 v[6:9], v150 offset:1024
	ds_read_b128 v[10:13], v150 offset:2048
	ds_read_b128 v[14:17], v150 offset:3072
	ds_read_b128 v[18:21], v151
	ds_read_b128 v[22:25], v151 offset:1024
	ds_read_b128 v[26:29], v151 offset:2048
	ds_read_b128 v[30:33], v151 offset:3072
	s_lshl_b64 s[44:45], s[42:43], 21
	s_add_u32 s44, s24, s44
	s_addc_u32 s45, s25, s45
	s_and_b64 s[46:47], s[4:5], exec
	s_cselect_b32 s43, s45, s53
	s_cselect_b32 s71, s44, s52
	s_ashr_i32 s41, s40, 31
	s_lshl_b64 s[46:47], s[40:41], 21
	s_add_u32 s46, s26, s46
	s_addc_u32 s47, s27, s47
	s_and_b64 s[54:55], s[4:5], exec
	s_cselect_b32 s41, s47, s51
	s_cselect_b32 s72, s46, s50
	s_add_u32 s54, s52, 0x100080
	s_addc_u32 s55, s53, 0
	s_add_i32 s73, s49, 0xc000
	v_lshl_add_u64 v[66:67], s[54:55], 0, v[130:131]
	s_mov_b32 m0, s73
	s_add_i32 s74, s49, 0xe000
	ds_read_b128 v[34:37], v152
	ds_read_b128 v[38:41], v152 offset:1024
	ds_read_b128 v[42:45], v152 offset:2048
	ds_read_b128 v[46:49], v152 offset:3072
	ds_read_b128 v[50:53], v152 offset:4096
	ds_read_b128 v[54:57], v152 offset:5120
	ds_read_b128 v[58:61], v152 offset:6144
	ds_read_b128 v[62:65], v152 offset:7168
	global_load_lds_dwordx4 v[66:67], off
	v_lshl_add_u64 v[66:67], s[54:55], 0, v[134:135]
	s_mov_b32 m0, s74
	s_nop 0
	global_load_lds_dwordx4 v[66:67], off
	s_waitcnt vmcnt(24)
	s_waitcnt lgkmcnt(0)
	s_setprio 1
	s_barrier
	v_mfma_f32_16x16x32_bf16 v[90:93], v[2:5], v[58:61], 0
	v_mfma_f32_16x16x32_bf16 v[66:69], v[2:5], v[34:37], 0
	v_mfma_f32_16x16x32_bf16 v[70:73], v[10:13], v[34:37], 0
	v_mfma_f32_16x16x32_bf16 v[74:77], v[2:5], v[42:45], 0
	v_mfma_f32_16x16x32_bf16 v[78:81], v[10:13], v[42:45], 0
	v_mfma_f32_16x16x32_bf16 v[82:85], v[2:5], v[50:53], 0
	v_mfma_f32_16x16x32_bf16 v[86:89], v[10:13], v[50:53], 0
	v_mfma_f32_16x16x32_bf16 v[94:97], v[6:9], v[62:65], v[90:93]
	v_mfma_f32_16x16x32_bf16 v[90:93], v[10:13], v[58:61], 0
	v_mfma_f32_16x16x32_bf16 v[66:69], v[6:9], v[38:41], v[66:69]
	v_mfma_f32_16x16x32_bf16 v[126:129], v[14:17], v[38:41], v[70:73]
	v_mfma_f32_16x16x32_bf16 v[74:77], v[6:9], v[46:49], v[74:77]
	v_mfma_f32_16x16x32_bf16 v[78:81], v[14:17], v[46:49], v[78:81]
	v_mfma_f32_16x16x32_bf16 v[82:85], v[6:9], v[54:57], v[82:85]
	v_mfma_f32_16x16x32_bf16 v[86:89], v[14:17], v[54:57], v[86:89]
	v_mfma_f32_16x16x32_bf16 v[102:105], v[14:17], v[62:65], v[90:93]
	v_mfma_f32_16x16x32_bf16 v[90:93], v[18:21], v[34:37], 0
	v_mfma_f32_16x16x32_bf16 v[34:37], v[26:29], v[34:37], 0
	v_mfma_f32_16x16x32_bf16 v[110:113], v[22:25], v[38:41], v[90:93]
	v_mfma_f32_16x16x32_bf16 v[34:37], v[30:33], v[38:41], v[34:37]
	v_mfma_f32_16x16x32_bf16 v[38:41], v[18:21], v[42:45], 0
	v_mfma_f32_16x16x32_bf16 v[42:45], v[26:29], v[42:45], 0
	v_mfma_f32_16x16x32_bf16 v[38:41], v[22:25], v[46:49], v[38:41]
	v_mfma_f32_16x16x32_bf16 v[42:45], v[30:33], v[46:49], v[42:45]
	v_mfma_f32_16x16x32_bf16 v[46:49], v[18:21], v[50:53], 0
	v_mfma_f32_16x16x32_bf16 v[50:53], v[26:29], v[50:53], 0
	v_mfma_f32_16x16x32_bf16 v[46:49], v[22:25], v[54:57], v[46:49]
	v_mfma_f32_16x16x32_bf16 v[54:57], v[30:33], v[54:57], v[50:53]
	v_mfma_f32_16x16x32_bf16 v[50:53], v[18:21], v[58:61], 0
	v_mfma_f32_16x16x32_bf16 v[154:157], v[22:25], v[62:65], v[50:53]
	v_mfma_f32_16x16x32_bf16 v[50:53], v[26:29], v[58:61], 0
	v_mfma_f32_16x16x32_bf16 v[158:161], v[30:33], v[62:65], v[50:53]
	s_setprio 0
	s_barrier
	s_add_i32 s75, s64, s56
	v_lshl_add_u64 v[142:143], s[50:51], 0, v[132:133]
	s_add_i32 s76, s75, 0x2000
	v_lshl_add_u64 v[122:123], v[142:143], 0, s[14:15]
	s_mov_b32 m0, s75
	v_lshl_add_u64 v[144:145], s[50:51], 0, v[136:137]
	s_add_u32 s54, s50, 0x100100
	ds_read_b128 v[50:53], v152 offset:16384
	ds_read_b128 v[58:61], v152 offset:17408
	ds_read_b128 v[62:65], v152 offset:18432
	ds_read_b128 v[90:93], v152 offset:19456
	ds_read_b128 v[98:101], v152 offset:20480
	ds_read_b128 v[106:109], v152 offset:21504
	ds_read_b128 v[114:117], v152 offset:22528
	ds_read_b128 v[118:121], v152 offset:23552
	global_load_lds_dwordx4 v[122:123], off
	v_lshl_add_u64 v[122:123], v[144:145], 0, s[14:15]
	s_mov_b32 m0, s76
	s_addc_u32 s55, s51, 0
	s_add_i32 s77, s65, s56
	global_load_lds_dwordx4 v[122:123], off
	v_lshl_add_u64 v[122:123], s[54:55], 0, v[132:133]
	s_mov_b32 m0, s77
	s_add_i32 s78, s77, 0x2000
	global_load_lds_dwordx4 v[122:123], off
	v_lshl_add_u64 v[122:123], s[54:55], 0, v[136:137]
	s_mov_b32 m0, s78
	v_lshl_add_u64 v[148:149], s[52:53], 0, v[130:131]
	global_load_lds_dwordx4 v[122:123], off
	v_lshl_add_u64 v[122:123], v[148:149], 0, s[14:15]
	s_mov_b32 m0, s49
	v_lshl_add_u64 v[70:71], s[52:53], 0, v[134:135]
	global_load_lds_dwordx4 v[122:123], off
	v_lshl_add_u64 v[72:73], v[70:71], 0, s[14:15]
	s_mov_b32 m0, s57
	s_nop 0
	global_load_lds_dwordx4 v[72:73], off
	s_waitcnt vmcnt(24)
	s_waitcnt lgkmcnt(0)
	s_setprio 1
	s_barrier
	v_mfma_f32_16x16x32_bf16 v[122:125], v[2:5], v[50:53], 0
	v_mfma_f32_16x16x32_bf16 v[162:165], v[6:9], v[58:61], v[122:125]
	v_mfma_f32_16x16x32_bf16 v[122:125], v[10:13], v[50:53], 0
	v_mfma_f32_16x16x32_bf16 v[166:169], v[14:17], v[58:61], v[122:125]
	v_mfma_f32_16x16x32_bf16 v[122:125], v[2:5], v[62:65], 0
	v_mfma_f32_16x16x32_bf16 v[170:173], v[6:9], v[90:93], v[122:125]
	v_mfma_f32_16x16x32_bf16 v[122:125], v[10:13], v[62:65], 0
	v_mfma_f32_16x16x32_bf16 v[174:177], v[14:17], v[90:93], v[122:125]
	v_mfma_f32_16x16x32_bf16 v[122:125], v[2:5], v[98:101], 0
	v_mfma_f32_16x16x32_bf16 v[2:5], v[2:5], v[114:117], 0
	v_mfma_f32_16x16x32_bf16 v[178:181], v[6:9], v[106:109], v[122:125]
	v_mfma_f32_16x16x32_bf16 v[2:5], v[6:9], v[118:121], v[2:5]
	v_mfma_f32_16x16x32_bf16 v[6:9], v[10:13], v[114:117], 0
	v_mfma_f32_16x16x32_bf16 v[122:125], v[10:13], v[98:101], 0
	v_mfma_f32_16x16x32_bf16 v[6:9], v[14:17], v[118:121], v[6:9]
	v_mfma_f32_16x16x32_bf16 v[182:185], v[14:17], v[106:109], v[122:125]
	v_mfma_f32_16x16x32_bf16 v[14:17], v[26:29], v[50:53], 0
	v_mfma_f32_16x16x32_bf16 v[186:189], v[30:33], v[58:61], v[14:17]
	v_mfma_f32_16x16x32_bf16 v[14:17], v[18:21], v[62:65], 0
	v_mfma_f32_16x16x32_bf16 v[190:193], v[22:25], v[90:93], v[14:17]
	v_mfma_f32_16x16x32_bf16 v[14:17], v[26:29], v[62:65], 0
	v_mfma_f32_16x16x32_bf16 v[194:197], v[30:33], v[90:93], v[14:17]
	v_mfma_f32_16x16x32_bf16 v[14:17], v[18:21], v[98:101], 0
	v_mfma_f32_16x16x32_bf16 v[198:201], v[22:25], v[106:109], v[14:17]
	v_mfma_f32_16x16x32_bf16 v[14:17], v[26:29], v[98:101], 0
	v_mfma_f32_16x16x32_bf16 v[10:13], v[18:21], v[50:53], 0
	v_mfma_f32_16x16x32_bf16 v[202:205], v[30:33], v[106:109], v[14:17]
	v_mfma_f32_16x16x32_bf16 v[14:17], v[18:21], v[114:117], 0
	v_mfma_f32_16x16x32_bf16 v[10:13], v[22:25], v[58:61], v[10:13]
	v_mfma_f32_16x16x32_bf16 v[206:209], v[22:25], v[118:121], v[14:17]
	v_mfma_f32_16x16x32_bf16 v[14:17], v[26:29], v[114:117], 0
	v_mfma_f32_16x16x32_bf16 v[210:213], v[30:33], v[118:121], v[14:17]
	s_setprio 0
	s_barrier
	s_add_i32 s79, 0, 0x18000
	s_add_i32 s81, 0, 0x1c000
	v_add_u32_e32 v146, s79, v153
	v_add_u32_e32 v147, s81, v153
	s_nop 0
	ds_read_b128 v[14:17], v146
	ds_read_b128 v[18:21], v146 offset:1024
	ds_read_b128 v[26:29], v146 offset:2048
	ds_read_b128 v[214:217], v146 offset:3072
	ds_read_b128 v[218:221], v147
	ds_read_b128 v[222:225], v147 offset:1024
	ds_read_b128 v[226:229], v147 offset:2048
	ds_read_b128 v[230:233], v147 offset:3072
	s_add_u32 s54, s52, 0x100100
	s_addc_u32 s55, s53, 0
	s_mov_b32 m0, s58
	v_lshl_add_u64 v[50:51], s[54:55], 0, v[130:131]
	ds_read_b128 v[22:25], v152 offset:32768
	ds_read_b128 v[30:33], v152 offset:33792
	ds_read_b128 v[62:65], v152 offset:34816
	ds_read_b128 v[234:237], v152 offset:35840
	ds_read_b128 v[238:241], v152 offset:36864
	ds_read_b128 v[242:245], v152 offset:37888
	ds_read_b128 v[246:249], v152 offset:38912
	ds_read_b128 v[250:253], v152 offset:39936
	global_load_lds_dwordx4 v[50:51], off
	v_lshl_add_u64 v[50:51], s[54:55], 0, v[134:135]
	s_mov_b32 m0, s59
	s_nop 0
	global_load_lds_dwordx4 v[50:51], off
	s_waitcnt vmcnt(8)
	s_waitcnt lgkmcnt(0)
	s_setprio 1
	s_barrier
	v_mfma_f32_16x16x32_bf16 v[50:53], v[14:17], v[22:25], v[66:69]
	v_mfma_f32_16x16x32_bf16 v[122:125], v[18:21], v[30:33], v[50:53]
	v_mfma_f32_16x16x32_bf16 v[50:53], v[26:29], v[22:25], v[126:129]
	v_mfma_f32_16x16x32_bf16 v[114:117], v[214:217], v[30:33], v[50:53]
	v_mfma_f32_16x16x32_bf16 v[50:53], v[14:17], v[62:65], v[74:77]
	v_mfma_f32_16x16x32_bf16 v[106:109], v[18:21], v[234:237], v[50:53]
	v_mfma_f32_16x16x32_bf16 v[50:53], v[26:29], v[62:65], v[78:81]
	v_mfma_f32_16x16x32_bf16 v[98:101], v[214:217], v[234:237], v[50:53]
	v_mfma_f32_16x16x32_bf16 v[50:53], v[14:17], v[238:241], v[82:85]
	v_mfma_f32_16x16x32_bf16 v[90:93], v[18:21], v[242:245], v[50:53]
	v_mfma_f32_16x16x32_bf16 v[50:53], v[26:29], v[238:241], v[86:89]
	v_mfma_f32_16x16x32_bf16 v[82:85], v[214:217], v[242:245], v[50:53]
	v_mfma_f32_16x16x32_bf16 v[50:53], v[14:17], v[246:249], v[94:97]
	v_mfma_f32_16x16x32_bf16 v[58:61], v[18:21], v[250:253], v[50:53]
	v_mfma_f32_16x16x32_bf16 v[50:53], v[26:29], v[246:249], v[102:105]
	v_mfma_f32_16x16x32_bf16 v[50:53], v[214:217], v[250:253], v[50:53]
	v_mfma_f32_16x16x32_bf16 v[66:69], v[218:221], v[22:25], v[110:113]
	v_mfma_f32_16x16x32_bf16 v[22:25], v[226:229], v[22:25], v[34:37]
	v_mfma_f32_16x16x32_bf16 v[118:121], v[230:233], v[30:33], v[22:25]
	v_mfma_f32_16x16x32_bf16 v[22:25], v[218:221], v[62:65], v[38:41]
	v_mfma_f32_16x16x32_bf16 v[110:113], v[222:225], v[234:237], v[22:25]
	v_mfma_f32_16x16x32_bf16 v[22:25], v[226:229], v[62:65], v[42:45]
	v_mfma_f32_16x16x32_bf16 v[102:105], v[230:233], v[234:237], v[22:25]
	v_mfma_f32_16x16x32_bf16 v[22:25], v[218:221], v[238:241], v[46:49]
	v_mfma_f32_16x16x32_bf16 v[94:97], v[222:225], v[242:245], v[22:25]
	v_mfma_f32_16x16x32_bf16 v[22:25], v[226:229], v[238:241], v[54:57]
	v_mfma_f32_16x16x32_bf16 v[86:89], v[230:233], v[242:245], v[22:25]
	v_mfma_f32_16x16x32_bf16 v[22:25], v[218:221], v[246:249], v[154:157]
	v_mfma_f32_16x16x32_bf16 v[62:65], v[222:225], v[250:253], v[22:25]
	v_mfma_f32_16x16x32_bf16 v[22:25], v[226:229], v[246:249], v[158:161]
	v_mfma_f32_16x16x32_bf16 v[126:129], v[222:225], v[30:33], v[66:69]
	v_mfma_f32_16x16x32_bf16 v[54:57], v[230:233], v[250:253], v[22:25]
	s_setprio 0
	s_barrier
	s_add_i32 s79, s79, s56
	s_add_i32 s80, s79, 0x2000
	s_nop 1
	v_lshl_add_u64 v[22:23], v[142:143], 0, s[16:17]
	s_mov_b32 m0, s79
	s_add_u32 s54, s50, 0x100180
	ds_read_b128 v[34:37], v152 offset:49152
	ds_read_b128 v[42:45], v152 offset:50176
	ds_read_b128 v[154:157], v152 offset:51200
	ds_read_b128 v[158:161], v152 offset:52224
	ds_read_b128 v[234:237], v152 offset:53248
	ds_read_b128 v[238:241], v152 offset:54272
	ds_read_b128 v[242:245], v152 offset:55296
	ds_read_b128 v[246:249], v152 offset:56320
	global_load_lds_dwordx4 v[22:23], off
	v_lshl_add_u64 v[22:23], v[144:145], 0, s[16:17]
	s_mov_b32 m0, s80
	s_addc_u32 s55, s51, 0
	s_add_i32 s81, s81, s56
	global_load_lds_dwordx4 v[22:23], off
	v_lshl_add_u64 v[22:23], s[54:55], 0, v[132:133]
	s_mov_b32 m0, s81
	s_add_i32 s82, s81, 0x2000
	global_load_lds_dwordx4 v[22:23], off
	v_lshl_add_u64 v[22:23], s[54:55], 0, v[136:137]
	s_mov_b32 m0, s82
	s_nop 0
	global_load_lds_dwordx4 v[22:23], off
	v_lshl_add_u64 v[22:23], v[148:149], 0, s[16:17]
	s_mov_b32 m0, s61
	s_nop 0
	global_load_lds_dwordx4 v[22:23], off
	v_lshl_add_u64 v[22:23], v[70:71], 0, s[16:17]
	s_mov_b32 m0, s62
	s_nop 0
	global_load_lds_dwordx4 v[22:23], off
	s_waitcnt vmcnt(8)
	s_waitcnt lgkmcnt(0)
	s_setprio 1
	s_barrier
	v_mfma_f32_16x16x32_bf16 v[22:25], v[14:17], v[34:37], v[162:165]
	v_mfma_f32_16x16x32_bf16 v[78:81], v[18:21], v[42:45], v[22:25]
	v_mfma_f32_16x16x32_bf16 v[22:25], v[26:29], v[34:37], v[166:169]
	v_mfma_f32_16x16x32_bf16 v[70:73], v[214:217], v[42:45], v[22:25]
	v_mfma_f32_16x16x32_bf16 v[22:25], v[14:17], v[154:157], v[170:173]
	v_mfma_f32_16x16x32_bf16 v[46:49], v[18:21], v[158:161], v[22:25]
	v_mfma_f32_16x16x32_bf16 v[22:25], v[26:29], v[154:157], v[174:177]
	v_mfma_f32_16x16x32_bf16 v[38:41], v[214:217], v[158:161], v[22:25]
	v_mfma_f32_16x16x32_bf16 v[22:25], v[14:17], v[234:237], v[178:181]
	v_mfma_f32_16x16x32_bf16 v[2:5], v[14:17], v[242:245], v[2:5]
	v_mfma_f32_16x16x32_bf16 v[30:33], v[18:21], v[238:241], v[22:25]
	v_mfma_f32_16x16x32_bf16 v[22:25], v[26:29], v[234:237], v[182:185]
	v_mfma_f32_16x16x32_bf16 v[14:17], v[18:21], v[246:249], v[2:5]
	v_mfma_f32_16x16x32_bf16 v[2:5], v[26:29], v[242:245], v[6:9]
	v_mfma_f32_16x16x32_bf16 v[22:25], v[214:217], v[238:241], v[22:25]
	v_mfma_f32_16x16x32_bf16 v[6:9], v[214:217], v[246:249], v[2:5]
	v_mfma_f32_16x16x32_bf16 v[2:5], v[218:221], v[34:37], v[10:13]
	v_mfma_f32_16x16x32_bf16 v[74:77], v[222:225], v[42:45], v[2:5]
	v_mfma_f32_16x16x32_bf16 v[2:5], v[226:229], v[34:37], v[186:189]
	v_mfma_f32_16x16x32_bf16 v[66:69], v[230:233], v[42:45], v[2:5]
	v_mfma_f32_16x16x32_bf16 v[2:5], v[218:221], v[154:157], v[190:193]
	v_mfma_f32_16x16x32_bf16 v[42:45], v[222:225], v[158:161], v[2:5]
	v_mfma_f32_16x16x32_bf16 v[2:5], v[226:229], v[154:157], v[194:197]
	v_mfma_f32_16x16x32_bf16 v[34:37], v[230:233], v[158:161], v[2:5]
	v_mfma_f32_16x16x32_bf16 v[2:5], v[218:221], v[234:237], v[198:201]
	v_mfma_f32_16x16x32_bf16 v[26:29], v[222:225], v[238:241], v[2:5]
	v_mfma_f32_16x16x32_bf16 v[2:5], v[226:229], v[234:237], v[202:205]
	v_mfma_f32_16x16x32_bf16 v[18:21], v[230:233], v[238:241], v[2:5]
	v_mfma_f32_16x16x32_bf16 v[2:5], v[218:221], v[242:245], v[206:209]
	v_mfma_f32_16x16x32_bf16 v[10:13], v[222:225], v[246:249], v[2:5]
	v_mfma_f32_16x16x32_bf16 v[2:5], v[226:229], v[242:245], v[210:213]
	v_mfma_f32_16x16x32_bf16 v[2:5], v[230:233], v[246:249], v[2:5]
	s_setprio 0
	s_barrier
	s_add_u32 s83, s50, 0x200
	s_addc_u32 s84, s51, 0
	s_add_u32 s50, s52, 0x100180
	s_addc_u32 s51, s53, 0
	s_mov_b32 s85, 0
.LBB0_1174:
	ds_read_b128 v[154:157], v150
	ds_read_b128 v[158:161], v150 offset:1024
	ds_read_b128 v[162:165], v150 offset:2048
	ds_read_b128 v[166:169], v150 offset:3072
	ds_read_b128 v[170:173], v151
	ds_read_b128 v[174:177], v151 offset:1024
	ds_read_b128 v[178:181], v151 offset:2048
	ds_read_b128 v[182:185], v151 offset:3072
	s_add_u32 s52, s50, 0xfff00080
	s_addc_u32 s53, s51, -1
	s_cmp_eq_u32 s85, 60
	s_cselect_b32 s55, s43, s53
	s_cselect_b32 s54, s71, s52
	s_cselect_b32 s53, s41, s84
	s_cselect_b32 s52, s72, s83
	s_mov_b32 m0, s73
	v_lshl_add_u64 v[142:143], s[50:51], 0, v[140:141]
	ds_read_b128 v[186:189], v152
	ds_read_b128 v[190:193], v152 offset:1024
	ds_read_b128 v[194:197], v152 offset:2048
	ds_read_b128 v[198:201], v152 offset:3072
	ds_read_b128 v[202:205], v152 offset:4096
	ds_read_b128 v[206:209], v152 offset:5120
	ds_read_b128 v[210:213], v152 offset:6144
	ds_read_b128 v[214:217], v152 offset:7168
	global_load_lds_dwordx4 v[142:143], off
	v_lshl_add_u64 v[142:143], s[50:51], 0, v[138:139]
	s_mov_b32 m0, s74
	s_nop 0
	global_load_lds_dwordx4 v[142:143], off
	s_waitcnt vmcnt(8)
	s_waitcnt lgkmcnt(0)
	s_setprio 1
	s_barrier
	v_mfma_f32_16x16x32_bf16 v[122:125], v[154:157], v[186:189], v[122:125]
	v_mfma_f32_16x16x32_bf16 v[114:117], v[162:165], v[186:189], v[114:117]
	v_mfma_f32_16x16x32_bf16 v[106:109], v[154:157], v[194:197], v[106:109]
	v_mfma_f32_16x16x32_bf16 v[98:101], v[162:165], v[194:197], v[98:101]
	v_mfma_f32_16x16x32_bf16 v[90:93], v[154:157], v[202:205], v[90:93]
	v_mfma_f32_16x16x32_bf16 v[82:85], v[162:165], v[202:205], v[82:85]
	v_mfma_f32_16x16x32_bf16 v[58:61], v[154:157], v[210:213], v[58:61]
	v_mfma_f32_16x16x32_bf16 v[50:53], v[162:165], v[210:213], v[50:53]
	v_mfma_f32_16x16x32_bf16 v[122:125], v[158:161], v[190:193], v[122:125]
	v_mfma_f32_16x16x32_bf16 v[114:117], v[166:169], v[190:193], v[114:117]
	v_mfma_f32_16x16x32_bf16 v[106:109], v[158:161], v[198:201], v[106:109]
	v_mfma_f32_16x16x32_bf16 v[98:101], v[166:169], v[198:201], v[98:101]
	v_mfma_f32_16x16x32_bf16 v[90:93], v[158:161], v[206:209], v[90:93]
	v_mfma_f32_16x16x32_bf16 v[82:85], v[166:169], v[206:209], v[82:85]
	v_mfma_f32_16x16x32_bf16 v[58:61], v[158:161], v[214:217], v[58:61]
	v_mfma_f32_16x16x32_bf16 v[50:53], v[166:169], v[214:217], v[50:53]
	v_mfma_f32_16x16x32_bf16 v[126:129], v[170:173], v[186:189], v[126:129]
	v_mfma_f32_16x16x32_bf16 v[118:121], v[178:181], v[186:189], v[118:121]
	v_mfma_f32_16x16x32_bf16 v[110:113], v[170:173], v[194:197], v[110:113]
	v_mfma_f32_16x16x32_bf16 v[102:105], v[178:181], v[194:197], v[102:105]
	v_mfma_f32_16x16x32_bf16 v[94:97], v[170:173], v[202:205], v[94:97]
	v_mfma_f32_16x16x32_bf16 v[86:89], v[178:181], v[202:205], v[86:89]
	v_mfma_f32_16x16x32_bf16 v[62:65], v[170:173], v[210:213], v[62:65]
	v_mfma_f32_16x16x32_bf16 v[54:57], v[178:181], v[210:213], v[54:57]
	v_mfma_f32_16x16x32_bf16 v[126:129], v[174:177], v[190:193], v[126:129]
	v_mfma_f32_16x16x32_bf16 v[118:121], v[182:185], v[190:193], v[118:121]
	v_mfma_f32_16x16x32_bf16 v[110:113], v[174:177], v[198:201], v[110:113]
	v_mfma_f32_16x16x32_bf16 v[102:105], v[182:185], v[198:201], v[102:105]
	v_mfma_f32_16x16x32_bf16 v[94:97], v[174:177], v[206:209], v[94:97]
	v_mfma_f32_16x16x32_bf16 v[86:89], v[182:185], v[206:209], v[86:89]
	v_mfma_f32_16x16x32_bf16 v[62:65], v[174:177], v[214:217], v[62:65]
	v_mfma_f32_16x16x32_bf16 v[54:57], v[182:185], v[214:217], v[54:57]
	s_setprio 0
	s_barrier
	s_mov_b32 m0, s75
	v_lshl_add_u64 v[142:143], s[52:53], 0, v[132:133]
	s_add_u32 s86, s52, 0x100000
	ds_read_b128 v[186:189], v152 offset:16384
	ds_read_b128 v[190:193], v152 offset:17408
	ds_read_b128 v[194:197], v152 offset:18432
	ds_read_b128 v[198:201], v152 offset:19456
	ds_read_b128 v[202:205], v152 offset:20480
	ds_read_b128 v[206:209], v152 offset:21504
	ds_read_b128 v[210:213], v152 offset:22528
	ds_read_b128 v[214:217], v152 offset:23552
	global_load_lds_dwordx4 v[142:143], off
	v_lshl_add_u64 v[144:145], s[52:53], 0, v[136:137]
	s_mov_b32 m0, s76
	s_addc_u32 s87, s53, 0
	global_load_lds_dwordx4 v[144:145], off
	v_lshl_add_u64 v[148:149], s[86:87], 0, v[132:133]
	s_mov_b32 m0, s77
	v_lshl_add_u64 v[218:219], s[54:55], 0, v[134:135]
	global_load_lds_dwordx4 v[148:149], off
	v_lshl_add_u64 v[148:149], s[86:87], 0, v[136:137]
	s_mov_b32 m0, s78
	s_nop 0
	global_load_lds_dwordx4 v[148:149], off
	v_lshl_add_u64 v[148:149], s[54:55], 0, v[130:131]
	s_mov_b32 m0, s49
	s_nop 0
	global_load_lds_dwordx4 v[148:149], off
	s_mov_b32 m0, s57
	s_nop 0
	global_load_lds_dwordx4 v[218:219], off
	s_waitcnt vmcnt(8)
	s_waitcnt lgkmcnt(0)
	s_setprio 1
	s_barrier
	v_mfma_f32_16x16x32_bf16 v[78:81], v[154:157], v[186:189], v[78:81]
	v_mfma_f32_16x16x32_bf16 v[70:73], v[162:165], v[186:189], v[70:73]
	v_mfma_f32_16x16x32_bf16 v[46:49], v[154:157], v[194:197], v[46:49]
	v_mfma_f32_16x16x32_bf16 v[38:41], v[162:165], v[194:197], v[38:41]
	v_mfma_f32_16x16x32_bf16 v[30:33], v[154:157], v[202:205], v[30:33]
	v_mfma_f32_16x16x32_bf16 v[22:25], v[162:165], v[202:205], v[22:25]
	v_mfma_f32_16x16x32_bf16 v[14:17], v[154:157], v[210:213], v[14:17]
	v_mfma_f32_16x16x32_bf16 v[6:9], v[162:165], v[210:213], v[6:9]
	v_mfma_f32_16x16x32_bf16 v[78:81], v[158:161], v[190:193], v[78:81]
	v_mfma_f32_16x16x32_bf16 v[70:73], v[166:169], v[190:193], v[70:73]
	v_mfma_f32_16x16x32_bf16 v[46:49], v[158:161], v[198:201], v[46:49]
	v_mfma_f32_16x16x32_bf16 v[38:41], v[166:169], v[198:201], v[38:41]
	v_mfma_f32_16x16x32_bf16 v[30:33], v[158:161], v[206:209], v[30:33]
	v_mfma_f32_16x16x32_bf16 v[22:25], v[166:169], v[206:209], v[22:25]
	v_mfma_f32_16x16x32_bf16 v[14:17], v[158:161], v[214:217], v[14:17]
	v_mfma_f32_16x16x32_bf16 v[6:9], v[166:169], v[214:217], v[6:9]
	v_mfma_f32_16x16x32_bf16 v[74:77], v[170:173], v[186:189], v[74:77]
	v_mfma_f32_16x16x32_bf16 v[66:69], v[178:181], v[186:189], v[66:69]
	v_mfma_f32_16x16x32_bf16 v[42:45], v[170:173], v[194:197], v[42:45]
	v_mfma_f32_16x16x32_bf16 v[34:37], v[178:181], v[194:197], v[34:37]
	v_mfma_f32_16x16x32_bf16 v[26:29], v[170:173], v[202:205], v[26:29]
	v_mfma_f32_16x16x32_bf16 v[18:21], v[178:181], v[202:205], v[18:21]
	v_mfma_f32_16x16x32_bf16 v[10:13], v[170:173], v[210:213], v[10:13]
	v_mfma_f32_16x16x32_bf16 v[2:5], v[178:181], v[210:213], v[2:5]
	v_mfma_f32_16x16x32_bf16 v[74:77], v[174:177], v[190:193], v[74:77]
	v_mfma_f32_16x16x32_bf16 v[66:69], v[182:185], v[190:193], v[66:69]
	v_mfma_f32_16x16x32_bf16 v[42:45], v[174:177], v[198:201], v[42:45]
	v_mfma_f32_16x16x32_bf16 v[34:37], v[182:185], v[198:201], v[34:37]
	v_mfma_f32_16x16x32_bf16 v[26:29], v[174:177], v[206:209], v[26:29]
	v_mfma_f32_16x16x32_bf16 v[18:21], v[182:185], v[206:209], v[18:21]
	v_mfma_f32_16x16x32_bf16 v[10:13], v[174:177], v[214:217], v[10:13]
	v_mfma_f32_16x16x32_bf16 v[2:5], v[182:185], v[214:217], v[2:5]
	s_setprio 0
	s_barrier
	ds_read_b128 v[154:157], v146
	ds_read_b128 v[158:161], v146 offset:1024
	ds_read_b128 v[162:165], v146 offset:2048
	ds_read_b128 v[166:169], v146 offset:3072
	ds_read_b128 v[170:173], v147
	ds_read_b128 v[174:177], v147 offset:1024
	ds_read_b128 v[178:181], v147 offset:2048
	ds_read_b128 v[182:185], v147 offset:3072
	s_add_u32 s54, s54, 0x100000
	s_addc_u32 s55, s55, 0
	s_mov_b32 m0, s58
	v_lshl_add_u64 v[220:221], s[54:55], 0, v[130:131]
	ds_read_b128 v[186:189], v152 offset:32768
	ds_read_b128 v[190:193], v152 offset:33792
	ds_read_b128 v[194:197], v152 offset:34816
	ds_read_b128 v[198:201], v152 offset:35840
	ds_read_b128 v[202:205], v152 offset:36864
	ds_read_b128 v[206:209], v152 offset:37888
	ds_read_b128 v[210:213], v152 offset:38912
	ds_read_b128 v[214:217], v152 offset:39936
	global_load_lds_dwordx4 v[220:221], off
	v_lshl_add_u64 v[220:221], s[54:55], 0, v[134:135]
	s_mov_b32 m0, s59
	s_nop 0
	global_load_lds_dwordx4 v[220:221], off
	s_waitcnt vmcnt(8)
	s_waitcnt lgkmcnt(0)
	s_setprio 1
	s_barrier
	v_mfma_f32_16x16x32_bf16 v[122:125], v[154:157], v[186:189], v[122:125]
	v_mfma_f32_16x16x32_bf16 v[114:117], v[162:165], v[186:189], v[114:117]
	v_mfma_f32_16x16x32_bf16 v[106:109], v[154:157], v[194:197], v[106:109]
	v_mfma_f32_16x16x32_bf16 v[98:101], v[162:165], v[194:197], v[98:101]
	v_mfma_f32_16x16x32_bf16 v[90:93], v[154:157], v[202:205], v[90:93]
	v_mfma_f32_16x16x32_bf16 v[82:85], v[162:165], v[202:205], v[82:85]
	v_mfma_f32_16x16x32_bf16 v[58:61], v[154:157], v[210:213], v[58:61]
	v_mfma_f32_16x16x32_bf16 v[50:53], v[162:165], v[210:213], v[50:53]
	v_mfma_f32_16x16x32_bf16 v[122:125], v[158:161], v[190:193], v[122:125]
	v_mfma_f32_16x16x32_bf16 v[114:117], v[166:169], v[190:193], v[114:117]
	v_mfma_f32_16x16x32_bf16 v[106:109], v[158:161], v[198:201], v[106:109]
	v_mfma_f32_16x16x32_bf16 v[98:101], v[166:169], v[198:201], v[98:101]
	v_mfma_f32_16x16x32_bf16 v[90:93], v[158:161], v[206:209], v[90:93]
	v_mfma_f32_16x16x32_bf16 v[82:85], v[166:169], v[206:209], v[82:85]
	v_mfma_f32_16x16x32_bf16 v[58:61], v[158:161], v[214:217], v[58:61]
	v_mfma_f32_16x16x32_bf16 v[50:53], v[166:169], v[214:217], v[50:53]
	v_mfma_f32_16x16x32_bf16 v[126:129], v[170:173], v[186:189], v[126:129]
	v_mfma_f32_16x16x32_bf16 v[118:121], v[178:181], v[186:189], v[118:121]
	v_mfma_f32_16x16x32_bf16 v[110:113], v[170:173], v[194:197], v[110:113]
	v_mfma_f32_16x16x32_bf16 v[102:105], v[178:181], v[194:197], v[102:105]
	v_mfma_f32_16x16x32_bf16 v[94:97], v[170:173], v[202:205], v[94:97]
	v_mfma_f32_16x16x32_bf16 v[86:89], v[178:181], v[202:205], v[86:89]
	v_mfma_f32_16x16x32_bf16 v[62:65], v[170:173], v[210:213], v[62:65]
	v_mfma_f32_16x16x32_bf16 v[54:57], v[178:181], v[210:213], v[54:57]
	v_mfma_f32_16x16x32_bf16 v[126:129], v[174:177], v[190:193], v[126:129]
	v_mfma_f32_16x16x32_bf16 v[118:121], v[182:185], v[190:193], v[118:121]
	v_mfma_f32_16x16x32_bf16 v[110:113], v[174:177], v[198:201], v[110:113]
	v_mfma_f32_16x16x32_bf16 v[102:105], v[182:185], v[198:201], v[102:105]
	v_mfma_f32_16x16x32_bf16 v[94:97], v[174:177], v[206:209], v[94:97]
	v_mfma_f32_16x16x32_bf16 v[86:89], v[182:185], v[206:209], v[86:89]
	v_mfma_f32_16x16x32_bf16 v[62:65], v[174:177], v[214:217], v[62:65]
	v_mfma_f32_16x16x32_bf16 v[54:57], v[182:185], v[214:217], v[54:57]
	s_setprio 0
	s_barrier
	s_mov_b32 m0, s79
	v_lshl_add_u64 v[142:143], v[142:143], 0, s[10:11]
	s_add_u32 s52, s52, 0x100080
	ds_read_b128 v[186:189], v152 offset:49152
	ds_read_b128 v[190:193], v152 offset:50176
	ds_read_b128 v[194:197], v152 offset:51200
	ds_read_b128 v[198:201], v152 offset:52224
	ds_read_b128 v[202:205], v152 offset:53248
	ds_read_b128 v[206:209], v152 offset:54272
	ds_read_b128 v[210:213], v152 offset:55296
	ds_read_b128 v[214:217], v152 offset:56320
	global_load_lds_dwordx4 v[142:143], off
	v_lshl_add_u64 v[142:143], v[144:145], 0, s[10:11]
	s_mov_b32 m0, s80
	s_addc_u32 s53, s53, 0
	global_load_lds_dwordx4 v[142:143], off
	v_lshl_add_u64 v[142:143], s[52:53], 0, v[132:133]
	s_mov_b32 m0, s81
	s_nop 0
	global_load_lds_dwordx4 v[142:143], off
	v_lshl_add_u64 v[142:143], s[52:53], 0, v[136:137]
	s_mov_b32 m0, s82
	s_nop 0
	global_load_lds_dwordx4 v[142:143], off
	v_lshl_add_u64 v[142:143], v[148:149], 0, s[10:11]
	s_mov_b32 m0, s61
	s_nop 0
	global_load_lds_dwordx4 v[142:143], off
	v_lshl_add_u64 v[142:143], v[218:219], 0, s[10:11]
	s_mov_b32 m0, s62
	s_nop 0
	global_load_lds_dwordx4 v[142:143], off
	s_waitcnt vmcnt(8)
	s_waitcnt lgkmcnt(0)
	s_setprio 1
	s_barrier
	v_mfma_f32_16x16x32_bf16 v[78:81], v[154:157], v[186:189], v[78:81]
	v_mfma_f32_16x16x32_bf16 v[70:73], v[162:165], v[186:189], v[70:73]
	v_mfma_f32_16x16x32_bf16 v[46:49], v[154:157], v[194:197], v[46:49]
	v_mfma_f32_16x16x32_bf16 v[38:41], v[162:165], v[194:197], v[38:41]
	v_mfma_f32_16x16x32_bf16 v[30:33], v[154:157], v[202:205], v[30:33]
	v_mfma_f32_16x16x32_bf16 v[22:25], v[162:165], v[202:205], v[22:25]
	v_mfma_f32_16x16x32_bf16 v[14:17], v[154:157], v[210:213], v[14:17]
	v_mfma_f32_16x16x32_bf16 v[6:9], v[162:165], v[210:213], v[6:9]
	v_mfma_f32_16x16x32_bf16 v[78:81], v[158:161], v[190:193], v[78:81]
	v_mfma_f32_16x16x32_bf16 v[70:73], v[166:169], v[190:193], v[70:73]
	v_mfma_f32_16x16x32_bf16 v[46:49], v[158:161], v[198:201], v[46:49]
	v_mfma_f32_16x16x32_bf16 v[38:41], v[166:169], v[198:201], v[38:41]
	v_mfma_f32_16x16x32_bf16 v[30:33], v[158:161], v[206:209], v[30:33]
	v_mfma_f32_16x16x32_bf16 v[22:25], v[166:169], v[206:209], v[22:25]
	v_mfma_f32_16x16x32_bf16 v[14:17], v[158:161], v[214:217], v[14:17]
	v_mfma_f32_16x16x32_bf16 v[6:9], v[166:169], v[214:217], v[6:9]
	v_mfma_f32_16x16x32_bf16 v[74:77], v[170:173], v[186:189], v[74:77]
	v_mfma_f32_16x16x32_bf16 v[66:69], v[178:181], v[186:189], v[66:69]
	v_mfma_f32_16x16x32_bf16 v[42:45], v[170:173], v[194:197], v[42:45]
	v_mfma_f32_16x16x32_bf16 v[34:37], v[178:181], v[194:197], v[34:37]
	v_mfma_f32_16x16x32_bf16 v[26:29], v[170:173], v[202:205], v[26:29]
	v_mfma_f32_16x16x32_bf16 v[18:21], v[178:181], v[202:205], v[18:21]
	v_mfma_f32_16x16x32_bf16 v[10:13], v[170:173], v[210:213], v[10:13]
	v_mfma_f32_16x16x32_bf16 v[2:5], v[178:181], v[210:213], v[2:5]
	v_mfma_f32_16x16x32_bf16 v[74:77], v[174:177], v[190:193], v[74:77]
	v_mfma_f32_16x16x32_bf16 v[66:69], v[182:185], v[190:193], v[66:69]
	v_mfma_f32_16x16x32_bf16 v[42:45], v[174:177], v[198:201], v[42:45]
	v_mfma_f32_16x16x32_bf16 v[34:37], v[182:185], v[198:201], v[34:37]
	v_mfma_f32_16x16x32_bf16 v[26:29], v[174:177], v[206:209], v[26:29]
	v_mfma_f32_16x16x32_bf16 v[18:21], v[182:185], v[206:209], v[18:21]
	v_mfma_f32_16x16x32_bf16 v[10:13], v[174:177], v[214:217], v[10:13]
	v_mfma_f32_16x16x32_bf16 v[2:5], v[182:185], v[214:217], v[2:5]
	s_setprio 0
	s_barrier
	s_add_i32 s85, s85, 2
	s_add_u32 s83, s83, 0x100
	s_addc_u32 s84, s84, 0
	s_add_u32 s50, s50, 0x100
	s_addc_u32 s51, s51, 0
	s_cmp_gt_u32 s85, 61
	s_cbranch_scc0 .LBB0_1174
	s_and_b64 vcc, exec, s[12:13]
	s_cbranch_vccz .LBB0_1177
	s_barrier

.LBB0_1327:
	s_ashr_i32 s43, s42, 31
	ds_read_b128 v[2:5], v150
	ds_read_b128 v[6:9], v150 offset:1024
	ds_read_b128 v[10:13], v150 offset:2048
	ds_read_b128 v[14:17], v150 offset:3072
	ds_read_b128 v[18:21], v151
	ds_read_b128 v[22:25], v151 offset:1024
	ds_read_b128 v[26:29], v151 offset:2048
	ds_read_b128 v[30:33], v151 offset:3072
	s_lshl_b64 s[44:45], s[42:43], 21
	s_add_u32 s44, s24, s44
	s_addc_u32 s45, s25, s45
	s_and_b64 s[46:47], s[4:5], exec
	s_cselect_b32 s43, s45, s53
	s_cselect_b32 s71, s44, s52
	s_ashr_i32 s41, s40, 31
	s_lshl_b64 s[46:47], s[40:41], 21
	s_add_u32 s46, s26, s46
	s_addc_u32 s47, s27, s47
	s_and_b64 s[54:55], s[4:5], exec
	s_cselect_b32 s41, s47, s51
	s_cselect_b32 s72, s46, s50
	s_add_u32 s54, s52, 0x100080
	s_addc_u32 s55, s53, 0
	s_add_i32 s73, s49, 0xc000
	v_lshl_add_u64 v[66:67], s[54:55], 0, v[130:131]
	s_mov_b32 m0, s73
	s_add_i32 s74, s49, 0xe000
	ds_read_b128 v[34:37], v152
	ds_read_b128 v[38:41], v152 offset:1024
	ds_read_b128 v[42:45], v152 offset:2048
	ds_read_b128 v[46:49], v152 offset:3072
	ds_read_b128 v[50:53], v152 offset:4096
	ds_read_b128 v[54:57], v152 offset:5120
	ds_read_b128 v[58:61], v152 offset:6144
	ds_read_b128 v[62:65], v152 offset:7168
	global_load_lds_dwordx4 v[66:67], off
	v_lshl_add_u64 v[66:67], s[54:55], 0, v[134:135]
	s_mov_b32 m0, s74
	s_nop 0
	global_load_lds_dwordx4 v[66:67], off
	s_waitcnt vmcnt(24)
	s_waitcnt lgkmcnt(0)
	s_setprio 1
	s_barrier
	v_mfma_f32_16x16x32_bf16 v[90:93], v[2:5], v[58:61], 0
	v_mfma_f32_16x16x32_bf16 v[66:69], v[2:5], v[34:37], 0
	v_mfma_f32_16x16x32_bf16 v[70:73], v[10:13], v[34:37], 0
	v_mfma_f32_16x16x32_bf16 v[74:77], v[2:5], v[42:45], 0
	v_mfma_f32_16x16x32_bf16 v[78:81], v[10:13], v[42:45], 0
	v_mfma_f32_16x16x32_bf16 v[82:85], v[2:5], v[50:53], 0
	v_mfma_f32_16x16x32_bf16 v[86:89], v[10:13], v[50:53], 0
	v_mfma_f32_16x16x32_bf16 v[94:97], v[6:9], v[62:65], v[90:93]
	v_mfma_f32_16x16x32_bf16 v[90:93], v[10:13], v[58:61], 0
	v_mfma_f32_16x16x32_bf16 v[66:69], v[6:9], v[38:41], v[66:69]
	v_mfma_f32_16x16x32_bf16 v[126:129], v[14:17], v[38:41], v[70:73]
	v_mfma_f32_16x16x32_bf16 v[74:77], v[6:9], v[46:49], v[74:77]
	v_mfma_f32_16x16x32_bf16 v[78:81], v[14:17], v[46:49], v[78:81]
	v_mfma_f32_16x16x32_bf16 v[82:85], v[6:9], v[54:57], v[82:85]
	v_mfma_f32_16x16x32_bf16 v[86:89], v[14:17], v[54:57], v[86:89]
	v_mfma_f32_16x16x32_bf16 v[102:105], v[14:17], v[62:65], v[90:93]
	v_mfma_f32_16x16x32_bf16 v[90:93], v[18:21], v[34:37], 0
	v_mfma_f32_16x16x32_bf16 v[34:37], v[26:29], v[34:37], 0
	v_mfma_f32_16x16x32_bf16 v[110:113], v[22:25], v[38:41], v[90:93]
	v_mfma_f32_16x16x32_bf16 v[34:37], v[30:33], v[38:41], v[34:37]
	v_mfma_f32_16x16x32_bf16 v[38:41], v[18:21], v[42:45], 0
	v_mfma_f32_16x16x32_bf16 v[42:45], v[26:29], v[42:45], 0
	v_mfma_f32_16x16x32_bf16 v[38:41], v[22:25], v[46:49], v[38:41]
	v_mfma_f32_16x16x32_bf16 v[42:45], v[30:33], v[46:49], v[42:45]
	v_mfma_f32_16x16x32_bf16 v[46:49], v[18:21], v[50:53], 0
	v_mfma_f32_16x16x32_bf16 v[50:53], v[26:29], v[50:53], 0
	v_mfma_f32_16x16x32_bf16 v[46:49], v[22:25], v[54:57], v[46:49]
	v_mfma_f32_16x16x32_bf16 v[54:57], v[30:33], v[54:57], v[50:53]
	v_mfma_f32_16x16x32_bf16 v[50:53], v[18:21], v[58:61], 0
	v_mfma_f32_16x16x32_bf16 v[154:157], v[22:25], v[62:65], v[50:53]
	v_mfma_f32_16x16x32_bf16 v[50:53], v[26:29], v[58:61], 0
	v_mfma_f32_16x16x32_bf16 v[158:161], v[30:33], v[62:65], v[50:53]
	s_setprio 0
	s_barrier
	s_add_i32 s75, s64, s56
	v_lshl_add_u64 v[142:143], s[50:51], 0, v[132:133]
	s_add_i32 s76, s75, 0x2000
	v_lshl_add_u64 v[122:123], v[142:143], 0, s[16:17]
	s_mov_b32 m0, s75
	v_lshl_add_u64 v[144:145], s[50:51], 0, v[136:137]
	s_add_u32 s54, s50, 0x100100
	ds_read_b128 v[50:53], v152 offset:16384
	ds_read_b128 v[58:61], v152 offset:17408
	ds_read_b128 v[62:65], v152 offset:18432
	ds_read_b128 v[90:93], v152 offset:19456
	ds_read_b128 v[98:101], v152 offset:20480
	ds_read_b128 v[106:109], v152 offset:21504
	ds_read_b128 v[114:117], v152 offset:22528
	ds_read_b128 v[118:121], v152 offset:23552
	global_load_lds_dwordx4 v[122:123], off
	v_lshl_add_u64 v[122:123], v[144:145], 0, s[16:17]
	s_mov_b32 m0, s76
	s_addc_u32 s55, s51, 0
	s_add_i32 s77, s65, s56
	global_load_lds_dwordx4 v[122:123], off
	v_lshl_add_u64 v[122:123], s[54:55], 0, v[132:133]
	s_mov_b32 m0, s77
	s_add_i32 s78, s77, 0x2000
	global_load_lds_dwordx4 v[122:123], off
	v_lshl_add_u64 v[122:123], s[54:55], 0, v[136:137]
	s_mov_b32 m0, s78
	v_lshl_add_u64 v[148:149], s[52:53], 0, v[130:131]
	global_load_lds_dwordx4 v[122:123], off
	v_lshl_add_u64 v[122:123], v[148:149], 0, s[16:17]
	s_mov_b32 m0, s49
	v_lshl_add_u64 v[70:71], s[52:53], 0, v[134:135]
	global_load_lds_dwordx4 v[122:123], off
	v_lshl_add_u64 v[72:73], v[70:71], 0, s[16:17]
	s_mov_b32 m0, s57
	s_nop 0
	global_load_lds_dwordx4 v[72:73], off
	s_waitcnt vmcnt(24)
	s_waitcnt lgkmcnt(0)
	s_setprio 1
	s_barrier
	v_mfma_f32_16x16x32_bf16 v[122:125], v[2:5], v[50:53], 0
	v_mfma_f32_16x16x32_bf16 v[162:165], v[6:9], v[58:61], v[122:125]
	v_mfma_f32_16x16x32_bf16 v[122:125], v[10:13], v[50:53], 0
	v_mfma_f32_16x16x32_bf16 v[166:169], v[14:17], v[58:61], v[122:125]
	v_mfma_f32_16x16x32_bf16 v[122:125], v[2:5], v[62:65], 0
	v_mfma_f32_16x16x32_bf16 v[170:173], v[6:9], v[90:93], v[122:125]
	v_mfma_f32_16x16x32_bf16 v[122:125], v[10:13], v[62:65], 0
	v_mfma_f32_16x16x32_bf16 v[174:177], v[14:17], v[90:93], v[122:125]
	v_mfma_f32_16x16x32_bf16 v[122:125], v[2:5], v[98:101], 0
	v_mfma_f32_16x16x32_bf16 v[2:5], v[2:5], v[114:117], 0
	v_mfma_f32_16x16x32_bf16 v[178:181], v[6:9], v[106:109], v[122:125]
	v_mfma_f32_16x16x32_bf16 v[2:5], v[6:9], v[118:121], v[2:5]
	v_mfma_f32_16x16x32_bf16 v[6:9], v[10:13], v[114:117], 0
	v_mfma_f32_16x16x32_bf16 v[122:125], v[10:13], v[98:101], 0
	v_mfma_f32_16x16x32_bf16 v[6:9], v[14:17], v[118:121], v[6:9]
	v_mfma_f32_16x16x32_bf16 v[182:185], v[14:17], v[106:109], v[122:125]
	v_mfma_f32_16x16x32_bf16 v[14:17], v[26:29], v[50:53], 0
	v_mfma_f32_16x16x32_bf16 v[186:189], v[30:33], v[58:61], v[14:17]
	v_mfma_f32_16x16x32_bf16 v[14:17], v[18:21], v[62:65], 0
	v_mfma_f32_16x16x32_bf16 v[190:193], v[22:25], v[90:93], v[14:17]
	v_mfma_f32_16x16x32_bf16 v[14:17], v[26:29], v[62:65], 0
	v_mfma_f32_16x16x32_bf16 v[194:197], v[30:33], v[90:93], v[14:17]
	v_mfma_f32_16x16x32_bf16 v[14:17], v[18:21], v[98:101], 0
	v_mfma_f32_16x16x32_bf16 v[198:201], v[22:25], v[106:109], v[14:17]
	v_mfma_f32_16x16x32_bf16 v[14:17], v[26:29], v[98:101], 0
	v_mfma_f32_16x16x32_bf16 v[10:13], v[18:21], v[50:53], 0
	v_mfma_f32_16x16x32_bf16 v[202:205], v[30:33], v[106:109], v[14:17]
	v_mfma_f32_16x16x32_bf16 v[14:17], v[18:21], v[114:117], 0
	v_mfma_f32_16x16x32_bf16 v[10:13], v[22:25], v[58:61], v[10:13]
	v_mfma_f32_16x16x32_bf16 v[206:209], v[22:25], v[118:121], v[14:17]
	v_mfma_f32_16x16x32_bf16 v[14:17], v[26:29], v[114:117], 0
	v_mfma_f32_16x16x32_bf16 v[210:213], v[30:33], v[118:121], v[14:17]
	s_setprio 0
	s_barrier
	s_add_i32 s79, 0, 0x18000
	s_add_i32 s81, 0, 0x1c000
	v_add_u32_e32 v146, s79, v153
	v_add_u32_e32 v147, s81, v153
	s_nop 0
	ds_read_b128 v[14:17], v146
	ds_read_b128 v[18:21], v146 offset:1024
	ds_read_b128 v[26:29], v146 offset:2048
	ds_read_b128 v[214:217], v146 offset:3072
	ds_read_b128 v[218:221], v147
	ds_read_b128 v[222:225], v147 offset:1024
	ds_read_b128 v[226:229], v147 offset:2048
	ds_read_b128 v[230:233], v147 offset:3072
	s_add_u32 s54, s52, 0x100100
	s_addc_u32 s55, s53, 0
	s_mov_b32 m0, s58
	v_lshl_add_u64 v[50:51], s[54:55], 0, v[130:131]
	ds_read_b128 v[22:25], v152 offset:32768
	ds_read_b128 v[30:33], v152 offset:33792
	ds_read_b128 v[62:65], v152 offset:34816
	ds_read_b128 v[234:237], v152 offset:35840
	ds_read_b128 v[238:241], v152 offset:36864
	ds_read_b128 v[242:245], v152 offset:37888
	ds_read_b128 v[246:249], v152 offset:38912
	ds_read_b128 v[250:253], v152 offset:39936
	global_load_lds_dwordx4 v[50:51], off
	v_lshl_add_u64 v[50:51], s[54:55], 0, v[134:135]
	s_mov_b32 m0, s59
	s_nop 0
	global_load_lds_dwordx4 v[50:51], off
	s_waitcnt vmcnt(8)
	s_waitcnt lgkmcnt(0)
	s_setprio 1
	s_barrier
	v_mfma_f32_16x16x32_bf16 v[50:53], v[14:17], v[22:25], v[66:69]
	v_mfma_f32_16x16x32_bf16 v[122:125], v[18:21], v[30:33], v[50:53]
	v_mfma_f32_16x16x32_bf16 v[50:53], v[26:29], v[22:25], v[126:129]
	v_mfma_f32_16x16x32_bf16 v[114:117], v[214:217], v[30:33], v[50:53]
	v_mfma_f32_16x16x32_bf16 v[50:53], v[14:17], v[62:65], v[74:77]
	v_mfma_f32_16x16x32_bf16 v[106:109], v[18:21], v[234:237], v[50:53]
	v_mfma_f32_16x16x32_bf16 v[50:53], v[26:29], v[62:65], v[78:81]
	v_mfma_f32_16x16x32_bf16 v[98:101], v[214:217], v[234:237], v[50:53]
	v_mfma_f32_16x16x32_bf16 v[50:53], v[14:17], v[238:241], v[82:85]
	v_mfma_f32_16x16x32_bf16 v[90:93], v[18:21], v[242:245], v[50:53]
	v_mfma_f32_16x16x32_bf16 v[50:53], v[26:29], v[238:241], v[86:89]
	v_mfma_f32_16x16x32_bf16 v[82:85], v[214:217], v[242:245], v[50:53]
	v_mfma_f32_16x16x32_bf16 v[50:53], v[14:17], v[246:249], v[94:97]
	v_mfma_f32_16x16x32_bf16 v[58:61], v[18:21], v[250:253], v[50:53]
	v_mfma_f32_16x16x32_bf16 v[50:53], v[26:29], v[246:249], v[102:105]
	v_mfma_f32_16x16x32_bf16 v[50:53], v[214:217], v[250:253], v[50:53]
	v_mfma_f32_16x16x32_bf16 v[66:69], v[218:221], v[22:25], v[110:113]
	v_mfma_f32_16x16x32_bf16 v[22:25], v[226:229], v[22:25], v[34:37]
	v_mfma_f32_16x16x32_bf16 v[118:121], v[230:233], v[30:33], v[22:25]
	v_mfma_f32_16x16x32_bf16 v[22:25], v[218:221], v[62:65], v[38:41]
	v_mfma_f32_16x16x32_bf16 v[110:113], v[222:225], v[234:237], v[22:25]
	v_mfma_f32_16x16x32_bf16 v[22:25], v[226:229], v[62:65], v[42:45]
	v_mfma_f32_16x16x32_bf16 v[102:105], v[230:233], v[234:237], v[22:25]
	v_mfma_f32_16x16x32_bf16 v[22:25], v[218:221], v[238:241], v[46:49]
	v_mfma_f32_16x16x32_bf16 v[94:97], v[222:225], v[242:245], v[22:25]
	v_mfma_f32_16x16x32_bf16 v[22:25], v[226:229], v[238:241], v[54:57]
	v_mfma_f32_16x16x32_bf16 v[86:89], v[230:233], v[242:245], v[22:25]
	v_mfma_f32_16x16x32_bf16 v[22:25], v[218:221], v[246:249], v[154:157]
	v_mfma_f32_16x16x32_bf16 v[62:65], v[222:225], v[250:253], v[22:25]
	v_mfma_f32_16x16x32_bf16 v[22:25], v[226:229], v[246:249], v[158:161]
	v_mfma_f32_16x16x32_bf16 v[126:129], v[222:225], v[30:33], v[66:69]
	v_mfma_f32_16x16x32_bf16 v[54:57], v[230:233], v[250:253], v[22:25]
	s_setprio 0
	s_barrier
	s_add_i32 s79, s79, s56
	s_add_i32 s80, s79, 0x2000
	s_nop 1
	v_lshl_add_u64 v[22:23], v[142:143], 0, s[30:31]
	s_mov_b32 m0, s79
	s_add_u32 s54, s50, 0x100180
	ds_read_b128 v[34:37], v152 offset:49152
	ds_read_b128 v[42:45], v152 offset:50176
	ds_read_b128 v[154:157], v152 offset:51200
	ds_read_b128 v[158:161], v152 offset:52224
	ds_read_b128 v[234:237], v152 offset:53248
	ds_read_b128 v[238:241], v152 offset:54272
	ds_read_b128 v[242:245], v152 offset:55296
	ds_read_b128 v[246:249], v152 offset:56320
	global_load_lds_dwordx4 v[22:23], off
	v_lshl_add_u64 v[22:23], v[144:145], 0, s[30:31]
	s_mov_b32 m0, s80
	s_addc_u32 s55, s51, 0
	s_add_i32 s81, s81, s56
	global_load_lds_dwordx4 v[22:23], off
	v_lshl_add_u64 v[22:23], s[54:55], 0, v[132:133]
	s_mov_b32 m0, s81
	s_add_i32 s82, s81, 0x2000
	global_load_lds_dwordx4 v[22:23], off
	v_lshl_add_u64 v[22:23], s[54:55], 0, v[136:137]
	s_mov_b32 m0, s82
	s_nop 0
	global_load_lds_dwordx4 v[22:23], off
	v_lshl_add_u64 v[22:23], v[148:149], 0, s[30:31]
	s_mov_b32 m0, s61
	s_nop 0
	global_load_lds_dwordx4 v[22:23], off
	v_lshl_add_u64 v[22:23], v[70:71], 0, s[30:31]
	s_mov_b32 m0, s62
	s_nop 0
	global_load_lds_dwordx4 v[22:23], off
	s_waitcnt vmcnt(8)
	s_waitcnt lgkmcnt(0)
	s_setprio 1
	s_barrier
	v_mfma_f32_16x16x32_bf16 v[22:25], v[14:17], v[34:37], v[162:165]
	v_mfma_f32_16x16x32_bf16 v[78:81], v[18:21], v[42:45], v[22:25]
	v_mfma_f32_16x16x32_bf16 v[22:25], v[26:29], v[34:37], v[166:169]
	v_mfma_f32_16x16x32_bf16 v[70:73], v[214:217], v[42:45], v[22:25]
	v_mfma_f32_16x16x32_bf16 v[22:25], v[14:17], v[154:157], v[170:173]
	v_mfma_f32_16x16x32_bf16 v[46:49], v[18:21], v[158:161], v[22:25]
	v_mfma_f32_16x16x32_bf16 v[22:25], v[26:29], v[154:157], v[174:177]
	v_mfma_f32_16x16x32_bf16 v[38:41], v[214:217], v[158:161], v[22:25]
	v_mfma_f32_16x16x32_bf16 v[22:25], v[14:17], v[234:237], v[178:181]
	v_mfma_f32_16x16x32_bf16 v[2:5], v[14:17], v[242:245], v[2:5]
	v_mfma_f32_16x16x32_bf16 v[30:33], v[18:21], v[238:241], v[22:25]
	v_mfma_f32_16x16x32_bf16 v[22:25], v[26:29], v[234:237], v[182:185]
	v_mfma_f32_16x16x32_bf16 v[14:17], v[18:21], v[246:249], v[2:5]
	v_mfma_f32_16x16x32_bf16 v[2:5], v[26:29], v[242:245], v[6:9]
	v_mfma_f32_16x16x32_bf16 v[22:25], v[214:217], v[238:241], v[22:25]
	v_mfma_f32_16x16x32_bf16 v[6:9], v[214:217], v[246:249], v[2:5]
	v_mfma_f32_16x16x32_bf16 v[2:5], v[218:221], v[34:37], v[10:13]
	v_mfma_f32_16x16x32_bf16 v[74:77], v[222:225], v[42:45], v[2:5]
	v_mfma_f32_16x16x32_bf16 v[2:5], v[226:229], v[34:37], v[186:189]
	v_mfma_f32_16x16x32_bf16 v[66:69], v[230:233], v[42:45], v[2:5]
	v_mfma_f32_16x16x32_bf16 v[2:5], v[218:221], v[154:157], v[190:193]
	v_mfma_f32_16x16x32_bf16 v[42:45], v[222:225], v[158:161], v[2:5]
	v_mfma_f32_16x16x32_bf16 v[2:5], v[226:229], v[154:157], v[194:197]
	v_mfma_f32_16x16x32_bf16 v[34:37], v[230:233], v[158:161], v[2:5]
	v_mfma_f32_16x16x32_bf16 v[2:5], v[218:221], v[234:237], v[198:201]
	v_mfma_f32_16x16x32_bf16 v[26:29], v[222:225], v[238:241], v[2:5]
	v_mfma_f32_16x16x32_bf16 v[2:5], v[226:229], v[234:237], v[202:205]
	v_mfma_f32_16x16x32_bf16 v[18:21], v[230:233], v[238:241], v[2:5]
	v_mfma_f32_16x16x32_bf16 v[2:5], v[218:221], v[242:245], v[206:209]
	v_mfma_f32_16x16x32_bf16 v[10:13], v[222:225], v[246:249], v[2:5]
	v_mfma_f32_16x16x32_bf16 v[2:5], v[226:229], v[242:245], v[210:213]
	v_mfma_f32_16x16x32_bf16 v[2:5], v[230:233], v[246:249], v[2:5]
	s_setprio 0
	s_barrier
	s_add_u32 s83, s50, 0x200
	s_addc_u32 s84, s51, 0
	s_add_u32 s50, s52, 0x100180
	s_addc_u32 s51, s53, 0
	s_mov_b32 s85, 0
.LBB0_1328:
	ds_read_b128 v[154:157], v150
	ds_read_b128 v[158:161], v150 offset:1024
	ds_read_b128 v[162:165], v150 offset:2048
	ds_read_b128 v[166:169], v150 offset:3072
	ds_read_b128 v[170:173], v151
	ds_read_b128 v[174:177], v151 offset:1024
	ds_read_b128 v[178:181], v151 offset:2048
	ds_read_b128 v[182:185], v151 offset:3072
	s_add_u32 s52, s50, 0xfff00080
	s_addc_u32 s53, s51, -1
	s_cmp_eq_u32 s85, 60
	s_cselect_b32 s55, s43, s53
	s_cselect_b32 s54, s71, s52
	s_cselect_b32 s53, s41, s84
	s_cselect_b32 s52, s72, s83
	s_mov_b32 m0, s73
	v_lshl_add_u64 v[142:143], s[50:51], 0, v[140:141]
	ds_read_b128 v[186:189], v152
	ds_read_b128 v[190:193], v152 offset:1024
	ds_read_b128 v[194:197], v152 offset:2048
	ds_read_b128 v[198:201], v152 offset:3072
	ds_read_b128 v[202:205], v152 offset:4096
	ds_read_b128 v[206:209], v152 offset:5120
	ds_read_b128 v[210:213], v152 offset:6144
	ds_read_b128 v[214:217], v152 offset:7168
	global_load_lds_dwordx4 v[142:143], off
	v_lshl_add_u64 v[142:143], s[50:51], 0, v[138:139]
	s_mov_b32 m0, s74
	s_nop 0
	global_load_lds_dwordx4 v[142:143], off
	s_waitcnt vmcnt(8)
	s_waitcnt lgkmcnt(0)
	s_setprio 1
	s_barrier
	v_mfma_f32_16x16x32_bf16 v[122:125], v[154:157], v[186:189], v[122:125]
	v_mfma_f32_16x16x32_bf16 v[114:117], v[162:165], v[186:189], v[114:117]
	v_mfma_f32_16x16x32_bf16 v[106:109], v[154:157], v[194:197], v[106:109]
	v_mfma_f32_16x16x32_bf16 v[98:101], v[162:165], v[194:197], v[98:101]
	v_mfma_f32_16x16x32_bf16 v[90:93], v[154:157], v[202:205], v[90:93]
	v_mfma_f32_16x16x32_bf16 v[82:85], v[162:165], v[202:205], v[82:85]
	v_mfma_f32_16x16x32_bf16 v[58:61], v[154:157], v[210:213], v[58:61]
	v_mfma_f32_16x16x32_bf16 v[50:53], v[162:165], v[210:213], v[50:53]
	v_mfma_f32_16x16x32_bf16 v[122:125], v[158:161], v[190:193], v[122:125]
	v_mfma_f32_16x16x32_bf16 v[114:117], v[166:169], v[190:193], v[114:117]
	v_mfma_f32_16x16x32_bf16 v[106:109], v[158:161], v[198:201], v[106:109]
	v_mfma_f32_16x16x32_bf16 v[98:101], v[166:169], v[198:201], v[98:101]
	v_mfma_f32_16x16x32_bf16 v[90:93], v[158:161], v[206:209], v[90:93]
	v_mfma_f32_16x16x32_bf16 v[82:85], v[166:169], v[206:209], v[82:85]
	v_mfma_f32_16x16x32_bf16 v[58:61], v[158:161], v[214:217], v[58:61]
	v_mfma_f32_16x16x32_bf16 v[50:53], v[166:169], v[214:217], v[50:53]
	v_mfma_f32_16x16x32_bf16 v[126:129], v[170:173], v[186:189], v[126:129]
	v_mfma_f32_16x16x32_bf16 v[118:121], v[178:181], v[186:189], v[118:121]
	v_mfma_f32_16x16x32_bf16 v[110:113], v[170:173], v[194:197], v[110:113]
	v_mfma_f32_16x16x32_bf16 v[102:105], v[178:181], v[194:197], v[102:105]
	v_mfma_f32_16x16x32_bf16 v[94:97], v[170:173], v[202:205], v[94:97]
	v_mfma_f32_16x16x32_bf16 v[86:89], v[178:181], v[202:205], v[86:89]
	v_mfma_f32_16x16x32_bf16 v[62:65], v[170:173], v[210:213], v[62:65]
	v_mfma_f32_16x16x32_bf16 v[54:57], v[178:181], v[210:213], v[54:57]
	v_mfma_f32_16x16x32_bf16 v[126:129], v[174:177], v[190:193], v[126:129]
	v_mfma_f32_16x16x32_bf16 v[118:121], v[182:185], v[190:193], v[118:121]
	v_mfma_f32_16x16x32_bf16 v[110:113], v[174:177], v[198:201], v[110:113]
	v_mfma_f32_16x16x32_bf16 v[102:105], v[182:185], v[198:201], v[102:105]
	v_mfma_f32_16x16x32_bf16 v[94:97], v[174:177], v[206:209], v[94:97]
	v_mfma_f32_16x16x32_bf16 v[86:89], v[182:185], v[206:209], v[86:89]
	v_mfma_f32_16x16x32_bf16 v[62:65], v[174:177], v[214:217], v[62:65]
	v_mfma_f32_16x16x32_bf16 v[54:57], v[182:185], v[214:217], v[54:57]
	s_setprio 0
	s_barrier
	s_mov_b32 m0, s75
	v_lshl_add_u64 v[142:143], s[52:53], 0, v[132:133]
	s_add_u32 s86, s52, 0x100000
	ds_read_b128 v[186:189], v152 offset:16384
	ds_read_b128 v[190:193], v152 offset:17408
	ds_read_b128 v[194:197], v152 offset:18432
	ds_read_b128 v[198:201], v152 offset:19456
	ds_read_b128 v[202:205], v152 offset:20480
	ds_read_b128 v[206:209], v152 offset:21504
	ds_read_b128 v[210:213], v152 offset:22528
	ds_read_b128 v[214:217], v152 offset:23552
	global_load_lds_dwordx4 v[142:143], off
	v_lshl_add_u64 v[144:145], s[52:53], 0, v[136:137]
	s_mov_b32 m0, s76
	s_addc_u32 s87, s53, 0
	global_load_lds_dwordx4 v[144:145], off
	v_lshl_add_u64 v[148:149], s[86:87], 0, v[132:133]
	s_mov_b32 m0, s77
	v_lshl_add_u64 v[218:219], s[54:55], 0, v[134:135]
	global_load_lds_dwordx4 v[148:149], off
	v_lshl_add_u64 v[148:149], s[86:87], 0, v[136:137]
	s_mov_b32 m0, s78
	s_nop 0
	global_load_lds_dwordx4 v[148:149], off
	v_lshl_add_u64 v[148:149], s[54:55], 0, v[130:131]
	s_mov_b32 m0, s49
	s_nop 0
	global_load_lds_dwordx4 v[148:149], off
	s_mov_b32 m0, s57
	s_nop 0
	global_load_lds_dwordx4 v[218:219], off
	s_waitcnt vmcnt(8)
	s_waitcnt lgkmcnt(0)
	s_setprio 1
	s_barrier
	v_mfma_f32_16x16x32_bf16 v[78:81], v[154:157], v[186:189], v[78:81]
	v_mfma_f32_16x16x32_bf16 v[70:73], v[162:165], v[186:189], v[70:73]
	v_mfma_f32_16x16x32_bf16 v[46:49], v[154:157], v[194:197], v[46:49]
	v_mfma_f32_16x16x32_bf16 v[38:41], v[162:165], v[194:197], v[38:41]
	v_mfma_f32_16x16x32_bf16 v[30:33], v[154:157], v[202:205], v[30:33]
	v_mfma_f32_16x16x32_bf16 v[22:25], v[162:165], v[202:205], v[22:25]
	v_mfma_f32_16x16x32_bf16 v[14:17], v[154:157], v[210:213], v[14:17]
	v_mfma_f32_16x16x32_bf16 v[6:9], v[162:165], v[210:213], v[6:9]
	v_mfma_f32_16x16x32_bf16 v[78:81], v[158:161], v[190:193], v[78:81]
	v_mfma_f32_16x16x32_bf16 v[70:73], v[166:169], v[190:193], v[70:73]
	v_mfma_f32_16x16x32_bf16 v[46:49], v[158:161], v[198:201], v[46:49]
	v_mfma_f32_16x16x32_bf16 v[38:41], v[166:169], v[198:201], v[38:41]
	v_mfma_f32_16x16x32_bf16 v[30:33], v[158:161], v[206:209], v[30:33]
	v_mfma_f32_16x16x32_bf16 v[22:25], v[166:169], v[206:209], v[22:25]
	v_mfma_f32_16x16x32_bf16 v[14:17], v[158:161], v[214:217], v[14:17]
	v_mfma_f32_16x16x32_bf16 v[6:9], v[166:169], v[214:217], v[6:9]
	v_mfma_f32_16x16x32_bf16 v[74:77], v[170:173], v[186:189], v[74:77]
	v_mfma_f32_16x16x32_bf16 v[66:69], v[178:181], v[186:189], v[66:69]
	v_mfma_f32_16x16x32_bf16 v[42:45], v[170:173], v[194:197], v[42:45]
	v_mfma_f32_16x16x32_bf16 v[34:37], v[178:181], v[194:197], v[34:37]
	v_mfma_f32_16x16x32_bf16 v[26:29], v[170:173], v[202:205], v[26:29]
	v_mfma_f32_16x16x32_bf16 v[18:21], v[178:181], v[202:205], v[18:21]
	v_mfma_f32_16x16x32_bf16 v[10:13], v[170:173], v[210:213], v[10:13]
	v_mfma_f32_16x16x32_bf16 v[2:5], v[178:181], v[210:213], v[2:5]
	v_mfma_f32_16x16x32_bf16 v[74:77], v[174:177], v[190:193], v[74:77]
	v_mfma_f32_16x16x32_bf16 v[66:69], v[182:185], v[190:193], v[66:69]
	v_mfma_f32_16x16x32_bf16 v[42:45], v[174:177], v[198:201], v[42:45]
	v_mfma_f32_16x16x32_bf16 v[34:37], v[182:185], v[198:201], v[34:37]
	v_mfma_f32_16x16x32_bf16 v[26:29], v[174:177], v[206:209], v[26:29]
	v_mfma_f32_16x16x32_bf16 v[18:21], v[182:185], v[206:209], v[18:21]
	v_mfma_f32_16x16x32_bf16 v[10:13], v[174:177], v[214:217], v[10:13]
	v_mfma_f32_16x16x32_bf16 v[2:5], v[182:185], v[214:217], v[2:5]
	s_setprio 0
	s_barrier
	ds_read_b128 v[154:157], v146
	ds_read_b128 v[158:161], v146 offset:1024
	ds_read_b128 v[162:165], v146 offset:2048
	ds_read_b128 v[166:169], v146 offset:3072
	ds_read_b128 v[170:173], v147
	ds_read_b128 v[174:177], v147 offset:1024
	ds_read_b128 v[178:181], v147 offset:2048
	ds_read_b128 v[182:185], v147 offset:3072
	s_add_u32 s54, s54, 0x100000
	s_addc_u32 s55, s55, 0
	s_mov_b32 m0, s58
	v_lshl_add_u64 v[220:221], s[54:55], 0, v[130:131]
	ds_read_b128 v[186:189], v152 offset:32768
	ds_read_b128 v[190:193], v152 offset:33792
	ds_read_b128 v[194:197], v152 offset:34816
	ds_read_b128 v[198:201], v152 offset:35840
	ds_read_b128 v[202:205], v152 offset:36864
	ds_read_b128 v[206:209], v152 offset:37888
	ds_read_b128 v[210:213], v152 offset:38912
	ds_read_b128 v[214:217], v152 offset:39936
	global_load_lds_dwordx4 v[220:221], off
	v_lshl_add_u64 v[220:221], s[54:55], 0, v[134:135]
	s_mov_b32 m0, s59
	s_nop 0
	global_load_lds_dwordx4 v[220:221], off
	s_waitcnt vmcnt(8)
	s_waitcnt lgkmcnt(0)
	s_setprio 1
	s_barrier
	v_mfma_f32_16x16x32_bf16 v[122:125], v[154:157], v[186:189], v[122:125]
	v_mfma_f32_16x16x32_bf16 v[114:117], v[162:165], v[186:189], v[114:117]
	v_mfma_f32_16x16x32_bf16 v[106:109], v[154:157], v[194:197], v[106:109]
	v_mfma_f32_16x16x32_bf16 v[98:101], v[162:165], v[194:197], v[98:101]
	v_mfma_f32_16x16x32_bf16 v[90:93], v[154:157], v[202:205], v[90:93]
	v_mfma_f32_16x16x32_bf16 v[82:85], v[162:165], v[202:205], v[82:85]
	v_mfma_f32_16x16x32_bf16 v[58:61], v[154:157], v[210:213], v[58:61]
	v_mfma_f32_16x16x32_bf16 v[50:53], v[162:165], v[210:213], v[50:53]
	v_mfma_f32_16x16x32_bf16 v[122:125], v[158:161], v[190:193], v[122:125]
	v_mfma_f32_16x16x32_bf16 v[114:117], v[166:169], v[190:193], v[114:117]
	v_mfma_f32_16x16x32_bf16 v[106:109], v[158:161], v[198:201], v[106:109]
	v_mfma_f32_16x16x32_bf16 v[98:101], v[166:169], v[198:201], v[98:101]
	v_mfma_f32_16x16x32_bf16 v[90:93], v[158:161], v[206:209], v[90:93]
	v_mfma_f32_16x16x32_bf16 v[82:85], v[166:169], v[206:209], v[82:85]
	v_mfma_f32_16x16x32_bf16 v[58:61], v[158:161], v[214:217], v[58:61]
	v_mfma_f32_16x16x32_bf16 v[50:53], v[166:169], v[214:217], v[50:53]
	v_mfma_f32_16x16x32_bf16 v[126:129], v[170:173], v[186:189], v[126:129]
	v_mfma_f32_16x16x32_bf16 v[118:121], v[178:181], v[186:189], v[118:121]
	v_mfma_f32_16x16x32_bf16 v[110:113], v[170:173], v[194:197], v[110:113]
	v_mfma_f32_16x16x32_bf16 v[102:105], v[178:181], v[194:197], v[102:105]
	v_mfma_f32_16x16x32_bf16 v[94:97], v[170:173], v[202:205], v[94:97]
	v_mfma_f32_16x16x32_bf16 v[86:89], v[178:181], v[202:205], v[86:89]
	v_mfma_f32_16x16x32_bf16 v[62:65], v[170:173], v[210:213], v[62:65]
	v_mfma_f32_16x16x32_bf16 v[54:57], v[178:181], v[210:213], v[54:57]
	v_mfma_f32_16x16x32_bf16 v[126:129], v[174:177], v[190:193], v[126:129]
	v_mfma_f32_16x16x32_bf16 v[118:121], v[182:185], v[190:193], v[118:121]
	v_mfma_f32_16x16x32_bf16 v[110:113], v[174:177], v[198:201], v[110:113]
	v_mfma_f32_16x16x32_bf16 v[102:105], v[182:185], v[198:201], v[102:105]
	v_mfma_f32_16x16x32_bf16 v[94:97], v[174:177], v[206:209], v[94:97]
	v_mfma_f32_16x16x32_bf16 v[86:89], v[182:185], v[206:209], v[86:89]
	v_mfma_f32_16x16x32_bf16 v[62:65], v[174:177], v[214:217], v[62:65]
	v_mfma_f32_16x16x32_bf16 v[54:57], v[182:185], v[214:217], v[54:57]
	s_setprio 0
	s_barrier
	s_mov_b32 m0, s79
	v_lshl_add_u64 v[142:143], v[142:143], 0, s[12:13]
	s_add_u32 s52, s52, 0x100080
	ds_read_b128 v[186:189], v152 offset:49152
	ds_read_b128 v[190:193], v152 offset:50176
	ds_read_b128 v[194:197], v152 offset:51200
	ds_read_b128 v[198:201], v152 offset:52224
	ds_read_b128 v[202:205], v152 offset:53248
	ds_read_b128 v[206:209], v152 offset:54272
	ds_read_b128 v[210:213], v152 offset:55296
	ds_read_b128 v[214:217], v152 offset:56320
	global_load_lds_dwordx4 v[142:143], off
	v_lshl_add_u64 v[142:143], v[144:145], 0, s[12:13]
	s_mov_b32 m0, s80
	s_addc_u32 s53, s53, 0
	global_load_lds_dwordx4 v[142:143], off
	v_lshl_add_u64 v[142:143], s[52:53], 0, v[132:133]
	s_mov_b32 m0, s81
	s_nop 0
	global_load_lds_dwordx4 v[142:143], off
	v_lshl_add_u64 v[142:143], s[52:53], 0, v[136:137]
	s_mov_b32 m0, s82
	s_nop 0
	global_load_lds_dwordx4 v[142:143], off
	v_lshl_add_u64 v[142:143], v[148:149], 0, s[12:13]
	s_mov_b32 m0, s61
	s_nop 0
	global_load_lds_dwordx4 v[142:143], off
	v_lshl_add_u64 v[142:143], v[218:219], 0, s[12:13]
	s_mov_b32 m0, s62
	s_nop 0
	global_load_lds_dwordx4 v[142:143], off
	s_waitcnt vmcnt(8)
	s_waitcnt lgkmcnt(0)
	s_setprio 1
	s_barrier
	v_mfma_f32_16x16x32_bf16 v[78:81], v[154:157], v[186:189], v[78:81]
	v_mfma_f32_16x16x32_bf16 v[70:73], v[162:165], v[186:189], v[70:73]
	v_mfma_f32_16x16x32_bf16 v[46:49], v[154:157], v[194:197], v[46:49]
	v_mfma_f32_16x16x32_bf16 v[38:41], v[162:165], v[194:197], v[38:41]
	v_mfma_f32_16x16x32_bf16 v[30:33], v[154:157], v[202:205], v[30:33]
	v_mfma_f32_16x16x32_bf16 v[22:25], v[162:165], v[202:205], v[22:25]
	v_mfma_f32_16x16x32_bf16 v[14:17], v[154:157], v[210:213], v[14:17]
	v_mfma_f32_16x16x32_bf16 v[6:9], v[162:165], v[210:213], v[6:9]
	v_mfma_f32_16x16x32_bf16 v[78:81], v[158:161], v[190:193], v[78:81]
	v_mfma_f32_16x16x32_bf16 v[70:73], v[166:169], v[190:193], v[70:73]
	v_mfma_f32_16x16x32_bf16 v[46:49], v[158:161], v[198:201], v[46:49]
	v_mfma_f32_16x16x32_bf16 v[38:41], v[166:169], v[198:201], v[38:41]
	v_mfma_f32_16x16x32_bf16 v[30:33], v[158:161], v[206:209], v[30:33]
	v_mfma_f32_16x16x32_bf16 v[22:25], v[166:169], v[206:209], v[22:25]
	v_mfma_f32_16x16x32_bf16 v[14:17], v[158:161], v[214:217], v[14:17]
	v_mfma_f32_16x16x32_bf16 v[6:9], v[166:169], v[214:217], v[6:9]
	v_mfma_f32_16x16x32_bf16 v[74:77], v[170:173], v[186:189], v[74:77]
	v_mfma_f32_16x16x32_bf16 v[66:69], v[178:181], v[186:189], v[66:69]
	v_mfma_f32_16x16x32_bf16 v[42:45], v[170:173], v[194:197], v[42:45]
	v_mfma_f32_16x16x32_bf16 v[34:37], v[178:181], v[194:197], v[34:37]
	v_mfma_f32_16x16x32_bf16 v[26:29], v[170:173], v[202:205], v[26:29]
	v_mfma_f32_16x16x32_bf16 v[18:21], v[178:181], v[202:205], v[18:21]
	v_mfma_f32_16x16x32_bf16 v[10:13], v[170:173], v[210:213], v[10:13]
	v_mfma_f32_16x16x32_bf16 v[2:5], v[178:181], v[210:213], v[2:5]
	v_mfma_f32_16x16x32_bf16 v[74:77], v[174:177], v[190:193], v[74:77]
	v_mfma_f32_16x16x32_bf16 v[66:69], v[182:185], v[190:193], v[66:69]
	v_mfma_f32_16x16x32_bf16 v[42:45], v[174:177], v[198:201], v[42:45]
	v_mfma_f32_16x16x32_bf16 v[34:37], v[182:185], v[198:201], v[34:37]
	v_mfma_f32_16x16x32_bf16 v[26:29], v[174:177], v[206:209], v[26:29]
	v_mfma_f32_16x16x32_bf16 v[18:21], v[182:185], v[206:209], v[18:21]
	v_mfma_f32_16x16x32_bf16 v[10:13], v[174:177], v[214:217], v[10:13]
	v_mfma_f32_16x16x32_bf16 v[2:5], v[182:185], v[214:217], v[2:5]
	s_setprio 0
	s_barrier
	s_add_i32 s85, s85, 2
	s_add_u32 s83, s83, 0x100
	s_addc_u32 s84, s84, 0
	s_add_u32 s50, s50, 0x100
	s_addc_u32 s51, s51, 0
	s_cmp_gt_u32 s85, 61
	s_cbranch_scc0 .LBB0_1328
	s_and_b64 vcc, exec, s[14:15]
	s_cbranch_vccz .LBB0_1331
	s_barrier

.LBB0_1459:
	s_ashr_i32 s49, s48, 31
	ds_read_b128 v[2:5], v188
	ds_read_b128 v[6:9], v188 offset:1024
	ds_read_b128 v[10:13], v188 offset:2048
	ds_read_b128 v[14:17], v188 offset:3072
	ds_read_b128 v[18:21], v189
	ds_read_b128 v[22:25], v189 offset:1024
	ds_read_b128 v[26:29], v189 offset:2048
	ds_read_b128 v[30:33], v189 offset:3072
	s_lshl_b64 s[8:9], s[48:49], 20
	s_add_u32 s50, s19, s8
	s_addc_u32 s51, s24, s9
	s_and_b64 s[8:9], s[4:5], exec
	s_cselect_b32 s49, s51, s59
	s_cselect_b32 s74, s50, s58
	s_ashr_i32 s47, s46, 31
	s_lshl_b64 s[8:9], s[46:47], 20
	s_add_u32 s52, s25, s8
	s_addc_u32 s53, s26, s9
	s_and_b64 s[8:9], s[4:5], exec
	s_cselect_b32 s47, s53, s57
	s_cselect_b32 s75, s52, s56
	s_add_u32 s8, s58, 0x80080
	s_addc_u32 s9, s59, 0
	s_add_i32 s76, s55, 0xc000
	v_lshl_add_u64 v[34:35], s[8:9], 0, v[168:169]
	s_mov_b32 m0, s76
	s_add_i32 s77, s55, 0xe000
	ds_read_b128 v[38:41], v190
	ds_read_b128 v[42:45], v190 offset:1024
	ds_read_b128 v[46:49], v190 offset:2048
	ds_read_b128 v[50:53], v190 offset:3072
	ds_read_b128 v[54:57], v190 offset:4096
	ds_read_b128 v[58:61], v190 offset:5120
	ds_read_b128 v[62:65], v190 offset:6144
	ds_read_b128 v[66:69], v190 offset:7168
	global_load_lds_dwordx4 v[34:35], off
	v_lshl_add_u64 v[34:35], s[8:9], 0, v[164:165]
	s_mov_b32 m0, s77
	s_nop 0
	global_load_lds_dwordx4 v[34:35], off
	s_waitcnt vmcnt(24)
	s_waitcnt lgkmcnt(0)
	s_setprio 1
	s_barrier
	s_mov_b32 s8, 0
	s_mov_b32 s10, s8
	s_mov_b32 s11, s8
	s_mov_b32 s9, s8
	v_mov_b64_e32 v[36:37], s[10:11]
	v_mov_b64_e32 v[160:161], s[10:11]
	v_mov_b64_e32 v[156:157], s[10:11]
	v_mov_b64_e32 v[144:145], s[10:11]
	v_mov_b64_e32 v[140:141], s[10:11]
	v_mov_b64_e32 v[128:129], s[10:11]
	v_mov_b64_e32 v[120:121], s[10:11]
	v_mov_b64_e32 v[92:93], s[10:11]
	v_mov_b64_e32 v[84:85], s[10:11]
	v_mov_b64_e32 v[34:35], s[8:9]
	v_mov_b64_e32 v[158:159], s[8:9]
	v_mov_b64_e32 v[154:155], s[8:9]
	v_mov_b64_e32 v[142:143], s[8:9]
	v_mov_b64_e32 v[138:139], s[8:9]
	v_mov_b64_e32 v[126:127], s[8:9]
	v_mov_b64_e32 v[118:119], s[8:9]
	v_mov_b64_e32 v[90:91], s[8:9]
	v_mov_b64_e32 v[82:83], s[8:9]
	s_waitcnt lgkmcnt(0)
	v_mfma_f32_16x16x128_f8f6f4 v[158:161], v[2:9], v[38:45], v[158:161]
	v_mfma_f32_16x16x128_f8f6f4 v[154:157], v[10:17], v[38:45], v[154:157]
	v_mfma_f32_16x16x128_f8f6f4 v[142:145], v[2:9], v[46:53], v[142:145]
	v_mfma_f32_16x16x128_f8f6f4 v[138:141], v[10:17], v[46:53], v[138:141]
	v_mfma_f32_16x16x128_f8f6f4 v[126:129], v[2:9], v[54:61], v[126:129]
	v_mfma_f32_16x16x128_f8f6f4 v[118:121], v[10:17], v[54:61], v[118:121]
	v_mfma_f32_16x16x128_f8f6f4 v[90:93], v[2:9], v[62:69], v[90:93]
	v_mfma_f32_16x16x128_f8f6f4 v[82:85], v[10:17], v[62:69], v[82:85]
	v_mov_b64_e32 v[152:153], s[10:11]
	v_mov_b64_e32 v[148:149], s[10:11]
	v_mov_b64_e32 v[136:137], s[10:11]
	v_mov_b64_e32 v[132:133], s[10:11]
	v_mov_b64_e32 v[112:113], s[10:11]
	v_mov_b64_e32 v[108:109], s[10:11]
	v_mov_b64_e32 v[80:81], s[10:11]
	v_mov_b64_e32 v[76:77], s[10:11]
	v_mov_b64_e32 v[150:151], s[8:9]
	v_mov_b64_e32 v[146:147], s[8:9]
	v_mov_b64_e32 v[134:135], s[8:9]
	v_mov_b64_e32 v[130:131], s[8:9]
	v_mov_b64_e32 v[110:111], s[8:9]
	v_mov_b64_e32 v[106:107], s[8:9]
	v_mov_b64_e32 v[78:79], s[8:9]
	v_mov_b64_e32 v[74:75], s[8:9]
	v_mfma_f32_16x16x128_f8f6f4 v[150:153], v[18:25], v[38:45], v[150:153]
	v_mfma_f32_16x16x128_f8f6f4 v[146:149], v[26:33], v[38:45], v[146:149]
	v_mfma_f32_16x16x128_f8f6f4 v[134:137], v[18:25], v[46:53], v[134:137]
	v_mfma_f32_16x16x128_f8f6f4 v[130:133], v[26:33], v[46:53], v[130:133]
	v_mfma_f32_16x16x128_f8f6f4 v[110:113], v[18:25], v[54:61], v[110:113]
	v_mfma_f32_16x16x128_f8f6f4 v[106:109], v[26:33], v[54:61], v[106:109]
	v_mfma_f32_16x16x128_f8f6f4 v[78:81], v[18:25], v[62:69], v[78:81]
	v_mfma_f32_16x16x128_f8f6f4 v[74:77], v[26:33], v[62:69], v[74:77]
	s_setprio 0
	s_barrier
	s_add_i32 s9, s67, s27
	v_lshl_add_u64 v[178:179], s[56:57], 0, v[166:167]
	s_add_i32 s78, s9, 0x2000
	v_lshl_add_u64 v[38:39], v[178:179], 0, s[34:35]
	s_mov_b32 m0, s9
	v_lshl_add_u64 v[180:181], s[56:57], 0, v[162:163]
	s_add_u32 s10, s56, 0x80100
	ds_read_b128 v[50:53], v190 offset:16384
	ds_read_b128 v[54:57], v190 offset:17408
	ds_read_b128 v[192:195], v190 offset:18432
	ds_read_b128 v[196:199], v190 offset:19456
	ds_read_b128 v[200:203], v190 offset:20480
	ds_read_b128 v[204:207], v190 offset:21504
	ds_read_b128 v[208:211], v190 offset:22528
	ds_read_b128 v[212:215], v190 offset:23552
	global_load_lds_dwordx4 v[38:39], off
	v_lshl_add_u64 v[38:39], v[180:181], 0, s[34:35]
	s_mov_b32 m0, s78
	s_addc_u32 s11, s57, 0
	s_add_i32 s79, s68, s27
	global_load_lds_dwordx4 v[38:39], off
	v_lshl_add_u64 v[38:39], s[10:11], 0, v[166:167]
	s_mov_b32 m0, s79
	s_add_i32 s80, s79, 0x2000
	global_load_lds_dwordx4 v[38:39], off
	v_lshl_add_u64 v[38:39], s[10:11], 0, v[162:163]
	s_mov_b32 m0, s80
	v_lshl_add_u64 v[182:183], s[58:59], 0, v[168:169]
	global_load_lds_dwordx4 v[38:39], off
	v_lshl_add_u64 v[38:39], v[182:183], 0, s[34:35]
	s_mov_b32 m0, s55
	v_lshl_add_u64 v[184:185], s[58:59], 0, v[164:165]
	global_load_lds_dwordx4 v[38:39], off
	v_lshl_add_u64 v[38:39], v[184:185], 0, s[34:35]
	s_mov_b32 m0, s60
	s_nop 0
	global_load_lds_dwordx4 v[38:39], off
	s_waitcnt vmcnt(24)
	s_waitcnt lgkmcnt(0)
	s_setprio 1
	s_barrier
	v_mov_b64_e32 v[124:125], v[36:37]
	v_mov_b64_e32 v[116:117], v[36:37]
	v_mov_b64_e32 v[96:97], v[36:37]
	v_mov_b64_e32 v[88:89], v[36:37]
	v_mov_b64_e32 v[64:65], v[36:37]
	v_mov_b64_e32 v[60:61], v[36:37]
	v_mov_b64_e32 v[48:49], v[36:37]
	v_mov_b64_e32 v[44:45], v[36:37]
	v_mov_b64_e32 v[122:123], v[34:35]
	v_mov_b64_e32 v[114:115], v[34:35]
	v_mov_b64_e32 v[94:95], v[34:35]
	v_mov_b64_e32 v[86:87], v[34:35]
	v_mov_b64_e32 v[62:63], v[34:35]
	v_mov_b64_e32 v[58:59], v[34:35]
	v_mov_b64_e32 v[46:47], v[34:35]
	v_mov_b64_e32 v[42:43], v[34:35]
	s_waitcnt lgkmcnt(0)
	v_mfma_f32_16x16x128_f8f6f4 v[122:125], v[2:9], v[50:57], v[122:125]
	v_mfma_f32_16x16x128_f8f6f4 v[114:117], v[10:17], v[50:57], v[114:117]
	v_mfma_f32_16x16x128_f8f6f4 v[94:97], v[2:9], v[192:199], v[94:97]
	v_mfma_f32_16x16x128_f8f6f4 v[86:89], v[10:17], v[192:199], v[86:89]
	v_mfma_f32_16x16x128_f8f6f4 v[62:65], v[2:9], v[200:207], v[62:65]
	v_mfma_f32_16x16x128_f8f6f4 v[58:61], v[10:17], v[200:207], v[58:61]
	v_mfma_f32_16x16x128_f8f6f4 v[46:49], v[2:9], v[208:215], v[46:49]
	v_mfma_f32_16x16x128_f8f6f4 v[42:45], v[10:17], v[208:215], v[42:45]
	v_mov_b64_e32 v[104:105], v[36:37]
	v_mov_b64_e32 v[100:101], v[36:37]
	v_mov_b64_e32 v[102:103], v[34:35]
	v_mov_b64_e32 v[98:99], v[34:35]
	v_mfma_f32_16x16x128_f8f6f4 v[102:105], v[18:25], v[50:57], v[102:105]
	v_mfma_f32_16x16x128_f8f6f4 v[98:101], v[26:33], v[50:57], v[98:101]
	v_mov_b64_e32 v[72:73], v[36:37]
	v_mov_b64_e32 v[68:69], v[36:37]
	v_mov_b64_e32 v[56:57], v[36:37]
	v_mov_b64_e32 v[52:53], v[36:37]
	v_mov_b64_e32 v[40:41], v[36:37]
	v_mov_b64_e32 v[70:71], v[34:35]
	v_mov_b64_e32 v[66:67], v[34:35]
	v_mov_b64_e32 v[54:55], v[34:35]
	v_mov_b64_e32 v[50:51], v[34:35]
	v_mov_b64_e32 v[38:39], v[34:35]
	v_mfma_f32_16x16x128_f8f6f4 v[70:73], v[18:25], v[192:199], v[70:73]
	v_mfma_f32_16x16x128_f8f6f4 v[66:69], v[26:33], v[192:199], v[66:69]
	v_mfma_f32_16x16x128_f8f6f4 v[54:57], v[18:25], v[200:207], v[54:57]
	v_mfma_f32_16x16x128_f8f6f4 v[50:53], v[26:33], v[200:207], v[50:53]
	v_mfma_f32_16x16x128_f8f6f4 v[38:41], v[18:25], v[208:215], v[38:41]
	v_mfma_f32_16x16x128_f8f6f4 v[34:37], v[26:33], v[208:215], v[34:37]
	s_setprio 0
	s_barrier
	s_add_i32 s81, 0, 0x18000
	s_add_i32 s83, 0, 0x1c000
	v_add_u32_e32 v191, s81, v186
	v_add_u32_e32 v192, s83, v186
	ds_read_b128 v[18:21], v191
	ds_read_b128 v[22:25], v191 offset:1024
	ds_read_b128 v[26:29], v191 offset:2048
	ds_read_b128 v[30:33], v191 offset:3072
	ds_read_b128 v[2:5], v192
	ds_read_b128 v[6:9], v192 offset:1024
	ds_read_b128 v[10:13], v192 offset:2048
	ds_read_b128 v[14:17], v192 offset:3072
	s_add_u32 s10, s58, 0x80100
	s_addc_u32 s11, s59, 0
	s_mov_b32 m0, s61
	v_lshl_add_u64 v[226:227], s[10:11], 0, v[168:169]
	ds_read_b128 v[194:197], v190 offset:32768
	ds_read_b128 v[198:201], v190 offset:33792
	ds_read_b128 v[202:205], v190 offset:34816
	ds_read_b128 v[206:209], v190 offset:35840
	ds_read_b128 v[210:213], v190 offset:36864
	ds_read_b128 v[214:217], v190 offset:37888
	ds_read_b128 v[218:221], v190 offset:38912
	ds_read_b128 v[222:225], v190 offset:39936
	global_load_lds_dwordx4 v[226:227], off
	v_lshl_add_u64 v[226:227], s[10:11], 0, v[164:165]
	s_mov_b32 m0, s62
	s_nop 0
	global_load_lds_dwordx4 v[226:227], off
	s_waitcnt vmcnt(8)
	s_waitcnt lgkmcnt(0)
	s_setprio 1
	s_barrier
	v_mfma_f32_16x16x128_f8f6f4 v[158:161], v[18:25], v[194:201], v[158:161]
	v_mfma_f32_16x16x128_f8f6f4 v[154:157], v[26:33], v[194:201], v[154:157]
	v_mfma_f32_16x16x128_f8f6f4 v[142:145], v[18:25], v[202:209], v[142:145]
	v_mfma_f32_16x16x128_f8f6f4 v[138:141], v[26:33], v[202:209], v[138:141]
	v_mfma_f32_16x16x128_f8f6f4 v[126:129], v[18:25], v[210:217], v[126:129]
	v_mfma_f32_16x16x128_f8f6f4 v[118:121], v[26:33], v[210:217], v[118:121]
	v_mfma_f32_16x16x128_f8f6f4 v[90:93], v[18:25], v[218:225], v[90:93]
	v_mfma_f32_16x16x128_f8f6f4 v[82:85], v[26:33], v[218:225], v[82:85]
	v_mfma_f32_16x16x128_f8f6f4 v[150:153], v[2:9], v[194:201], v[150:153]
	v_mfma_f32_16x16x128_f8f6f4 v[146:149], v[10:17], v[194:201], v[146:149]
	v_mfma_f32_16x16x128_f8f6f4 v[134:137], v[2:9], v[202:209], v[134:137]
	v_mfma_f32_16x16x128_f8f6f4 v[130:133], v[10:17], v[202:209], v[130:133]
	v_mfma_f32_16x16x128_f8f6f4 v[110:113], v[2:9], v[210:217], v[110:113]
	v_mfma_f32_16x16x128_f8f6f4 v[106:109], v[10:17], v[210:217], v[106:109]
	v_mfma_f32_16x16x128_f8f6f4 v[78:81], v[2:9], v[218:225], v[78:81]
	v_mfma_f32_16x16x128_f8f6f4 v[74:77], v[10:17], v[218:225], v[74:77]
	s_setprio 0
	s_barrier
	s_add_i32 s81, s81, s27
	s_add_i32 s82, s81, 0x2000
	v_lshl_add_u64 v[178:179], v[178:179], 0, s[36:37]
	s_mov_b32 m0, s81
	s_add_u32 s10, s56, 0x80180
	ds_read_b128 v[194:197], v190 offset:49152
	ds_read_b128 v[198:201], v190 offset:50176
	ds_read_b128 v[202:205], v190 offset:51200
	ds_read_b128 v[206:209], v190 offset:52224
	ds_read_b128 v[210:213], v190 offset:53248
	ds_read_b128 v[214:217], v190 offset:54272
	ds_read_b128 v[218:221], v190 offset:55296
	ds_read_b128 v[222:225], v190 offset:56320
	global_load_lds_dwordx4 v[178:179], off
	v_lshl_add_u64 v[178:179], v[180:181], 0, s[36:37]
	s_mov_b32 m0, s82
	s_addc_u32 s11, s57, 0
	s_add_i32 s83, s83, s27
	global_load_lds_dwordx4 v[178:179], off
	v_lshl_add_u64 v[178:179], s[10:11], 0, v[166:167]
	s_mov_b32 m0, s83
	s_add_i32 s84, s83, 0x2000
	global_load_lds_dwordx4 v[178:179], off
	v_lshl_add_u64 v[178:179], s[10:11], 0, v[162:163]
	s_mov_b32 m0, s84
	s_nop 0
	global_load_lds_dwordx4 v[178:179], off
	v_lshl_add_u64 v[178:179], v[182:183], 0, s[36:37]
	s_mov_b32 m0, s64
	s_nop 0
	global_load_lds_dwordx4 v[178:179], off
	v_lshl_add_u64 v[178:179], v[184:185], 0, s[36:37]
	s_mov_b32 m0, s65
	s_nop 0
	global_load_lds_dwordx4 v[178:179], off
	s_waitcnt vmcnt(8)
	s_waitcnt lgkmcnt(0)
	s_setprio 1
	s_barrier
	v_mfma_f32_16x16x128_f8f6f4 v[122:125], v[18:25], v[194:201], v[122:125]
	v_mfma_f32_16x16x128_f8f6f4 v[114:117], v[26:33], v[194:201], v[114:117]
	v_mfma_f32_16x16x128_f8f6f4 v[94:97], v[18:25], v[202:209], v[94:97]
	v_mfma_f32_16x16x128_f8f6f4 v[86:89], v[26:33], v[202:209], v[86:89]
	v_mfma_f32_16x16x128_f8f6f4 v[62:65], v[18:25], v[210:217], v[62:65]
	v_mfma_f32_16x16x128_f8f6f4 v[58:61], v[26:33], v[210:217], v[58:61]
	v_mfma_f32_16x16x128_f8f6f4 v[46:49], v[18:25], v[218:225], v[46:49]
	v_mfma_f32_16x16x128_f8f6f4 v[42:45], v[26:33], v[218:225], v[42:45]
	v_mfma_f32_16x16x128_f8f6f4 v[102:105], v[2:9], v[194:201], v[102:105]
	v_mfma_f32_16x16x128_f8f6f4 v[98:101], v[10:17], v[194:201], v[98:101]
	v_mfma_f32_16x16x128_f8f6f4 v[70:73], v[2:9], v[202:209], v[70:73]
	v_mfma_f32_16x16x128_f8f6f4 v[66:69], v[10:17], v[202:209], v[66:69]
	v_mfma_f32_16x16x128_f8f6f4 v[54:57], v[2:9], v[210:217], v[54:57]
	v_mfma_f32_16x16x128_f8f6f4 v[50:53], v[10:17], v[210:217], v[50:53]
	v_mfma_f32_16x16x128_f8f6f4 v[38:41], v[2:9], v[218:225], v[38:41]
	v_mfma_f32_16x16x128_f8f6f4 v[34:37], v[10:17], v[218:225], v[34:37]
	s_setprio 0
	s_barrier
	s_add_u32 s85, s56, 0x200
	s_addc_u32 s86, s57, 0
	s_add_u32 s10, s58, 0x80180
	s_addc_u32 s11, s59, 0
.LBB0_1460:
	ds_read_b128 v[2:5], v188
	ds_read_b128 v[6:9], v188 offset:1024
	ds_read_b128 v[18:21], v188 offset:2048
	ds_read_b128 v[22:25], v188 offset:3072
	ds_read_b128 v[26:29], v189
	ds_read_b128 v[30:33], v189 offset:1024
	ds_read_b128 v[178:181], v189 offset:2048
	ds_read_b128 v[182:185], v189 offset:3072
	s_add_u32 s56, s10, 0xfff80080
	s_addc_u32 s57, s11, -1
	s_cmp_eq_u32 s8, 28
	s_cselect_b32 s59, s49, s57
	s_cselect_b32 s58, s74, s56
	s_cselect_b32 s57, s47, s86
	s_cselect_b32 s56, s75, s85
	s_mov_b32 m0, s76
	v_lshl_add_u64 v[218:219], s[10:11], 0, v[172:173]
	ds_read_b128 v[10:13], v190
	ds_read_b128 v[14:17], v190 offset:1024
	ds_read_b128 v[194:197], v190 offset:2048
	ds_read_b128 v[198:201], v190 offset:3072
	ds_read_b128 v[202:205], v190 offset:4096
	ds_read_b128 v[206:209], v190 offset:5120
	ds_read_b128 v[210:213], v190 offset:6144
	ds_read_b128 v[214:217], v190 offset:7168
	global_load_lds_dwordx4 v[218:219], off
	v_lshl_add_u64 v[218:219], s[10:11], 0, v[170:171]
	s_mov_b32 m0, s77
	s_nop 0
	global_load_lds_dwordx4 v[218:219], off
	s_waitcnt vmcnt(8)
	s_waitcnt lgkmcnt(0)
	s_setprio 1
	s_barrier
	v_mfma_f32_16x16x128_f8f6f4 v[158:161], v[2:9], v[10:17], v[158:161]
	v_mfma_f32_16x16x128_f8f6f4 v[154:157], v[18:25], v[10:17], v[154:157]
	v_mfma_f32_16x16x128_f8f6f4 v[142:145], v[2:9], v[194:201], v[142:145]
	v_mfma_f32_16x16x128_f8f6f4 v[138:141], v[18:25], v[194:201], v[138:141]
	v_mfma_f32_16x16x128_f8f6f4 v[126:129], v[2:9], v[202:209], v[126:129]
	v_mfma_f32_16x16x128_f8f6f4 v[118:121], v[18:25], v[202:209], v[118:121]
	v_mfma_f32_16x16x128_f8f6f4 v[90:93], v[2:9], v[210:217], v[90:93]
	v_mfma_f32_16x16x128_f8f6f4 v[82:85], v[18:25], v[210:217], v[82:85]
	v_mfma_f32_16x16x128_f8f6f4 v[150:153], v[26:33], v[10:17], v[150:153]
	v_mfma_f32_16x16x128_f8f6f4 v[146:149], v[178:185], v[10:17], v[146:149]
	v_mfma_f32_16x16x128_f8f6f4 v[134:137], v[26:33], v[194:201], v[134:137]
	v_mfma_f32_16x16x128_f8f6f4 v[130:133], v[178:185], v[194:201], v[130:133]
	v_mfma_f32_16x16x128_f8f6f4 v[110:113], v[26:33], v[202:209], v[110:113]
	v_mfma_f32_16x16x128_f8f6f4 v[106:109], v[178:185], v[202:209], v[106:109]
	v_mfma_f32_16x16x128_f8f6f4 v[78:81], v[26:33], v[210:217], v[78:81]
	v_mfma_f32_16x16x128_f8f6f4 v[74:77], v[178:185], v[210:217], v[74:77]
	s_setprio 0
	s_barrier
	s_mov_b32 m0, s9
	v_lshl_add_u64 v[10:11], s[56:57], 0, v[166:167]
	s_add_u32 s88, s56, 0x80000
	ds_read_b128 v[194:197], v190 offset:16384
	ds_read_b128 v[198:201], v190 offset:17408
	ds_read_b128 v[202:205], v190 offset:18432
	ds_read_b128 v[206:209], v190 offset:19456
	ds_read_b128 v[210:213], v190 offset:20480
	ds_read_b128 v[214:217], v190 offset:21504
	ds_read_b128 v[218:221], v190 offset:22528
	ds_read_b128 v[222:225], v190 offset:23552
	global_load_lds_dwordx4 v[10:11], off
	v_lshl_add_u64 v[12:13], s[56:57], 0, v[162:163]
	s_mov_b32 m0, s78
	s_addc_u32 s89, s57, 0
	global_load_lds_dwordx4 v[12:13], off
	v_lshl_add_u64 v[14:15], s[88:89], 0, v[166:167]
	s_mov_b32 m0, s79
	v_lshl_add_u64 v[16:17], s[58:59], 0, v[164:165]
	global_load_lds_dwordx4 v[14:15], off
	v_lshl_add_u64 v[14:15], s[88:89], 0, v[162:163]
	s_mov_b32 m0, s80
	s_nop 0
	global_load_lds_dwordx4 v[14:15], off
	v_lshl_add_u64 v[14:15], s[58:59], 0, v[168:169]
	s_mov_b32 m0, s55
	s_nop 0
	global_load_lds_dwordx4 v[14:15], off
	s_mov_b32 m0, s60
	s_nop 0
	global_load_lds_dwordx4 v[16:17], off
	s_waitcnt vmcnt(8)
	s_waitcnt lgkmcnt(0)
	s_setprio 1
	s_barrier
	v_mfma_f32_16x16x128_f8f6f4 v[122:125], v[2:9], v[194:201], v[122:125]
	v_mfma_f32_16x16x128_f8f6f4 v[114:117], v[18:25], v[194:201], v[114:117]
	v_mfma_f32_16x16x128_f8f6f4 v[94:97], v[2:9], v[202:209], v[94:97]
	v_mfma_f32_16x16x128_f8f6f4 v[86:89], v[18:25], v[202:209], v[86:89]
	v_mfma_f32_16x16x128_f8f6f4 v[62:65], v[2:9], v[210:217], v[62:65]
	v_mfma_f32_16x16x128_f8f6f4 v[58:61], v[18:25], v[210:217], v[58:61]
	v_mfma_f32_16x16x128_f8f6f4 v[46:49], v[2:9], v[218:225], v[46:49]
	v_mfma_f32_16x16x128_f8f6f4 v[42:45], v[18:25], v[218:225], v[42:45]
	v_mfma_f32_16x16x128_f8f6f4 v[102:105], v[26:33], v[194:201], v[102:105]
	v_mfma_f32_16x16x128_f8f6f4 v[98:101], v[178:185], v[194:201], v[98:101]
	v_mfma_f32_16x16x128_f8f6f4 v[70:73], v[26:33], v[202:209], v[70:73]
	v_mfma_f32_16x16x128_f8f6f4 v[66:69], v[178:185], v[202:209], v[66:69]
	v_mfma_f32_16x16x128_f8f6f4 v[54:57], v[26:33], v[210:217], v[54:57]
	v_mfma_f32_16x16x128_f8f6f4 v[50:53], v[178:185], v[210:217], v[50:53]
	v_mfma_f32_16x16x128_f8f6f4 v[38:41], v[26:33], v[218:225], v[38:41]
	v_mfma_f32_16x16x128_f8f6f4 v[34:37], v[178:185], v[218:225], v[34:37]
	s_setprio 0
	s_barrier
	ds_read_b128 v[18:21], v191
	ds_read_b128 v[22:25], v191 offset:1024
	ds_read_b128 v[26:29], v191 offset:2048
	ds_read_b128 v[30:33], v191 offset:3072
	ds_read_b128 v[2:5], v192
	ds_read_b128 v[6:9], v192 offset:1024
	ds_read_b128 v[178:181], v192 offset:2048
	ds_read_b128 v[182:185], v192 offset:3072
	s_add_u32 s58, s58, 0x80000
	s_addc_u32 s59, s59, 0
	s_mov_b32 m0, s61
	v_lshl_add_u64 v[226:227], s[58:59], 0, v[168:169]
	ds_read_b128 v[194:197], v190 offset:32768
	ds_read_b128 v[198:201], v190 offset:33792
	ds_read_b128 v[202:205], v190 offset:34816
	ds_read_b128 v[206:209], v190 offset:35840
	ds_read_b128 v[210:213], v190 offset:36864
	ds_read_b128 v[214:217], v190 offset:37888
	ds_read_b128 v[218:221], v190 offset:38912
	ds_read_b128 v[222:225], v190 offset:39936
	global_load_lds_dwordx4 v[226:227], off
	v_lshl_add_u64 v[226:227], s[58:59], 0, v[164:165]
	s_mov_b32 m0, s62
	s_nop 0
	global_load_lds_dwordx4 v[226:227], off
	s_waitcnt vmcnt(8)
	s_waitcnt lgkmcnt(0)
	s_setprio 1
	s_barrier
	v_mfma_f32_16x16x128_f8f6f4 v[158:161], v[18:25], v[194:201], v[158:161]
	v_mfma_f32_16x16x128_f8f6f4 v[154:157], v[26:33], v[194:201], v[154:157]
	v_mfma_f32_16x16x128_f8f6f4 v[142:145], v[18:25], v[202:209], v[142:145]
	v_mfma_f32_16x16x128_f8f6f4 v[138:141], v[26:33], v[202:209], v[138:141]
	v_mfma_f32_16x16x128_f8f6f4 v[126:129], v[18:25], v[210:217], v[126:129]
	v_mfma_f32_16x16x128_f8f6f4 v[118:121], v[26:33], v[210:217], v[118:121]
	v_mfma_f32_16x16x128_f8f6f4 v[90:93], v[18:25], v[218:225], v[90:93]
	v_mfma_f32_16x16x128_f8f6f4 v[82:85], v[26:33], v[218:225], v[82:85]
	v_mfma_f32_16x16x128_f8f6f4 v[150:153], v[2:9], v[194:201], v[150:153]
	v_mfma_f32_16x16x128_f8f6f4 v[146:149], v[178:185], v[194:201], v[146:149]
	v_mfma_f32_16x16x128_f8f6f4 v[134:137], v[2:9], v[202:209], v[134:137]
	v_mfma_f32_16x16x128_f8f6f4 v[130:133], v[178:185], v[202:209], v[130:133]
	v_mfma_f32_16x16x128_f8f6f4 v[110:113], v[2:9], v[210:217], v[110:113]
	v_mfma_f32_16x16x128_f8f6f4 v[106:109], v[178:185], v[210:217], v[106:109]
	v_mfma_f32_16x16x128_f8f6f4 v[78:81], v[2:9], v[218:225], v[78:81]
	v_mfma_f32_16x16x128_f8f6f4 v[74:77], v[178:185], v[218:225], v[74:77]
	s_setprio 0
	s_barrier
	s_mov_b32 m0, s81
	v_lshl_add_u64 v[10:11], v[10:11], 0, s[16:17]
	s_add_u32 s56, s56, 0x80080
	ds_read_b128 v[194:197], v190 offset:49152
	ds_read_b128 v[198:201], v190 offset:50176
	ds_read_b128 v[202:205], v190 offset:51200
	ds_read_b128 v[206:209], v190 offset:52224
	ds_read_b128 v[210:213], v190 offset:53248
	ds_read_b128 v[214:217], v190 offset:54272
	ds_read_b128 v[218:221], v190 offset:55296
	ds_read_b128 v[222:225], v190 offset:56320
	global_load_lds_dwordx4 v[10:11], off
	v_lshl_add_u64 v[10:11], v[12:13], 0, s[16:17]
	s_mov_b32 m0, s82
	s_addc_u32 s57, s57, 0
	global_load_lds_dwordx4 v[10:11], off
	v_lshl_add_u64 v[10:11], s[56:57], 0, v[166:167]
	s_mov_b32 m0, s83
	s_nop 0
	global_load_lds_dwordx4 v[10:11], off
	v_lshl_add_u64 v[10:11], s[56:57], 0, v[162:163]
	s_mov_b32 m0, s84
	s_nop 0
	global_load_lds_dwordx4 v[10:11], off
	v_lshl_add_u64 v[10:11], v[14:15], 0, s[16:17]
	s_mov_b32 m0, s64
	s_nop 0
	global_load_lds_dwordx4 v[10:11], off
	v_lshl_add_u64 v[10:11], v[16:17], 0, s[16:17]
	s_mov_b32 m0, s65
	s_nop 0
	global_load_lds_dwordx4 v[10:11], off
	s_waitcnt vmcnt(8)
	s_waitcnt lgkmcnt(0)
	s_setprio 1
	s_barrier
	v_mfma_f32_16x16x128_f8f6f4 v[122:125], v[18:25], v[194:201], v[122:125]
	v_mfma_f32_16x16x128_f8f6f4 v[114:117], v[26:33], v[194:201], v[114:117]
	v_mfma_f32_16x16x128_f8f6f4 v[94:97], v[18:25], v[202:209], v[94:97]
	v_mfma_f32_16x16x128_f8f6f4 v[86:89], v[26:33], v[202:209], v[86:89]
	v_mfma_f32_16x16x128_f8f6f4 v[62:65], v[18:25], v[210:217], v[62:65]
	v_mfma_f32_16x16x128_f8f6f4 v[58:61], v[26:33], v[210:217], v[58:61]
	v_mfma_f32_16x16x128_f8f6f4 v[46:49], v[18:25], v[218:225], v[46:49]
	v_mfma_f32_16x16x128_f8f6f4 v[42:45], v[26:33], v[218:225], v[42:45]
	v_mfma_f32_16x16x128_f8f6f4 v[102:105], v[2:9], v[194:201], v[102:105]
	v_mfma_f32_16x16x128_f8f6f4 v[98:101], v[178:185], v[194:201], v[98:101]
	v_mfma_f32_16x16x128_f8f6f4 v[70:73], v[2:9], v[202:209], v[70:73]
	v_mfma_f32_16x16x128_f8f6f4 v[66:69], v[178:185], v[202:209], v[66:69]
	v_mfma_f32_16x16x128_f8f6f4 v[54:57], v[2:9], v[210:217], v[54:57]
	v_mfma_f32_16x16x128_f8f6f4 v[50:53], v[178:185], v[210:217], v[50:53]
	v_mfma_f32_16x16x128_f8f6f4 v[38:41], v[2:9], v[218:225], v[38:41]
	v_mfma_f32_16x16x128_f8f6f4 v[34:37], v[178:185], v[218:225], v[34:37]
	s_setprio 0
	s_barrier
	s_add_i32 s8, s8, 2
	s_add_u32 s85, s85, 0x100
	s_addc_u32 s86, s86, 0
	s_add_u32 s10, s10, 0x100
	s_addc_u32 s11, s11, 0
	s_cmp_gt_u32 s8, 29
	s_cbranch_scc0 .LBB0_1460
	s_and_b64 vcc, exec, s[30:31]
	s_cbranch_vccz .LBB0_1463
	s_barrier

.LBB0_1590:
	s_ashr_i32 s49, s48, 31
	ds_read_b128 v[2:5], v188
	ds_read_b128 v[6:9], v188 offset:1024
	ds_read_b128 v[10:13], v188 offset:2048
	ds_read_b128 v[14:17], v188 offset:3072
	ds_read_b128 v[18:21], v189
	ds_read_b128 v[22:25], v189 offset:1024
	ds_read_b128 v[26:29], v189 offset:2048
	ds_read_b128 v[30:33], v189 offset:3072
	s_lshl_b64 s[8:9], s[48:49], 18
	s_add_u32 s50, s18, s8
	s_addc_u32 s51, s19, s9
	s_and_b64 s[8:9], s[4:5], exec
	s_cselect_b32 s49, s51, s59
	s_cselect_b32 s74, s50, s58
	s_ashr_i32 s47, s46, 31
	s_lshl_b64 s[8:9], s[46:47], 18
	s_add_u32 s52, s24, s8
	s_addc_u32 s53, s25, s9
	s_and_b64 s[8:9], s[4:5], exec
	s_cselect_b32 s47, s53, s57
	s_cselect_b32 s75, s52, s56
	s_add_u32 s8, s58, 0x20080
	s_addc_u32 s9, s59, 0
	s_add_i32 s76, s55, 0xc000
	v_lshl_add_u64 v[34:35], s[8:9], 0, v[168:169]
	s_mov_b32 m0, s76
	s_add_i32 s77, s55, 0xe000
	ds_read_b128 v[38:41], v190
	ds_read_b128 v[42:45], v190 offset:1024
	ds_read_b128 v[46:49], v190 offset:2048
	ds_read_b128 v[50:53], v190 offset:3072
	ds_read_b128 v[54:57], v190 offset:4096
	ds_read_b128 v[58:61], v190 offset:5120
	ds_read_b128 v[62:65], v190 offset:6144
	ds_read_b128 v[66:69], v190 offset:7168
	global_load_lds_dwordx4 v[34:35], off
	v_lshl_add_u64 v[34:35], s[8:9], 0, v[164:165]
	s_mov_b32 m0, s77
	s_nop 0
	global_load_lds_dwordx4 v[34:35], off
	s_waitcnt vmcnt(24)
	s_waitcnt lgkmcnt(0)
	s_setprio 1
	s_barrier
	s_mov_b32 s8, 0
	s_mov_b32 s10, s8
	s_mov_b32 s11, s8
	s_mov_b32 s9, s8
	v_mov_b64_e32 v[36:37], s[10:11]
	v_mov_b64_e32 v[160:161], s[10:11]
	v_mov_b64_e32 v[156:157], s[10:11]
	v_mov_b64_e32 v[144:145], s[10:11]
	v_mov_b64_e32 v[140:141], s[10:11]
	v_mov_b64_e32 v[128:129], s[10:11]
	v_mov_b64_e32 v[120:121], s[10:11]
	v_mov_b64_e32 v[92:93], s[10:11]
	v_mov_b64_e32 v[84:85], s[10:11]
	v_mov_b64_e32 v[34:35], s[8:9]
	v_mov_b64_e32 v[158:159], s[8:9]
	v_mov_b64_e32 v[154:155], s[8:9]
	v_mov_b64_e32 v[142:143], s[8:9]
	v_mov_b64_e32 v[138:139], s[8:9]
	v_mov_b64_e32 v[126:127], s[8:9]
	v_mov_b64_e32 v[118:119], s[8:9]
	v_mov_b64_e32 v[90:91], s[8:9]
	v_mov_b64_e32 v[82:83], s[8:9]
	s_waitcnt lgkmcnt(0)
	v_mfma_f32_16x16x128_f8f6f4 v[158:161], v[2:9], v[38:45], v[158:161]
	v_mfma_f32_16x16x128_f8f6f4 v[154:157], v[10:17], v[38:45], v[154:157]
	v_mfma_f32_16x16x128_f8f6f4 v[142:145], v[2:9], v[46:53], v[142:145]
	v_mfma_f32_16x16x128_f8f6f4 v[138:141], v[10:17], v[46:53], v[138:141]
	v_mfma_f32_16x16x128_f8f6f4 v[126:129], v[2:9], v[54:61], v[126:129]
	v_mfma_f32_16x16x128_f8f6f4 v[118:121], v[10:17], v[54:61], v[118:121]
	v_mfma_f32_16x16x128_f8f6f4 v[90:93], v[2:9], v[62:69], v[90:93]
	v_mfma_f32_16x16x128_f8f6f4 v[82:85], v[10:17], v[62:69], v[82:85]
	v_mov_b64_e32 v[152:153], s[10:11]
	v_mov_b64_e32 v[148:149], s[10:11]
	v_mov_b64_e32 v[136:137], s[10:11]
	v_mov_b64_e32 v[132:133], s[10:11]
	v_mov_b64_e32 v[112:113], s[10:11]
	v_mov_b64_e32 v[108:109], s[10:11]
	v_mov_b64_e32 v[80:81], s[10:11]
	v_mov_b64_e32 v[76:77], s[10:11]
	v_mov_b64_e32 v[150:151], s[8:9]
	v_mov_b64_e32 v[146:147], s[8:9]
	v_mov_b64_e32 v[134:135], s[8:9]
	v_mov_b64_e32 v[130:131], s[8:9]
	v_mov_b64_e32 v[110:111], s[8:9]
	v_mov_b64_e32 v[106:107], s[8:9]
	v_mov_b64_e32 v[78:79], s[8:9]
	v_mov_b64_e32 v[74:75], s[8:9]
	v_mfma_f32_16x16x128_f8f6f4 v[150:153], v[18:25], v[38:45], v[150:153]
	v_mfma_f32_16x16x128_f8f6f4 v[146:149], v[26:33], v[38:45], v[146:149]
	v_mfma_f32_16x16x128_f8f6f4 v[134:137], v[18:25], v[46:53], v[134:137]
	v_mfma_f32_16x16x128_f8f6f4 v[130:133], v[26:33], v[46:53], v[130:133]
	v_mfma_f32_16x16x128_f8f6f4 v[110:113], v[18:25], v[54:61], v[110:113]
	v_mfma_f32_16x16x128_f8f6f4 v[106:109], v[26:33], v[54:61], v[106:109]
	v_mfma_f32_16x16x128_f8f6f4 v[78:81], v[18:25], v[62:69], v[78:81]
	v_mfma_f32_16x16x128_f8f6f4 v[74:77], v[26:33], v[62:69], v[74:77]
	s_setprio 0
	s_barrier
	s_add_i32 s9, s67, s26
	v_lshl_add_u64 v[178:179], s[56:57], 0, v[166:167]
	s_add_i32 s78, s9, 0x2000
	v_lshl_add_u64 v[38:39], v[178:179], 0, s[30:31]
	s_mov_b32 m0, s9
	v_lshl_add_u64 v[180:181], s[56:57], 0, v[162:163]
	s_add_u32 s10, s56, 0x20100
	ds_read_b128 v[50:53], v190 offset:16384
	ds_read_b128 v[54:57], v190 offset:17408
	ds_read_b128 v[192:195], v190 offset:18432
	ds_read_b128 v[196:199], v190 offset:19456
	ds_read_b128 v[200:203], v190 offset:20480
	ds_read_b128 v[204:207], v190 offset:21504
	ds_read_b128 v[208:211], v190 offset:22528
	ds_read_b128 v[212:215], v190 offset:23552
	global_load_lds_dwordx4 v[38:39], off
	v_lshl_add_u64 v[38:39], v[180:181], 0, s[30:31]
	s_mov_b32 m0, s78
	s_addc_u32 s11, s57, 0
	s_add_i32 s79, s68, s26
	global_load_lds_dwordx4 v[38:39], off
	v_lshl_add_u64 v[38:39], s[10:11], 0, v[166:167]
	s_mov_b32 m0, s79
	s_add_i32 s80, s79, 0x2000
	global_load_lds_dwordx4 v[38:39], off
	v_lshl_add_u64 v[38:39], s[10:11], 0, v[162:163]
	s_mov_b32 m0, s80
	v_lshl_add_u64 v[182:183], s[58:59], 0, v[168:169]
	global_load_lds_dwordx4 v[38:39], off
	v_lshl_add_u64 v[38:39], v[182:183], 0, s[30:31]
	s_mov_b32 m0, s55
	v_lshl_add_u64 v[184:185], s[58:59], 0, v[164:165]
	global_load_lds_dwordx4 v[38:39], off
	v_lshl_add_u64 v[38:39], v[184:185], 0, s[30:31]
	s_mov_b32 m0, s60
	s_nop 0
	global_load_lds_dwordx4 v[38:39], off
	s_waitcnt vmcnt(24)
	s_waitcnt lgkmcnt(0)
	s_setprio 1
	s_barrier
	v_mov_b64_e32 v[124:125], v[36:37]
	v_mov_b64_e32 v[116:117], v[36:37]
	v_mov_b64_e32 v[96:97], v[36:37]
	v_mov_b64_e32 v[88:89], v[36:37]
	v_mov_b64_e32 v[64:65], v[36:37]
	v_mov_b64_e32 v[60:61], v[36:37]
	v_mov_b64_e32 v[48:49], v[36:37]
	v_mov_b64_e32 v[44:45], v[36:37]
	v_mov_b64_e32 v[122:123], v[34:35]
	v_mov_b64_e32 v[114:115], v[34:35]
	v_mov_b64_e32 v[94:95], v[34:35]
	v_mov_b64_e32 v[86:87], v[34:35]
	v_mov_b64_e32 v[62:63], v[34:35]
	v_mov_b64_e32 v[58:59], v[34:35]
	v_mov_b64_e32 v[46:47], v[34:35]
	v_mov_b64_e32 v[42:43], v[34:35]
	s_waitcnt lgkmcnt(0)
	v_mfma_f32_16x16x128_f8f6f4 v[122:125], v[2:9], v[50:57], v[122:125]
	v_mfma_f32_16x16x128_f8f6f4 v[114:117], v[10:17], v[50:57], v[114:117]
	v_mfma_f32_16x16x128_f8f6f4 v[94:97], v[2:9], v[192:199], v[94:97]
	v_mfma_f32_16x16x128_f8f6f4 v[86:89], v[10:17], v[192:199], v[86:89]
	v_mfma_f32_16x16x128_f8f6f4 v[62:65], v[2:9], v[200:207], v[62:65]
	v_mfma_f32_16x16x128_f8f6f4 v[58:61], v[10:17], v[200:207], v[58:61]
	v_mfma_f32_16x16x128_f8f6f4 v[46:49], v[2:9], v[208:215], v[46:49]
	v_mfma_f32_16x16x128_f8f6f4 v[42:45], v[10:17], v[208:215], v[42:45]
	v_mov_b64_e32 v[104:105], v[36:37]
	v_mov_b64_e32 v[100:101], v[36:37]
	v_mov_b64_e32 v[102:103], v[34:35]
	v_mov_b64_e32 v[98:99], v[34:35]
	v_mfma_f32_16x16x128_f8f6f4 v[102:105], v[18:25], v[50:57], v[102:105]
	v_mfma_f32_16x16x128_f8f6f4 v[98:101], v[26:33], v[50:57], v[98:101]
	v_mov_b64_e32 v[72:73], v[36:37]
	v_mov_b64_e32 v[68:69], v[36:37]
	v_mov_b64_e32 v[56:57], v[36:37]
	v_mov_b64_e32 v[52:53], v[36:37]
	v_mov_b64_e32 v[40:41], v[36:37]
	v_mov_b64_e32 v[70:71], v[34:35]
	v_mov_b64_e32 v[66:67], v[34:35]
	v_mov_b64_e32 v[54:55], v[34:35]
	v_mov_b64_e32 v[50:51], v[34:35]
	v_mov_b64_e32 v[38:39], v[34:35]
	v_mfma_f32_16x16x128_f8f6f4 v[70:73], v[18:25], v[192:199], v[70:73]
	v_mfma_f32_16x16x128_f8f6f4 v[66:69], v[26:33], v[192:199], v[66:69]
	v_mfma_f32_16x16x128_f8f6f4 v[54:57], v[18:25], v[200:207], v[54:57]
	v_mfma_f32_16x16x128_f8f6f4 v[50:53], v[26:33], v[200:207], v[50:53]
	v_mfma_f32_16x16x128_f8f6f4 v[38:41], v[18:25], v[208:215], v[38:41]
	v_mfma_f32_16x16x128_f8f6f4 v[34:37], v[26:33], v[208:215], v[34:37]
	s_setprio 0
	s_barrier
	s_add_i32 s81, 0, 0x18000
	s_add_i32 s83, 0, 0x1c000
	v_add_u32_e32 v191, s81, v186
	v_add_u32_e32 v192, s83, v186
	ds_read_b128 v[18:21], v191
	ds_read_b128 v[22:25], v191 offset:1024
	ds_read_b128 v[26:29], v191 offset:2048
	ds_read_b128 v[30:33], v191 offset:3072
	ds_read_b128 v[2:5], v192
	ds_read_b128 v[6:9], v192 offset:1024
	ds_read_b128 v[10:13], v192 offset:2048
	ds_read_b128 v[14:17], v192 offset:3072
	s_add_u32 s10, s58, 0x20100
	s_addc_u32 s11, s59, 0
	s_mov_b32 m0, s61
	v_lshl_add_u64 v[226:227], s[10:11], 0, v[168:169]
	ds_read_b128 v[194:197], v190 offset:32768
	ds_read_b128 v[198:201], v190 offset:33792
	ds_read_b128 v[202:205], v190 offset:34816
	ds_read_b128 v[206:209], v190 offset:35840
	ds_read_b128 v[210:213], v190 offset:36864
	ds_read_b128 v[214:217], v190 offset:37888
	ds_read_b128 v[218:221], v190 offset:38912
	ds_read_b128 v[222:225], v190 offset:39936
	global_load_lds_dwordx4 v[226:227], off
	v_lshl_add_u64 v[226:227], s[10:11], 0, v[164:165]
	s_mov_b32 m0, s62
	s_nop 0
	global_load_lds_dwordx4 v[226:227], off
	s_waitcnt vmcnt(8)
	s_waitcnt lgkmcnt(0)
	s_setprio 1
	s_barrier
	v_mfma_f32_16x16x128_f8f6f4 v[158:161], v[18:25], v[194:201], v[158:161]
	v_mfma_f32_16x16x128_f8f6f4 v[154:157], v[26:33], v[194:201], v[154:157]
	v_mfma_f32_16x16x128_f8f6f4 v[142:145], v[18:25], v[202:209], v[142:145]
	v_mfma_f32_16x16x128_f8f6f4 v[138:141], v[26:33], v[202:209], v[138:141]
	v_mfma_f32_16x16x128_f8f6f4 v[126:129], v[18:25], v[210:217], v[126:129]
	v_mfma_f32_16x16x128_f8f6f4 v[118:121], v[26:33], v[210:217], v[118:121]
	v_mfma_f32_16x16x128_f8f6f4 v[90:93], v[18:25], v[218:225], v[90:93]
	v_mfma_f32_16x16x128_f8f6f4 v[82:85], v[26:33], v[218:225], v[82:85]
	v_mfma_f32_16x16x128_f8f6f4 v[150:153], v[2:9], v[194:201], v[150:153]
	v_mfma_f32_16x16x128_f8f6f4 v[146:149], v[10:17], v[194:201], v[146:149]
	v_mfma_f32_16x16x128_f8f6f4 v[134:137], v[2:9], v[202:209], v[134:137]
	v_mfma_f32_16x16x128_f8f6f4 v[130:133], v[10:17], v[202:209], v[130:133]
	v_mfma_f32_16x16x128_f8f6f4 v[110:113], v[2:9], v[210:217], v[110:113]
	v_mfma_f32_16x16x128_f8f6f4 v[106:109], v[10:17], v[210:217], v[106:109]
	v_mfma_f32_16x16x128_f8f6f4 v[78:81], v[2:9], v[218:225], v[78:81]
	v_mfma_f32_16x16x128_f8f6f4 v[74:77], v[10:17], v[218:225], v[74:77]
	s_setprio 0
	s_barrier
	s_add_i32 s81, s81, s26
	s_add_i32 s82, s81, 0x2000
	v_lshl_add_u64 v[178:179], v[178:179], 0, s[34:35]
	s_mov_b32 m0, s81
	s_add_u32 s10, s56, 0x20180
	ds_read_b128 v[194:197], v190 offset:49152
	ds_read_b128 v[198:201], v190 offset:50176
	ds_read_b128 v[202:205], v190 offset:51200
	ds_read_b128 v[206:209], v190 offset:52224
	ds_read_b128 v[210:213], v190 offset:53248
	ds_read_b128 v[214:217], v190 offset:54272
	ds_read_b128 v[218:221], v190 offset:55296
	ds_read_b128 v[222:225], v190 offset:56320
	global_load_lds_dwordx4 v[178:179], off
	v_lshl_add_u64 v[178:179], v[180:181], 0, s[34:35]
	s_mov_b32 m0, s82
	s_addc_u32 s11, s57, 0
	s_add_i32 s83, s83, s26
	global_load_lds_dwordx4 v[178:179], off
	v_lshl_add_u64 v[178:179], s[10:11], 0, v[166:167]
	s_mov_b32 m0, s83
	s_add_i32 s84, s83, 0x2000
	global_load_lds_dwordx4 v[178:179], off
	v_lshl_add_u64 v[178:179], s[10:11], 0, v[162:163]
	s_mov_b32 m0, s84
	s_nop 0
	global_load_lds_dwordx4 v[178:179], off
	v_lshl_add_u64 v[178:179], v[182:183], 0, s[34:35]
	s_mov_b32 m0, s64
	s_nop 0
	global_load_lds_dwordx4 v[178:179], off
	v_lshl_add_u64 v[178:179], v[184:185], 0, s[34:35]
	s_mov_b32 m0, s65
	s_nop 0
	global_load_lds_dwordx4 v[178:179], off
	s_waitcnt vmcnt(8)
	s_waitcnt lgkmcnt(0)
	s_setprio 1
	s_barrier
	v_mfma_f32_16x16x128_f8f6f4 v[122:125], v[18:25], v[194:201], v[122:125]
	v_mfma_f32_16x16x128_f8f6f4 v[114:117], v[26:33], v[194:201], v[114:117]
	v_mfma_f32_16x16x128_f8f6f4 v[94:97], v[18:25], v[202:209], v[94:97]
	v_mfma_f32_16x16x128_f8f6f4 v[86:89], v[26:33], v[202:209], v[86:89]
	v_mfma_f32_16x16x128_f8f6f4 v[62:65], v[18:25], v[210:217], v[62:65]
	v_mfma_f32_16x16x128_f8f6f4 v[58:61], v[26:33], v[210:217], v[58:61]
	v_mfma_f32_16x16x128_f8f6f4 v[46:49], v[18:25], v[218:225], v[46:49]
	v_mfma_f32_16x16x128_f8f6f4 v[42:45], v[26:33], v[218:225], v[42:45]
	v_mfma_f32_16x16x128_f8f6f4 v[102:105], v[2:9], v[194:201], v[102:105]
	v_mfma_f32_16x16x128_f8f6f4 v[98:101], v[10:17], v[194:201], v[98:101]
	v_mfma_f32_16x16x128_f8f6f4 v[70:73], v[2:9], v[202:209], v[70:73]
	v_mfma_f32_16x16x128_f8f6f4 v[66:69], v[10:17], v[202:209], v[66:69]
	v_mfma_f32_16x16x128_f8f6f4 v[54:57], v[2:9], v[210:217], v[54:57]
	v_mfma_f32_16x16x128_f8f6f4 v[50:53], v[10:17], v[210:217], v[50:53]
	v_mfma_f32_16x16x128_f8f6f4 v[38:41], v[2:9], v[218:225], v[38:41]
	v_mfma_f32_16x16x128_f8f6f4 v[34:37], v[10:17], v[218:225], v[34:37]
	s_setprio 0
	s_barrier
	s_add_u32 s85, s56, 0x200
	s_addc_u32 s86, s57, 0
	s_add_u32 s10, s58, 0x20180
	s_addc_u32 s11, s59, 0
.LBB0_1591:
	ds_read_b128 v[2:5], v188
	ds_read_b128 v[6:9], v188 offset:1024
	ds_read_b128 v[18:21], v188 offset:2048
	ds_read_b128 v[22:25], v188 offset:3072
	ds_read_b128 v[26:29], v189
	ds_read_b128 v[30:33], v189 offset:1024
	ds_read_b128 v[178:181], v189 offset:2048
	ds_read_b128 v[182:185], v189 offset:3072
	s_add_u32 s56, s10, 0xfffe0080
	s_addc_u32 s57, s11, -1
	s_cmp_eq_u32 s8, 4
	s_cselect_b32 s59, s49, s57
	s_cselect_b32 s58, s74, s56
	s_cselect_b32 s57, s47, s86
	s_cselect_b32 s56, s75, s85
	s_mov_b32 m0, s76
	v_lshl_add_u64 v[218:219], s[10:11], 0, v[172:173]
	ds_read_b128 v[10:13], v190
	ds_read_b128 v[14:17], v190 offset:1024
	ds_read_b128 v[194:197], v190 offset:2048
	ds_read_b128 v[198:201], v190 offset:3072
	ds_read_b128 v[202:205], v190 offset:4096
	ds_read_b128 v[206:209], v190 offset:5120
	ds_read_b128 v[210:213], v190 offset:6144
	ds_read_b128 v[214:217], v190 offset:7168
	global_load_lds_dwordx4 v[218:219], off
	v_lshl_add_u64 v[218:219], s[10:11], 0, v[170:171]
	s_mov_b32 m0, s77
	s_nop 0
	global_load_lds_dwordx4 v[218:219], off
	s_waitcnt vmcnt(8)
	s_waitcnt lgkmcnt(0)
	s_setprio 1
	s_barrier
	v_mfma_f32_16x16x128_f8f6f4 v[158:161], v[2:9], v[10:17], v[158:161]
	v_mfma_f32_16x16x128_f8f6f4 v[154:157], v[18:25], v[10:17], v[154:157]
	v_mfma_f32_16x16x128_f8f6f4 v[142:145], v[2:9], v[194:201], v[142:145]
	v_mfma_f32_16x16x128_f8f6f4 v[138:141], v[18:25], v[194:201], v[138:141]
	v_mfma_f32_16x16x128_f8f6f4 v[126:129], v[2:9], v[202:209], v[126:129]
	v_mfma_f32_16x16x128_f8f6f4 v[118:121], v[18:25], v[202:209], v[118:121]
	v_mfma_f32_16x16x128_f8f6f4 v[90:93], v[2:9], v[210:217], v[90:93]
	v_mfma_f32_16x16x128_f8f6f4 v[82:85], v[18:25], v[210:217], v[82:85]
	v_mfma_f32_16x16x128_f8f6f4 v[150:153], v[26:33], v[10:17], v[150:153]
	v_mfma_f32_16x16x128_f8f6f4 v[146:149], v[178:185], v[10:17], v[146:149]
	v_mfma_f32_16x16x128_f8f6f4 v[134:137], v[26:33], v[194:201], v[134:137]
	v_mfma_f32_16x16x128_f8f6f4 v[130:133], v[178:185], v[194:201], v[130:133]
	v_mfma_f32_16x16x128_f8f6f4 v[110:113], v[26:33], v[202:209], v[110:113]
	v_mfma_f32_16x16x128_f8f6f4 v[106:109], v[178:185], v[202:209], v[106:109]
	v_mfma_f32_16x16x128_f8f6f4 v[78:81], v[26:33], v[210:217], v[78:81]
	v_mfma_f32_16x16x128_f8f6f4 v[74:77], v[178:185], v[210:217], v[74:77]
	s_setprio 0
	s_barrier
	s_mov_b32 m0, s9
	v_lshl_add_u64 v[10:11], s[56:57], 0, v[166:167]
	s_add_u32 s88, s56, 0x20000
	ds_read_b128 v[194:197], v190 offset:16384
	ds_read_b128 v[198:201], v190 offset:17408
	ds_read_b128 v[202:205], v190 offset:18432
	ds_read_b128 v[206:209], v190 offset:19456
	ds_read_b128 v[210:213], v190 offset:20480
	ds_read_b128 v[214:217], v190 offset:21504
	ds_read_b128 v[218:221], v190 offset:22528
	ds_read_b128 v[222:225], v190 offset:23552
	global_load_lds_dwordx4 v[10:11], off
	v_lshl_add_u64 v[12:13], s[56:57], 0, v[162:163]
	s_mov_b32 m0, s78
	s_addc_u32 s89, s57, 0
	global_load_lds_dwordx4 v[12:13], off
	v_lshl_add_u64 v[14:15], s[88:89], 0, v[166:167]
	s_mov_b32 m0, s79
	v_lshl_add_u64 v[16:17], s[58:59], 0, v[164:165]
	global_load_lds_dwordx4 v[14:15], off
	v_lshl_add_u64 v[14:15], s[88:89], 0, v[162:163]
	s_mov_b32 m0, s80
	s_nop 0
	global_load_lds_dwordx4 v[14:15], off
	v_lshl_add_u64 v[14:15], s[58:59], 0, v[168:169]
	s_mov_b32 m0, s55
	s_nop 0
	global_load_lds_dwordx4 v[14:15], off
	s_mov_b32 m0, s60
	s_nop 0
	global_load_lds_dwordx4 v[16:17], off
	s_waitcnt vmcnt(8)
	s_waitcnt lgkmcnt(0)
	s_setprio 1
	s_barrier
	v_mfma_f32_16x16x128_f8f6f4 v[122:125], v[2:9], v[194:201], v[122:125]
	v_mfma_f32_16x16x128_f8f6f4 v[114:117], v[18:25], v[194:201], v[114:117]
	v_mfma_f32_16x16x128_f8f6f4 v[94:97], v[2:9], v[202:209], v[94:97]
	v_mfma_f32_16x16x128_f8f6f4 v[86:89], v[18:25], v[202:209], v[86:89]
	v_mfma_f32_16x16x128_f8f6f4 v[62:65], v[2:9], v[210:217], v[62:65]
	v_mfma_f32_16x16x128_f8f6f4 v[58:61], v[18:25], v[210:217], v[58:61]
	v_mfma_f32_16x16x128_f8f6f4 v[46:49], v[2:9], v[218:225], v[46:49]
	v_mfma_f32_16x16x128_f8f6f4 v[42:45], v[18:25], v[218:225], v[42:45]
	v_mfma_f32_16x16x128_f8f6f4 v[102:105], v[26:33], v[194:201], v[102:105]
	v_mfma_f32_16x16x128_f8f6f4 v[98:101], v[178:185], v[194:201], v[98:101]
	v_mfma_f32_16x16x128_f8f6f4 v[70:73], v[26:33], v[202:209], v[70:73]
	v_mfma_f32_16x16x128_f8f6f4 v[66:69], v[178:185], v[202:209], v[66:69]
	v_mfma_f32_16x16x128_f8f6f4 v[54:57], v[26:33], v[210:217], v[54:57]
	v_mfma_f32_16x16x128_f8f6f4 v[50:53], v[178:185], v[210:217], v[50:53]
	v_mfma_f32_16x16x128_f8f6f4 v[38:41], v[26:33], v[218:225], v[38:41]
	v_mfma_f32_16x16x128_f8f6f4 v[34:37], v[178:185], v[218:225], v[34:37]
	s_setprio 0
	s_barrier
	ds_read_b128 v[18:21], v191
	ds_read_b128 v[22:25], v191 offset:1024
	ds_read_b128 v[26:29], v191 offset:2048
	ds_read_b128 v[30:33], v191 offset:3072
	ds_read_b128 v[2:5], v192
	ds_read_b128 v[6:9], v192 offset:1024
	ds_read_b128 v[178:181], v192 offset:2048
	ds_read_b128 v[182:185], v192 offset:3072
	s_add_u32 s58, s58, 0x20000
	s_addc_u32 s59, s59, 0
	s_mov_b32 m0, s61
	v_lshl_add_u64 v[226:227], s[58:59], 0, v[168:169]
	ds_read_b128 v[194:197], v190 offset:32768
	ds_read_b128 v[198:201], v190 offset:33792
	ds_read_b128 v[202:205], v190 offset:34816
	ds_read_b128 v[206:209], v190 offset:35840
	ds_read_b128 v[210:213], v190 offset:36864
	ds_read_b128 v[214:217], v190 offset:37888
	ds_read_b128 v[218:221], v190 offset:38912
	ds_read_b128 v[222:225], v190 offset:39936
	global_load_lds_dwordx4 v[226:227], off
	v_lshl_add_u64 v[226:227], s[58:59], 0, v[164:165]
	s_mov_b32 m0, s62
	s_nop 0
	global_load_lds_dwordx4 v[226:227], off
	s_waitcnt vmcnt(8)
	s_waitcnt lgkmcnt(0)
	s_setprio 1
	s_barrier
	v_mfma_f32_16x16x128_f8f6f4 v[158:161], v[18:25], v[194:201], v[158:161]
	v_mfma_f32_16x16x128_f8f6f4 v[154:157], v[26:33], v[194:201], v[154:157]
	v_mfma_f32_16x16x128_f8f6f4 v[142:145], v[18:25], v[202:209], v[142:145]
	v_mfma_f32_16x16x128_f8f6f4 v[138:141], v[26:33], v[202:209], v[138:141]
	v_mfma_f32_16x16x128_f8f6f4 v[126:129], v[18:25], v[210:217], v[126:129]
	v_mfma_f32_16x16x128_f8f6f4 v[118:121], v[26:33], v[210:217], v[118:121]
	v_mfma_f32_16x16x128_f8f6f4 v[90:93], v[18:25], v[218:225], v[90:93]
	v_mfma_f32_16x16x128_f8f6f4 v[82:85], v[26:33], v[218:225], v[82:85]
	v_mfma_f32_16x16x128_f8f6f4 v[150:153], v[2:9], v[194:201], v[150:153]
	v_mfma_f32_16x16x128_f8f6f4 v[146:149], v[178:185], v[194:201], v[146:149]
	v_mfma_f32_16x16x128_f8f6f4 v[134:137], v[2:9], v[202:209], v[134:137]
	v_mfma_f32_16x16x128_f8f6f4 v[130:133], v[178:185], v[202:209], v[130:133]
	v_mfma_f32_16x16x128_f8f6f4 v[110:113], v[2:9], v[210:217], v[110:113]
	v_mfma_f32_16x16x128_f8f6f4 v[106:109], v[178:185], v[210:217], v[106:109]
	v_mfma_f32_16x16x128_f8f6f4 v[78:81], v[2:9], v[218:225], v[78:81]
	v_mfma_f32_16x16x128_f8f6f4 v[74:77], v[178:185], v[218:225], v[74:77]
	s_setprio 0
	s_barrier
	s_mov_b32 m0, s81
	v_lshl_add_u64 v[10:11], v[10:11], 0, s[14:15]
	s_add_u32 s56, s56, 0x20080
	ds_read_b128 v[194:197], v190 offset:49152
	ds_read_b128 v[198:201], v190 offset:50176
	ds_read_b128 v[202:205], v190 offset:51200
	ds_read_b128 v[206:209], v190 offset:52224
	ds_read_b128 v[210:213], v190 offset:53248
	ds_read_b128 v[214:217], v190 offset:54272
	ds_read_b128 v[218:221], v190 offset:55296
	ds_read_b128 v[222:225], v190 offset:56320
	global_load_lds_dwordx4 v[10:11], off
	v_lshl_add_u64 v[10:11], v[12:13], 0, s[14:15]
	s_mov_b32 m0, s82
	s_addc_u32 s57, s57, 0
	global_load_lds_dwordx4 v[10:11], off
	v_lshl_add_u64 v[10:11], s[56:57], 0, v[166:167]
	s_mov_b32 m0, s83
	s_nop 0
	global_load_lds_dwordx4 v[10:11], off
	v_lshl_add_u64 v[10:11], s[56:57], 0, v[162:163]
	s_mov_b32 m0, s84
	s_nop 0
	global_load_lds_dwordx4 v[10:11], off
	v_lshl_add_u64 v[10:11], v[14:15], 0, s[14:15]
	s_mov_b32 m0, s64
	s_nop 0
	global_load_lds_dwordx4 v[10:11], off
	v_lshl_add_u64 v[10:11], v[16:17], 0, s[14:15]
	s_mov_b32 m0, s65
	s_nop 0
	global_load_lds_dwordx4 v[10:11], off
	s_waitcnt vmcnt(8)
	s_waitcnt lgkmcnt(0)
	s_setprio 1
	s_barrier
	v_mfma_f32_16x16x128_f8f6f4 v[122:125], v[18:25], v[194:201], v[122:125]
	v_mfma_f32_16x16x128_f8f6f4 v[114:117], v[26:33], v[194:201], v[114:117]
	v_mfma_f32_16x16x128_f8f6f4 v[94:97], v[18:25], v[202:209], v[94:97]
	v_mfma_f32_16x16x128_f8f6f4 v[86:89], v[26:33], v[202:209], v[86:89]
	v_mfma_f32_16x16x128_f8f6f4 v[62:65], v[18:25], v[210:217], v[62:65]
	v_mfma_f32_16x16x128_f8f6f4 v[58:61], v[26:33], v[210:217], v[58:61]
	v_mfma_f32_16x16x128_f8f6f4 v[46:49], v[18:25], v[218:225], v[46:49]
	v_mfma_f32_16x16x128_f8f6f4 v[42:45], v[26:33], v[218:225], v[42:45]
	v_mfma_f32_16x16x128_f8f6f4 v[102:105], v[2:9], v[194:201], v[102:105]
	v_mfma_f32_16x16x128_f8f6f4 v[98:101], v[178:185], v[194:201], v[98:101]
	v_mfma_f32_16x16x128_f8f6f4 v[70:73], v[2:9], v[202:209], v[70:73]
	v_mfma_f32_16x16x128_f8f6f4 v[66:69], v[178:185], v[202:209], v[66:69]
	v_mfma_f32_16x16x128_f8f6f4 v[54:57], v[2:9], v[210:217], v[54:57]
	v_mfma_f32_16x16x128_f8f6f4 v[50:53], v[178:185], v[210:217], v[50:53]
	v_mfma_f32_16x16x128_f8f6f4 v[38:41], v[2:9], v[218:225], v[38:41]
	v_mfma_f32_16x16x128_f8f6f4 v[34:37], v[178:185], v[218:225], v[34:37]
	s_setprio 0
	s_barrier
	s_add_i32 s8, s8, 2
	s_add_u32 s85, s85, 0x100
	s_addc_u32 s86, s86, 0
	s_add_u32 s10, s10, 0x100
	s_addc_u32 s11, s11, 0
	s_cmp_gt_u32 s8, 5
	s_cbranch_scc0 .LBB0_1591
	s_and_b64 vcc, exec, s[16:17]
	s_cbranch_vccz .LBB0_1594
	s_barrier
